# speedup vs baseline: 1.0084x; 1.0084x over previous
; #define hw_tid() ((g_wid << 6) | hw_lane())
; #define STA(P, br, kt) STAGE(P, A, aoff0, aoff1, lda, br, kt)
; #define STB(P, br, kt) STAGE(P, Bt, boff0, boff1, ldb, br, kt)
; #define BAR __builtin_amdgcn_s_barrier()
; __device__ __forceinline__ void gemm256(const u16* __restrict__ A, int lda, const u16* __restrict__ Bt, int ldb, int K,
;                                         f32x4 (&acc)[2][2][4][2], const int g_wid) {
;   int tid = hw_tid(); asm volatile("" : "+v"(tid));
;   const int wid = tid >> 6, lane = tid & 63, wr = wid >> 2, wc = wid & 3, fr = lane & 15, fq = lane >> 4;
;   int r0, c0, r1, c1;
;   stage_rc(tid * 16, r0, c0);
;   stage_rc(tid * 16 + 8192, r1, c1);
;   const int aoff0 = r0 * lda + c0, aoff1 = r1 * lda + c1, boff0 = r0 * ldb + c0, boff1 = r1 * ldb + c1;
;   bf16x8 At[4][2], B0[2][2], B1[2][2];
;   const int nt = K / BK;
;   STB(SB(0, 0), 0, 0); STA(SA(0, 0), 0, 0);
;   STB(SB(0, 1), HALF, 0); STA(SA(0, 1), HALF, 0);
;   if (wr == 1) BAR;
.LBB0_106:
	s_mov_b32 s36, -1
	s_lshl_b32 s34, s21, 10
	v_mbcnt_lo_u32_b32 v0, s36, 0
	v_mbcnt_hi_u32_b32 v0, s36, v0
	v_or_b32_e32 v0, s37, v0
	s_add_i32 s34, s23, s34
	v_ashrrev_i32_e32 v2, 31, v0
	v_lshrrev_b32_e32 v2, 26, v2
	v_add_u32_e32 v2, v0, v2
	v_ashrrev_i32_e32 v10, 6, v2
	v_bfe_i32 v2, v0, 27, 1
	v_lshlrev_b32_e32 v16, 4, v0
	v_lshrrev_b32_e32 v2, 22, v2
	v_add_u32_e32 v2, v16, v2
	v_and_b32_e32 v2, 0xfffffc00, v2
	v_sub_u32_e32 v2, v16, v2
	v_lshrrev_b32_e32 v3, 4, v2
	v_bitop3_b32 v2, v3, v2, 32 bitop3:0x6c
	v_ashrrev_i32_e32 v4, 31, v2
	v_lshrrev_b32_e32 v4, 26, v4
	v_add_u32_e32 v4, v2, v4
	v_ashrrev_i32_e32 v12, 6, v4
	v_and_b32_e32 v4, 0xc0, v4
	v_sub_u32_e32 v2, v2, v4
	v_ashrrev_i16_sdwa v14, v151, sext(v2) dst_sel:DWORD dst_unused:UNUSED_PAD src0_sel:DWORD src1_sel:BYTE_0
	v_add_u32_e32 v2, 0x2000, v16
	v_ashrrev_i32_e32 v4, 31, v2
	v_lshrrev_b32_e32 v4, 22, v4
	v_add_u32_e32 v4, v2, v4
	v_ashrrev_i32_e32 v15, 10, v4
	v_mul_i32_i24_e32 v4, 0x400, v15
	v_sub_u32_e32 v2, v2, v4
	v_lshrrev_b32_e32 v4, 4, v2
	v_lshlrev_b32_e32 v5, 5, v10
	v_bitop3_b32 v2, v4, v2, 32 bitop3:0x6c
	v_and_b32_e32 v13, 32, v5
	v_ashrrev_i32_e32 v5, 31, v2
	v_lshrrev_b32_e32 v5, 26, v5
	v_lshlrev_b32_e32 v3, 3, v10
	v_add_u32_e32 v5, v2, v5
	v_and_b32_e32 v3, 0x3ffff0, v3
	v_lshlrev_b32_e32 v4, 3, v15
	v_ashrrev_i32_e32 v17, 6, v5
	v_and_b32_e32 v5, 0xc0, v5
	v_add_u32_e32 v3, v12, v3
	v_and_b32_e32 v4, 0x3ffff0, v4
	v_lshlrev_b32_e32 v6, 5, v15
	v_sub_u32_e32 v2, v2, v5
	v_add_u32_e32 v4, v17, v4
	v_and_b32_e32 v18, 32, v6
	v_ashrrev_i16_sdwa v19, v151, sext(v2) dst_sel:DWORD dst_unused:UNUSED_PAD src0_sel:DWORD src1_sel:BYTE_0
	v_lshl_or_b32 v2, v3, 10, v13
	v_add_u32_sdwa v132, v2, sext(v14) dst_sel:DWORD dst_unused:UNUSED_PAD src0_sel:DWORD src1_sel:WORD_0
	v_lshl_or_b32 v2, v4, 10, v18
	v_readlane_b32 s10, v254, 40
	s_ashr_i32 s35, s34, 31
	v_add_u32_sdwa v130, v2, sext(v19) dst_sel:DWORD dst_unused:UNUSED_PAD src0_sel:DWORD src1_sel:WORD_0
	v_ashrrev_i32_e32 v133, 31, v132
	v_add_u32_e32 v161, s10, v16
	s_lshl_b64 s[34:35], s[34:35], 11
	v_lshlrev_b64 v[20:21], 1, v[132:133]
	v_readfirstlane_b32 s36, v161
	v_ashrrev_i32_e32 v131, 31, v130
	v_add_u32_e32 v162, 0x2000, v161
	s_add_u32 s34, s4, s34
	v_lshl_add_u64 v[2:3], s[24:25], 0, v[20:21]
	s_mov_b32 m0, s36
	v_lshlrev_b64 v[22:23], 1, v[130:131]
	v_readfirstlane_b32 s36, v162
	v_add_u32_e32 v163, 0, v16
	s_addc_u32 s35, s5, s35
	global_load_lds_dwordx4 v[2:3], off
	v_lshl_add_u64 v[6:7], s[24:25], 0, v[22:23]
	s_mov_b32 m0, s36
	v_readfirstlane_b32 s36, v163
	v_add_u32_e32 v164, 0x2000, v163
	v_readlane_b32 s10, v254, 41
	global_load_lds_dwordx4 v[6:7], off
	v_lshl_add_u64 v[8:9], s[34:35], 0, v[20:21]
	s_mov_b32 m0, s36
	v_readfirstlane_b32 s36, v164
	v_add_u32_e32 v165, s10, v16
	global_load_lds_dwordx4 v[8:9], off
	v_lshl_add_u64 v[4:5], s[34:35], 0, v[22:23]
	s_mov_b32 m0, s36
	v_readfirstlane_b32 s36, v165
	v_add_u32_e32 v166, 0x2000, v165
	global_load_lds_dwordx4 v[4:5], off
	v_lshl_add_u64 v[24:25], s[26:27], 0, v[20:21]
	s_mov_b32 m0, s36
	v_readfirstlane_b32 s36, v166
	global_load_lds_dwordx4 v[24:25], off
	s_mov_b32 m0, s36
	s_add_u32 s36, s34, 0x40000
	v_add_u32_e32 v168, 0x4000, v163
	v_lshl_add_u64 v[24:25], s[26:27], 0, v[22:23]
	s_addc_u32 s37, s35, 0
	v_readfirstlane_b32 s54, v168
	global_load_lds_dwordx4 v[24:25], off
	v_lshl_add_u64 v[20:21], s[36:37], 0, v[20:21]
	s_mov_b32 m0, s54
	v_add_u32_e32 v169, 0x6000, v163
	global_load_lds_dwordx4 v[20:21], off
	v_lshl_add_u64 v[20:21], s[36:37], 0, v[22:23]
	v_readfirstlane_b32 s36, v169
	s_mov_b32 m0, s36
	v_ashrrev_i32_e32 v11, 8, v0
	global_load_lds_dwordx4 v[20:21], off
	v_cmp_eq_u32_e32 vcc, 1, v11
	s_and_saveexec_b64 s[36:37], vcc
	s_cbranch_execz .LBB0_108
	s_setprio 3
	s_barrier

; #define STA(P, br, kt) STAGE(P, A, aoff0, aoff1, lda, br, kt)
; #define STB(P, br, kt) STAGE(P, Bt, boff0, boff1, ldb, br, kt)
; #define LDA(dst, b, h) _Pragma("unroll") for (int m = 0; m < 4; ++m) _Pragma("unroll") for (int k = 0; k < 2; ++k) \
;     dst[m][k] = *reinterpret_cast<const bf16x8*>((char*)SA(b, h) + lds_byte(wr * 64 + m * 16 + fr, k * 32 + fq * 8))
; #define LDB(dst, b, h) _Pragma("unroll") for (int n = 0; n < 2; ++n) _Pragma("unroll") for (int k = 0; k < 2; ++k) \
;     dst[n][k] = *reinterpret_cast<const bf16x8*>((char*)SB(b, h) + lds_byte(wc * 32 + n * 16 + fr, k * 32 + fq * 8))
; #define MMA(ai, bj, At, Bq) do { __builtin_amdgcn_s_setprio(1); \
;     _Pragma("unroll") for (int m = 0; m < 4; ++m) _Pragma("unroll") for (int n = 0; n < 2; ++n) _Pragma("unroll") for (int k = 0; k < 2; ++k) \
;       acc[ai][bj][m][n] = __builtin_amdgcn_mfma_f32_16x16x32_bf16(At[m][k], Bq[n][k], acc[ai][bj][m][n], 0, 0, 0); \
;     __builtin_amdgcn_s_setprio(0); } while (0)
; #define WAIT_L(n) asm volatile("s_waitcnt lgkmcnt(" #n ")" ::: "memory")
; #define BAR __builtin_amdgcn_s_barrier()
; #define SCHED __builtin_amdgcn_sched_barrier(0)
; __device__ __forceinline__ void gemm256(const u16* __restrict__ A, int lda, const u16* __restrict__ Bt, int ldb, int K,
;                                         f32x4 (&acc)[2][2][4][2], const int g_wid) {
;     ...
;     LDB(B0, 0, 0); SCHED; LDA(At, 0, 0); STA(SA(1, 1), HALF, t + 1);
;     WAIT_L(8); BAR; WAIT_L(0); MMA(0, 0, At, B0); BAR; SCHED;
;     LDB(B1, 0, 1); STB(SB(0, 0), 0, t + 2);
;     BAR; WAIT_L(0); MMA(0, 1, At, B1); BAR;
;     LDA(At, 0, 1); STA(SA(0, 0), 0, t + 2);
;     BAR; WAIT_L(0); MMA(1, 0, At, B0); BAR; SCHED;
.LBB0_109:
	ds_read_b128 v[180:183], v177
	ds_read_b128 v[184:187], v177 offset:1024
	ds_read_b128 v[188:191], v177 offset:2048
	ds_read_b128 v[192:195], v177 offset:3072
	v_add_u32_e32 v178, 0xc000, v163
	v_lshl_add_u64 v[244:245], v[142:143], 0, s[36:37]
	v_readfirstlane_b32 s10, v178
	v_add_u32_e32 v179, 0xe000, v163
	v_lshl_add_u64 v[228:229], v[244:245], 0, s[72:73]
	s_mov_b32 m0, s10
	v_lshl_add_u64 v[246:247], v[138:139], 0, s[36:37]
	v_readfirstlane_b32 s10, v179
	ds_read_b128 v[196:199], v159
	ds_read_b128 v[200:203], v159 offset:1024
	ds_read_b128 v[204:207], v147
	ds_read_b128 v[208:211], v147 offset:1024
	ds_read_b128 v[212:215], v146
	ds_read_b128 v[216:219], v146 offset:1024
	ds_read_b128 v[220:223], v145
	ds_read_b128 v[224:227], v145 offset:1024
	global_load_lds_dwordx4 v[228:229], off
	v_lshl_add_u64 v[228:229], v[246:247], 0, s[72:73]
	s_mov_b32 m0, s10
	s_nop 0
	global_load_lds_dwordx4 v[228:229], off
	s_waitcnt lgkmcnt(8)
	s_barrier
	s_waitcnt lgkmcnt(0)
	v_mfma_f32_16x16x32_bf16 v[126:129], v[196:199], v[180:183], v[126:129]
	v_mfma_f32_16x16x32_bf16 v[122:125], v[196:199], v[188:191], v[122:125]
	v_mfma_f32_16x16x32_bf16 v[118:121], v[204:207], v[180:183], v[118:121]
	v_mfma_f32_16x16x32_bf16 v[114:117], v[204:207], v[188:191], v[114:117]
	v_mfma_f32_16x16x32_bf16 v[110:113], v[212:215], v[180:183], v[110:113]
	v_mfma_f32_16x16x32_bf16 v[106:109], v[212:215], v[188:191], v[106:109]
	v_mfma_f32_16x16x32_bf16 v[102:105], v[220:223], v[180:183], v[102:105]
	v_mfma_f32_16x16x32_bf16 v[98:101], v[220:223], v[188:191], v[98:101]
	v_mfma_f32_16x16x32_bf16 v[126:129], v[200:203], v[184:187], v[126:129]
	v_mfma_f32_16x16x32_bf16 v[122:125], v[200:203], v[192:195], v[122:125]
	v_mfma_f32_16x16x32_bf16 v[118:121], v[208:211], v[184:187], v[118:121]
	v_mfma_f32_16x16x32_bf16 v[114:117], v[208:211], v[192:195], v[114:117]
	v_mfma_f32_16x16x32_bf16 v[110:113], v[216:219], v[184:187], v[110:113]
	v_mfma_f32_16x16x32_bf16 v[106:109], v[216:219], v[192:195], v[106:109]
	v_mfma_f32_16x16x32_bf16 v[102:105], v[224:227], v[184:187], v[102:105]
	v_mfma_f32_16x16x32_bf16 v[98:101], v[224:227], v[192:195], v[98:101]
	s_barrier
	v_lshl_add_u64 v[248:249], v[136:137], 0, s[36:37]
	v_readfirstlane_b32 s10, v161
	v_lshl_add_u64 v[250:251], v[248:249], 0, s[74:75]
	s_mov_b32 m0, s10
	ds_read_b128 v[228:231], v176
	ds_read_b128 v[232:235], v176 offset:1024
	ds_read_b128 v[236:239], v176 offset:2048
	ds_read_b128 v[240:243], v176 offset:3072
	global_load_lds_dwordx4 v[250:251], off
	v_lshl_add_u64 v[250:251], v[134:135], 0, s[36:37]
	v_readfirstlane_b32 s10, v162
	v_lshl_add_u64 v[252:253], v[250:251], 0, s[74:75]
	s_mov_b32 m0, s10
	s_nop 0
	global_load_lds_dwordx4 v[252:253], off
	s_barrier
	s_waitcnt lgkmcnt(0)
	v_mfma_f32_16x16x32_bf16 v[94:97], v[196:199], v[228:231], v[94:97]
	v_mfma_f32_16x16x32_bf16 v[90:93], v[196:199], v[236:239], v[90:93]
	v_mfma_f32_16x16x32_bf16 v[86:89], v[204:207], v[228:231], v[86:89]
	v_mfma_f32_16x16x32_bf16 v[82:85], v[204:207], v[236:239], v[82:85]
	v_mfma_f32_16x16x32_bf16 v[78:81], v[212:215], v[228:231], v[78:81]
	v_mfma_f32_16x16x32_bf16 v[74:77], v[212:215], v[236:239], v[74:77]
	v_mfma_f32_16x16x32_bf16 v[70:73], v[220:223], v[228:231], v[70:73]
	v_mfma_f32_16x16x32_bf16 v[66:69], v[220:223], v[236:239], v[66:69]
	v_mfma_f32_16x16x32_bf16 v[94:97], v[200:203], v[232:235], v[94:97]
	v_mfma_f32_16x16x32_bf16 v[90:93], v[200:203], v[240:243], v[90:93]
	v_mfma_f32_16x16x32_bf16 v[86:89], v[208:211], v[232:235], v[86:89]
	v_mfma_f32_16x16x32_bf16 v[82:85], v[208:211], v[240:243], v[82:85]
	v_mfma_f32_16x16x32_bf16 v[78:81], v[216:219], v[232:235], v[78:81]
	v_mfma_f32_16x16x32_bf16 v[74:77], v[216:219], v[240:243], v[74:77]
	v_mfma_f32_16x16x32_bf16 v[70:73], v[224:227], v[232:235], v[70:73]
	v_mfma_f32_16x16x32_bf16 v[66:69], v[224:227], v[240:243], v[66:69]
	v_readfirstlane_b32 s10, v163
	v_lshl_add_u64 v[252:253], v[244:245], 0, s[76:77]
	s_mov_b32 m0, s10
	v_readfirstlane_b32 s10, v164
	s_barrier
	ds_read_b128 v[196:199], v159 offset:16384
	ds_read_b128 v[200:203], v159 offset:17408
	ds_read_b128 v[204:207], v147 offset:16384
	ds_read_b128 v[208:211], v147 offset:17408
	ds_read_b128 v[212:215], v146 offset:16384
	ds_read_b128 v[216:219], v146 offset:17408
	ds_read_b128 v[220:223], v145 offset:16384
	ds_read_b128 v[224:227], v145 offset:17408
	global_load_lds_dwordx4 v[252:253], off
	v_lshl_add_u64 v[252:253], v[246:247], 0, s[76:77]
	s_mov_b32 m0, s10
	s_nop 0
	global_load_lds_dwordx4 v[252:253], off
	s_barrier
	s_waitcnt lgkmcnt(0)
	v_mfma_f32_16x16x32_bf16 v[62:65], v[196:199], v[180:183], v[62:65]
	v_mfma_f32_16x16x32_bf16 v[58:61], v[196:199], v[188:191], v[58:61]
	v_mfma_f32_16x16x32_bf16 v[54:57], v[204:207], v[180:183], v[54:57]
	v_mfma_f32_16x16x32_bf16 v[50:53], v[204:207], v[188:191], v[50:53]
	v_mfma_f32_16x16x32_bf16 v[46:49], v[212:215], v[180:183], v[46:49]
	v_mfma_f32_16x16x32_bf16 v[42:45], v[212:215], v[188:191], v[42:45]
	v_mfma_f32_16x16x32_bf16 v[38:41], v[220:223], v[180:183], v[38:41]
	v_mfma_f32_16x16x32_bf16 v[34:37], v[220:223], v[188:191], v[34:37]
	v_mfma_f32_16x16x32_bf16 v[62:65], v[200:203], v[184:187], v[62:65]
	v_mfma_f32_16x16x32_bf16 v[58:61], v[200:203], v[192:195], v[58:61]
	v_mfma_f32_16x16x32_bf16 v[54:57], v[208:211], v[184:187], v[54:57]
	v_mfma_f32_16x16x32_bf16 v[50:53], v[208:211], v[192:195], v[50:53]
	v_mfma_f32_16x16x32_bf16 v[46:49], v[216:219], v[184:187], v[46:49]
	v_mfma_f32_16x16x32_bf16 v[42:45], v[216:219], v[192:195], v[42:45]
	v_mfma_f32_16x16x32_bf16 v[38:41], v[224:227], v[184:187], v[38:41]
	v_mfma_f32_16x16x32_bf16 v[34:37], v[224:227], v[192:195], v[34:37]
	s_barrier
; #define STA(P, br, kt) STAGE(P, A, aoff0, aoff1, lda, br, kt)
; #define STB(P, br, kt) STAGE(P, Bt, boff0, boff1, ldb, br, kt)
; #define LDA(dst, b, h) _Pragma("unroll") for (int m = 0; m < 4; ++m) _Pragma("unroll") for (int k = 0; k < 2; ++k) \
;     dst[m][k] = *reinterpret_cast<const bf16x8*>((char*)SA(b, h) + lds_byte(wr * 64 + m * 16 + fr, k * 32 + fq * 8))
; #define LDB(dst, b, h) _Pragma("unroll") for (int n = 0; n < 2; ++n) _Pragma("unroll") for (int k = 0; k < 2; ++k) \
;     dst[n][k] = *reinterpret_cast<const bf16x8*>((char*)SB(b, h) + lds_byte(wc * 32 + n * 16 + fr, k * 32 + fq * 8))
; #define MMA(ai, bj, At, Bq) do { __builtin_amdgcn_s_setprio(1); \
;     _Pragma("unroll") for (int m = 0; m < 4; ++m) _Pragma("unroll") for (int n = 0; n < 2; ++n) _Pragma("unroll") for (int k = 0; k < 2; ++k) \
;       acc[ai][bj][m][n] = __builtin_amdgcn_mfma_f32_16x16x32_bf16(At[m][k], Bq[n][k], acc[ai][bj][m][n], 0, 0, 0); \
;     __builtin_amdgcn_s_setprio(0); } while (0)
; #define WAIT_V(n) asm volatile("s_waitcnt vmcnt(" #n ")" ::: "memory")
; #define WAIT_L(n) asm volatile("s_waitcnt lgkmcnt(" #n ")" ::: "memory")
; #define BAR __builtin_amdgcn_s_barrier()
; #define SCHED __builtin_amdgcn_sched_barrier(0)
; __device__ __forceinline__ void gemm256(const u16* __restrict__ A, int lda, const u16* __restrict__ Bt, int ldb, int K,
;                                         f32x4 (&acc)[2][2][4][2], const int g_wid) {
;     ...
;     STB(SB(0, 1), HALF, t + 2);
;     WAIT_V(6); BAR; MMA(1, 1, At, B1); BAR;
;     LDB(B0, 1, 0); SCHED; LDA(At, 1, 0); STA(SA(0, 1), HALF, t + 2);
;     WAIT_L(8); BAR; WAIT_L(0); MMA(0, 0, At, B0); BAR; SCHED;
;     LDB(B1, 1, 1); STB(SB(1, 0), 0, t + 3);
;     BAR; WAIT_L(0); MMA(0, 1, At, B1); BAR;
;     LDA(At, 1, 1); STA(SA(1, 0), 0, t + 3);
	v_readfirstlane_b32 s10, v165
	v_lshl_add_u64 v[180:181], v[248:249], 0, s[78:79]
	s_mov_b32 m0, s10
	v_readfirstlane_b32 s10, v166
	global_load_lds_dwordx4 v[180:181], off
	v_lshl_add_u64 v[180:181], v[250:251], 0, s[78:79]
	s_mov_b32 m0, s10
	s_nop 0
	global_load_lds_dwordx4 v[180:181], off
	s_waitcnt vmcnt(6)
	s_barrier
	v_mfma_f32_16x16x32_bf16 v[30:33], v[196:199], v[228:231], v[30:33]
	v_mfma_f32_16x16x32_bf16 v[26:29], v[196:199], v[236:239], v[26:29]
	v_mfma_f32_16x16x32_bf16 v[22:25], v[204:207], v[228:231], v[22:25]
	v_mfma_f32_16x16x32_bf16 v[18:21], v[204:207], v[236:239], v[18:21]
	v_mfma_f32_16x16x32_bf16 v[14:17], v[212:215], v[228:231], v[14:17]
	v_mfma_f32_16x16x32_bf16 v[10:13], v[212:215], v[236:239], v[10:13]
	v_mfma_f32_16x16x32_bf16 v[6:9], v[220:223], v[228:231], v[6:9]
	v_mfma_f32_16x16x32_bf16 v[2:5], v[220:223], v[236:239], v[2:5]
	v_mfma_f32_16x16x32_bf16 v[30:33], v[200:203], v[232:235], v[30:33]
	v_mfma_f32_16x16x32_bf16 v[26:29], v[200:203], v[240:243], v[26:29]
	v_mfma_f32_16x16x32_bf16 v[22:25], v[208:211], v[232:235], v[22:25]
	v_mfma_f32_16x16x32_bf16 v[18:21], v[208:211], v[240:243], v[18:21]
	v_mfma_f32_16x16x32_bf16 v[14:17], v[216:219], v[232:235], v[14:17]
	v_mfma_f32_16x16x32_bf16 v[10:13], v[216:219], v[240:243], v[10:13]
	v_mfma_f32_16x16x32_bf16 v[6:9], v[224:227], v[232:235], v[6:9]
	v_mfma_f32_16x16x32_bf16 v[2:5], v[224:227], v[240:243], v[2:5]
	s_barrier
	ds_read_b128 v[180:183], v167
	ds_read_b128 v[184:187], v167 offset:1024
	ds_read_b128 v[188:191], v167 offset:2048
	ds_read_b128 v[192:195], v167 offset:3072
	v_readfirstlane_b32 s10, v168
	v_lshl_add_u64 v[228:229], v[244:245], 0, s[80:81]
	s_mov_b32 m0, s10
	v_readfirstlane_b32 s10, v169
	ds_read_b128 v[196:199], v159 offset:32768
	ds_read_b128 v[200:203], v159 offset:33792
	ds_read_b128 v[204:207], v147 offset:32768
	ds_read_b128 v[208:211], v147 offset:33792
	ds_read_b128 v[212:215], v146 offset:32768
	ds_read_b128 v[216:219], v146 offset:33792
	ds_read_b128 v[220:223], v145 offset:32768
	ds_read_b128 v[224:227], v145 offset:33792
	global_load_lds_dwordx4 v[228:229], off
	v_lshl_add_u64 v[228:229], v[246:247], 0, s[80:81]
	s_mov_b32 m0, s10
	s_nop 0
	global_load_lds_dwordx4 v[228:229], off
	s_waitcnt lgkmcnt(8)
	s_barrier
	s_waitcnt lgkmcnt(0)
	v_mfma_f32_16x16x32_bf16 v[126:129], v[196:199], v[180:183], v[126:129]
	v_mfma_f32_16x16x32_bf16 v[122:125], v[196:199], v[188:191], v[122:125]
	v_mfma_f32_16x16x32_bf16 v[118:121], v[204:207], v[180:183], v[118:121]
	v_mfma_f32_16x16x32_bf16 v[114:117], v[204:207], v[188:191], v[114:117]
	v_mfma_f32_16x16x32_bf16 v[110:113], v[212:215], v[180:183], v[110:113]
	v_mfma_f32_16x16x32_bf16 v[106:109], v[212:215], v[188:191], v[106:109]
	v_mfma_f32_16x16x32_bf16 v[102:105], v[220:223], v[180:183], v[102:105]
	v_mfma_f32_16x16x32_bf16 v[98:101], v[220:223], v[188:191], v[98:101]
	v_mfma_f32_16x16x32_bf16 v[126:129], v[200:203], v[184:187], v[126:129]
	v_mfma_f32_16x16x32_bf16 v[122:125], v[200:203], v[192:195], v[122:125]
	v_mfma_f32_16x16x32_bf16 v[118:121], v[208:211], v[184:187], v[118:121]
	v_mfma_f32_16x16x32_bf16 v[114:117], v[208:211], v[192:195], v[114:117]
	v_mfma_f32_16x16x32_bf16 v[110:113], v[216:219], v[184:187], v[110:113]
	v_mfma_f32_16x16x32_bf16 v[106:109], v[216:219], v[192:195], v[106:109]
	v_mfma_f32_16x16x32_bf16 v[102:105], v[224:227], v[184:187], v[102:105]
	v_mfma_f32_16x16x32_bf16 v[98:101], v[224:227], v[192:195], v[98:101]
	s_barrier
	v_readfirstlane_b32 s10, v170
	v_lshl_add_u64 v[252:253], v[248:249], 0, s[82:83]
	s_mov_b32 m0, s10
	v_readfirstlane_b32 s10, v171
	ds_read_b128 v[228:231], v160
	ds_read_b128 v[232:235], v160 offset:1024
	ds_read_b128 v[236:239], v160 offset:2048
	ds_read_b128 v[240:243], v160 offset:3072
	global_load_lds_dwordx4 v[252:253], off
	v_lshl_add_u64 v[252:253], v[250:251], 0, s[82:83]
	s_mov_b32 m0, s10
	s_nop 0
	global_load_lds_dwordx4 v[252:253], off
	s_barrier
	s_waitcnt lgkmcnt(0)
	v_mfma_f32_16x16x32_bf16 v[94:97], v[196:199], v[228:231], v[94:97]
	v_mfma_f32_16x16x32_bf16 v[90:93], v[196:199], v[236:239], v[90:93]
	v_mfma_f32_16x16x32_bf16 v[86:89], v[204:207], v[228:231], v[86:89]
	v_mfma_f32_16x16x32_bf16 v[82:85], v[204:207], v[236:239], v[82:85]
	v_mfma_f32_16x16x32_bf16 v[78:81], v[212:215], v[228:231], v[78:81]
	v_mfma_f32_16x16x32_bf16 v[74:77], v[212:215], v[236:239], v[74:77]
	v_mfma_f32_16x16x32_bf16 v[70:73], v[220:223], v[228:231], v[70:73]
	v_mfma_f32_16x16x32_bf16 v[66:69], v[220:223], v[236:239], v[66:69]
	v_mfma_f32_16x16x32_bf16 v[94:97], v[200:203], v[232:235], v[94:97]
	v_mfma_f32_16x16x32_bf16 v[90:93], v[200:203], v[240:243], v[90:93]
	v_mfma_f32_16x16x32_bf16 v[86:89], v[208:211], v[232:235], v[86:89]
	v_mfma_f32_16x16x32_bf16 v[82:85], v[208:211], v[240:243], v[82:85]
	v_mfma_f32_16x16x32_bf16 v[78:81], v[216:219], v[232:235], v[78:81]
	v_mfma_f32_16x16x32_bf16 v[74:77], v[216:219], v[240:243], v[74:77]
	v_mfma_f32_16x16x32_bf16 v[70:73], v[224:227], v[232:235], v[70:73]
	v_mfma_f32_16x16x32_bf16 v[66:69], v[224:227], v[240:243], v[66:69]
	v_readfirstlane_b32 s10, v172
	v_lshl_add_u64 v[244:245], v[244:245], 0, s[84:85]
	s_mov_b32 m0, s10
	v_readfirstlane_b32 s10, v173
	s_barrier
	ds_read_b128 v[196:199], v159 offset:49152
	ds_read_b128 v[200:203], v159 offset:50176
	ds_read_b128 v[204:207], v147 offset:49152
	ds_read_b128 v[208:211], v147 offset:50176
	ds_read_b128 v[212:215], v146 offset:49152
	ds_read_b128 v[216:219], v146 offset:50176
	ds_read_b128 v[220:223], v145 offset:49152
	ds_read_b128 v[224:227], v145 offset:50176
	global_load_lds_dwordx4 v[244:245], off
	v_lshl_add_u64 v[244:245], v[246:247], 0, s[84:85]
	s_mov_b32 m0, s10
	s_nop 0
	global_load_lds_dwordx4 v[244:245], off
	s_barrier
; #define STA(P, br, kt) STAGE(P, A, aoff0, aoff1, lda, br, kt)
; #define STB(P, br, kt) STAGE(P, Bt, boff0, boff1, ldb, br, kt)
; #define LDA(dst, b, h) _Pragma("unroll") for (int m = 0; m < 4; ++m) _Pragma("unroll") for (int k = 0; k < 2; ++k) \
;     dst[m][k] = *reinterpret_cast<const bf16x8*>((char*)SA(b, h) + lds_byte(wr * 64 + m * 16 + fr, k * 32 + fq * 8))
; #define LDB(dst, b, h) _Pragma("unroll") for (int n = 0; n < 2; ++n) _Pragma("unroll") for (int k = 0; k < 2; ++k) \
;     dst[n][k] = *reinterpret_cast<const bf16x8*>((char*)SB(b, h) + lds_byte(wc * 32 + n * 16 + fr, k * 32 + fq * 8))
; #define MMA(ai, bj, At, Bq) do { __builtin_amdgcn_s_setprio(1); \
;     _Pragma("unroll") for (int m = 0; m < 4; ++m) _Pragma("unroll") for (int n = 0; n < 2; ++n) _Pragma("unroll") for (int k = 0; k < 2; ++k) \
;       acc[ai][bj][m][n] = __builtin_amdgcn_mfma_f32_16x16x32_bf16(At[m][k], Bq[n][k], acc[ai][bj][m][n], 0, 0, 0); \
;     __builtin_amdgcn_s_setprio(0); } while (0)
; #define WAIT_V(n) asm volatile("s_waitcnt vmcnt(" #n ")" ::: "memory")
; #define WAIT_L(n) asm volatile("s_waitcnt lgkmcnt(" #n ")" ::: "memory")
; #define BAR __builtin_amdgcn_s_barrier()
; #define SCHED __builtin_amdgcn_sched_barrier(0)
; __device__ __forceinline__ void gemm256(const u16* __restrict__ A, int lda, const u16* __restrict__ Bt, int ldb, int K,
;                                         f32x4 (&acc)[2][2][4][2], const int g_wid) {
;     ...
;     BAR; WAIT_L(0); MMA(1, 0, At, B0); BAR; SCHED;
;     STB(SB(1, 1), HALF, t + 3);
;     WAIT_V(6); BAR; MMA(1, 1, At, B1); BAR;
;   }
;   { LDB(B0, 0, 0); LDA(At, 0, 0); STA(SA(1, 1), HALF, nt - 1);
;     BAR; WAIT_L(0); MMA(0, 0, At, B0); BAR;
;     LDB(B1, 0, 1); BAR; WAIT_L(0); MMA(0, 1, At, B1); BAR;
	s_waitcnt lgkmcnt(0)
	v_mfma_f32_16x16x32_bf16 v[62:65], v[196:199], v[180:183], v[62:65]
	v_mfma_f32_16x16x32_bf16 v[58:61], v[196:199], v[188:191], v[58:61]
	v_mfma_f32_16x16x32_bf16 v[54:57], v[204:207], v[180:183], v[54:57]
	v_mfma_f32_16x16x32_bf16 v[50:53], v[204:207], v[188:191], v[50:53]
	v_mfma_f32_16x16x32_bf16 v[46:49], v[212:215], v[180:183], v[46:49]
	v_mfma_f32_16x16x32_bf16 v[42:45], v[212:215], v[188:191], v[42:45]
	v_mfma_f32_16x16x32_bf16 v[38:41], v[220:223], v[180:183], v[38:41]
	v_mfma_f32_16x16x32_bf16 v[34:37], v[220:223], v[188:191], v[34:37]
	v_mfma_f32_16x16x32_bf16 v[62:65], v[200:203], v[184:187], v[62:65]
	v_mfma_f32_16x16x32_bf16 v[58:61], v[200:203], v[192:195], v[58:61]
	v_mfma_f32_16x16x32_bf16 v[54:57], v[208:211], v[184:187], v[54:57]
	v_mfma_f32_16x16x32_bf16 v[50:53], v[208:211], v[192:195], v[50:53]
	v_mfma_f32_16x16x32_bf16 v[46:49], v[216:219], v[184:187], v[46:49]
	v_mfma_f32_16x16x32_bf16 v[42:45], v[216:219], v[192:195], v[42:45]
	v_mfma_f32_16x16x32_bf16 v[38:41], v[224:227], v[184:187], v[38:41]
	v_mfma_f32_16x16x32_bf16 v[34:37], v[224:227], v[192:195], v[34:37]
	s_barrier
	v_readfirstlane_b32 s10, v174
	v_lshl_add_u64 v[180:181], v[248:249], 0, s[86:87]
	s_mov_b32 m0, s10
	v_readfirstlane_b32 s10, v175
	global_load_lds_dwordx4 v[180:181], off
	v_lshl_add_u64 v[180:181], v[250:251], 0, s[86:87]
	s_mov_b32 m0, s10
	s_nop 0
	global_load_lds_dwordx4 v[180:181], off
	s_waitcnt vmcnt(6)
	s_barrier
	v_mfma_f32_16x16x32_bf16 v[30:33], v[196:199], v[228:231], v[30:33]
	v_mfma_f32_16x16x32_bf16 v[26:29], v[196:199], v[236:239], v[26:29]
	v_mfma_f32_16x16x32_bf16 v[22:25], v[204:207], v[228:231], v[22:25]
	v_mfma_f32_16x16x32_bf16 v[18:21], v[204:207], v[236:239], v[18:21]
	v_mfma_f32_16x16x32_bf16 v[14:17], v[212:215], v[228:231], v[14:17]
	v_mfma_f32_16x16x32_bf16 v[10:13], v[212:215], v[236:239], v[10:13]
	v_mfma_f32_16x16x32_bf16 v[6:9], v[220:223], v[228:231], v[6:9]
	v_mfma_f32_16x16x32_bf16 v[2:5], v[220:223], v[236:239], v[2:5]
	v_mfma_f32_16x16x32_bf16 v[30:33], v[200:203], v[232:235], v[30:33]
	v_mfma_f32_16x16x32_bf16 v[26:29], v[200:203], v[240:243], v[26:29]
	v_mfma_f32_16x16x32_bf16 v[22:25], v[208:211], v[232:235], v[22:25]
	v_mfma_f32_16x16x32_bf16 v[18:21], v[208:211], v[240:243], v[18:21]
	v_mfma_f32_16x16x32_bf16 v[14:17], v[216:219], v[232:235], v[14:17]
	v_mfma_f32_16x16x32_bf16 v[10:13], v[216:219], v[240:243], v[10:13]
	v_mfma_f32_16x16x32_bf16 v[6:9], v[224:227], v[232:235], v[6:9]
	v_mfma_f32_16x16x32_bf16 v[2:5], v[224:227], v[240:243], v[2:5]
	s_add_i32 s54, s54, 2
	s_add_u32 s36, s36, 0x100
	s_addc_u32 s37, s37, 0
	s_cmp_lt_u32 s54, 12
	s_barrier
	s_cbranch_scc1 .LBB0_109
	s_add_u32 s34, s34, 0x40780
	s_addc_u32 s35, s35, 0
	v_readfirstlane_b32 s10, v178
	v_lshl_add_u64 v[132:133], v[132:133], 1, s[34:35]
	s_mov_b32 m0, s10
	v_readfirstlane_b32 s10, v179
	ds_read_b128 v[134:137], v177
	ds_read_b128 v[162:165], v177 offset:1024
	ds_read_b128 v[168:171], v177 offset:2048
	ds_read_b128 v[172:175], v177 offset:3072
	ds_read_b128 v[180:183], v159
	ds_read_b128 v[184:187], v159 offset:1024
	ds_read_b128 v[188:191], v147
	ds_read_b128 v[192:195], v147 offset:1024
	ds_read_b128 v[196:199], v146
	ds_read_b128 v[200:203], v146 offset:1024
	ds_read_b128 v[204:207], v145
	ds_read_b128 v[208:211], v145 offset:1024
	global_load_lds_dwordx4 v[132:133], off
	v_lshl_add_u64 v[130:131], v[130:131], 1, s[34:35]
	s_mov_b32 m0, s10
	s_nop 0
	global_load_lds_dwordx4 v[130:131], off
	s_barrier
	s_waitcnt lgkmcnt(0)
	v_mfma_f32_16x16x32_bf16 v[126:129], v[180:183], v[134:137], v[126:129]
	v_mfma_f32_16x16x32_bf16 v[122:125], v[180:183], v[168:171], v[122:125]
	v_mfma_f32_16x16x32_bf16 v[118:121], v[188:191], v[134:137], v[118:121]
	v_mfma_f32_16x16x32_bf16 v[114:117], v[188:191], v[168:171], v[114:117]
	v_mfma_f32_16x16x32_bf16 v[110:113], v[196:199], v[134:137], v[110:113]
	v_mfma_f32_16x16x32_bf16 v[106:109], v[196:199], v[168:171], v[106:109]
	v_mfma_f32_16x16x32_bf16 v[102:105], v[204:207], v[134:137], v[102:105]
	v_mfma_f32_16x16x32_bf16 v[98:101], v[204:207], v[168:171], v[98:101]
	v_mfma_f32_16x16x32_bf16 v[126:129], v[184:187], v[162:165], v[126:129]
	v_mfma_f32_16x16x32_bf16 v[122:125], v[184:187], v[172:175], v[122:125]
	v_mfma_f32_16x16x32_bf16 v[118:121], v[192:195], v[162:165], v[118:121]
	v_mfma_f32_16x16x32_bf16 v[114:117], v[192:195], v[172:175], v[114:117]
	v_mfma_f32_16x16x32_bf16 v[110:113], v[200:203], v[162:165], v[110:113]
	v_mfma_f32_16x16x32_bf16 v[106:109], v[200:203], v[172:175], v[106:109]
	v_mfma_f32_16x16x32_bf16 v[102:105], v[208:211], v[162:165], v[102:105]
	v_mfma_f32_16x16x32_bf16 v[98:101], v[208:211], v[172:175], v[98:101]
	s_barrier
	ds_read_b128 v[130:133], v176
	ds_read_b128 v[212:215], v176 offset:1024
	ds_read_b128 v[216:219], v176 offset:2048
	ds_read_b128 v[176:179], v176 offset:3072
	s_barrier
	s_waitcnt lgkmcnt(0)
	v_mfma_f32_16x16x32_bf16 v[94:97], v[180:183], v[130:133], v[94:97]
	v_mfma_f32_16x16x32_bf16 v[90:93], v[180:183], v[216:219], v[90:93]
	v_mfma_f32_16x16x32_bf16 v[86:89], v[188:191], v[130:133], v[86:89]
	v_mfma_f32_16x16x32_bf16 v[82:85], v[188:191], v[216:219], v[82:85]
	v_mfma_f32_16x16x32_bf16 v[78:81], v[196:199], v[130:133], v[78:81]
	v_mfma_f32_16x16x32_bf16 v[74:77], v[196:199], v[216:219], v[74:77]
	v_mfma_f32_16x16x32_bf16 v[70:73], v[204:207], v[130:133], v[70:73]
	v_mfma_f32_16x16x32_bf16 v[66:69], v[204:207], v[216:219], v[66:69]
	v_mfma_f32_16x16x32_bf16 v[94:97], v[184:187], v[212:215], v[94:97]
	v_mfma_f32_16x16x32_bf16 v[90:93], v[184:187], v[176:179], v[90:93]
	v_mfma_f32_16x16x32_bf16 v[86:89], v[192:195], v[212:215], v[86:89]
	v_mfma_f32_16x16x32_bf16 v[82:85], v[192:195], v[176:179], v[82:85]
	v_mfma_f32_16x16x32_bf16 v[78:81], v[200:203], v[212:215], v[78:81]
	v_mfma_f32_16x16x32_bf16 v[74:77], v[200:203], v[176:179], v[74:77]
	v_mfma_f32_16x16x32_bf16 v[70:73], v[208:211], v[212:215], v[70:73]
	v_mfma_f32_16x16x32_bf16 v[66:69], v[208:211], v[176:179], v[66:69]
	s_barrier
; #define LDA(dst, b, h) _Pragma("unroll") for (int m = 0; m < 4; ++m) _Pragma("unroll") for (int k = 0; k < 2; ++k) \
;     dst[m][k] = *reinterpret_cast<const bf16x8*>((char*)SA(b, h) + lds_byte(wr * 64 + m * 16 + fr, k * 32 + fq * 8))
; #define LDB(dst, b, h) _Pragma("unroll") for (int n = 0; n < 2; ++n) _Pragma("unroll") for (int k = 0; k < 2; ++k) \
;     dst[n][k] = *reinterpret_cast<const bf16x8*>((char*)SB(b, h) + lds_byte(wc * 32 + n * 16 + fr, k * 32 + fq * 8))
; #define MMA(ai, bj, At, Bq) do { __builtin_amdgcn_s_setprio(1); \
;     _Pragma("unroll") for (int m = 0; m < 4; ++m) _Pragma("unroll") for (int n = 0; n < 2; ++n) _Pragma("unroll") for (int k = 0; k < 2; ++k) \
;       acc[ai][bj][m][n] = __builtin_amdgcn_mfma_f32_16x16x32_bf16(At[m][k], Bq[n][k], acc[ai][bj][m][n], 0, 0, 0); \
;     __builtin_amdgcn_s_setprio(0); } while (0)
; #define WAIT_V(n) asm volatile("s_waitcnt vmcnt(" #n ")" ::: "memory")
; #define WAIT_L(n) asm volatile("s_waitcnt lgkmcnt(" #n ")" ::: "memory")
; #define BAR __builtin_amdgcn_s_barrier()
; __device__ __forceinline__ void gemm256(const u16* __restrict__ A, int lda, const u16* __restrict__ Bt, int ldb, int K,
;                                         f32x4 (&acc)[2][2][4][2], const int g_wid) {
;     ...
;     LDA(At, 0, 1); WAIT_V(4); BAR; WAIT_L(0); MMA(1, 0, At, B0); MMA(1, 1, At, B1); BAR; }
;   { LDB(B0, 1, 0); LDA(At, 1, 0); WAIT_V(2); BAR; WAIT_L(0); MMA(0, 0, At, B0); BAR;
	ds_read_b128 v[180:183], v159 offset:16384
	ds_read_b128 v[184:187], v159 offset:17408
	ds_read_b128 v[188:191], v147 offset:16384
	ds_read_b128 v[192:195], v147 offset:17408
	ds_read_b128 v[196:199], v146 offset:16384
	ds_read_b128 v[200:203], v146 offset:17408
	ds_read_b128 v[204:207], v145 offset:16384
	ds_read_b128 v[208:211], v145 offset:17408
	s_waitcnt vmcnt(4)
	s_barrier
	s_waitcnt lgkmcnt(0)
	v_mfma_f32_16x16x32_bf16 v[62:65], v[180:183], v[134:137], v[62:65]
	v_mfma_f32_16x16x32_bf16 v[58:61], v[180:183], v[168:171], v[58:61]
	v_mfma_f32_16x16x32_bf16 v[54:57], v[188:191], v[134:137], v[54:57]
	v_mfma_f32_16x16x32_bf16 v[50:53], v[188:191], v[168:171], v[50:53]
	v_mfma_f32_16x16x32_bf16 v[46:49], v[196:199], v[134:137], v[46:49]
	v_mfma_f32_16x16x32_bf16 v[42:45], v[196:199], v[168:171], v[42:45]
	v_mfma_f32_16x16x32_bf16 v[38:41], v[204:207], v[134:137], v[38:41]
	v_mfma_f32_16x16x32_bf16 v[34:37], v[204:207], v[168:171], v[34:37]
	v_mfma_f32_16x16x32_bf16 v[220:223], v[184:187], v[162:165], v[62:65]
	v_mfma_f32_16x16x32_bf16 v[224:227], v[184:187], v[172:175], v[58:61]
	v_mfma_f32_16x16x32_bf16 v[228:231], v[192:195], v[162:165], v[54:57]
	v_mfma_f32_16x16x32_bf16 v[232:235], v[192:195], v[172:175], v[50:53]
	v_mfma_f32_16x16x32_bf16 v[236:239], v[200:203], v[162:165], v[46:49]
	v_mfma_f32_16x16x32_bf16 v[240:243], v[200:203], v[172:175], v[42:45]
	v_mfma_f32_16x16x32_bf16 v[134:137], v[208:211], v[162:165], v[38:41]
	v_mfma_f32_16x16x32_bf16 v[162:165], v[208:211], v[172:175], v[34:37]
	v_mfma_f32_16x16x32_bf16 v[30:33], v[180:183], v[130:133], v[30:33]
	v_mfma_f32_16x16x32_bf16 v[26:29], v[180:183], v[216:219], v[26:29]
	v_mfma_f32_16x16x32_bf16 v[22:25], v[188:191], v[130:133], v[22:25]
	v_mfma_f32_16x16x32_bf16 v[18:21], v[188:191], v[216:219], v[18:21]
	v_mfma_f32_16x16x32_bf16 v[14:17], v[196:199], v[130:133], v[14:17]
	v_mfma_f32_16x16x32_bf16 v[10:13], v[196:199], v[216:219], v[10:13]
	v_mfma_f32_16x16x32_bf16 v[6:9], v[204:207], v[130:133], v[6:9]
	v_mfma_f32_16x16x32_bf16 v[2:5], v[204:207], v[216:219], v[2:5]
	v_mfma_f32_16x16x32_bf16 v[30:33], v[184:187], v[212:215], v[30:33]
	v_mfma_f32_16x16x32_bf16 v[26:29], v[184:187], v[176:179], v[26:29]
	v_mfma_f32_16x16x32_bf16 v[22:25], v[192:195], v[212:215], v[22:25]
	v_mfma_f32_16x16x32_bf16 v[18:21], v[192:195], v[176:179], v[18:21]
	v_mfma_f32_16x16x32_bf16 v[14:17], v[200:203], v[212:215], v[14:17]
	v_mfma_f32_16x16x32_bf16 v[10:13], v[200:203], v[176:179], v[10:13]
	v_mfma_f32_16x16x32_bf16 v[6:9], v[208:211], v[212:215], v[6:9]
	v_mfma_f32_16x16x32_bf16 v[2:5], v[208:211], v[176:179], v[2:5]
	s_barrier
	ds_read_b128 v[130:133], v167
	ds_read_b128 v[168:171], v167 offset:1024
	ds_read_b128 v[172:175], v167 offset:2048
	ds_read_b128 v[176:179], v167 offset:3072
	ds_read_b128 v[34:37], v159 offset:32768
	ds_read_b128 v[38:41], v159 offset:33792
	ds_read_b128 v[42:45], v147 offset:32768
	ds_read_b128 v[46:49], v147 offset:33792
	ds_read_b128 v[180:183], v146 offset:32768
	ds_read_b128 v[184:187], v146 offset:33792
	ds_read_b128 v[188:191], v145 offset:32768
	ds_read_b128 v[192:195], v145 offset:33792
	s_waitcnt vmcnt(2)
	s_barrier
	s_waitcnt lgkmcnt(0)
	v_mfma_f32_16x16x32_bf16 v[50:53], v[34:37], v[130:133], v[126:129]
	v_mfma_f32_16x16x32_bf16 v[126:129], v[38:41], v[168:171], v[50:53]
	v_mfma_f32_16x16x32_bf16 v[50:53], v[34:37], v[172:175], v[122:125]
	v_mfma_f32_16x16x32_bf16 v[122:125], v[38:41], v[176:179], v[50:53]
	v_mfma_f32_16x16x32_bf16 v[50:53], v[42:45], v[130:133], v[118:121]
	v_mfma_f32_16x16x32_bf16 v[118:121], v[46:49], v[168:171], v[50:53]
	v_mfma_f32_16x16x32_bf16 v[50:53], v[42:45], v[172:175], v[114:117]
	v_mfma_f32_16x16x32_bf16 v[114:117], v[46:49], v[176:179], v[50:53]
	v_mfma_f32_16x16x32_bf16 v[50:53], v[180:183], v[130:133], v[110:113]
	v_mfma_f32_16x16x32_bf16 v[110:113], v[184:187], v[168:171], v[50:53]
	v_mfma_f32_16x16x32_bf16 v[50:53], v[180:183], v[172:175], v[106:109]
	v_mfma_f32_16x16x32_bf16 v[106:109], v[184:187], v[176:179], v[50:53]
	v_mfma_f32_16x16x32_bf16 v[50:53], v[188:191], v[130:133], v[102:105]
	v_mfma_f32_16x16x32_bf16 v[102:105], v[192:195], v[168:171], v[50:53]
	v_mfma_f32_16x16x32_bf16 v[50:53], v[188:191], v[172:175], v[98:101]
	v_mfma_f32_16x16x32_bf16 v[98:101], v[192:195], v[176:179], v[50:53]
	s_barrier
; #define LDA(dst, b, h) _Pragma("unroll") for (int m = 0; m < 4; ++m) _Pragma("unroll") for (int k = 0; k < 2; ++k) \
;     dst[m][k] = *reinterpret_cast<const bf16x8*>((char*)SA(b, h) + lds_byte(wr * 64 + m * 16 + fr, k * 32 + fq * 8))
; #define LDB(dst, b, h) _Pragma("unroll") for (int n = 0; n < 2; ++n) _Pragma("unroll") for (int k = 0; k < 2; ++k) \
;     dst[n][k] = *reinterpret_cast<const bf16x8*>((char*)SB(b, h) + lds_byte(wc * 32 + n * 16 + fr, k * 32 + fq * 8))
; #define MMA(ai, bj, At, Bq) do { __builtin_amdgcn_s_setprio(1); \
;     _Pragma("unroll") for (int m = 0; m < 4; ++m) _Pragma("unroll") for (int n = 0; n < 2; ++n) _Pragma("unroll") for (int k = 0; k < 2; ++k) \
;       acc[ai][bj][m][n] = __builtin_amdgcn_mfma_f32_16x16x32_bf16(At[m][k], Bq[n][k], acc[ai][bj][m][n], 0, 0, 0); \
;     __builtin_amdgcn_s_setprio(0); } while (0)
; #define WAIT_V(n) asm volatile("s_waitcnt vmcnt(" #n ")" ::: "memory")
; #define WAIT_L(n) asm volatile("s_waitcnt lgkmcnt(" #n ")" ::: "memory")
; #define BAR __builtin_amdgcn_s_barrier()
; __device__ __forceinline__ void gemm256(const u16* __restrict__ A, int lda, const u16* __restrict__ Bt, int ldb, int K,
;                                         f32x4 (&acc)[2][2][4][2], const int g_wid) {
;     ...
;     LDB(B1, 1, 1); WAIT_V(0); BAR; WAIT_L(0); MMA(0, 1, At, B1); BAR;
;     LDA(At, 1, 1); BAR; WAIT_L(0); MMA(1, 0, At, B0); MMA(1, 1, At, B1); BAR; }
;   if (wr == 0) BAR;
	ds_read_b128 v[196:199], v160
	ds_read_b128 v[200:203], v160 offset:1024
	ds_read_b128 v[204:207], v160 offset:2048
	ds_read_b128 v[208:211], v160 offset:3072
	s_waitcnt vmcnt(0)
	s_barrier
	s_waitcnt lgkmcnt(0)
	v_mfma_f32_16x16x32_bf16 v[50:53], v[34:37], v[196:199], v[94:97]
	v_mfma_f32_16x16x32_bf16 v[34:37], v[34:37], v[204:207], v[90:93]
	v_mfma_f32_16x16x32_bf16 v[58:61], v[38:41], v[208:211], v[34:37]
	v_mfma_f32_16x16x32_bf16 v[34:37], v[42:45], v[196:199], v[86:89]
	v_mfma_f32_16x16x32_bf16 v[54:57], v[46:49], v[200:203], v[34:37]
	v_mfma_f32_16x16x32_bf16 v[34:37], v[42:45], v[204:207], v[82:85]
	v_mfma_f32_16x16x32_bf16 v[62:65], v[38:41], v[200:203], v[50:53]
	v_mfma_f32_16x16x32_bf16 v[50:53], v[46:49], v[208:211], v[34:37]
	v_mfma_f32_16x16x32_bf16 v[34:37], v[180:183], v[196:199], v[78:81]
	v_mfma_f32_16x16x32_bf16 v[46:49], v[184:187], v[200:203], v[34:37]
	v_mfma_f32_16x16x32_bf16 v[34:37], v[180:183], v[204:207], v[74:77]
	v_mfma_f32_16x16x32_bf16 v[42:45], v[184:187], v[208:211], v[34:37]
	v_mfma_f32_16x16x32_bf16 v[34:37], v[188:191], v[196:199], v[70:73]
	v_mfma_f32_16x16x32_bf16 v[38:41], v[192:195], v[200:203], v[34:37]
	v_mfma_f32_16x16x32_bf16 v[34:37], v[188:191], v[204:207], v[66:69]
	v_mfma_f32_16x16x32_bf16 v[34:37], v[192:195], v[208:211], v[34:37]
	s_barrier
	ds_read_b128 v[180:183], v159 offset:49152
	ds_read_b128 v[184:187], v159 offset:50176
	ds_read_b128 v[188:191], v147 offset:49152
	ds_read_b128 v[192:195], v147 offset:50176
	ds_read_b128 v[212:215], v146 offset:49152
	ds_read_b128 v[216:219], v146 offset:50176
	ds_read_b128 v[244:247], v145 offset:49152
	ds_read_b128 v[248:251], v145 offset:50176
	s_barrier
	s_waitcnt lgkmcnt(0)
	v_mfma_f32_16x16x32_bf16 v[66:69], v[180:183], v[130:133], v[220:223]
	v_mfma_f32_16x16x32_bf16 v[94:97], v[184:187], v[168:171], v[66:69]
	v_mfma_f32_16x16x32_bf16 v[66:69], v[180:183], v[172:175], v[224:227]
	v_mfma_f32_16x16x32_bf16 v[90:93], v[184:187], v[176:179], v[66:69]
	v_mfma_f32_16x16x32_bf16 v[66:69], v[188:191], v[130:133], v[228:231]
	v_mfma_f32_16x16x32_bf16 v[86:89], v[192:195], v[168:171], v[66:69]
	v_mfma_f32_16x16x32_bf16 v[66:69], v[188:191], v[172:175], v[232:235]
	v_mfma_f32_16x16x32_bf16 v[82:85], v[192:195], v[176:179], v[66:69]
	v_mfma_f32_16x16x32_bf16 v[66:69], v[212:215], v[130:133], v[236:239]
	v_mfma_f32_16x16x32_bf16 v[78:81], v[216:219], v[168:171], v[66:69]
	v_mfma_f32_16x16x32_bf16 v[66:69], v[212:215], v[172:175], v[240:243]
	v_mfma_f32_16x16x32_bf16 v[74:77], v[216:219], v[176:179], v[66:69]
	v_mfma_f32_16x16x32_bf16 v[66:69], v[244:247], v[130:133], v[134:137]
	v_mfma_f32_16x16x32_bf16 v[70:73], v[248:251], v[168:171], v[66:69]
	v_mfma_f32_16x16x32_bf16 v[66:69], v[244:247], v[172:175], v[162:165]
	v_mfma_f32_16x16x32_bf16 v[66:69], v[248:251], v[176:179], v[66:69]
	v_mfma_f32_16x16x32_bf16 v[30:33], v[180:183], v[196:199], v[30:33]
	v_mfma_f32_16x16x32_bf16 v[26:29], v[180:183], v[204:207], v[26:29]
	v_mfma_f32_16x16x32_bf16 v[22:25], v[188:191], v[196:199], v[22:25]
	v_mfma_f32_16x16x32_bf16 v[18:21], v[188:191], v[204:207], v[18:21]
	v_mfma_f32_16x16x32_bf16 v[14:17], v[212:215], v[196:199], v[14:17]
	v_mfma_f32_16x16x32_bf16 v[10:13], v[212:215], v[204:207], v[10:13]
	v_mfma_f32_16x16x32_bf16 v[6:9], v[244:247], v[196:199], v[6:9]
	v_mfma_f32_16x16x32_bf16 v[2:5], v[244:247], v[204:207], v[2:5]
	v_mfma_f32_16x16x32_bf16 v[30:33], v[184:187], v[200:203], v[30:33]
	v_mfma_f32_16x16x32_bf16 v[26:29], v[184:187], v[208:211], v[26:29]
	v_mfma_f32_16x16x32_bf16 v[22:25], v[192:195], v[200:203], v[22:25]
	v_mfma_f32_16x16x32_bf16 v[18:21], v[192:195], v[208:211], v[18:21]
	v_mfma_f32_16x16x32_bf16 v[14:17], v[216:219], v[200:203], v[14:17]
	v_mfma_f32_16x16x32_bf16 v[10:13], v[216:219], v[208:211], v[10:13]
	v_mfma_f32_16x16x32_bf16 v[6:9], v[248:251], v[200:203], v[6:9]
	v_mfma_f32_16x16x32_bf16 v[2:5], v[248:251], v[208:211], v[2:5]
	s_setprio 0
	s_movk_i32 s10, 0x100
	v_cmp_gt_u32_e32 vcc, s10, v0
	s_barrier
	s_and_saveexec_b64 s[34:35], vcc
	s_cbranch_execz .LBB0_105
	s_barrier
	s_branch .LBB0_105

; #define hw_tid() ((g_wid << 6) | hw_lane())
; #define STA(P, br, kt) STAGE(P, A, aoff0, aoff1, lda, br, kt)
; #define STB(P, br, kt) STAGE(P, Bt, boff0, boff1, ldb, br, kt)
; #define BAR __builtin_amdgcn_s_barrier()
; __device__ __forceinline__ void gemm256(const u16* __restrict__ A, int lda, const u16* __restrict__ Bt, int ldb, int K,
;                                         f32x4 (&acc)[2][2][4][2], const int g_wid) {
;   int tid = hw_tid(); asm volatile("" : "+v"(tid));
;   const int wid = tid >> 6, lane = tid & 63, wr = wid >> 2, wc = wid & 3, fr = lane & 15, fq = lane >> 4;
;   int r0, c0, r1, c1;
;   stage_rc(tid * 16, r0, c0);
;   stage_rc(tid * 16 + 8192, r1, c1);
;   const int aoff0 = r0 * lda + c0, aoff1 = r1 * lda + c1, boff0 = r0 * ldb + c0, boff1 = r1 * ldb + c1;
;   bf16x8 At[4][2], B0[2][2], B1[2][2];
;   const int nt = K / BK;
;   STB(SB(0, 0), 0, 0); STA(SA(0, 0), 0, 0);
;   STB(SB(0, 1), HALF, 0); STA(SA(0, 1), HALF, 0);
;   if (wr == 1) BAR;
; __device__ __forceinline__ void phase_g4(PP p, const int g_wid) {
;     ...
;     for (int b = 0; b < 3; ++b) {
;       gemm256(p->Wm + 7602176L + (long)b * 524288 + (long)pn * 256 * 512, 512, p->X + X_BO + (long)pm * 256 * 1536 + b * 512, 1536, 512, acc, g_wid);
.LBB0_114:
	s_lshl_b64 s[24:25], s[54:55], 20
	s_add_u32 s24, s30, s24
	s_addc_u32 s25, s31, s25
	s_lshl_b32 s10, s54, 10
	s_add_u32 s26, s34, s10
	s_mov_b32 s10, -1
	s_addc_u32 s27, s35, 0
	v_mbcnt_lo_u32_b32 v0, s10, 0
	v_mbcnt_hi_u32_b32 v0, s10, v0
	v_or_b32_e32 v0, s37, v0
	v_readlane_b32 s10, v254, 40
	v_ashrrev_i32_e32 v2, 31, v0
	v_lshrrev_b32_e32 v2, 26, v2
	v_add_u32_e32 v2, v0, v2
	v_ashrrev_i32_e32 v162, 6, v2
	v_bfe_i32 v2, v0, 27, 1
	v_lshlrev_b32_e32 v173, 4, v0
	v_lshrrev_b32_e32 v2, 22, v2
	v_add_u32_e32 v2, v173, v2
	v_and_b32_e32 v2, 0xfffffc00, v2
	v_sub_u32_e32 v2, v173, v2
	v_lshrrev_b32_e32 v3, 4, v2
	v_bitop3_b32 v2, v3, v2, 32 bitop3:0x6c
	v_ashrrev_i32_e32 v132, 31, v2
	v_lshrrev_b32_e32 v132, 26, v132
	v_add_u32_e32 v132, v2, v132
	v_ashrrev_i32_e32 v168, 6, v132
	v_and_b32_e32 v132, 0xc0, v132
	v_sub_u32_e32 v2, v2, v132
	v_ashrrev_i16_sdwa v2, v151, sext(v2) dst_sel:DWORD dst_unused:UNUSED_PAD src0_sel:DWORD src1_sel:BYTE_0
	v_bfe_i32 v176, v2, 0, 16
	v_add_u32_e32 v2, 0x2000, v173
	v_ashrrev_i32_e32 v132, 31, v2
	v_lshrrev_b32_e32 v132, 22, v132
	v_add_u32_e32 v132, v2, v132
	v_ashrrev_i32_e32 v177, 10, v132
	v_mul_i32_i24_e32 v132, 0x400, v177
	v_sub_u32_e32 v2, v2, v132
	v_lshrrev_b32_e32 v132, 4, v2
	v_lshlrev_b32_e32 v133, 5, v162
	v_bitop3_b32 v2, v132, v2, 32 bitop3:0x6c
	v_and_b32_e32 v175, 32, v133
	v_ashrrev_i32_e32 v133, 31, v2
	v_lshrrev_b32_e32 v133, 26, v133
	v_lshlrev_b32_e32 v132, 3, v177
	v_add_u32_e32 v133, v2, v133
	v_and_b32_e32 v132, -16, v132
	v_ashrrev_i32_e32 v179, 6, v133
	v_add_u32_e32 v134, v179, v132
	v_lshlrev_b32_e32 v132, 5, v177
	v_lshlrev_b32_e32 v3, 3, v162
	v_and_b32_e32 v178, 32, v132
	v_and_b32_e32 v132, 0xc0, v133
	v_and_b32_e32 v3, -16, v3
	v_sub_u32_e32 v2, v2, v132
	v_add_u32_e32 v3, v168, v3
	v_ashrrev_i16_sdwa v2, v151, sext(v2) dst_sel:DWORD dst_unused:UNUSED_PAD src0_sel:DWORD src1_sel:BYTE_0
	v_bfe_i32 v180, v2, 0, 16
	v_lshlrev_b32_e32 v2, 9, v3
	v_add3_u32 v132, v175, v176, v2
	v_lshlrev_b32_e32 v2, 9, v134
	v_add3_u32 v2, v178, v180, v2
	v_lshl_add_u32 v136, v3, 10, v132
	v_lshl_add_u32 v134, v134, 10, v2
	v_ashrrev_i32_e32 v137, 31, v136
	v_add_u32_e32 v159, s10, v173
	v_lshlrev_b64 v[164:165], 1, v[136:137]
	v_readfirstlane_b32 s10, v159
	v_ashrrev_i32_e32 v135, 31, v134
	v_add_u32_e32 v160, 0x2000, v159
	v_lshl_add_u64 v[138:139], s[26:27], 0, v[164:165]
	s_mov_b32 m0, s10
	v_lshlrev_b64 v[166:167], 1, v[134:135]
	v_readfirstlane_b32 s10, v160
	v_ashrrev_i32_e32 v133, 31, v132
	v_add_u32_e32 v161, 0, v173
	global_load_lds_dwordx4 v[138:139], off
	v_lshl_add_u64 v[142:143], s[26:27], 0, v[166:167]
	s_mov_b32 m0, s10
	v_lshlrev_b64 v[170:171], 1, v[132:133]
	v_readfirstlane_b32 s10, v161
	v_add_u32_e32 v163, 0x2000, v161
	global_load_lds_dwordx4 v[142:143], off
	v_lshl_add_u64 v[144:145], s[24:25], 0, v[170:171]
	s_mov_b32 m0, s10
	v_readfirstlane_b32 s10, v163
	s_add_u32 s28, s26, 0x60000
	global_load_lds_dwordx4 v[144:145], off
	v_ashrrev_i32_e32 v3, 31, v2
	s_mov_b32 m0, s10
	s_addc_u32 s29, s27, 0
	v_readlane_b32 s10, v254, 41
	v_lshlrev_b64 v[182:183], 1, v[2:3]
	v_lshl_add_u64 v[184:185], s[28:29], 0, v[164:165]
	v_add_u32_e32 v164, s10, v173
	v_lshl_add_u64 v[146:147], s[24:25], 0, v[182:183]
	v_readfirstlane_b32 s10, v164
	v_add_u32_e32 v165, 0x2000, v164
	global_load_lds_dwordx4 v[146:147], off
	s_mov_b32 m0, s10
	v_readfirstlane_b32 s10, v165
	global_load_lds_dwordx4 v[184:185], off
	v_lshl_add_u64 v[166:167], s[28:29], 0, v[166:167]
	s_mov_b32 m0, s10
	s_add_u32 s28, s24, 0x20000
	global_load_lds_dwordx4 v[166:167], off
	v_add_u32_e32 v166, 0x4000, v161
	s_addc_u32 s29, s25, 0
	v_readfirstlane_b32 s10, v166
	v_add_u32_e32 v167, 0x6000, v161
	v_lshl_add_u64 v[170:171], s[28:29], 0, v[170:171]
	s_mov_b32 m0, s10
	v_readfirstlane_b32 s10, v167
	global_load_lds_dwordx4 v[170:171], off
	v_lshl_add_u64 v[170:171], s[28:29], 0, v[182:183]
	s_mov_b32 m0, s10
	v_ashrrev_i32_e32 v181, 8, v0
	global_load_lds_dwordx4 v[170:171], off
	v_cmp_eq_u32_e32 vcc, 1, v181
	s_and_saveexec_b64 s[28:29], vcc
	s_cbranch_execz .LBB0_116
	s_setprio 3
	s_barrier

; #define STA(P, br, kt) STAGE(P, A, aoff0, aoff1, lda, br, kt)
; #define STB(P, br, kt) STAGE(P, Bt, boff0, boff1, ldb, br, kt)
; #define LDA(dst, b, h) _Pragma("unroll") for (int m = 0; m < 4; ++m) _Pragma("unroll") for (int k = 0; k < 2; ++k) \
;     dst[m][k] = *reinterpret_cast<const bf16x8*>((char*)SA(b, h) + lds_byte(wr * 64 + m * 16 + fr, k * 32 + fq * 8))
; #define LDB(dst, b, h) _Pragma("unroll") for (int n = 0; n < 2; ++n) _Pragma("unroll") for (int k = 0; k < 2; ++k) \
;     dst[n][k] = *reinterpret_cast<const bf16x8*>((char*)SB(b, h) + lds_byte(wc * 32 + n * 16 + fr, k * 32 + fq * 8))
; #define MMA(ai, bj, At, Bq) do { __builtin_amdgcn_s_setprio(1); \
;     _Pragma("unroll") for (int m = 0; m < 4; ++m) _Pragma("unroll") for (int n = 0; n < 2; ++n) _Pragma("unroll") for (int k = 0; k < 2; ++k) \
;       acc[ai][bj][m][n] = __builtin_amdgcn_mfma_f32_16x16x32_bf16(At[m][k], Bq[n][k], acc[ai][bj][m][n], 0, 0, 0); \
;     __builtin_amdgcn_s_setprio(0); } while (0)
; #define WAIT_L(n) asm volatile("s_waitcnt lgkmcnt(" #n ")" ::: "memory")
; #define BAR __builtin_amdgcn_s_barrier()
; #define SCHED __builtin_amdgcn_sched_barrier(0)
; __device__ __forceinline__ void gemm256(const u16* __restrict__ A, int lda, const u16* __restrict__ Bt, int ldb, int K,
;                                         f32x4 (&acc)[2][2][4][2], const int g_wid) {
;     ...
;     LDB(B0, 0, 0); SCHED; LDA(At, 0, 0); STA(SA(1, 1), HALF, t + 1);
;     WAIT_L(8); BAR; WAIT_L(0); MMA(0, 0, At, B0); BAR; SCHED;
;     LDB(B1, 0, 1); STB(SB(0, 0), 0, t + 2);
;     BAR; WAIT_L(0); MMA(0, 1, At, B1); BAR;
;     LDA(At, 0, 1); STA(SA(0, 0), 0, t + 2);
;     BAR; WAIT_L(0); MMA(1, 0, At, B0); BAR; SCHED;
.LBB0_117:
	ds_read_b128 v[180:183], v176
	ds_read_b128 v[184:187], v176 offset:1024
	ds_read_b128 v[188:191], v176 offset:2048
	ds_read_b128 v[192:195], v176 offset:3072
	v_add_u32_e32 v177, 0xc000, v161
	v_lshl_add_u64 v[244:245], v[142:143], 0, s[26:27]
	v_readfirstlane_b32 s10, v177
	v_lshl_add_u64 v[178:179], v[244:245], 0, s[88:89]
	s_mov_b32 m0, s10
	ds_read_b128 v[196:199], v147
	ds_read_b128 v[200:203], v147 offset:1024
	ds_read_b128 v[204:207], v146
	ds_read_b128 v[208:211], v146 offset:1024
	ds_read_b128 v[212:215], v145
	ds_read_b128 v[216:219], v145 offset:1024
	ds_read_b128 v[220:223], v144
	ds_read_b128 v[224:227], v144 offset:1024
	global_load_lds_dwordx4 v[178:179], off
	v_add_u32_e32 v178, 0xe000, v161
	v_lshl_add_u64 v[246:247], v[138:139], 0, s[26:27]
	v_readfirstlane_b32 s10, v178
	v_lshl_add_u64 v[228:229], v[246:247], 0, s[88:89]
	s_mov_b32 m0, s10
	s_nop 0
	global_load_lds_dwordx4 v[228:229], off
	s_waitcnt lgkmcnt(8)
	s_barrier
	s_waitcnt lgkmcnt(0)
	v_mfma_f32_16x16x32_bf16 v[8:11], v[196:199], v[180:183], v[8:11]
	v_mfma_f32_16x16x32_bf16 v[4:7], v[196:199], v[188:191], v[4:7]
	v_mfma_f32_16x16x32_bf16 v[24:27], v[204:207], v[180:183], v[24:27]
	v_mfma_f32_16x16x32_bf16 v[20:23], v[204:207], v[188:191], v[20:23]
	v_mfma_f32_16x16x32_bf16 v[56:59], v[212:215], v[180:183], v[56:59]
	v_mfma_f32_16x16x32_bf16 v[52:55], v[212:215], v[188:191], v[52:55]
	v_mfma_f32_16x16x32_bf16 v[88:91], v[220:223], v[180:183], v[88:91]
	v_mfma_f32_16x16x32_bf16 v[84:87], v[220:223], v[188:191], v[84:87]
	v_mfma_f32_16x16x32_bf16 v[8:11], v[200:203], v[184:187], v[8:11]
	v_mfma_f32_16x16x32_bf16 v[4:7], v[200:203], v[192:195], v[4:7]
	v_mfma_f32_16x16x32_bf16 v[24:27], v[208:211], v[184:187], v[24:27]
	v_mfma_f32_16x16x32_bf16 v[20:23], v[208:211], v[192:195], v[20:23]
	v_mfma_f32_16x16x32_bf16 v[56:59], v[216:219], v[184:187], v[56:59]
	v_mfma_f32_16x16x32_bf16 v[52:55], v[216:219], v[192:195], v[52:55]
	v_mfma_f32_16x16x32_bf16 v[88:91], v[224:227], v[184:187], v[88:91]
	v_mfma_f32_16x16x32_bf16 v[84:87], v[224:227], v[192:195], v[84:87]
	s_barrier
	v_lshl_add_u64 v[248:249], v[136:137], 0, s[26:27]
	v_readfirstlane_b32 s10, v159
	v_lshl_add_u64 v[250:251], v[248:249], 0, s[90:91]
	s_mov_b32 m0, s10
	ds_read_b128 v[228:231], v175
	ds_read_b128 v[232:235], v175 offset:1024
	ds_read_b128 v[236:239], v175 offset:2048
	ds_read_b128 v[240:243], v175 offset:3072
	global_load_lds_dwordx4 v[250:251], off
	v_lshl_add_u64 v[250:251], v[134:135], 0, s[26:27]
	v_readfirstlane_b32 s10, v160
	v_lshl_add_u64 v[252:253], v[250:251], 0, s[90:91]
	s_mov_b32 m0, s10
	s_nop 0
	global_load_lds_dwordx4 v[252:253], off
	s_barrier
	s_waitcnt lgkmcnt(0)
	v_mfma_f32_16x16x32_bf16 v[16:19], v[196:199], v[228:231], v[16:19]
	v_mfma_f32_16x16x32_bf16 v[12:15], v[196:199], v[236:239], v[12:15]
	v_mfma_f32_16x16x32_bf16 v[40:43], v[204:207], v[228:231], v[40:43]
	v_mfma_f32_16x16x32_bf16 v[36:39], v[204:207], v[236:239], v[36:39]
	v_mfma_f32_16x16x32_bf16 v[72:75], v[212:215], v[228:231], v[72:75]
	v_mfma_f32_16x16x32_bf16 v[64:67], v[212:215], v[236:239], v[64:67]
	v_mfma_f32_16x16x32_bf16 v[104:107], v[220:223], v[228:231], v[104:107]
	v_mfma_f32_16x16x32_bf16 v[92:95], v[220:223], v[236:239], v[92:95]
	v_mfma_f32_16x16x32_bf16 v[16:19], v[200:203], v[232:235], v[16:19]
	v_mfma_f32_16x16x32_bf16 v[12:15], v[200:203], v[240:243], v[12:15]
	v_mfma_f32_16x16x32_bf16 v[40:43], v[208:211], v[232:235], v[40:43]
	v_mfma_f32_16x16x32_bf16 v[36:39], v[208:211], v[240:243], v[36:39]
	v_mfma_f32_16x16x32_bf16 v[72:75], v[216:219], v[232:235], v[72:75]
	v_mfma_f32_16x16x32_bf16 v[64:67], v[216:219], v[240:243], v[64:67]
	v_mfma_f32_16x16x32_bf16 v[104:107], v[224:227], v[232:235], v[104:107]
	v_mfma_f32_16x16x32_bf16 v[92:95], v[224:227], v[240:243], v[92:95]
	v_readfirstlane_b32 s10, v161
	v_lshl_add_u64 v[252:253], v[244:245], 0, s[92:93]
	s_mov_b32 m0, s10
	v_readfirstlane_b32 s10, v163
	s_barrier
	ds_read_b128 v[196:199], v147 offset:16384
	ds_read_b128 v[200:203], v147 offset:17408
	ds_read_b128 v[204:207], v146 offset:16384
	ds_read_b128 v[208:211], v146 offset:17408
	ds_read_b128 v[212:215], v145 offset:16384
	ds_read_b128 v[216:219], v145 offset:17408
	ds_read_b128 v[220:223], v144 offset:16384
	ds_read_b128 v[224:227], v144 offset:17408
	global_load_lds_dwordx4 v[252:253], off
	v_lshl_add_u64 v[252:253], v[246:247], 0, s[92:93]
	s_mov_b32 m0, s10
	s_nop 0
	global_load_lds_dwordx4 v[252:253], off
	s_barrier
	s_waitcnt lgkmcnt(0)
	v_mfma_f32_16x16x32_bf16 v[120:123], v[196:199], v[180:183], v[120:123]
	v_mfma_f32_16x16x32_bf16 v[116:119], v[196:199], v[188:191], v[116:119]
	v_mfma_f32_16x16x32_bf16 v[112:115], v[204:207], v[180:183], v[112:115]
	v_mfma_f32_16x16x32_bf16 v[108:111], v[204:207], v[188:191], v[108:111]
	v_mfma_f32_16x16x32_bf16 v[80:83], v[212:215], v[180:183], v[80:83]
	v_mfma_f32_16x16x32_bf16 v[76:79], v[212:215], v[188:191], v[76:79]
	v_mfma_f32_16x16x32_bf16 v[48:51], v[220:223], v[180:183], v[48:51]
	v_mfma_f32_16x16x32_bf16 v[44:47], v[220:223], v[188:191], v[44:47]
	v_mfma_f32_16x16x32_bf16 v[120:123], v[200:203], v[184:187], v[120:123]
	v_mfma_f32_16x16x32_bf16 v[116:119], v[200:203], v[192:195], v[116:119]
	v_mfma_f32_16x16x32_bf16 v[112:115], v[208:211], v[184:187], v[112:115]
	v_mfma_f32_16x16x32_bf16 v[108:111], v[208:211], v[192:195], v[108:111]
	v_mfma_f32_16x16x32_bf16 v[80:83], v[216:219], v[184:187], v[80:83]
	v_mfma_f32_16x16x32_bf16 v[76:79], v[216:219], v[192:195], v[76:79]
	v_mfma_f32_16x16x32_bf16 v[48:51], v[224:227], v[184:187], v[48:51]
	v_mfma_f32_16x16x32_bf16 v[44:47], v[224:227], v[192:195], v[44:47]
	s_barrier
; #define STA(P, br, kt) STAGE(P, A, aoff0, aoff1, lda, br, kt)
; #define STB(P, br, kt) STAGE(P, Bt, boff0, boff1, ldb, br, kt)
; #define LDA(dst, b, h) _Pragma("unroll") for (int m = 0; m < 4; ++m) _Pragma("unroll") for (int k = 0; k < 2; ++k) \
;     dst[m][k] = *reinterpret_cast<const bf16x8*>((char*)SA(b, h) + lds_byte(wr * 64 + m * 16 + fr, k * 32 + fq * 8))
; #define LDB(dst, b, h) _Pragma("unroll") for (int n = 0; n < 2; ++n) _Pragma("unroll") for (int k = 0; k < 2; ++k) \
;     dst[n][k] = *reinterpret_cast<const bf16x8*>((char*)SB(b, h) + lds_byte(wc * 32 + n * 16 + fr, k * 32 + fq * 8))
; #define MMA(ai, bj, At, Bq) do { __builtin_amdgcn_s_setprio(1); \
;     _Pragma("unroll") for (int m = 0; m < 4; ++m) _Pragma("unroll") for (int n = 0; n < 2; ++n) _Pragma("unroll") for (int k = 0; k < 2; ++k) \
;       acc[ai][bj][m][n] = __builtin_amdgcn_mfma_f32_16x16x32_bf16(At[m][k], Bq[n][k], acc[ai][bj][m][n], 0, 0, 0); \
;     __builtin_amdgcn_s_setprio(0); } while (0)
; #define WAIT_V(n) asm volatile("s_waitcnt vmcnt(" #n ")" ::: "memory")
; #define WAIT_L(n) asm volatile("s_waitcnt lgkmcnt(" #n ")" ::: "memory")
; #define BAR __builtin_amdgcn_s_barrier()
; #define SCHED __builtin_amdgcn_sched_barrier(0)
; __device__ __forceinline__ void gemm256(const u16* __restrict__ A, int lda, const u16* __restrict__ Bt, int ldb, int K,
;                                         f32x4 (&acc)[2][2][4][2], const int g_wid) {
;     ...
;     STB(SB(0, 1), HALF, t + 2);
;     WAIT_V(6); BAR; MMA(1, 1, At, B1); BAR;
;     LDB(B0, 1, 0); SCHED; LDA(At, 1, 0); STA(SA(0, 1), HALF, t + 2);
;     WAIT_L(8); BAR; WAIT_L(0); MMA(0, 0, At, B0); BAR; SCHED;
;     LDB(B1, 1, 1); STB(SB(1, 0), 0, t + 3);
;     BAR; WAIT_L(0); MMA(0, 1, At, B1); BAR;
;     LDA(At, 1, 1); STA(SA(1, 0), 0, t + 3);
	v_readfirstlane_b32 s10, v164
	v_lshl_add_u64 v[180:181], v[248:249], 0, s[94:95]
	s_mov_b32 m0, s10
	v_readfirstlane_b32 s10, v165
	global_load_lds_dwordx4 v[180:181], off
	v_lshl_add_u64 v[180:181], v[250:251], 0, s[94:95]
	s_mov_b32 m0, s10
	s_nop 0
	global_load_lds_dwordx4 v[180:181], off
	s_waitcnt vmcnt(6)
	s_barrier
	v_mfma_f32_16x16x32_bf16 v[128:131], v[196:199], v[228:231], v[128:131]
	v_mfma_f32_16x16x32_bf16 v[124:127], v[196:199], v[236:239], v[124:127]
	v_mfma_f32_16x16x32_bf16 v[100:103], v[204:207], v[228:231], v[100:103]
	v_mfma_f32_16x16x32_bf16 v[96:99], v[204:207], v[236:239], v[96:99]
	v_mfma_f32_16x16x32_bf16 v[68:71], v[212:215], v[228:231], v[68:71]
	v_mfma_f32_16x16x32_bf16 v[60:63], v[212:215], v[236:239], v[60:63]
	v_mfma_f32_16x16x32_bf16 v[32:35], v[220:223], v[228:231], v[32:35]
	v_mfma_f32_16x16x32_bf16 v[28:31], v[220:223], v[236:239], v[28:31]
	v_mfma_f32_16x16x32_bf16 v[128:131], v[200:203], v[232:235], v[128:131]
	v_mfma_f32_16x16x32_bf16 v[124:127], v[200:203], v[240:243], v[124:127]
	v_mfma_f32_16x16x32_bf16 v[100:103], v[208:211], v[232:235], v[100:103]
	v_mfma_f32_16x16x32_bf16 v[96:99], v[208:211], v[240:243], v[96:99]
	v_mfma_f32_16x16x32_bf16 v[68:71], v[216:219], v[232:235], v[68:71]
	v_mfma_f32_16x16x32_bf16 v[60:63], v[216:219], v[240:243], v[60:63]
	v_mfma_f32_16x16x32_bf16 v[32:35], v[224:227], v[232:235], v[32:35]
	v_mfma_f32_16x16x32_bf16 v[28:31], v[224:227], v[240:243], v[28:31]
	s_barrier
	ds_read_b128 v[180:183], v168
	ds_read_b128 v[184:187], v168 offset:1024
	ds_read_b128 v[188:191], v168 offset:2048
	ds_read_b128 v[192:195], v168 offset:3072
	v_readfirstlane_b32 s10, v166
	v_lshl_add_u64 v[228:229], v[244:245], 0, s[96:97]
	s_mov_b32 m0, s10
	v_readfirstlane_b32 s10, v167
	ds_read_b128 v[196:199], v147 offset:32768
	ds_read_b128 v[200:203], v147 offset:33792
	ds_read_b128 v[204:207], v146 offset:32768
	ds_read_b128 v[208:211], v146 offset:33792
	ds_read_b128 v[212:215], v145 offset:32768
	ds_read_b128 v[216:219], v145 offset:33792
	ds_read_b128 v[220:223], v144 offset:32768
	ds_read_b128 v[224:227], v144 offset:33792
	global_load_lds_dwordx4 v[228:229], off
	v_lshl_add_u64 v[228:229], v[246:247], 0, s[96:97]
	s_mov_b32 m0, s10
	s_nop 0
	global_load_lds_dwordx4 v[228:229], off
	s_waitcnt lgkmcnt(8)
	s_barrier
	s_waitcnt lgkmcnt(0)
	v_mfma_f32_16x16x32_bf16 v[8:11], v[196:199], v[180:183], v[8:11]
	v_mfma_f32_16x16x32_bf16 v[4:7], v[196:199], v[188:191], v[4:7]
	v_mfma_f32_16x16x32_bf16 v[24:27], v[204:207], v[180:183], v[24:27]
	v_mfma_f32_16x16x32_bf16 v[20:23], v[204:207], v[188:191], v[20:23]
	v_mfma_f32_16x16x32_bf16 v[56:59], v[212:215], v[180:183], v[56:59]
	v_mfma_f32_16x16x32_bf16 v[52:55], v[212:215], v[188:191], v[52:55]
	v_mfma_f32_16x16x32_bf16 v[88:91], v[220:223], v[180:183], v[88:91]
	v_mfma_f32_16x16x32_bf16 v[84:87], v[220:223], v[188:191], v[84:87]
	v_mfma_f32_16x16x32_bf16 v[8:11], v[200:203], v[184:187], v[8:11]
	v_mfma_f32_16x16x32_bf16 v[4:7], v[200:203], v[192:195], v[4:7]
	v_mfma_f32_16x16x32_bf16 v[24:27], v[208:211], v[184:187], v[24:27]
	v_mfma_f32_16x16x32_bf16 v[20:23], v[208:211], v[192:195], v[20:23]
	v_mfma_f32_16x16x32_bf16 v[56:59], v[216:219], v[184:187], v[56:59]
	v_mfma_f32_16x16x32_bf16 v[52:55], v[216:219], v[192:195], v[52:55]
	v_mfma_f32_16x16x32_bf16 v[88:91], v[224:227], v[184:187], v[88:91]
	v_mfma_f32_16x16x32_bf16 v[84:87], v[224:227], v[192:195], v[84:87]
	s_barrier
	v_readfirstlane_b32 s10, v169
	v_lshl_add_u64 v[252:253], v[248:249], 0, s[66:67]
	s_mov_b32 m0, s10
	v_readfirstlane_b32 s10, v170
	ds_read_b128 v[228:231], v162
	ds_read_b128 v[232:235], v162 offset:1024
	ds_read_b128 v[236:239], v162 offset:2048
	ds_read_b128 v[240:243], v162 offset:3072
	global_load_lds_dwordx4 v[252:253], off
	v_lshl_add_u64 v[252:253], v[250:251], 0, s[66:67]
	s_mov_b32 m0, s10
	s_nop 0
	global_load_lds_dwordx4 v[252:253], off
	s_barrier
	s_waitcnt lgkmcnt(0)
	v_mfma_f32_16x16x32_bf16 v[16:19], v[196:199], v[228:231], v[16:19]
	v_mfma_f32_16x16x32_bf16 v[12:15], v[196:199], v[236:239], v[12:15]
	v_mfma_f32_16x16x32_bf16 v[40:43], v[204:207], v[228:231], v[40:43]
	v_mfma_f32_16x16x32_bf16 v[36:39], v[204:207], v[236:239], v[36:39]
	v_mfma_f32_16x16x32_bf16 v[72:75], v[212:215], v[228:231], v[72:75]
	v_mfma_f32_16x16x32_bf16 v[64:67], v[212:215], v[236:239], v[64:67]
	v_mfma_f32_16x16x32_bf16 v[104:107], v[220:223], v[228:231], v[104:107]
	v_mfma_f32_16x16x32_bf16 v[92:95], v[220:223], v[236:239], v[92:95]
	v_mfma_f32_16x16x32_bf16 v[16:19], v[200:203], v[232:235], v[16:19]
	v_mfma_f32_16x16x32_bf16 v[12:15], v[200:203], v[240:243], v[12:15]
	v_mfma_f32_16x16x32_bf16 v[40:43], v[208:211], v[232:235], v[40:43]
	v_mfma_f32_16x16x32_bf16 v[36:39], v[208:211], v[240:243], v[36:39]
	v_mfma_f32_16x16x32_bf16 v[72:75], v[216:219], v[232:235], v[72:75]
	v_mfma_f32_16x16x32_bf16 v[64:67], v[216:219], v[240:243], v[64:67]
	v_mfma_f32_16x16x32_bf16 v[104:107], v[224:227], v[232:235], v[104:107]
	v_mfma_f32_16x16x32_bf16 v[92:95], v[224:227], v[240:243], v[92:95]
	v_readfirstlane_b32 s10, v171
	v_lshl_add_u64 v[244:245], v[244:245], 0, s[62:63]
	s_mov_b32 m0, s10
	v_readfirstlane_b32 s10, v172
	s_barrier
	ds_read_b128 v[196:199], v147 offset:49152
	ds_read_b128 v[200:203], v147 offset:50176
	ds_read_b128 v[204:207], v146 offset:49152
	ds_read_b128 v[208:211], v146 offset:50176
	ds_read_b128 v[212:215], v145 offset:49152
	ds_read_b128 v[216:219], v145 offset:50176
	ds_read_b128 v[220:223], v144 offset:49152
	ds_read_b128 v[224:227], v144 offset:50176
	global_load_lds_dwordx4 v[244:245], off
	v_lshl_add_u64 v[244:245], v[246:247], 0, s[62:63]
	s_mov_b32 m0, s10
	s_nop 0
	global_load_lds_dwordx4 v[244:245], off
	s_barrier
; #define STA(P, br, kt) STAGE(P, A, aoff0, aoff1, lda, br, kt)
; #define STB(P, br, kt) STAGE(P, Bt, boff0, boff1, ldb, br, kt)
; #define LDA(dst, b, h) _Pragma("unroll") for (int m = 0; m < 4; ++m) _Pragma("unroll") for (int k = 0; k < 2; ++k) \
;     dst[m][k] = *reinterpret_cast<const bf16x8*>((char*)SA(b, h) + lds_byte(wr * 64 + m * 16 + fr, k * 32 + fq * 8))
; #define LDB(dst, b, h) _Pragma("unroll") for (int n = 0; n < 2; ++n) _Pragma("unroll") for (int k = 0; k < 2; ++k) \
;     dst[n][k] = *reinterpret_cast<const bf16x8*>((char*)SB(b, h) + lds_byte(wc * 32 + n * 16 + fr, k * 32 + fq * 8))
; #define MMA(ai, bj, At, Bq) do { __builtin_amdgcn_s_setprio(1); \
;     _Pragma("unroll") for (int m = 0; m < 4; ++m) _Pragma("unroll") for (int n = 0; n < 2; ++n) _Pragma("unroll") for (int k = 0; k < 2; ++k) \
;       acc[ai][bj][m][n] = __builtin_amdgcn_mfma_f32_16x16x32_bf16(At[m][k], Bq[n][k], acc[ai][bj][m][n], 0, 0, 0); \
;     __builtin_amdgcn_s_setprio(0); } while (0)
; #define WAIT_V(n) asm volatile("s_waitcnt vmcnt(" #n ")" ::: "memory")
; #define WAIT_L(n) asm volatile("s_waitcnt lgkmcnt(" #n ")" ::: "memory")
; #define BAR __builtin_amdgcn_s_barrier()
; #define SCHED __builtin_amdgcn_sched_barrier(0)
; __device__ __forceinline__ void gemm256(const u16* __restrict__ A, int lda, const u16* __restrict__ Bt, int ldb, int K,
;                                         f32x4 (&acc)[2][2][4][2], const int g_wid) {
;     ...
;     BAR; WAIT_L(0); MMA(1, 0, At, B0); BAR; SCHED;
;     STB(SB(1, 1), HALF, t + 3);
;     WAIT_V(6); BAR; MMA(1, 1, At, B1); BAR;
;   }
;   { LDB(B0, 0, 0); LDA(At, 0, 0); STA(SA(1, 1), HALF, nt - 1);
;     BAR; WAIT_L(0); MMA(0, 0, At, B0); BAR;
;     LDB(B1, 0, 1); BAR; WAIT_L(0); MMA(0, 1, At, B1); BAR;
	s_waitcnt lgkmcnt(0)
	v_mfma_f32_16x16x32_bf16 v[120:123], v[196:199], v[180:183], v[120:123]
	v_mfma_f32_16x16x32_bf16 v[116:119], v[196:199], v[188:191], v[116:119]
	v_mfma_f32_16x16x32_bf16 v[112:115], v[204:207], v[180:183], v[112:115]
	v_mfma_f32_16x16x32_bf16 v[108:111], v[204:207], v[188:191], v[108:111]
	v_mfma_f32_16x16x32_bf16 v[80:83], v[212:215], v[180:183], v[80:83]
	v_mfma_f32_16x16x32_bf16 v[76:79], v[212:215], v[188:191], v[76:79]
	v_mfma_f32_16x16x32_bf16 v[48:51], v[220:223], v[180:183], v[48:51]
	v_mfma_f32_16x16x32_bf16 v[44:47], v[220:223], v[188:191], v[44:47]
	v_mfma_f32_16x16x32_bf16 v[120:123], v[200:203], v[184:187], v[120:123]
	v_mfma_f32_16x16x32_bf16 v[116:119], v[200:203], v[192:195], v[116:119]
	v_mfma_f32_16x16x32_bf16 v[112:115], v[208:211], v[184:187], v[112:115]
	v_mfma_f32_16x16x32_bf16 v[108:111], v[208:211], v[192:195], v[108:111]
	v_mfma_f32_16x16x32_bf16 v[80:83], v[216:219], v[184:187], v[80:83]
	v_mfma_f32_16x16x32_bf16 v[76:79], v[216:219], v[192:195], v[76:79]
	v_mfma_f32_16x16x32_bf16 v[48:51], v[224:227], v[184:187], v[48:51]
	v_mfma_f32_16x16x32_bf16 v[44:47], v[224:227], v[192:195], v[44:47]
	s_barrier
	v_readfirstlane_b32 s10, v173
	v_lshl_add_u64 v[180:181], v[248:249], 0, s[56:57]
	s_mov_b32 m0, s10
	v_readfirstlane_b32 s10, v174
	global_load_lds_dwordx4 v[180:181], off
	v_lshl_add_u64 v[180:181], v[250:251], 0, s[56:57]
	s_mov_b32 m0, s10
	s_nop 0
	global_load_lds_dwordx4 v[180:181], off
	s_waitcnt vmcnt(6)
	s_barrier
	v_mfma_f32_16x16x32_bf16 v[128:131], v[196:199], v[228:231], v[128:131]
	v_mfma_f32_16x16x32_bf16 v[124:127], v[196:199], v[236:239], v[124:127]
	v_mfma_f32_16x16x32_bf16 v[100:103], v[204:207], v[228:231], v[100:103]
	v_mfma_f32_16x16x32_bf16 v[96:99], v[204:207], v[236:239], v[96:99]
	v_mfma_f32_16x16x32_bf16 v[68:71], v[212:215], v[228:231], v[68:71]
	v_mfma_f32_16x16x32_bf16 v[60:63], v[212:215], v[236:239], v[60:63]
	v_mfma_f32_16x16x32_bf16 v[32:35], v[220:223], v[228:231], v[32:35]
	v_mfma_f32_16x16x32_bf16 v[28:31], v[220:223], v[236:239], v[28:31]
	v_mfma_f32_16x16x32_bf16 v[128:131], v[200:203], v[232:235], v[128:131]
	v_mfma_f32_16x16x32_bf16 v[124:127], v[200:203], v[240:243], v[124:127]
	v_mfma_f32_16x16x32_bf16 v[100:103], v[208:211], v[232:235], v[100:103]
	v_mfma_f32_16x16x32_bf16 v[96:99], v[208:211], v[240:243], v[96:99]
	v_mfma_f32_16x16x32_bf16 v[68:71], v[216:219], v[232:235], v[68:71]
	v_mfma_f32_16x16x32_bf16 v[60:63], v[216:219], v[240:243], v[60:63]
	v_mfma_f32_16x16x32_bf16 v[32:35], v[224:227], v[232:235], v[32:35]
	v_mfma_f32_16x16x32_bf16 v[28:31], v[224:227], v[240:243], v[28:31]
	s_add_i32 s28, s28, 2
	s_add_u32 s26, s26, 0x100
	s_addc_u32 s27, s27, 0
	s_cmp_lt_u32 s28, 4
	s_barrier
	s_cbranch_scc1 .LBB0_117
	s_add_u32 s24, s24, 0x20380
	s_addc_u32 s25, s25, 0
	v_readfirstlane_b32 s10, v177
	v_lshl_add_u64 v[132:133], v[132:133], 1, s[24:25]
	s_mov_b32 m0, s10
	v_readfirstlane_b32 s10, v178
	ds_read_b128 v[134:137], v176
	ds_read_b128 v[164:167], v176 offset:1024
	ds_read_b128 v[170:173], v176 offset:2048
	ds_read_b128 v[180:183], v176 offset:3072
	ds_read_b128 v[184:187], v147
	ds_read_b128 v[188:191], v147 offset:1024
	ds_read_b128 v[192:195], v146
	ds_read_b128 v[196:199], v146 offset:1024
	ds_read_b128 v[200:203], v145
	ds_read_b128 v[204:207], v145 offset:1024
	ds_read_b128 v[208:211], v144
	ds_read_b128 v[212:215], v144 offset:1024
	global_load_lds_dwordx4 v[132:133], off
	v_lshl_add_u64 v[2:3], v[2:3], 1, s[24:25]
	s_mov_b32 m0, s10
	s_nop 0
	global_load_lds_dwordx4 v[2:3], off
	s_barrier
	s_waitcnt lgkmcnt(0)
	v_mfma_f32_16x16x32_bf16 v[8:11], v[184:187], v[134:137], v[8:11]
	v_mfma_f32_16x16x32_bf16 v[2:5], v[184:187], v[170:173], v[4:7]
	v_mfma_f32_16x16x32_bf16 v[24:27], v[192:195], v[134:137], v[24:27]
	v_mfma_f32_16x16x32_bf16 v[20:23], v[192:195], v[170:173], v[20:23]
	v_mfma_f32_16x16x32_bf16 v[56:59], v[200:203], v[134:137], v[56:59]
	v_mfma_f32_16x16x32_bf16 v[52:55], v[200:203], v[170:173], v[52:55]
	v_mfma_f32_16x16x32_bf16 v[88:91], v[208:211], v[134:137], v[88:91]
	v_mfma_f32_16x16x32_bf16 v[84:87], v[208:211], v[170:173], v[84:87]
	v_mfma_f32_16x16x32_bf16 v[8:11], v[188:191], v[164:167], v[8:11]
	v_mfma_f32_16x16x32_bf16 v[2:5], v[188:191], v[180:183], v[2:5]
	v_mfma_f32_16x16x32_bf16 v[24:27], v[196:199], v[164:167], v[24:27]
	v_mfma_f32_16x16x32_bf16 v[20:23], v[196:199], v[180:183], v[20:23]
	v_mfma_f32_16x16x32_bf16 v[56:59], v[204:207], v[164:167], v[56:59]
	v_mfma_f32_16x16x32_bf16 v[52:55], v[204:207], v[180:183], v[52:55]
	v_mfma_f32_16x16x32_bf16 v[88:91], v[212:215], v[164:167], v[88:91]
	v_mfma_f32_16x16x32_bf16 v[84:87], v[212:215], v[180:183], v[84:87]
	s_barrier
	ds_read_b128 v[176:179], v175
	ds_read_b128 v[216:219], v175 offset:1024
	ds_read_b128 v[220:223], v175 offset:2048
	ds_read_b128 v[224:227], v175 offset:3072
	s_barrier
	s_waitcnt lgkmcnt(0)
	v_mfma_f32_16x16x32_bf16 v[16:19], v[184:187], v[176:179], v[16:19]
	v_mfma_f32_16x16x32_bf16 v[12:15], v[184:187], v[220:223], v[12:15]
	v_mfma_f32_16x16x32_bf16 v[40:43], v[192:195], v[176:179], v[40:43]
	v_mfma_f32_16x16x32_bf16 v[36:39], v[192:195], v[220:223], v[36:39]
	v_mfma_f32_16x16x32_bf16 v[72:75], v[200:203], v[176:179], v[72:75]
	v_mfma_f32_16x16x32_bf16 v[64:67], v[200:203], v[220:223], v[64:67]
	v_mfma_f32_16x16x32_bf16 v[104:107], v[208:211], v[176:179], v[104:107]
	v_mfma_f32_16x16x32_bf16 v[92:95], v[208:211], v[220:223], v[92:95]
	v_mfma_f32_16x16x32_bf16 v[16:19], v[188:191], v[216:219], v[16:19]
	v_mfma_f32_16x16x32_bf16 v[12:15], v[188:191], v[224:227], v[12:15]
	v_mfma_f32_16x16x32_bf16 v[40:43], v[196:199], v[216:219], v[40:43]
	v_mfma_f32_16x16x32_bf16 v[36:39], v[196:199], v[224:227], v[36:39]
	v_mfma_f32_16x16x32_bf16 v[72:75], v[204:207], v[216:219], v[72:75]
	v_mfma_f32_16x16x32_bf16 v[64:67], v[204:207], v[224:227], v[64:67]
	v_mfma_f32_16x16x32_bf16 v[104:107], v[212:215], v[216:219], v[104:107]
	v_mfma_f32_16x16x32_bf16 v[92:95], v[212:215], v[224:227], v[92:95]
	s_barrier
; #define LDA(dst, b, h) _Pragma("unroll") for (int m = 0; m < 4; ++m) _Pragma("unroll") for (int k = 0; k < 2; ++k) \
;     dst[m][k] = *reinterpret_cast<const bf16x8*>((char*)SA(b, h) + lds_byte(wr * 64 + m * 16 + fr, k * 32 + fq * 8))
; #define LDB(dst, b, h) _Pragma("unroll") for (int n = 0; n < 2; ++n) _Pragma("unroll") for (int k = 0; k < 2; ++k) \
;     dst[n][k] = *reinterpret_cast<const bf16x8*>((char*)SB(b, h) + lds_byte(wc * 32 + n * 16 + fr, k * 32 + fq * 8))
; #define MMA(ai, bj, At, Bq) do { __builtin_amdgcn_s_setprio(1); \
;     _Pragma("unroll") for (int m = 0; m < 4; ++m) _Pragma("unroll") for (int n = 0; n < 2; ++n) _Pragma("unroll") for (int k = 0; k < 2; ++k) \
;       acc[ai][bj][m][n] = __builtin_amdgcn_mfma_f32_16x16x32_bf16(At[m][k], Bq[n][k], acc[ai][bj][m][n], 0, 0, 0); \
;     __builtin_amdgcn_s_setprio(0); } while (0)
; #define WAIT_V(n) asm volatile("s_waitcnt vmcnt(" #n ")" ::: "memory")
; #define WAIT_L(n) asm volatile("s_waitcnt lgkmcnt(" #n ")" ::: "memory")
; #define BAR __builtin_amdgcn_s_barrier()
; __device__ __forceinline__ void gemm256(const u16* __restrict__ A, int lda, const u16* __restrict__ Bt, int ldb, int K,
;                                         f32x4 (&acc)[2][2][4][2], const int g_wid) {
;     ...
;     LDA(At, 0, 1); WAIT_V(4); BAR; WAIT_L(0); MMA(1, 0, At, B0); MMA(1, 1, At, B1); BAR; }
;   { LDB(B0, 1, 0); LDA(At, 1, 0); WAIT_V(2); BAR; WAIT_L(0); MMA(0, 0, At, B0); BAR;
	ds_read_b128 v[184:187], v147 offset:16384
	ds_read_b128 v[188:191], v147 offset:17408
	ds_read_b128 v[192:195], v146 offset:16384
	ds_read_b128 v[196:199], v146 offset:17408
	ds_read_b128 v[200:203], v145 offset:16384
	ds_read_b128 v[204:207], v145 offset:17408
	ds_read_b128 v[208:211], v144 offset:16384
	ds_read_b128 v[212:215], v144 offset:17408
	s_waitcnt vmcnt(4)
	s_barrier
	s_waitcnt lgkmcnt(0)
	v_mfma_f32_16x16x32_bf16 v[120:123], v[184:187], v[134:137], v[120:123]
	v_mfma_f32_16x16x32_bf16 v[116:119], v[184:187], v[170:173], v[116:119]
	v_mfma_f32_16x16x32_bf16 v[112:115], v[192:195], v[134:137], v[112:115]
	v_mfma_f32_16x16x32_bf16 v[108:111], v[192:195], v[170:173], v[108:111]
	v_mfma_f32_16x16x32_bf16 v[80:83], v[200:203], v[134:137], v[80:83]
	v_mfma_f32_16x16x32_bf16 v[76:79], v[200:203], v[170:173], v[76:79]
	v_mfma_f32_16x16x32_bf16 v[48:51], v[208:211], v[134:137], v[48:51]
	v_mfma_f32_16x16x32_bf16 v[44:47], v[208:211], v[170:173], v[44:47]
	v_mfma_f32_16x16x32_bf16 v[120:123], v[188:191], v[164:167], v[120:123]
	v_mfma_f32_16x16x32_bf16 v[116:119], v[188:191], v[180:183], v[116:119]
	v_mfma_f32_16x16x32_bf16 v[112:115], v[196:199], v[164:167], v[112:115]
	v_mfma_f32_16x16x32_bf16 v[108:111], v[196:199], v[180:183], v[108:111]
	v_mfma_f32_16x16x32_bf16 v[80:83], v[204:207], v[164:167], v[80:83]
	v_mfma_f32_16x16x32_bf16 v[76:79], v[204:207], v[180:183], v[76:79]
	v_mfma_f32_16x16x32_bf16 v[48:51], v[212:215], v[164:167], v[48:51]
	v_mfma_f32_16x16x32_bf16 v[44:47], v[212:215], v[180:183], v[44:47]
	v_mfma_f32_16x16x32_bf16 v[128:131], v[184:187], v[176:179], v[128:131]
	v_mfma_f32_16x16x32_bf16 v[124:127], v[184:187], v[220:223], v[124:127]
	v_mfma_f32_16x16x32_bf16 v[100:103], v[192:195], v[176:179], v[100:103]
	v_mfma_f32_16x16x32_bf16 v[96:99], v[192:195], v[220:223], v[96:99]
	v_mfma_f32_16x16x32_bf16 v[68:71], v[200:203], v[176:179], v[68:71]
	v_mfma_f32_16x16x32_bf16 v[60:63], v[200:203], v[220:223], v[60:63]
	v_mfma_f32_16x16x32_bf16 v[32:35], v[208:211], v[176:179], v[32:35]
	v_mfma_f32_16x16x32_bf16 v[28:31], v[208:211], v[220:223], v[28:31]
	v_mfma_f32_16x16x32_bf16 v[128:131], v[188:191], v[216:219], v[128:131]
	v_mfma_f32_16x16x32_bf16 v[124:127], v[188:191], v[224:227], v[124:127]
	v_mfma_f32_16x16x32_bf16 v[100:103], v[196:199], v[216:219], v[100:103]
	v_mfma_f32_16x16x32_bf16 v[96:99], v[196:199], v[224:227], v[96:99]
	v_mfma_f32_16x16x32_bf16 v[68:71], v[204:207], v[216:219], v[68:71]
	v_mfma_f32_16x16x32_bf16 v[60:63], v[204:207], v[224:227], v[60:63]
	v_mfma_f32_16x16x32_bf16 v[32:35], v[212:215], v[216:219], v[32:35]
	v_mfma_f32_16x16x32_bf16 v[28:31], v[212:215], v[224:227], v[28:31]
	s_barrier
	ds_read_b128 v[132:135], v168
	ds_read_b128 v[136:139], v168 offset:1024
	ds_read_b128 v[164:167], v168 offset:2048
	ds_read_b128 v[168:171], v168 offset:3072
	ds_read_b128 v[172:175], v147 offset:32768
	ds_read_b128 v[176:179], v147 offset:33792
	ds_read_b128 v[180:183], v146 offset:32768
	ds_read_b128 v[184:187], v146 offset:33792
	ds_read_b128 v[188:191], v145 offset:32768
	ds_read_b128 v[192:195], v145 offset:33792
	ds_read_b128 v[196:199], v144 offset:32768
	ds_read_b128 v[200:203], v144 offset:33792
	s_waitcnt vmcnt(2)
	s_barrier
	s_waitcnt lgkmcnt(0)
	v_mfma_f32_16x16x32_bf16 v[6:9], v[172:175], v[132:135], v[8:11]
	v_mfma_f32_16x16x32_bf16 v[2:5], v[172:175], v[164:167], v[2:5]
	v_mfma_f32_16x16x32_bf16 v[24:27], v[180:183], v[132:135], v[24:27]
	v_mfma_f32_16x16x32_bf16 v[20:23], v[180:183], v[164:167], v[20:23]
	v_mfma_f32_16x16x32_bf16 v[56:59], v[188:191], v[132:135], v[56:59]
	v_mfma_f32_16x16x32_bf16 v[52:55], v[188:191], v[164:167], v[52:55]
	v_mfma_f32_16x16x32_bf16 v[88:91], v[196:199], v[132:135], v[88:91]
	v_mfma_f32_16x16x32_bf16 v[84:87], v[196:199], v[164:167], v[84:87]
	v_mfma_f32_16x16x32_bf16 v[8:11], v[176:179], v[136:139], v[6:9]
	v_mfma_f32_16x16x32_bf16 v[4:7], v[176:179], v[168:171], v[2:5]
	v_mfma_f32_16x16x32_bf16 v[24:27], v[184:187], v[136:139], v[24:27]
	v_mfma_f32_16x16x32_bf16 v[20:23], v[184:187], v[168:171], v[20:23]
	v_mfma_f32_16x16x32_bf16 v[56:59], v[192:195], v[136:139], v[56:59]
	v_mfma_f32_16x16x32_bf16 v[52:55], v[192:195], v[168:171], v[52:55]
	v_mfma_f32_16x16x32_bf16 v[88:91], v[200:203], v[136:139], v[88:91]
	v_mfma_f32_16x16x32_bf16 v[84:87], v[200:203], v[168:171], v[84:87]
	s_barrier
; #define LDA(dst, b, h) _Pragma("unroll") for (int m = 0; m < 4; ++m) _Pragma("unroll") for (int k = 0; k < 2; ++k) \
;     dst[m][k] = *reinterpret_cast<const bf16x8*>((char*)SA(b, h) + lds_byte(wr * 64 + m * 16 + fr, k * 32 + fq * 8))
; #define LDB(dst, b, h) _Pragma("unroll") for (int n = 0; n < 2; ++n) _Pragma("unroll") for (int k = 0; k < 2; ++k) \
;     dst[n][k] = *reinterpret_cast<const bf16x8*>((char*)SB(b, h) + lds_byte(wc * 32 + n * 16 + fr, k * 32 + fq * 8))
; #define MMA(ai, bj, At, Bq) do { __builtin_amdgcn_s_setprio(1); \
;     _Pragma("unroll") for (int m = 0; m < 4; ++m) _Pragma("unroll") for (int n = 0; n < 2; ++n) _Pragma("unroll") for (int k = 0; k < 2; ++k) \
;       acc[ai][bj][m][n] = __builtin_amdgcn_mfma_f32_16x16x32_bf16(At[m][k], Bq[n][k], acc[ai][bj][m][n], 0, 0, 0); \
;     __builtin_amdgcn_s_setprio(0); } while (0)
; #define WAIT_V(n) asm volatile("s_waitcnt vmcnt(" #n ")" ::: "memory")
; #define WAIT_L(n) asm volatile("s_waitcnt lgkmcnt(" #n ")" ::: "memory")
; #define BAR __builtin_amdgcn_s_barrier()
; __device__ __forceinline__ void gemm256(const u16* __restrict__ A, int lda, const u16* __restrict__ Bt, int ldb, int K,
;                                         f32x4 (&acc)[2][2][4][2], const int g_wid) {
;     ...
;     LDB(B1, 1, 1); WAIT_V(0); BAR; WAIT_L(0); MMA(0, 1, At, B1); BAR;
;     LDA(At, 1, 1); BAR; WAIT_L(0); MMA(1, 0, At, B0); MMA(1, 1, At, B1); BAR; }
;   if (wr == 0) BAR;
	ds_read_b128 v[204:207], v162
	ds_read_b128 v[208:211], v162 offset:1024
	ds_read_b128 v[212:215], v162 offset:2048
	ds_read_b128 v[160:163], v162 offset:3072
	s_waitcnt vmcnt(0)
	s_barrier
	s_waitcnt lgkmcnt(0)
	v_mfma_f32_16x16x32_bf16 v[16:19], v[172:175], v[204:207], v[16:19]
	v_mfma_f32_16x16x32_bf16 v[12:15], v[172:175], v[212:215], v[12:15]
	v_mfma_f32_16x16x32_bf16 v[40:43], v[180:183], v[204:207], v[40:43]
	v_mfma_f32_16x16x32_bf16 v[36:39], v[180:183], v[212:215], v[36:39]
	v_mfma_f32_16x16x32_bf16 v[72:75], v[188:191], v[204:207], v[72:75]
	v_mfma_f32_16x16x32_bf16 v[64:67], v[188:191], v[212:215], v[64:67]
	v_mfma_f32_16x16x32_bf16 v[104:107], v[196:199], v[204:207], v[104:107]
	v_mfma_f32_16x16x32_bf16 v[92:95], v[196:199], v[212:215], v[92:95]
	v_mfma_f32_16x16x32_bf16 v[16:19], v[176:179], v[208:211], v[16:19]
	v_mfma_f32_16x16x32_bf16 v[12:15], v[176:179], v[160:163], v[12:15]
	v_mfma_f32_16x16x32_bf16 v[40:43], v[184:187], v[208:211], v[40:43]
	v_mfma_f32_16x16x32_bf16 v[36:39], v[184:187], v[160:163], v[36:39]
	v_mfma_f32_16x16x32_bf16 v[72:75], v[192:195], v[208:211], v[72:75]
	v_mfma_f32_16x16x32_bf16 v[64:67], v[192:195], v[160:163], v[64:67]
	v_mfma_f32_16x16x32_bf16 v[104:107], v[200:203], v[208:211], v[104:107]
	v_mfma_f32_16x16x32_bf16 v[92:95], v[200:203], v[160:163], v[92:95]
	s_barrier
	ds_read_b128 v[172:175], v147 offset:49152
	ds_read_b128 v[176:179], v147 offset:50176
	ds_read_b128 v[180:183], v146 offset:49152
	ds_read_b128 v[184:187], v146 offset:50176
	ds_read_b128 v[188:191], v145 offset:49152
	ds_read_b128 v[192:195], v145 offset:50176
	ds_read_b128 v[196:199], v144 offset:49152
	ds_read_b128 v[142:145], v144 offset:50176
	s_barrier
	s_waitcnt lgkmcnt(0)
	v_mfma_f32_16x16x32_bf16 v[120:123], v[172:175], v[132:135], v[120:123]
	v_mfma_f32_16x16x32_bf16 v[116:119], v[172:175], v[164:167], v[116:119]
	v_mfma_f32_16x16x32_bf16 v[112:115], v[180:183], v[132:135], v[112:115]
	v_mfma_f32_16x16x32_bf16 v[108:111], v[180:183], v[164:167], v[108:111]
	v_mfma_f32_16x16x32_bf16 v[80:83], v[188:191], v[132:135], v[80:83]
	v_mfma_f32_16x16x32_bf16 v[76:79], v[188:191], v[164:167], v[76:79]
	v_mfma_f32_16x16x32_bf16 v[48:51], v[196:199], v[132:135], v[48:51]
	v_mfma_f32_16x16x32_bf16 v[44:47], v[196:199], v[164:167], v[44:47]
	v_mfma_f32_16x16x32_bf16 v[120:123], v[176:179], v[136:139], v[120:123]
	v_mfma_f32_16x16x32_bf16 v[116:119], v[176:179], v[168:171], v[116:119]
	v_mfma_f32_16x16x32_bf16 v[112:115], v[184:187], v[136:139], v[112:115]
	v_mfma_f32_16x16x32_bf16 v[108:111], v[184:187], v[168:171], v[108:111]
	v_mfma_f32_16x16x32_bf16 v[80:83], v[192:195], v[136:139], v[80:83]
	v_mfma_f32_16x16x32_bf16 v[76:79], v[192:195], v[168:171], v[76:79]
	v_mfma_f32_16x16x32_bf16 v[48:51], v[142:145], v[136:139], v[48:51]
	v_mfma_f32_16x16x32_bf16 v[44:47], v[142:145], v[168:171], v[44:47]
	v_mfma_f32_16x16x32_bf16 v[128:131], v[172:175], v[204:207], v[128:131]
	v_mfma_f32_16x16x32_bf16 v[124:127], v[172:175], v[212:215], v[124:127]
	v_mfma_f32_16x16x32_bf16 v[100:103], v[180:183], v[204:207], v[100:103]
	v_mfma_f32_16x16x32_bf16 v[96:99], v[180:183], v[212:215], v[96:99]
	v_mfma_f32_16x16x32_bf16 v[68:71], v[188:191], v[204:207], v[68:71]
	v_mfma_f32_16x16x32_bf16 v[60:63], v[188:191], v[212:215], v[60:63]
	v_mfma_f32_16x16x32_bf16 v[32:35], v[196:199], v[204:207], v[32:35]
	v_mfma_f32_16x16x32_bf16 v[28:31], v[196:199], v[212:215], v[28:31]
	v_mfma_f32_16x16x32_bf16 v[128:131], v[176:179], v[208:211], v[128:131]
	v_mfma_f32_16x16x32_bf16 v[124:127], v[176:179], v[160:163], v[124:127]
	v_mfma_f32_16x16x32_bf16 v[100:103], v[184:187], v[208:211], v[100:103]
	v_mfma_f32_16x16x32_bf16 v[96:99], v[184:187], v[160:163], v[96:99]
	v_mfma_f32_16x16x32_bf16 v[68:71], v[192:195], v[208:211], v[68:71]
	v_mfma_f32_16x16x32_bf16 v[60:63], v[192:195], v[160:163], v[60:63]
	v_mfma_f32_16x16x32_bf16 v[32:35], v[142:145], v[208:211], v[32:35]
	v_mfma_f32_16x16x32_bf16 v[28:31], v[142:145], v[160:163], v[28:31]
	s_setprio 0
	s_movk_i32 s10, 0x100
	v_cmp_gt_u32_e32 vcc, s10, v0
	s_barrier
	s_and_saveexec_b64 s[24:25], vcc
	s_cbranch_execz .LBB0_113
	s_barrier
	s_branch .LBB0_113

; #define hw_tid() ((g_wid << 6) | hw_lane())
; #define STA(P, br, kt) STAGE(P, A, aoff0, aoff1, lda, br, kt)
; #define STB(P, br, kt) STAGE(P, Bt, boff0, boff1, ldb, br, kt)
; #define BAR __builtin_amdgcn_s_barrier()
; __device__ __forceinline__ void gemm256(const u16* __restrict__ A, int lda, const u16* __restrict__ Bt, int ldb, int K,
;                                         f32x4 (&acc)[2][2][4][2], const int g_wid) {
;   int tid = hw_tid(); asm volatile("" : "+v"(tid));
;   const int wid = tid >> 6, lane = tid & 63, wr = wid >> 2, wc = wid & 3, fr = lane & 15, fq = lane >> 4;
;   int r0, c0, r1, c1;
;   stage_rc(tid * 16, r0, c0);
;   stage_rc(tid * 16 + 8192, r1, c1);
;   const int aoff0 = r0 * lda + c0, aoff1 = r1 * lda + c1, boff0 = r0 * ldb + c0, boff1 = r1 * ldb + c1;
;   bf16x8 At[4][2], B0[2][2], B1[2][2];
;   const int nt = K / BK;
;   STB(SB(0, 0), 0, 0); STA(SA(0, 0), 0, 0);
;   STB(SB(0, 1), HALF, 0); STA(SA(0, 1), HALF, 0);
;   if (wr == 1) BAR;
; __device__ __forceinline__ void phase_g4(PP p, const int g_wid) {
;     ...
;   if (bid < 24) {
;     const int pn = bid & 3, pass = bid >> 2;
;     stage_rs(p, 192, par, tid);
;     f32x4 acc[2][2][4][2]; ZERO_ACC;
;     const bool isg = pass < 3;
;     if (isg) gemm256(p->Wm + (long)(4352 + pass * 1024 + pn * 256) * 1024, 1024, p->hb + (long)192 * 256 * 1024, 1024, 1024, acc, g_wid);
;     else gemm256(p->Wm + 7602176L + (long)(pass - 3) * 524288 + (long)pn * 256 * 512, 512, p->X + X_BO + (long)192 * 256 * 1536 + (pass - 3) * 512, 1536, 512, acc, g_wid);
.LBB0_124:
	s_or_b64 exec, exec, s[2:3]
	v_readlane_b32 s6, v254, 0
	v_readlane_b32 s7, v254, 1
	s_load_dwordx2 s[6:7], s[6:7], 0xc0
	s_and_b32 s23, s16, 3
	s_ashr_i32 s24, s16, 2
	s_cmp_gt_i32 s24, 2
	s_cselect_b64 s[2:3], -1, 0
	s_mov_b64 s[12:13], -1
	s_and_b64 vcc, exec, s[2:3]
	s_cbranch_vccz .LBB0_132
	s_mov_b32 s26, -1
	s_add_i32 s54, s24, -3
	v_mbcnt_lo_u32_b32 v0, s26, 0
	v_mbcnt_hi_u32_b32 v0, s26, v0
	v_readlane_b32 s26, v254, 63
	s_lshl_b64 s[14:15], s[54:55], 20
	s_waitcnt lgkmcnt(0)
	s_add_u32 s10, s6, s14
	v_or_b32_e32 v0, s26, v0
	s_addc_u32 s11, s7, s15
	v_ashrrev_i32_e32 v2, 31, v0
	v_lshrrev_b32_e32 v2, 26, v2
	v_add_u32_e32 v2, v0, v2
	v_ashrrev_i32_e32 v17, 6, v2
	v_bfe_i32 v2, v0, 27, 1
	v_lshlrev_b32_e32 v20, 4, v0
	v_lshrrev_b32_e32 v2, 22, v2
	v_add_u32_e32 v2, v20, v2
	v_and_b32_e32 v2, 0xfffffc00, v2
	v_sub_u32_e32 v2, v20, v2
	v_lshrrev_b32_e32 v3, 4, v2
	v_bitop3_b32 v2, v3, v2, 32 bitop3:0x6c
	v_ashrrev_i32_e32 v4, 31, v2
	v_lshrrev_b32_e32 v4, 26, v4
	v_add_u32_e32 v4, v2, v4
	v_ashrrev_i32_e32 v14, 6, v4
	v_and_b32_e32 v4, 0xc0, v4
	v_sub_u32_e32 v2, v2, v4
	v_ashrrev_i16_sdwa v2, v151, sext(v2) dst_sel:DWORD dst_unused:UNUSED_PAD src0_sel:DWORD src1_sel:BYTE_0
	v_bfe_i32 v16, v2, 0, 16
	v_add_u32_e32 v2, 0x2000, v20
	v_ashrrev_i32_e32 v4, 31, v2
	v_lshrrev_b32_e32 v4, 22, v4
	v_add_u32_e32 v4, v2, v4
	v_ashrrev_i32_e32 v19, 10, v4
	v_mul_i32_i24_e32 v4, 0x400, v19
	v_sub_u32_e32 v2, v2, v4
	v_lshrrev_b32_e32 v4, 4, v2
	v_lshlrev_b32_e32 v5, 5, v17
	v_bitop3_b32 v2, v4, v2, 32 bitop3:0x6c
	v_and_b32_e32 v15, 32, v5
	v_ashrrev_i32_e32 v5, 31, v2
	v_lshrrev_b32_e32 v5, 26, v5
	v_lshlrev_b32_e32 v4, 3, v19
	v_add_u32_e32 v5, v2, v5
	s_lshl_b32 s25, s23, 18
	v_and_b32_e32 v4, -16, v4
	v_ashrrev_i32_e32 v22, 6, v5
	s_add_u32 s10, s10, s25
	v_add_u32_e32 v6, v22, v4
	v_lshlrev_b32_e32 v4, 5, v19
	s_addc_u32 s11, s11, 0
	v_lshlrev_b32_e32 v3, 3, v17
	v_and_b32_e32 v21, 32, v4
	v_and_b32_e32 v4, 0xc0, v5
	s_add_u32 s12, s10, 0xe80000
	v_and_b32_e32 v3, -16, v3
	v_sub_u32_e32 v2, v2, v4
	s_addc_u32 s13, s11, 0
	s_lshl_b32 s54, s54, 9
	v_add_u32_e32 v3, v14, v3
	v_ashrrev_i16_sdwa v2, v151, sext(v2) dst_sel:DWORD dst_unused:UNUSED_PAD src0_sel:DWORD src1_sel:BYTE_0
	s_lshl_b64 s[16:17], s[54:55], 1
	v_readlane_b32 s8, v255, 2
	v_bfe_i32 v23, v2, 0, 16
	v_lshlrev_b32_e32 v2, 9, v3
	v_readlane_b32 s9, v255, 3
	s_add_u32 s20, s8, s16
	v_add3_u32 v132, v15, v16, v2
	v_lshlrev_b32_e32 v2, 9, v6
	s_addc_u32 s21, s9, s17
	v_add3_u32 v130, v21, v23, v2
	v_lshl_add_u32 v4, v3, 10, v132
	v_readlane_b32 s26, v254, 40
	s_add_u32 s18, s20, 0x16920000
	v_lshl_add_u32 v2, v6, 10, v130
	v_ashrrev_i32_e32 v5, 31, v4
	v_add_u32_e32 v142, s26, v20
	s_addc_u32 s19, s21, 0
	v_lshlrev_b64 v[24:25], 1, v[4:5]
	v_readfirstlane_b32 s26, v142
	v_ashrrev_i32_e32 v3, 31, v2
	v_add_u32_e32 v147, 0x2000, v142
	v_lshl_add_u64 v[6:7], s[18:19], 0, v[24:25]
	s_mov_b32 m0, s26
	v_lshlrev_b64 v[26:27], 1, v[2:3]
	v_readfirstlane_b32 s26, v147
	v_ashrrev_i32_e32 v133, 31, v132
	v_add_u32_e32 v159, 0, v20
	global_load_lds_dwordx4 v[6:7], off
	v_lshl_add_u64 v[8:9], s[18:19], 0, v[26:27]
	s_mov_b32 m0, s26
	v_lshlrev_b64 v[28:29], 1, v[132:133]
	v_readfirstlane_b32 s26, v159
	v_add_u32_e32 v160, 0x2000, v159
	global_load_lds_dwordx4 v[8:9], off
	v_lshl_add_u64 v[10:11], s[12:13], 0, v[28:29]
	s_mov_b32 m0, s26
	v_readfirstlane_b32 s26, v160
	global_load_lds_dwordx4 v[10:11], off
	v_ashrrev_i32_e32 v131, 31, v130
	s_mov_b32 m0, s26
	v_readlane_b32 s26, v254, 41
	v_lshlrev_b64 v[30:31], 1, v[130:131]
	s_add_u32 s20, s20, 0x16980000
	v_add_u32_e32 v162, s26, v20
	v_lshl_add_u64 v[12:13], s[12:13], 0, v[30:31]
	s_addc_u32 s21, s21, 0
	v_readfirstlane_b32 s26, v162
	global_load_lds_dwordx4 v[12:13], off
	v_lshl_add_u64 v[24:25], s[20:21], 0, v[24:25]
	s_mov_b32 m0, s26
	v_add_u32_e32 v163, 0x2000, v162
	global_load_lds_dwordx4 v[24:25], off
	v_lshl_add_u64 v[24:25], s[20:21], 0, v[26:27]
	v_readfirstlane_b32 s20, v163
	s_mov_b32 m0, s20
	s_add_u32 s20, s10, 0xea0000
	v_add_u32_e32 v164, 0x4000, v159
	s_addc_u32 s21, s11, 0
	v_readfirstlane_b32 s10, v164
	v_add_u32_e32 v165, 0x6000, v159
	global_load_lds_dwordx4 v[24:25], off
	v_lshl_add_u64 v[24:25], s[20:21], 0, v[28:29]
	s_mov_b32 m0, s10
	v_readfirstlane_b32 s10, v165
	global_load_lds_dwordx4 v[24:25], off
	v_lshl_add_u64 v[24:25], s[20:21], 0, v[30:31]
	s_mov_b32 m0, s10
	v_ashrrev_i32_e32 v18, 8, v0
	global_load_lds_dwordx4 v[24:25], off
	v_cmp_eq_u32_e32 vcc, 1, v18
	s_and_saveexec_b64 s[20:21], vcc
	s_cbranch_execz .LBB0_127
	s_setprio 3
	s_barrier

; #define STA(P, br, kt) STAGE(P, A, aoff0, aoff1, lda, br, kt)
; #define STB(P, br, kt) STAGE(P, Bt, boff0, boff1, ldb, br, kt)
; #define LDA(dst, b, h) _Pragma("unroll") for (int m = 0; m < 4; ++m) _Pragma("unroll") for (int k = 0; k < 2; ++k) \
;     dst[m][k] = *reinterpret_cast<const bf16x8*>((char*)SA(b, h) + lds_byte(wr * 64 + m * 16 + fr, k * 32 + fq * 8))
; #define LDB(dst, b, h) _Pragma("unroll") for (int n = 0; n < 2; ++n) _Pragma("unroll") for (int k = 0; k < 2; ++k) \
;     dst[n][k] = *reinterpret_cast<const bf16x8*>((char*)SB(b, h) + lds_byte(wc * 32 + n * 16 + fr, k * 32 + fq * 8))
; #define MMA(ai, bj, At, Bq) do { __builtin_amdgcn_s_setprio(1); \
;     _Pragma("unroll") for (int m = 0; m < 4; ++m) _Pragma("unroll") for (int n = 0; n < 2; ++n) _Pragma("unroll") for (int k = 0; k < 2; ++k) \
;       acc[ai][bj][m][n] = __builtin_amdgcn_mfma_f32_16x16x32_bf16(At[m][k], Bq[n][k], acc[ai][bj][m][n], 0, 0, 0); \
;     __builtin_amdgcn_s_setprio(0); } while (0)
; #define WAIT_L(n) asm volatile("s_waitcnt lgkmcnt(" #n ")" ::: "memory")
; #define BAR __builtin_amdgcn_s_barrier()
; #define SCHED __builtin_amdgcn_sched_barrier(0)
; __device__ __forceinline__ void gemm256(const u16* __restrict__ A, int lda, const u16* __restrict__ Bt, int ldb, int K,
;                                         f32x4 (&acc)[2][2][4][2], const int g_wid) {
;     ...
;     LDB(B0, 0, 0); SCHED; LDA(At, 0, 0); STA(SA(1, 1), HALF, t + 1);
;     WAIT_L(8); BAR; WAIT_L(0); MMA(0, 0, At, B0); BAR; SCHED;
;     LDB(B1, 0, 1); STB(SB(0, 0), 0, t + 2);
;     BAR; WAIT_L(0); MMA(0, 1, At, B1); BAR;
;     LDA(At, 0, 1); STA(SA(0, 0), 0, t + 2);
;     BAR; WAIT_L(0); MMA(1, 0, At, B0); BAR; SCHED;
.LBB0_128:
	ds_read_b128 v[178:181], v174
	ds_read_b128 v[182:185], v174 offset:1024
	ds_read_b128 v[186:189], v174 offset:2048
	ds_read_b128 v[190:193], v174 offset:3072
	v_add_u32_e32 v175, 0xc000, v159
	v_lshl_add_u64 v[242:243], v[140:141], 0, s[14:15]
	v_readfirstlane_b32 s10, v175
	v_lshl_add_u64 v[176:177], v[242:243], 0, s[88:89]
	s_mov_b32 m0, s10
	ds_read_b128 v[194:197], v146
	ds_read_b128 v[198:201], v146 offset:1024
	ds_read_b128 v[202:205], v145
	ds_read_b128 v[206:209], v145 offset:1024
	ds_read_b128 v[210:213], v144
	ds_read_b128 v[214:217], v144 offset:1024
	ds_read_b128 v[218:221], v143
	ds_read_b128 v[222:225], v143 offset:1024
	global_load_lds_dwordx4 v[176:177], off
	v_add_u32_e32 v176, 0xe000, v159
	v_lshl_add_u64 v[244:245], v[138:139], 0, s[14:15]
	v_readfirstlane_b32 s10, v176
	v_lshl_add_u64 v[226:227], v[244:245], 0, s[88:89]
	s_mov_b32 m0, s10
	s_nop 0
	global_load_lds_dwordx4 v[226:227], off
	s_waitcnt lgkmcnt(8)
	s_barrier
	s_waitcnt lgkmcnt(0)
	v_mfma_f32_16x16x32_bf16 v[126:129], v[194:197], v[178:181], v[126:129]
	v_mfma_f32_16x16x32_bf16 v[122:125], v[194:197], v[186:189], v[122:125]
	v_mfma_f32_16x16x32_bf16 v[118:121], v[202:205], v[178:181], v[118:121]
	v_mfma_f32_16x16x32_bf16 v[114:117], v[202:205], v[186:189], v[114:117]
	v_mfma_f32_16x16x32_bf16 v[110:113], v[210:213], v[178:181], v[110:113]
	v_mfma_f32_16x16x32_bf16 v[106:109], v[210:213], v[186:189], v[106:109]
	v_mfma_f32_16x16x32_bf16 v[102:105], v[218:221], v[178:181], v[102:105]
	v_mfma_f32_16x16x32_bf16 v[98:101], v[218:221], v[186:189], v[98:101]
	v_mfma_f32_16x16x32_bf16 v[126:129], v[198:201], v[182:185], v[126:129]
	v_mfma_f32_16x16x32_bf16 v[122:125], v[198:201], v[190:193], v[122:125]
	v_mfma_f32_16x16x32_bf16 v[118:121], v[206:209], v[182:185], v[118:121]
	v_mfma_f32_16x16x32_bf16 v[114:117], v[206:209], v[190:193], v[114:117]
	v_mfma_f32_16x16x32_bf16 v[110:113], v[214:217], v[182:185], v[110:113]
	v_mfma_f32_16x16x32_bf16 v[106:109], v[214:217], v[190:193], v[106:109]
	v_mfma_f32_16x16x32_bf16 v[102:105], v[222:225], v[182:185], v[102:105]
	v_mfma_f32_16x16x32_bf16 v[98:101], v[222:225], v[190:193], v[98:101]
	s_barrier
	v_lshl_add_u64 v[246:247], v[136:137], 0, s[14:15]
	v_readfirstlane_b32 s10, v142
	v_lshl_add_u64 v[248:249], v[246:247], 0, s[8:9]
	s_mov_b32 m0, s10
	ds_read_b128 v[226:229], v173
	ds_read_b128 v[230:233], v173 offset:1024
	ds_read_b128 v[234:237], v173 offset:2048
	ds_read_b128 v[238:241], v173 offset:3072
	global_load_lds_dwordx4 v[248:249], off
	v_lshl_add_u64 v[248:249], v[134:135], 0, s[14:15]
	v_readfirstlane_b32 s10, v147
	v_lshl_add_u64 v[250:251], v[248:249], 0, s[8:9]
	s_mov_b32 m0, s10
	s_nop 0
	global_load_lds_dwordx4 v[250:251], off
	s_barrier
	s_waitcnt lgkmcnt(0)
	v_mfma_f32_16x16x32_bf16 v[94:97], v[194:197], v[226:229], v[94:97]
	v_mfma_f32_16x16x32_bf16 v[90:93], v[194:197], v[234:237], v[90:93]
	v_mfma_f32_16x16x32_bf16 v[86:89], v[202:205], v[226:229], v[86:89]
	v_mfma_f32_16x16x32_bf16 v[82:85], v[202:205], v[234:237], v[82:85]
	v_mfma_f32_16x16x32_bf16 v[78:81], v[210:213], v[226:229], v[78:81]
	v_mfma_f32_16x16x32_bf16 v[74:77], v[210:213], v[234:237], v[74:77]
	v_mfma_f32_16x16x32_bf16 v[70:73], v[218:221], v[226:229], v[70:73]
	v_mfma_f32_16x16x32_bf16 v[66:69], v[218:221], v[234:237], v[66:69]
	v_mfma_f32_16x16x32_bf16 v[94:97], v[198:201], v[230:233], v[94:97]
	v_mfma_f32_16x16x32_bf16 v[90:93], v[198:201], v[238:241], v[90:93]
	v_mfma_f32_16x16x32_bf16 v[86:89], v[206:209], v[230:233], v[86:89]
	v_mfma_f32_16x16x32_bf16 v[82:85], v[206:209], v[238:241], v[82:85]
	v_mfma_f32_16x16x32_bf16 v[78:81], v[214:217], v[230:233], v[78:81]
	v_mfma_f32_16x16x32_bf16 v[74:77], v[214:217], v[238:241], v[74:77]
	v_mfma_f32_16x16x32_bf16 v[70:73], v[222:225], v[230:233], v[70:73]
	v_mfma_f32_16x16x32_bf16 v[66:69], v[222:225], v[238:241], v[66:69]
	v_readfirstlane_b32 s10, v159
	v_lshl_add_u64 v[250:251], v[242:243], 0, s[92:93]
	s_mov_b32 m0, s10
	v_readfirstlane_b32 s10, v160
	s_barrier
	ds_read_b128 v[194:197], v146 offset:16384
	ds_read_b128 v[198:201], v146 offset:17408
	ds_read_b128 v[202:205], v145 offset:16384
	ds_read_b128 v[206:209], v145 offset:17408
	ds_read_b128 v[210:213], v144 offset:16384
	ds_read_b128 v[214:217], v144 offset:17408
	ds_read_b128 v[218:221], v143 offset:16384
	ds_read_b128 v[222:225], v143 offset:17408
	global_load_lds_dwordx4 v[250:251], off
	v_lshl_add_u64 v[250:251], v[244:245], 0, s[92:93]
	s_mov_b32 m0, s10
	s_nop 0
	global_load_lds_dwordx4 v[250:251], off
	s_barrier
	s_waitcnt lgkmcnt(0)
	v_mfma_f32_16x16x32_bf16 v[62:65], v[194:197], v[178:181], v[62:65]
	v_mfma_f32_16x16x32_bf16 v[58:61], v[194:197], v[186:189], v[58:61]
	v_mfma_f32_16x16x32_bf16 v[54:57], v[202:205], v[178:181], v[54:57]
	v_mfma_f32_16x16x32_bf16 v[50:53], v[202:205], v[186:189], v[50:53]
	v_mfma_f32_16x16x32_bf16 v[46:49], v[210:213], v[178:181], v[46:49]
	v_mfma_f32_16x16x32_bf16 v[42:45], v[210:213], v[186:189], v[42:45]
	v_mfma_f32_16x16x32_bf16 v[38:41], v[218:221], v[178:181], v[38:41]
	v_mfma_f32_16x16x32_bf16 v[34:37], v[218:221], v[186:189], v[34:37]
	v_mfma_f32_16x16x32_bf16 v[62:65], v[198:201], v[182:185], v[62:65]
	v_mfma_f32_16x16x32_bf16 v[58:61], v[198:201], v[190:193], v[58:61]
	v_mfma_f32_16x16x32_bf16 v[54:57], v[206:209], v[182:185], v[54:57]
	v_mfma_f32_16x16x32_bf16 v[50:53], v[206:209], v[190:193], v[50:53]
	v_mfma_f32_16x16x32_bf16 v[46:49], v[214:217], v[182:185], v[46:49]
	v_mfma_f32_16x16x32_bf16 v[42:45], v[214:217], v[190:193], v[42:45]
	v_mfma_f32_16x16x32_bf16 v[38:41], v[222:225], v[182:185], v[38:41]
	v_mfma_f32_16x16x32_bf16 v[34:37], v[222:225], v[190:193], v[34:37]
	s_barrier
; #define STA(P, br, kt) STAGE(P, A, aoff0, aoff1, lda, br, kt)
; #define STB(P, br, kt) STAGE(P, Bt, boff0, boff1, ldb, br, kt)
; #define LDA(dst, b, h) _Pragma("unroll") for (int m = 0; m < 4; ++m) _Pragma("unroll") for (int k = 0; k < 2; ++k) \
;     dst[m][k] = *reinterpret_cast<const bf16x8*>((char*)SA(b, h) + lds_byte(wr * 64 + m * 16 + fr, k * 32 + fq * 8))
; #define LDB(dst, b, h) _Pragma("unroll") for (int n = 0; n < 2; ++n) _Pragma("unroll") for (int k = 0; k < 2; ++k) \
;     dst[n][k] = *reinterpret_cast<const bf16x8*>((char*)SB(b, h) + lds_byte(wc * 32 + n * 16 + fr, k * 32 + fq * 8))
; #define MMA(ai, bj, At, Bq) do { __builtin_amdgcn_s_setprio(1); \
;     _Pragma("unroll") for (int m = 0; m < 4; ++m) _Pragma("unroll") for (int n = 0; n < 2; ++n) _Pragma("unroll") for (int k = 0; k < 2; ++k) \
;       acc[ai][bj][m][n] = __builtin_amdgcn_mfma_f32_16x16x32_bf16(At[m][k], Bq[n][k], acc[ai][bj][m][n], 0, 0, 0); \
;     __builtin_amdgcn_s_setprio(0); } while (0)
; #define WAIT_V(n) asm volatile("s_waitcnt vmcnt(" #n ")" ::: "memory")
; #define WAIT_L(n) asm volatile("s_waitcnt lgkmcnt(" #n ")" ::: "memory")
; #define BAR __builtin_amdgcn_s_barrier()
; #define SCHED __builtin_amdgcn_sched_barrier(0)
; __device__ __forceinline__ void gemm256(const u16* __restrict__ A, int lda, const u16* __restrict__ Bt, int ldb, int K,
;                                         f32x4 (&acc)[2][2][4][2], const int g_wid) {
;     ...
;     STB(SB(0, 1), HALF, t + 2);
;     WAIT_V(6); BAR; MMA(1, 1, At, B1); BAR;
;     LDB(B0, 1, 0); SCHED; LDA(At, 1, 0); STA(SA(0, 1), HALF, t + 2);
;     WAIT_L(8); BAR; WAIT_L(0); MMA(0, 0, At, B0); BAR; SCHED;
;     LDB(B1, 1, 1); STB(SB(1, 0), 0, t + 3);
;     BAR; WAIT_L(0); MMA(0, 1, At, B1); BAR;
;     LDA(At, 1, 1); STA(SA(1, 0), 0, t + 3);
	v_readfirstlane_b32 s10, v162
	v_lshl_add_u64 v[178:179], v[246:247], 0, s[18:19]
	s_mov_b32 m0, s10
	v_readfirstlane_b32 s10, v163
	global_load_lds_dwordx4 v[178:179], off
	v_lshl_add_u64 v[178:179], v[248:249], 0, s[18:19]
	s_mov_b32 m0, s10
	s_nop 0
	global_load_lds_dwordx4 v[178:179], off
	s_waitcnt vmcnt(6)
	s_barrier
	v_mfma_f32_16x16x32_bf16 v[30:33], v[194:197], v[226:229], v[30:33]
	v_mfma_f32_16x16x32_bf16 v[26:29], v[194:197], v[234:237], v[26:29]
	v_mfma_f32_16x16x32_bf16 v[22:25], v[202:205], v[226:229], v[22:25]
	v_mfma_f32_16x16x32_bf16 v[18:21], v[202:205], v[234:237], v[18:21]
	v_mfma_f32_16x16x32_bf16 v[14:17], v[210:213], v[226:229], v[14:17]
	v_mfma_f32_16x16x32_bf16 v[10:13], v[210:213], v[234:237], v[10:13]
	v_mfma_f32_16x16x32_bf16 v[6:9], v[218:221], v[226:229], v[6:9]
	v_mfma_f32_16x16x32_bf16 v[2:5], v[218:221], v[234:237], v[2:5]
	v_mfma_f32_16x16x32_bf16 v[30:33], v[198:201], v[230:233], v[30:33]
	v_mfma_f32_16x16x32_bf16 v[26:29], v[198:201], v[238:241], v[26:29]
	v_mfma_f32_16x16x32_bf16 v[22:25], v[206:209], v[230:233], v[22:25]
	v_mfma_f32_16x16x32_bf16 v[18:21], v[206:209], v[238:241], v[18:21]
	v_mfma_f32_16x16x32_bf16 v[14:17], v[214:217], v[230:233], v[14:17]
	v_mfma_f32_16x16x32_bf16 v[10:13], v[214:217], v[238:241], v[10:13]
	v_mfma_f32_16x16x32_bf16 v[6:9], v[222:225], v[230:233], v[6:9]
	v_mfma_f32_16x16x32_bf16 v[2:5], v[222:225], v[238:241], v[2:5]
	s_barrier
	ds_read_b128 v[178:181], v166
	ds_read_b128 v[182:185], v166 offset:1024
	ds_read_b128 v[186:189], v166 offset:2048
	ds_read_b128 v[190:193], v166 offset:3072
	v_readfirstlane_b32 s10, v164
	v_lshl_add_u64 v[226:227], v[242:243], 0, s[96:97]
	s_mov_b32 m0, s10
	v_readfirstlane_b32 s10, v165
	ds_read_b128 v[194:197], v146 offset:32768
	ds_read_b128 v[198:201], v146 offset:33792
	ds_read_b128 v[202:205], v145 offset:32768
	ds_read_b128 v[206:209], v145 offset:33792
	ds_read_b128 v[210:213], v144 offset:32768
	ds_read_b128 v[214:217], v144 offset:33792
	ds_read_b128 v[218:221], v143 offset:32768
	ds_read_b128 v[222:225], v143 offset:33792
	global_load_lds_dwordx4 v[226:227], off
	v_lshl_add_u64 v[226:227], v[244:245], 0, s[96:97]
	s_mov_b32 m0, s10
	s_nop 0
	global_load_lds_dwordx4 v[226:227], off
	s_waitcnt lgkmcnt(8)
	s_barrier
	s_waitcnt lgkmcnt(0)
	v_mfma_f32_16x16x32_bf16 v[126:129], v[194:197], v[178:181], v[126:129]
	v_mfma_f32_16x16x32_bf16 v[122:125], v[194:197], v[186:189], v[122:125]
	v_mfma_f32_16x16x32_bf16 v[118:121], v[202:205], v[178:181], v[118:121]
	v_mfma_f32_16x16x32_bf16 v[114:117], v[202:205], v[186:189], v[114:117]
	v_mfma_f32_16x16x32_bf16 v[110:113], v[210:213], v[178:181], v[110:113]
	v_mfma_f32_16x16x32_bf16 v[106:109], v[210:213], v[186:189], v[106:109]
	v_mfma_f32_16x16x32_bf16 v[102:105], v[218:221], v[178:181], v[102:105]
	v_mfma_f32_16x16x32_bf16 v[98:101], v[218:221], v[186:189], v[98:101]
	v_mfma_f32_16x16x32_bf16 v[126:129], v[198:201], v[182:185], v[126:129]
	v_mfma_f32_16x16x32_bf16 v[122:125], v[198:201], v[190:193], v[122:125]
	v_mfma_f32_16x16x32_bf16 v[118:121], v[206:209], v[182:185], v[118:121]
	v_mfma_f32_16x16x32_bf16 v[114:117], v[206:209], v[190:193], v[114:117]
	v_mfma_f32_16x16x32_bf16 v[110:113], v[214:217], v[182:185], v[110:113]
	v_mfma_f32_16x16x32_bf16 v[106:109], v[214:217], v[190:193], v[106:109]
	v_mfma_f32_16x16x32_bf16 v[102:105], v[222:225], v[182:185], v[102:105]
	v_mfma_f32_16x16x32_bf16 v[98:101], v[222:225], v[190:193], v[98:101]
	s_barrier
	v_readfirstlane_b32 s10, v167
	v_lshl_add_u64 v[250:251], v[246:247], 0, s[20:21]
	s_mov_b32 m0, s10
	v_readfirstlane_b32 s10, v168
	ds_read_b128 v[226:229], v161
	ds_read_b128 v[230:233], v161 offset:1024
	ds_read_b128 v[234:237], v161 offset:2048
	ds_read_b128 v[238:241], v161 offset:3072
	global_load_lds_dwordx4 v[250:251], off
	v_lshl_add_u64 v[250:251], v[248:249], 0, s[20:21]
	s_mov_b32 m0, s10
	s_nop 0
	global_load_lds_dwordx4 v[250:251], off
	s_barrier
	s_waitcnt lgkmcnt(0)
	v_mfma_f32_16x16x32_bf16 v[94:97], v[194:197], v[226:229], v[94:97]
	v_mfma_f32_16x16x32_bf16 v[90:93], v[194:197], v[234:237], v[90:93]
	v_mfma_f32_16x16x32_bf16 v[86:89], v[202:205], v[226:229], v[86:89]
	v_mfma_f32_16x16x32_bf16 v[82:85], v[202:205], v[234:237], v[82:85]
	v_mfma_f32_16x16x32_bf16 v[78:81], v[210:213], v[226:229], v[78:81]
	v_mfma_f32_16x16x32_bf16 v[74:77], v[210:213], v[234:237], v[74:77]
	v_mfma_f32_16x16x32_bf16 v[70:73], v[218:221], v[226:229], v[70:73]
	v_mfma_f32_16x16x32_bf16 v[66:69], v[218:221], v[234:237], v[66:69]
	v_mfma_f32_16x16x32_bf16 v[94:97], v[198:201], v[230:233], v[94:97]
	v_mfma_f32_16x16x32_bf16 v[90:93], v[198:201], v[238:241], v[90:93]
	v_mfma_f32_16x16x32_bf16 v[86:89], v[206:209], v[230:233], v[86:89]
	v_mfma_f32_16x16x32_bf16 v[82:85], v[206:209], v[238:241], v[82:85]
	v_mfma_f32_16x16x32_bf16 v[78:81], v[214:217], v[230:233], v[78:81]
	v_mfma_f32_16x16x32_bf16 v[74:77], v[214:217], v[238:241], v[74:77]
	v_mfma_f32_16x16x32_bf16 v[70:73], v[222:225], v[230:233], v[70:73]
	v_mfma_f32_16x16x32_bf16 v[66:69], v[222:225], v[238:241], v[66:69]
	v_readfirstlane_b32 s10, v169
	v_lshl_add_u64 v[242:243], v[242:243], 0, s[62:63]
	s_mov_b32 m0, s10
	v_readfirstlane_b32 s10, v170
	s_barrier
	ds_read_b128 v[194:197], v146 offset:49152
	ds_read_b128 v[198:201], v146 offset:50176
	ds_read_b128 v[202:205], v145 offset:49152
	ds_read_b128 v[206:209], v145 offset:50176
	ds_read_b128 v[210:213], v144 offset:49152
	ds_read_b128 v[214:217], v144 offset:50176
	ds_read_b128 v[218:221], v143 offset:49152
	ds_read_b128 v[222:225], v143 offset:50176
	global_load_lds_dwordx4 v[242:243], off
	v_lshl_add_u64 v[242:243], v[244:245], 0, s[62:63]
	s_mov_b32 m0, s10
	s_nop 0
	global_load_lds_dwordx4 v[242:243], off
	s_barrier
; #define STA(P, br, kt) STAGE(P, A, aoff0, aoff1, lda, br, kt)
; #define STB(P, br, kt) STAGE(P, Bt, boff0, boff1, ldb, br, kt)
; #define LDA(dst, b, h) _Pragma("unroll") for (int m = 0; m < 4; ++m) _Pragma("unroll") for (int k = 0; k < 2; ++k) \
;     dst[m][k] = *reinterpret_cast<const bf16x8*>((char*)SA(b, h) + lds_byte(wr * 64 + m * 16 + fr, k * 32 + fq * 8))
; #define LDB(dst, b, h) _Pragma("unroll") for (int n = 0; n < 2; ++n) _Pragma("unroll") for (int k = 0; k < 2; ++k) \
;     dst[n][k] = *reinterpret_cast<const bf16x8*>((char*)SB(b, h) + lds_byte(wc * 32 + n * 16 + fr, k * 32 + fq * 8))
; #define MMA(ai, bj, At, Bq) do { __builtin_amdgcn_s_setprio(1); \
;     _Pragma("unroll") for (int m = 0; m < 4; ++m) _Pragma("unroll") for (int n = 0; n < 2; ++n) _Pragma("unroll") for (int k = 0; k < 2; ++k) \
;       acc[ai][bj][m][n] = __builtin_amdgcn_mfma_f32_16x16x32_bf16(At[m][k], Bq[n][k], acc[ai][bj][m][n], 0, 0, 0); \
;     __builtin_amdgcn_s_setprio(0); } while (0)
; #define WAIT_V(n) asm volatile("s_waitcnt vmcnt(" #n ")" ::: "memory")
; #define WAIT_L(n) asm volatile("s_waitcnt lgkmcnt(" #n ")" ::: "memory")
; #define BAR __builtin_amdgcn_s_barrier()
; #define SCHED __builtin_amdgcn_sched_barrier(0)
; __device__ __forceinline__ void gemm256(const u16* __restrict__ A, int lda, const u16* __restrict__ Bt, int ldb, int K,
;                                         f32x4 (&acc)[2][2][4][2], const int g_wid) {
;     ...
;     BAR; WAIT_L(0); MMA(1, 0, At, B0); BAR; SCHED;
;     STB(SB(1, 1), HALF, t + 3);
;     WAIT_V(6); BAR; MMA(1, 1, At, B1); BAR;
;   }
;   { LDB(B0, 0, 0); LDA(At, 0, 0); STA(SA(1, 1), HALF, nt - 1);
;     BAR; WAIT_L(0); MMA(0, 0, At, B0); BAR;
;     LDB(B1, 0, 1); BAR; WAIT_L(0); MMA(0, 1, At, B1); BAR;
	s_waitcnt lgkmcnt(0)
	v_mfma_f32_16x16x32_bf16 v[62:65], v[194:197], v[178:181], v[62:65]
	v_mfma_f32_16x16x32_bf16 v[58:61], v[194:197], v[186:189], v[58:61]
	v_mfma_f32_16x16x32_bf16 v[54:57], v[202:205], v[178:181], v[54:57]
	v_mfma_f32_16x16x32_bf16 v[50:53], v[202:205], v[186:189], v[50:53]
	v_mfma_f32_16x16x32_bf16 v[46:49], v[210:213], v[178:181], v[46:49]
	v_mfma_f32_16x16x32_bf16 v[42:45], v[210:213], v[186:189], v[42:45]
	v_mfma_f32_16x16x32_bf16 v[38:41], v[218:221], v[178:181], v[38:41]
	v_mfma_f32_16x16x32_bf16 v[34:37], v[218:221], v[186:189], v[34:37]
	v_mfma_f32_16x16x32_bf16 v[62:65], v[198:201], v[182:185], v[62:65]
	v_mfma_f32_16x16x32_bf16 v[58:61], v[198:201], v[190:193], v[58:61]
	v_mfma_f32_16x16x32_bf16 v[54:57], v[206:209], v[182:185], v[54:57]
	v_mfma_f32_16x16x32_bf16 v[50:53], v[206:209], v[190:193], v[50:53]
	v_mfma_f32_16x16x32_bf16 v[46:49], v[214:217], v[182:185], v[46:49]
	v_mfma_f32_16x16x32_bf16 v[42:45], v[214:217], v[190:193], v[42:45]
	v_mfma_f32_16x16x32_bf16 v[38:41], v[222:225], v[182:185], v[38:41]
	v_mfma_f32_16x16x32_bf16 v[34:37], v[222:225], v[190:193], v[34:37]
	s_barrier
	v_readfirstlane_b32 s10, v171
	v_lshl_add_u64 v[178:179], v[246:247], 0, s[26:27]
	s_mov_b32 m0, s10
	v_readfirstlane_b32 s10, v172
	global_load_lds_dwordx4 v[178:179], off
	v_lshl_add_u64 v[178:179], v[248:249], 0, s[26:27]
	s_mov_b32 m0, s10
	s_nop 0
	global_load_lds_dwordx4 v[178:179], off
	s_waitcnt vmcnt(6)
	s_barrier
	v_mfma_f32_16x16x32_bf16 v[30:33], v[194:197], v[226:229], v[30:33]
	v_mfma_f32_16x16x32_bf16 v[26:29], v[194:197], v[234:237], v[26:29]
	v_mfma_f32_16x16x32_bf16 v[22:25], v[202:205], v[226:229], v[22:25]
	v_mfma_f32_16x16x32_bf16 v[18:21], v[202:205], v[234:237], v[18:21]
	v_mfma_f32_16x16x32_bf16 v[14:17], v[210:213], v[226:229], v[14:17]
	v_mfma_f32_16x16x32_bf16 v[10:13], v[210:213], v[234:237], v[10:13]
	v_mfma_f32_16x16x32_bf16 v[6:9], v[218:221], v[226:229], v[6:9]
	v_mfma_f32_16x16x32_bf16 v[2:5], v[218:221], v[234:237], v[2:5]
	v_mfma_f32_16x16x32_bf16 v[30:33], v[198:201], v[230:233], v[30:33]
	v_mfma_f32_16x16x32_bf16 v[26:29], v[198:201], v[238:241], v[26:29]
	v_mfma_f32_16x16x32_bf16 v[22:25], v[206:209], v[230:233], v[22:25]
	v_mfma_f32_16x16x32_bf16 v[18:21], v[206:209], v[238:241], v[18:21]
	v_mfma_f32_16x16x32_bf16 v[14:17], v[214:217], v[230:233], v[14:17]
	v_mfma_f32_16x16x32_bf16 v[10:13], v[214:217], v[238:241], v[10:13]
	v_mfma_f32_16x16x32_bf16 v[6:9], v[222:225], v[230:233], v[6:9]
	v_mfma_f32_16x16x32_bf16 v[2:5], v[222:225], v[238:241], v[2:5]
	s_add_i32 s16, s16, 2
	s_add_u32 s14, s14, 0x100
	s_addc_u32 s15, s15, 0
	s_cmp_lt_u32 s16, 4
	s_barrier
	s_cbranch_scc1 .LBB0_128
	s_add_u32 s12, s12, 0x20380
	s_addc_u32 s13, s13, 0
	v_readfirstlane_b32 s10, v175
	v_lshl_add_u64 v[132:133], v[132:133], 1, s[12:13]
	s_mov_b32 m0, s10
	v_readfirstlane_b32 s10, v176
	ds_read_b128 v[134:137], v174
	ds_read_b128 v[138:141], v174 offset:1024
	ds_read_b128 v[162:165], v174 offset:2048
	ds_read_b128 v[168:171], v174 offset:3072
	ds_read_b128 v[178:181], v146
	ds_read_b128 v[182:185], v146 offset:1024
	ds_read_b128 v[186:189], v145
	ds_read_b128 v[190:193], v145 offset:1024
	ds_read_b128 v[194:197], v144
	ds_read_b128 v[198:201], v144 offset:1024
	ds_read_b128 v[202:205], v143
	ds_read_b128 v[206:209], v143 offset:1024
	global_load_lds_dwordx4 v[132:133], off
	v_lshl_add_u64 v[130:131], v[130:131], 1, s[12:13]
	s_mov_b32 m0, s10
	s_nop 0
	global_load_lds_dwordx4 v[130:131], off
	s_barrier
	s_waitcnt lgkmcnt(0)
	v_mfma_f32_16x16x32_bf16 v[126:129], v[178:181], v[134:137], v[126:129]
	v_mfma_f32_16x16x32_bf16 v[122:125], v[178:181], v[162:165], v[122:125]
	v_mfma_f32_16x16x32_bf16 v[118:121], v[186:189], v[134:137], v[118:121]
	v_mfma_f32_16x16x32_bf16 v[114:117], v[186:189], v[162:165], v[114:117]
	v_mfma_f32_16x16x32_bf16 v[110:113], v[194:197], v[134:137], v[110:113]
	v_mfma_f32_16x16x32_bf16 v[106:109], v[194:197], v[162:165], v[106:109]
	v_mfma_f32_16x16x32_bf16 v[102:105], v[202:205], v[134:137], v[102:105]
	v_mfma_f32_16x16x32_bf16 v[98:101], v[202:205], v[162:165], v[98:101]
	v_mfma_f32_16x16x32_bf16 v[126:129], v[182:185], v[138:141], v[126:129]
	v_mfma_f32_16x16x32_bf16 v[122:125], v[182:185], v[168:171], v[122:125]
	v_mfma_f32_16x16x32_bf16 v[118:121], v[190:193], v[138:141], v[118:121]
	v_mfma_f32_16x16x32_bf16 v[114:117], v[190:193], v[168:171], v[114:117]
	v_mfma_f32_16x16x32_bf16 v[110:113], v[198:201], v[138:141], v[110:113]
	v_mfma_f32_16x16x32_bf16 v[106:109], v[198:201], v[168:171], v[106:109]
	v_mfma_f32_16x16x32_bf16 v[102:105], v[206:209], v[138:141], v[102:105]
	v_mfma_f32_16x16x32_bf16 v[98:101], v[206:209], v[168:171], v[98:101]
	s_barrier
	ds_read_b128 v[130:133], v173
	ds_read_b128 v[174:177], v173 offset:1024
	ds_read_b128 v[210:213], v173 offset:2048
	ds_read_b128 v[214:217], v173 offset:3072
	s_barrier
	s_waitcnt lgkmcnt(0)
	v_mfma_f32_16x16x32_bf16 v[86:89], v[186:189], v[130:133], v[86:89]
	v_mfma_f32_16x16x32_bf16 v[74:77], v[194:197], v[210:213], v[74:77]
	v_mfma_f32_16x16x32_bf16 v[70:73], v[202:205], v[130:133], v[70:73]
	v_mfma_f32_16x16x32_bf16 v[66:69], v[202:205], v[210:213], v[66:69]
	v_mfma_f32_16x16x32_bf16 v[94:97], v[178:181], v[130:133], v[94:97]
	v_mfma_f32_16x16x32_bf16 v[90:93], v[178:181], v[210:213], v[90:93]
	v_mfma_f32_16x16x32_bf16 v[86:89], v[190:193], v[174:177], v[86:89]
	v_mfma_f32_16x16x32_bf16 v[82:85], v[186:189], v[210:213], v[82:85]
	v_mfma_f32_16x16x32_bf16 v[78:81], v[194:197], v[130:133], v[78:81]
	v_mfma_f32_16x16x32_bf16 v[74:77], v[198:201], v[214:217], v[74:77]
	v_mfma_f32_16x16x32_bf16 v[70:73], v[206:209], v[174:177], v[70:73]
	v_mfma_f32_16x16x32_bf16 v[66:69], v[206:209], v[214:217], v[66:69]
	v_mfma_f32_16x16x32_bf16 v[218:221], v[182:185], v[174:177], v[94:97]
	v_mfma_f32_16x16x32_bf16 v[178:181], v[182:185], v[214:217], v[90:93]
	v_mfma_f32_16x16x32_bf16 v[182:185], v[190:193], v[214:217], v[82:85]
	v_mfma_f32_16x16x32_bf16 v[186:189], v[198:201], v[174:177], v[78:81]
	s_barrier
; #define LDA(dst, b, h) _Pragma("unroll") for (int m = 0; m < 4; ++m) _Pragma("unroll") for (int k = 0; k < 2; ++k) \
;     dst[m][k] = *reinterpret_cast<const bf16x8*>((char*)SA(b, h) + lds_byte(wr * 64 + m * 16 + fr, k * 32 + fq * 8))
; #define LDB(dst, b, h) _Pragma("unroll") for (int n = 0; n < 2; ++n) _Pragma("unroll") for (int k = 0; k < 2; ++k) \
;     dst[n][k] = *reinterpret_cast<const bf16x8*>((char*)SB(b, h) + lds_byte(wc * 32 + n * 16 + fr, k * 32 + fq * 8))
; #define MMA(ai, bj, At, Bq) do { __builtin_amdgcn_s_setprio(1); \
;     _Pragma("unroll") for (int m = 0; m < 4; ++m) _Pragma("unroll") for (int n = 0; n < 2; ++n) _Pragma("unroll") for (int k = 0; k < 2; ++k) \
;       acc[ai][bj][m][n] = __builtin_amdgcn_mfma_f32_16x16x32_bf16(At[m][k], Bq[n][k], acc[ai][bj][m][n], 0, 0, 0); \
;     __builtin_amdgcn_s_setprio(0); } while (0)
; #define WAIT_V(n) asm volatile("s_waitcnt vmcnt(" #n ")" ::: "memory")
; #define WAIT_L(n) asm volatile("s_waitcnt lgkmcnt(" #n ")" ::: "memory")
; #define BAR __builtin_amdgcn_s_barrier()
; __device__ __forceinline__ void gemm256(const u16* __restrict__ A, int lda, const u16* __restrict__ Bt, int ldb, int K,
;                                         f32x4 (&acc)[2][2][4][2], const int g_wid) {
;     ...
;     LDA(At, 0, 1); WAIT_V(4); BAR; WAIT_L(0); MMA(1, 0, At, B0); MMA(1, 1, At, B1); BAR; }
;   { LDB(B0, 1, 0); LDA(At, 1, 0); WAIT_V(2); BAR; WAIT_L(0); MMA(0, 0, At, B0); BAR;
	s_nop 0
	ds_read_b128 v[78:81], v146 offset:16384
	ds_read_b128 v[82:85], v146 offset:17408
	ds_read_b128 v[90:93], v145 offset:16384
	ds_read_b128 v[94:97], v145 offset:17408
	ds_read_b128 v[190:193], v144 offset:16384
	ds_read_b128 v[194:197], v144 offset:17408
	ds_read_b128 v[198:201], v143 offset:16384
	ds_read_b128 v[202:205], v143 offset:17408
	s_waitcnt vmcnt(4)
	s_barrier
	s_waitcnt lgkmcnt(0)
	v_mfma_f32_16x16x32_bf16 v[54:57], v[90:93], v[134:137], v[54:57]
	v_mfma_f32_16x16x32_bf16 v[42:45], v[190:193], v[162:165], v[42:45]
	v_mfma_f32_16x16x32_bf16 v[38:41], v[198:201], v[134:137], v[38:41]
	v_mfma_f32_16x16x32_bf16 v[34:37], v[198:201], v[162:165], v[34:37]
	v_mfma_f32_16x16x32_bf16 v[62:65], v[78:81], v[134:137], v[62:65]
	v_mfma_f32_16x16x32_bf16 v[58:61], v[78:81], v[162:165], v[58:61]
	v_mfma_f32_16x16x32_bf16 v[54:57], v[94:97], v[138:141], v[54:57]
	v_mfma_f32_16x16x32_bf16 v[50:53], v[90:93], v[162:165], v[50:53]
	v_mfma_f32_16x16x32_bf16 v[46:49], v[190:193], v[134:137], v[46:49]
	v_mfma_f32_16x16x32_bf16 v[42:45], v[194:197], v[168:171], v[42:45]
	v_mfma_f32_16x16x32_bf16 v[38:41], v[202:205], v[138:141], v[38:41]
	v_mfma_f32_16x16x32_bf16 v[34:37], v[202:205], v[168:171], v[34:37]
	v_mfma_f32_16x16x32_bf16 v[206:209], v[82:85], v[138:141], v[62:65]
	v_mfma_f32_16x16x32_bf16 v[222:225], v[82:85], v[168:171], v[58:61]
	v_mfma_f32_16x16x32_bf16 v[226:229], v[94:97], v[168:171], v[50:53]
	v_mfma_f32_16x16x32_bf16 v[230:233], v[194:197], v[138:141], v[46:49]
	v_mfma_f32_16x16x32_bf16 v[2:5], v[198:201], v[210:213], v[2:5]
	v_mfma_f32_16x16x32_bf16 v[30:33], v[78:81], v[130:133], v[30:33]
	v_mfma_f32_16x16x32_bf16 v[26:29], v[78:81], v[210:213], v[26:29]
	v_mfma_f32_16x16x32_bf16 v[22:25], v[90:93], v[130:133], v[22:25]
	v_mfma_f32_16x16x32_bf16 v[18:21], v[90:93], v[210:213], v[18:21]
	v_mfma_f32_16x16x32_bf16 v[14:17], v[190:193], v[130:133], v[14:17]
	v_mfma_f32_16x16x32_bf16 v[10:13], v[190:193], v[210:213], v[10:13]
	v_mfma_f32_16x16x32_bf16 v[6:9], v[198:201], v[130:133], v[6:9]
	v_mfma_f32_16x16x32_bf16 v[2:5], v[202:205], v[214:217], v[2:5]
	v_mfma_f32_16x16x32_bf16 v[134:137], v[82:85], v[174:177], v[30:33]
	v_mfma_f32_16x16x32_bf16 v[138:141], v[82:85], v[214:217], v[26:29]
	v_mfma_f32_16x16x32_bf16 v[162:165], v[94:97], v[174:177], v[22:25]
	v_mfma_f32_16x16x32_bf16 v[168:171], v[94:97], v[214:217], v[18:21]
	v_mfma_f32_16x16x32_bf16 v[234:237], v[194:197], v[174:177], v[14:17]
	v_mfma_f32_16x16x32_bf16 v[190:193], v[194:197], v[214:217], v[10:13]
	v_mfma_f32_16x16x32_bf16 v[130:133], v[202:205], v[174:177], v[6:9]
	s_barrier
	s_nop 0
	ds_read_b128 v[6:9], v166
	ds_read_b128 v[10:13], v166 offset:1024
	ds_read_b128 v[22:25], v166 offset:2048
	ds_read_b128 v[172:175], v166 offset:3072
	ds_read_b128 v[14:17], v146 offset:32768
	ds_read_b128 v[18:21], v146 offset:33792
	ds_read_b128 v[26:29], v145 offset:32768
	ds_read_b128 v[46:49], v145 offset:33792
	ds_read_b128 v[194:197], v144 offset:32768
	ds_read_b128 v[198:201], v144 offset:33792
	ds_read_b128 v[202:205], v143 offset:32768
	ds_read_b128 v[210:213], v143 offset:33792
	s_waitcnt vmcnt(2)
	s_barrier
	s_waitcnt lgkmcnt(0)
	v_mfma_f32_16x16x32_bf16 v[30:33], v[14:17], v[6:9], v[126:129]
	v_mfma_f32_16x16x32_bf16 v[126:129], v[18:21], v[10:13], v[30:33]
	v_mfma_f32_16x16x32_bf16 v[30:33], v[14:17], v[22:25], v[122:125]
	v_mfma_f32_16x16x32_bf16 v[94:97], v[18:21], v[172:175], v[30:33]
	v_mfma_f32_16x16x32_bf16 v[30:33], v[26:29], v[6:9], v[118:121]
	v_mfma_f32_16x16x32_bf16 v[122:125], v[46:49], v[10:13], v[30:33]
	v_mfma_f32_16x16x32_bf16 v[30:33], v[26:29], v[22:25], v[114:117]
	v_mfma_f32_16x16x32_bf16 v[90:93], v[46:49], v[172:175], v[30:33]
	v_mfma_f32_16x16x32_bf16 v[30:33], v[194:197], v[6:9], v[110:113]
	v_mfma_f32_16x16x32_bf16 v[114:117], v[198:201], v[10:13], v[30:33]
	v_mfma_f32_16x16x32_bf16 v[30:33], v[194:197], v[22:25], v[106:109]
	v_mfma_f32_16x16x32_bf16 v[82:85], v[198:201], v[172:175], v[30:33]
	v_mfma_f32_16x16x32_bf16 v[30:33], v[202:205], v[6:9], v[102:105]
	v_mfma_f32_16x16x32_bf16 v[110:113], v[210:213], v[10:13], v[30:33]
	v_mfma_f32_16x16x32_bf16 v[30:33], v[202:205], v[22:25], v[98:101]
	v_mfma_f32_16x16x32_bf16 v[78:81], v[210:213], v[172:175], v[30:33]
	s_barrier
; #define LDA(dst, b, h) _Pragma("unroll") for (int m = 0; m < 4; ++m) _Pragma("unroll") for (int k = 0; k < 2; ++k) \
;     dst[m][k] = *reinterpret_cast<const bf16x8*>((char*)SA(b, h) + lds_byte(wr * 64 + m * 16 + fr, k * 32 + fq * 8))
; #define LDB(dst, b, h) _Pragma("unroll") for (int n = 0; n < 2; ++n) _Pragma("unroll") for (int k = 0; k < 2; ++k) \
;     dst[n][k] = *reinterpret_cast<const bf16x8*>((char*)SB(b, h) + lds_byte(wc * 32 + n * 16 + fr, k * 32 + fq * 8))
; #define MMA(ai, bj, At, Bq) do { __builtin_amdgcn_s_setprio(1); \
;     _Pragma("unroll") for (int m = 0; m < 4; ++m) _Pragma("unroll") for (int n = 0; n < 2; ++n) _Pragma("unroll") for (int k = 0; k < 2; ++k) \
;       acc[ai][bj][m][n] = __builtin_amdgcn_mfma_f32_16x16x32_bf16(At[m][k], Bq[n][k], acc[ai][bj][m][n], 0, 0, 0); \
;     __builtin_amdgcn_s_setprio(0); } while (0)
; #define WAIT_V(n) asm volatile("s_waitcnt vmcnt(" #n ")" ::: "memory")
; #define WAIT_L(n) asm volatile("s_waitcnt lgkmcnt(" #n ")" ::: "memory")
; #define BAR __builtin_amdgcn_s_barrier()
; __device__ __forceinline__ void gemm256(const u16* __restrict__ A, int lda, const u16* __restrict__ Bt, int ldb, int K,
;                                         f32x4 (&acc)[2][2][4][2], const int g_wid) {
;     ...
;     LDB(B1, 1, 1); WAIT_V(0); BAR; WAIT_L(0); MMA(0, 1, At, B1); BAR;
;     LDA(At, 1, 1); BAR; WAIT_L(0); MMA(1, 0, At, B0); MMA(1, 1, At, B1); BAR; }
;   if (wr == 0) BAR;
; __device__ __forceinline__ void phase_g4(PP p, const int g_wid) {
;     ...
;     else gemm256(p->Wm + 7602176L + (long)(pass - 3) * 524288 + (long)pn * 256 * 512, 512, p->X + X_BO + (long)192 * 256 * 1536 + (pass - 3) * 512, 1536, 512, acc, g_wid);
	ds_read_b128 v[214:217], v161
	ds_read_b128 v[238:241], v161 offset:1024
	ds_read_b128 v[242:245], v161 offset:2048
	ds_read_b128 v[246:249], v161 offset:3072
	s_waitcnt vmcnt(0)
	s_barrier
	s_waitcnt lgkmcnt(0)
	v_mfma_f32_16x16x32_bf16 v[30:33], v[14:17], v[214:217], v[218:221]
	v_mfma_f32_16x16x32_bf16 v[14:17], v[14:17], v[242:245], v[178:181]
	v_mfma_f32_16x16x32_bf16 v[62:65], v[18:21], v[238:241], v[30:33]
	v_mfma_f32_16x16x32_bf16 v[30:33], v[18:21], v[246:249], v[14:17]
	v_mfma_f32_16x16x32_bf16 v[14:17], v[26:29], v[214:217], v[86:89]
	v_mfma_f32_16x16x32_bf16 v[58:61], v[46:49], v[238:241], v[14:17]
	v_mfma_f32_16x16x32_bf16 v[14:17], v[26:29], v[242:245], v[182:185]
	v_mfma_f32_16x16x32_bf16 v[26:29], v[46:49], v[246:249], v[14:17]
	v_mfma_f32_16x16x32_bf16 v[14:17], v[194:197], v[214:217], v[186:189]
	v_mfma_f32_16x16x32_bf16 v[50:53], v[198:201], v[238:241], v[14:17]
	v_mfma_f32_16x16x32_bf16 v[14:17], v[194:197], v[242:245], v[74:77]
	v_mfma_f32_16x16x32_bf16 v[18:21], v[198:201], v[246:249], v[14:17]
	v_mfma_f32_16x16x32_bf16 v[14:17], v[202:205], v[214:217], v[70:73]
	v_mfma_f32_16x16x32_bf16 v[46:49], v[210:213], v[238:241], v[14:17]
	v_mfma_f32_16x16x32_bf16 v[14:17], v[202:205], v[242:245], v[66:69]
	v_mfma_f32_16x16x32_bf16 v[14:17], v[210:213], v[246:249], v[14:17]
	s_barrier
	ds_read_b128 v[176:179], v146 offset:49152
	ds_read_b128 v[180:183], v146 offset:50176
	ds_read_b128 v[184:187], v145 offset:49152
	ds_read_b128 v[194:197], v145 offset:50176
	ds_read_b128 v[198:201], v144 offset:49152
	ds_read_b128 v[144:147], v144 offset:50176
	ds_read_b128 v[202:205], v143 offset:49152
	ds_read_b128 v[210:213], v143 offset:50176
	s_barrier
	s_waitcnt lgkmcnt(0)
	v_mfma_f32_16x16x32_bf16 v[54:57], v[184:187], v[6:9], v[54:57]
	v_mfma_f32_16x16x32_bf16 v[106:109], v[194:197], v[10:13], v[54:57]
	v_mfma_f32_16x16x32_bf16 v[54:57], v[184:187], v[22:25], v[226:229]
	v_mfma_f32_16x16x32_bf16 v[66:69], v[176:179], v[6:9], v[206:209]
	v_mfma_f32_16x16x32_bf16 v[74:77], v[194:197], v[172:175], v[54:57]
	v_mfma_f32_16x16x32_bf16 v[54:57], v[198:201], v[6:9], v[230:233]
	v_mfma_f32_16x16x32_bf16 v[6:9], v[202:205], v[6:9], v[38:41]
	v_mfma_f32_16x16x32_bf16 v[118:121], v[180:183], v[10:13], v[66:69]
	v_mfma_f32_16x16x32_bf16 v[66:69], v[176:179], v[22:25], v[222:225]
	v_mfma_f32_16x16x32_bf16 v[42:45], v[198:201], v[22:25], v[42:45]
	v_mfma_f32_16x16x32_bf16 v[98:101], v[210:213], v[10:13], v[6:9]
	v_mfma_f32_16x16x32_bf16 v[6:9], v[202:205], v[22:25], v[34:37]
	v_mfma_f32_16x16x32_bf16 v[86:89], v[180:183], v[172:175], v[66:69]
	v_mfma_f32_16x16x32_bf16 v[102:105], v[144:147], v[10:13], v[54:57]
	v_mfma_f32_16x16x32_bf16 v[70:73], v[144:147], v[172:175], v[42:45]
	v_mfma_f32_16x16x32_bf16 v[66:69], v[210:213], v[172:175], v[6:9]
	v_mfma_f32_16x16x32_bf16 v[6:9], v[176:179], v[214:217], v[134:137]
	v_mfma_f32_16x16x32_bf16 v[54:57], v[180:183], v[238:241], v[6:9]
	v_mfma_f32_16x16x32_bf16 v[6:9], v[176:179], v[242:245], v[138:141]
	v_mfma_f32_16x16x32_bf16 v[22:25], v[180:183], v[246:249], v[6:9]
	v_mfma_f32_16x16x32_bf16 v[6:9], v[184:187], v[214:217], v[162:165]
	v_mfma_f32_16x16x32_bf16 v[42:45], v[194:197], v[238:241], v[6:9]
	v_mfma_f32_16x16x32_bf16 v[6:9], v[184:187], v[242:245], v[168:171]
	v_mfma_f32_16x16x32_bf16 v[10:13], v[194:197], v[246:249], v[6:9]
	v_mfma_f32_16x16x32_bf16 v[6:9], v[198:201], v[214:217], v[234:237]
	v_mfma_f32_16x16x32_bf16 v[38:41], v[144:147], v[238:241], v[6:9]
	v_mfma_f32_16x16x32_bf16 v[6:9], v[198:201], v[242:245], v[190:193]
	v_mfma_f32_16x16x32_bf16 v[34:37], v[202:205], v[214:217], v[130:133]
	v_mfma_f32_16x16x32_bf16 v[2:5], v[202:205], v[242:245], v[2:5]
	v_mfma_f32_16x16x32_bf16 v[6:9], v[144:147], v[246:249], v[6:9]
	v_mfma_f32_16x16x32_bf16 v[34:37], v[210:213], v[238:241], v[34:37]
	v_mfma_f32_16x16x32_bf16 v[2:5], v[210:213], v[246:249], v[2:5]
	s_setprio 0
	s_movk_i32 s10, 0x100
	v_cmp_gt_u32_e32 vcc, s10, v0
	s_barrier
	s_and_saveexec_b64 s[12:13], vcc
	s_cbranch_execz .LBB0_131
	s_barrier

; #define hw_tid() ((g_wid << 6) | hw_lane())
; #define STA(P, br, kt) STAGE(P, A, aoff0, aoff1, lda, br, kt)
; #define STB(P, br, kt) STAGE(P, Bt, boff0, boff1, ldb, br, kt)
; #define BAR __builtin_amdgcn_s_barrier()
; __device__ __forceinline__ void gemm256(const u16* __restrict__ A, int lda, const u16* __restrict__ Bt, int ldb, int K,
;                                         f32x4 (&acc)[2][2][4][2], const int g_wid) {
;   int tid = hw_tid(); asm volatile("" : "+v"(tid));
;   const int wid = tid >> 6, lane = tid & 63, wr = wid >> 2, wc = wid & 3, fr = lane & 15, fq = lane >> 4;
;   int r0, c0, r1, c1;
;   stage_rc(tid * 16, r0, c0);
;   stage_rc(tid * 16 + 8192, r1, c1);
;   const int aoff0 = r0 * lda + c0, aoff1 = r1 * lda + c1, boff0 = r0 * ldb + c0, boff1 = r1 * ldb + c1;
;   bf16x8 At[4][2], B0[2][2], B1[2][2];
;   const int nt = K / BK;
;   STB(SB(0, 0), 0, 0); STA(SA(0, 0), 0, 0);
;   STB(SB(0, 1), HALF, 0); STA(SA(0, 1), HALF, 0);
;   if (wr == 1) BAR;
; __device__ __forceinline__ void phase_g4(PP p, const int g_wid) {
;     ...
;     const bool isg = pass < 3;
;     if (isg) gemm256(p->Wm + (long)(4352 + pass * 1024 + pn * 256) * 1024, 1024, p->hb + (long)192 * 256 * 1024, 1024, 1024, acc, g_wid);
.LBB0_132:
	s_and_b64 vcc, exec, s[12:13]
	s_cbranch_vccz .LBB0_140
	s_lshl_b32 s10, s24, 10
	s_lshl_b32 s11, s23, 8
	s_or_b32 s10, s10, s11
	s_add_i32 s12, s10, 0x1100
	v_readlane_b32 s10, v254, 0
	v_readlane_b32 s11, v254, 1
	s_load_dwordx2 s[16:17], s[10:11], 0xc8
	s_mov_b32 s10, -1
	s_ashr_i32 s13, s12, 31
	v_mbcnt_lo_u32_b32 v0, s10, 0
	v_mbcnt_hi_u32_b32 v0, s10, v0
	v_readlane_b32 s10, v254, 63
	s_lshl_b64 s[14:15], s[12:13], 11
	s_waitcnt lgkmcnt(0)
	s_add_u32 s12, s6, s14
	v_or_b32_e32 v0, s10, v0
	s_addc_u32 s13, s7, s15
	v_ashrrev_i32_e32 v2, 31, v0
	v_lshrrev_b32_e32 v2, 26, v2
	v_add_u32_e32 v2, v0, v2
	v_ashrrev_i32_e32 v10, 6, v2
	v_bfe_i32 v2, v0, 27, 1
	v_lshlrev_b32_e32 v16, 4, v0
	v_lshrrev_b32_e32 v2, 22, v2
	v_add_u32_e32 v2, v16, v2
	v_and_b32_e32 v2, 0xfffffc00, v2
	v_sub_u32_e32 v2, v16, v2
	v_lshrrev_b32_e32 v3, 4, v2
	v_bitop3_b32 v2, v3, v2, 32 bitop3:0x6c
	v_ashrrev_i32_e32 v4, 31, v2
	v_lshrrev_b32_e32 v4, 26, v4
	v_add_u32_e32 v4, v2, v4
	v_ashrrev_i32_e32 v12, 6, v4
	v_and_b32_e32 v4, 0xc0, v4
	v_sub_u32_e32 v2, v2, v4
	v_ashrrev_i16_sdwa v14, v151, sext(v2) dst_sel:DWORD dst_unused:UNUSED_PAD src0_sel:DWORD src1_sel:BYTE_0
	v_add_u32_e32 v2, 0x2000, v16
	v_ashrrev_i32_e32 v4, 31, v2
	v_lshrrev_b32_e32 v4, 22, v4
	v_add_u32_e32 v4, v2, v4
	v_ashrrev_i32_e32 v15, 10, v4
	v_mul_i32_i24_e32 v4, 0x400, v15
	v_sub_u32_e32 v2, v2, v4
	v_lshrrev_b32_e32 v4, 4, v2
	v_lshlrev_b32_e32 v5, 5, v10
	v_bitop3_b32 v2, v4, v2, 32 bitop3:0x6c
	v_and_b32_e32 v13, 32, v5
	v_ashrrev_i32_e32 v5, 31, v2
	v_lshrrev_b32_e32 v5, 26, v5
	v_lshlrev_b32_e32 v3, 3, v10
	v_add_u32_e32 v5, v2, v5
	v_and_b32_e32 v3, 0x3ffff0, v3
	v_ashrrev_i32_e32 v17, 6, v5
	v_and_b32_e32 v5, 0xc0, v5
	v_add_u32_e32 v3, v12, v3
	v_lshlrev_b32_e32 v4, 3, v15
	v_sub_u32_e32 v2, v2, v5
	v_and_b32_e32 v4, 0x3ffff0, v4
	v_lshlrev_b32_e32 v6, 5, v15
	v_ashrrev_i16_sdwa v19, v151, sext(v2) dst_sel:DWORD dst_unused:UNUSED_PAD src0_sel:DWORD src1_sel:BYTE_0
	v_lshl_or_b32 v2, v3, 10, v13
	v_add_u32_e32 v4, v17, v4
	v_and_b32_e32 v18, 32, v6
	v_add_u32_sdwa v132, v2, sext(v14) dst_sel:DWORD dst_unused:UNUSED_PAD src0_sel:DWORD src1_sel:WORD_0
	v_readlane_b32 s10, v254, 40
	s_add_u32 s18, s16, 0x6000000
	v_lshl_or_b32 v2, v4, 10, v18
	v_ashrrev_i32_e32 v133, 31, v132
	v_add_u32_e32 v146, s10, v16
	s_addc_u32 s19, s17, 0
	v_add_u32_sdwa v130, v2, sext(v19) dst_sel:DWORD dst_unused:UNUSED_PAD src0_sel:DWORD src1_sel:WORD_0
	v_lshlrev_b64 v[2:3], 1, v[132:133]
	v_readfirstlane_b32 s10, v146
	v_lshl_add_u64 v[4:5], s[18:19], 0, v[2:3]
	s_mov_b32 m0, s10
	v_ashrrev_i32_e32 v131, 31, v130
	v_add_u32_e32 v147, 0x2000, v146
	global_load_lds_dwordx4 v[4:5], off
	v_lshlrev_b64 v[4:5], 1, v[130:131]
	v_readfirstlane_b32 s10, v147
	v_add_u32_e32 v160, 0, v16
	v_lshl_add_u64 v[6:7], s[18:19], 0, v[4:5]
	s_mov_b32 m0, s10
	v_readfirstlane_b32 s10, v160
	v_add_u32_e32 v161, 0x2000, v160
	global_load_lds_dwordx4 v[6:7], off
	v_lshl_add_u64 v[8:9], s[12:13], 0, v[2:3]
	s_mov_b32 m0, s10
	v_readfirstlane_b32 s10, v161
	global_load_lds_dwordx4 v[8:9], off
	s_mov_b32 m0, s10
	v_readlane_b32 s10, v254, 41
	s_add_u32 s18, s16, 0x6040000
	v_lshl_add_u64 v[6:7], s[12:13], 0, v[4:5]
	v_add_u32_e32 v162, s10, v16
	s_addc_u32 s19, s17, 0
	v_readfirstlane_b32 s10, v162
	global_load_lds_dwordx4 v[6:7], off
	v_lshl_add_u64 v[20:21], s[18:19], 0, v[2:3]
	s_mov_b32 m0, s10
	v_add_u32_e32 v163, 0x2000, v162
	global_load_lds_dwordx4 v[20:21], off
	v_lshl_add_u64 v[20:21], s[18:19], 0, v[4:5]
	v_readfirstlane_b32 s10, v163
	s_add_u32 s18, s12, 0x40000
	v_add_u32_e32 v164, 0x4000, v160
	s_mov_b32 m0, s10
	s_addc_u32 s19, s13, 0
	v_readfirstlane_b32 s10, v164
	v_add_u32_e32 v166, 0x6000, v160
	global_load_lds_dwordx4 v[20:21], off
	v_lshl_add_u64 v[20:21], s[18:19], 0, v[2:3]
	s_mov_b32 m0, s10
	v_readfirstlane_b32 s10, v166
	global_load_lds_dwordx4 v[20:21], off
	v_lshl_add_u64 v[20:21], s[18:19], 0, v[4:5]
	s_mov_b32 m0, s10
	v_ashrrev_i32_e32 v11, 8, v0
	global_load_lds_dwordx4 v[20:21], off
	v_cmp_eq_u32_e32 vcc, 1, v11
	s_and_saveexec_b64 s[18:19], vcc
	s_cbranch_execz .LBB0_135
	s_setprio 3
	s_barrier

; #define STA(P, br, kt) STAGE(P, A, aoff0, aoff1, lda, br, kt)
; #define STB(P, br, kt) STAGE(P, Bt, boff0, boff1, ldb, br, kt)
; #define LDA(dst, b, h) _Pragma("unroll") for (int m = 0; m < 4; ++m) _Pragma("unroll") for (int k = 0; k < 2; ++k) \
;     dst[m][k] = *reinterpret_cast<const bf16x8*>((char*)SA(b, h) + lds_byte(wr * 64 + m * 16 + fr, k * 32 + fq * 8))
; #define LDB(dst, b, h) _Pragma("unroll") for (int n = 0; n < 2; ++n) _Pragma("unroll") for (int k = 0; k < 2; ++k) \
;     dst[n][k] = *reinterpret_cast<const bf16x8*>((char*)SB(b, h) + lds_byte(wc * 32 + n * 16 + fr, k * 32 + fq * 8))
; #define MMA(ai, bj, At, Bq) do { __builtin_amdgcn_s_setprio(1); \
;     _Pragma("unroll") for (int m = 0; m < 4; ++m) _Pragma("unroll") for (int n = 0; n < 2; ++n) _Pragma("unroll") for (int k = 0; k < 2; ++k) \
;       acc[ai][bj][m][n] = __builtin_amdgcn_mfma_f32_16x16x32_bf16(At[m][k], Bq[n][k], acc[ai][bj][m][n], 0, 0, 0); \
;     __builtin_amdgcn_s_setprio(0); } while (0)
; #define WAIT_L(n) asm volatile("s_waitcnt lgkmcnt(" #n ")" ::: "memory")
; #define BAR __builtin_amdgcn_s_barrier()
; #define SCHED __builtin_amdgcn_sched_barrier(0)
; __device__ __forceinline__ void gemm256(const u16* __restrict__ A, int lda, const u16* __restrict__ Bt, int ldb, int K,
;                                         f32x4 (&acc)[2][2][4][2], const int g_wid) {
;     ...
;     LDB(B0, 0, 0); SCHED; LDA(At, 0, 0); STA(SA(1, 1), HALF, t + 1);
;     WAIT_L(8); BAR; WAIT_L(0); MMA(0, 0, At, B0); BAR; SCHED;
;     LDB(B1, 0, 1); STB(SB(0, 0), 0, t + 2);
;     BAR; WAIT_L(0); MMA(0, 1, At, B1); BAR;
;     LDA(At, 0, 1); STA(SA(0, 0), 0, t + 2);
;     BAR; WAIT_L(0); MMA(1, 0, At, B0); BAR; SCHED;
.LBB0_136:
	ds_read_b128 v[178:181], v174
	ds_read_b128 v[182:185], v174 offset:1024
	ds_read_b128 v[186:189], v174 offset:2048
	ds_read_b128 v[190:193], v174 offset:3072
	v_add_u32_e32 v175, 0xc000, v160
	v_lshl_add_u64 v[242:243], v[140:141], 0, s[6:7]
	v_readfirstlane_b32 s10, v175
	v_lshl_add_u64 v[176:177], v[242:243], 0, s[68:69]
	s_mov_b32 m0, s10
	ds_read_b128 v[194:197], v145
	ds_read_b128 v[198:201], v145 offset:1024
	ds_read_b128 v[202:205], v144
	ds_read_b128 v[206:209], v144 offset:1024
	ds_read_b128 v[210:213], v143
	ds_read_b128 v[214:217], v143 offset:1024
	ds_read_b128 v[218:221], v142
	ds_read_b128 v[222:225], v142 offset:1024
	global_load_lds_dwordx4 v[176:177], off
	v_add_u32_e32 v176, 0xe000, v160
	v_lshl_add_u64 v[244:245], v[138:139], 0, s[6:7]
	v_readfirstlane_b32 s10, v176
	v_lshl_add_u64 v[226:227], v[244:245], 0, s[68:69]
	s_mov_b32 m0, s10
	s_nop 0
	global_load_lds_dwordx4 v[226:227], off
	s_waitcnt lgkmcnt(8)
	s_barrier
	s_waitcnt lgkmcnt(0)
	v_mfma_f32_16x16x32_bf16 v[126:129], v[194:197], v[178:181], v[126:129]
	v_mfma_f32_16x16x32_bf16 v[122:125], v[194:197], v[186:189], v[122:125]
	v_mfma_f32_16x16x32_bf16 v[118:121], v[202:205], v[178:181], v[118:121]
	v_mfma_f32_16x16x32_bf16 v[114:117], v[202:205], v[186:189], v[114:117]
	v_mfma_f32_16x16x32_bf16 v[110:113], v[210:213], v[178:181], v[110:113]
	v_mfma_f32_16x16x32_bf16 v[106:109], v[210:213], v[186:189], v[106:109]
	v_mfma_f32_16x16x32_bf16 v[102:105], v[218:221], v[178:181], v[102:105]
	v_mfma_f32_16x16x32_bf16 v[98:101], v[218:221], v[186:189], v[98:101]
	v_mfma_f32_16x16x32_bf16 v[126:129], v[198:201], v[182:185], v[126:129]
	v_mfma_f32_16x16x32_bf16 v[122:125], v[198:201], v[190:193], v[122:125]
	v_mfma_f32_16x16x32_bf16 v[118:121], v[206:209], v[182:185], v[118:121]
	v_mfma_f32_16x16x32_bf16 v[114:117], v[206:209], v[190:193], v[114:117]
	v_mfma_f32_16x16x32_bf16 v[110:113], v[214:217], v[182:185], v[110:113]
	v_mfma_f32_16x16x32_bf16 v[106:109], v[214:217], v[190:193], v[106:109]
	v_mfma_f32_16x16x32_bf16 v[102:105], v[222:225], v[182:185], v[102:105]
	v_mfma_f32_16x16x32_bf16 v[98:101], v[222:225], v[190:193], v[98:101]
	s_barrier
	v_lshl_add_u64 v[246:247], v[136:137], 0, s[6:7]
	v_readfirstlane_b32 s10, v146
	v_lshl_add_u64 v[248:249], v[246:247], 0, s[8:9]
	s_mov_b32 m0, s10
	ds_read_b128 v[226:229], v173
	ds_read_b128 v[230:233], v173 offset:1024
	ds_read_b128 v[234:237], v173 offset:2048
	ds_read_b128 v[238:241], v173 offset:3072
	global_load_lds_dwordx4 v[248:249], off
	v_lshl_add_u64 v[248:249], v[134:135], 0, s[6:7]
	v_readfirstlane_b32 s10, v147
	v_lshl_add_u64 v[250:251], v[248:249], 0, s[8:9]
	s_mov_b32 m0, s10
	s_nop 0
	global_load_lds_dwordx4 v[250:251], off
	s_barrier
	s_waitcnt lgkmcnt(0)
	v_mfma_f32_16x16x32_bf16 v[94:97], v[194:197], v[226:229], v[94:97]
	v_mfma_f32_16x16x32_bf16 v[90:93], v[194:197], v[234:237], v[90:93]
	v_mfma_f32_16x16x32_bf16 v[86:89], v[202:205], v[226:229], v[86:89]
	v_mfma_f32_16x16x32_bf16 v[82:85], v[202:205], v[234:237], v[82:85]
	v_mfma_f32_16x16x32_bf16 v[78:81], v[210:213], v[226:229], v[78:81]
	v_mfma_f32_16x16x32_bf16 v[74:77], v[210:213], v[234:237], v[74:77]
	v_mfma_f32_16x16x32_bf16 v[70:73], v[218:221], v[226:229], v[70:73]
	v_mfma_f32_16x16x32_bf16 v[66:69], v[218:221], v[234:237], v[66:69]
	v_mfma_f32_16x16x32_bf16 v[94:97], v[198:201], v[230:233], v[94:97]
	v_mfma_f32_16x16x32_bf16 v[90:93], v[198:201], v[238:241], v[90:93]
	v_mfma_f32_16x16x32_bf16 v[86:89], v[206:209], v[230:233], v[86:89]
	v_mfma_f32_16x16x32_bf16 v[82:85], v[206:209], v[238:241], v[82:85]
	v_mfma_f32_16x16x32_bf16 v[78:81], v[214:217], v[230:233], v[78:81]
	v_mfma_f32_16x16x32_bf16 v[74:77], v[214:217], v[238:241], v[74:77]
	v_mfma_f32_16x16x32_bf16 v[70:73], v[222:225], v[230:233], v[70:73]
	v_mfma_f32_16x16x32_bf16 v[66:69], v[222:225], v[238:241], v[66:69]
	v_readfirstlane_b32 s10, v160
	v_lshl_add_u64 v[250:251], v[242:243], 0, s[74:75]
	s_mov_b32 m0, s10
	v_readfirstlane_b32 s10, v161
	s_barrier
	ds_read_b128 v[194:197], v145 offset:16384
	ds_read_b128 v[198:201], v145 offset:17408
	ds_read_b128 v[202:205], v144 offset:16384
	ds_read_b128 v[206:209], v144 offset:17408
	ds_read_b128 v[210:213], v143 offset:16384
	ds_read_b128 v[214:217], v143 offset:17408
	ds_read_b128 v[218:221], v142 offset:16384
	ds_read_b128 v[222:225], v142 offset:17408
	global_load_lds_dwordx4 v[250:251], off
	v_lshl_add_u64 v[250:251], v[244:245], 0, s[74:75]
	s_mov_b32 m0, s10
	s_nop 0
	global_load_lds_dwordx4 v[250:251], off
	s_barrier
	s_waitcnt lgkmcnt(0)
	v_mfma_f32_16x16x32_bf16 v[62:65], v[194:197], v[178:181], v[62:65]
	v_mfma_f32_16x16x32_bf16 v[58:61], v[194:197], v[186:189], v[58:61]
	v_mfma_f32_16x16x32_bf16 v[54:57], v[202:205], v[178:181], v[54:57]
	v_mfma_f32_16x16x32_bf16 v[50:53], v[202:205], v[186:189], v[50:53]
	v_mfma_f32_16x16x32_bf16 v[46:49], v[210:213], v[178:181], v[46:49]
	v_mfma_f32_16x16x32_bf16 v[42:45], v[210:213], v[186:189], v[42:45]
	v_mfma_f32_16x16x32_bf16 v[38:41], v[218:221], v[178:181], v[38:41]
	v_mfma_f32_16x16x32_bf16 v[34:37], v[218:221], v[186:189], v[34:37]
	v_mfma_f32_16x16x32_bf16 v[62:65], v[198:201], v[182:185], v[62:65]
	v_mfma_f32_16x16x32_bf16 v[58:61], v[198:201], v[190:193], v[58:61]
	v_mfma_f32_16x16x32_bf16 v[54:57], v[206:209], v[182:185], v[54:57]
	v_mfma_f32_16x16x32_bf16 v[50:53], v[206:209], v[190:193], v[50:53]
	v_mfma_f32_16x16x32_bf16 v[46:49], v[214:217], v[182:185], v[46:49]
	v_mfma_f32_16x16x32_bf16 v[42:45], v[214:217], v[190:193], v[42:45]
	v_mfma_f32_16x16x32_bf16 v[38:41], v[222:225], v[182:185], v[38:41]
	v_mfma_f32_16x16x32_bf16 v[34:37], v[222:225], v[190:193], v[34:37]
	s_barrier
; #define STA(P, br, kt) STAGE(P, A, aoff0, aoff1, lda, br, kt)
; #define STB(P, br, kt) STAGE(P, Bt, boff0, boff1, ldb, br, kt)
; #define LDA(dst, b, h) _Pragma("unroll") for (int m = 0; m < 4; ++m) _Pragma("unroll") for (int k = 0; k < 2; ++k) \
;     dst[m][k] = *reinterpret_cast<const bf16x8*>((char*)SA(b, h) + lds_byte(wr * 64 + m * 16 + fr, k * 32 + fq * 8))
; #define LDB(dst, b, h) _Pragma("unroll") for (int n = 0; n < 2; ++n) _Pragma("unroll") for (int k = 0; k < 2; ++k) \
;     dst[n][k] = *reinterpret_cast<const bf16x8*>((char*)SB(b, h) + lds_byte(wc * 32 + n * 16 + fr, k * 32 + fq * 8))
; #define MMA(ai, bj, At, Bq) do { __builtin_amdgcn_s_setprio(1); \
;     _Pragma("unroll") for (int m = 0; m < 4; ++m) _Pragma("unroll") for (int n = 0; n < 2; ++n) _Pragma("unroll") for (int k = 0; k < 2; ++k) \
;       acc[ai][bj][m][n] = __builtin_amdgcn_mfma_f32_16x16x32_bf16(At[m][k], Bq[n][k], acc[ai][bj][m][n], 0, 0, 0); \
;     __builtin_amdgcn_s_setprio(0); } while (0)
; #define WAIT_V(n) asm volatile("s_waitcnt vmcnt(" #n ")" ::: "memory")
; #define WAIT_L(n) asm volatile("s_waitcnt lgkmcnt(" #n ")" ::: "memory")
; #define BAR __builtin_amdgcn_s_barrier()
; #define SCHED __builtin_amdgcn_sched_barrier(0)
; __device__ __forceinline__ void gemm256(const u16* __restrict__ A, int lda, const u16* __restrict__ Bt, int ldb, int K,
;                                         f32x4 (&acc)[2][2][4][2], const int g_wid) {
;     ...
;     STB(SB(0, 1), HALF, t + 2);
;     WAIT_V(6); BAR; MMA(1, 1, At, B1); BAR;
;     LDB(B0, 1, 0); SCHED; LDA(At, 1, 0); STA(SA(0, 1), HALF, t + 2);
;     WAIT_L(8); BAR; WAIT_L(0); MMA(0, 0, At, B0); BAR; SCHED;
;     LDB(B1, 1, 1); STB(SB(1, 0), 0, t + 3);
;     BAR; WAIT_L(0); MMA(0, 1, At, B1); BAR;
;     LDA(At, 1, 1); STA(SA(1, 0), 0, t + 3);
	v_readfirstlane_b32 s10, v162
	v_lshl_add_u64 v[178:179], v[246:247], 0, s[16:17]
	s_mov_b32 m0, s10
	v_readfirstlane_b32 s10, v163
	global_load_lds_dwordx4 v[178:179], off
	v_lshl_add_u64 v[178:179], v[248:249], 0, s[16:17]
	s_mov_b32 m0, s10
	s_nop 0
	global_load_lds_dwordx4 v[178:179], off
	s_waitcnt vmcnt(6)
	s_barrier
	v_mfma_f32_16x16x32_bf16 v[30:33], v[194:197], v[226:229], v[30:33]
	v_mfma_f32_16x16x32_bf16 v[26:29], v[194:197], v[234:237], v[26:29]
	v_mfma_f32_16x16x32_bf16 v[22:25], v[202:205], v[226:229], v[22:25]
	v_mfma_f32_16x16x32_bf16 v[18:21], v[202:205], v[234:237], v[18:21]
	v_mfma_f32_16x16x32_bf16 v[14:17], v[210:213], v[226:229], v[14:17]
	v_mfma_f32_16x16x32_bf16 v[10:13], v[210:213], v[234:237], v[10:13]
	v_mfma_f32_16x16x32_bf16 v[6:9], v[218:221], v[226:229], v[6:9]
	v_mfma_f32_16x16x32_bf16 v[2:5], v[218:221], v[234:237], v[2:5]
	v_mfma_f32_16x16x32_bf16 v[30:33], v[198:201], v[230:233], v[30:33]
	v_mfma_f32_16x16x32_bf16 v[26:29], v[198:201], v[238:241], v[26:29]
	v_mfma_f32_16x16x32_bf16 v[22:25], v[206:209], v[230:233], v[22:25]
	v_mfma_f32_16x16x32_bf16 v[18:21], v[206:209], v[238:241], v[18:21]
	v_mfma_f32_16x16x32_bf16 v[14:17], v[214:217], v[230:233], v[14:17]
	v_mfma_f32_16x16x32_bf16 v[10:13], v[214:217], v[238:241], v[10:13]
	v_mfma_f32_16x16x32_bf16 v[6:9], v[222:225], v[230:233], v[6:9]
	v_mfma_f32_16x16x32_bf16 v[2:5], v[222:225], v[238:241], v[2:5]
	s_barrier
	ds_read_b128 v[178:181], v165
	ds_read_b128 v[182:185], v165 offset:1024
	ds_read_b128 v[186:189], v165 offset:2048
	ds_read_b128 v[190:193], v165 offset:3072
	v_readfirstlane_b32 s10, v164
	v_lshl_add_u64 v[226:227], v[242:243], 0, s[78:79]
	s_mov_b32 m0, s10
	v_readfirstlane_b32 s10, v166
	ds_read_b128 v[194:197], v145 offset:32768
	ds_read_b128 v[198:201], v145 offset:33792
	ds_read_b128 v[202:205], v144 offset:32768
	ds_read_b128 v[206:209], v144 offset:33792
	ds_read_b128 v[210:213], v143 offset:32768
	ds_read_b128 v[214:217], v143 offset:33792
	ds_read_b128 v[218:221], v142 offset:32768
	ds_read_b128 v[222:225], v142 offset:33792
	global_load_lds_dwordx4 v[226:227], off
	v_lshl_add_u64 v[226:227], v[244:245], 0, s[78:79]
	s_mov_b32 m0, s10
	s_nop 0
	global_load_lds_dwordx4 v[226:227], off
	s_waitcnt lgkmcnt(8)
	s_barrier
	s_waitcnt lgkmcnt(0)
	v_mfma_f32_16x16x32_bf16 v[126:129], v[194:197], v[178:181], v[126:129]
	v_mfma_f32_16x16x32_bf16 v[122:125], v[194:197], v[186:189], v[122:125]
	v_mfma_f32_16x16x32_bf16 v[118:121], v[202:205], v[178:181], v[118:121]
	v_mfma_f32_16x16x32_bf16 v[114:117], v[202:205], v[186:189], v[114:117]
	v_mfma_f32_16x16x32_bf16 v[110:113], v[210:213], v[178:181], v[110:113]
	v_mfma_f32_16x16x32_bf16 v[106:109], v[210:213], v[186:189], v[106:109]
	v_mfma_f32_16x16x32_bf16 v[102:105], v[218:221], v[178:181], v[102:105]
	v_mfma_f32_16x16x32_bf16 v[98:101], v[218:221], v[186:189], v[98:101]
	v_mfma_f32_16x16x32_bf16 v[126:129], v[198:201], v[182:185], v[126:129]
	v_mfma_f32_16x16x32_bf16 v[122:125], v[198:201], v[190:193], v[122:125]
	v_mfma_f32_16x16x32_bf16 v[118:121], v[206:209], v[182:185], v[118:121]
	v_mfma_f32_16x16x32_bf16 v[114:117], v[206:209], v[190:193], v[114:117]
	v_mfma_f32_16x16x32_bf16 v[110:113], v[214:217], v[182:185], v[110:113]
	v_mfma_f32_16x16x32_bf16 v[106:109], v[214:217], v[190:193], v[106:109]
	v_mfma_f32_16x16x32_bf16 v[102:105], v[222:225], v[182:185], v[102:105]
	v_mfma_f32_16x16x32_bf16 v[98:101], v[222:225], v[190:193], v[98:101]
	s_barrier
	v_readfirstlane_b32 s10, v167
	v_lshl_add_u64 v[250:251], v[246:247], 0, s[18:19]
	s_mov_b32 m0, s10
	v_readfirstlane_b32 s10, v168
	ds_read_b128 v[226:229], v159
	ds_read_b128 v[230:233], v159 offset:1024
	ds_read_b128 v[234:237], v159 offset:2048
	ds_read_b128 v[238:241], v159 offset:3072
	global_load_lds_dwordx4 v[250:251], off
	v_lshl_add_u64 v[250:251], v[248:249], 0, s[18:19]
	s_mov_b32 m0, s10
	s_nop 0
	global_load_lds_dwordx4 v[250:251], off
	s_barrier
	s_waitcnt lgkmcnt(0)
	v_mfma_f32_16x16x32_bf16 v[94:97], v[194:197], v[226:229], v[94:97]
	v_mfma_f32_16x16x32_bf16 v[90:93], v[194:197], v[234:237], v[90:93]
	v_mfma_f32_16x16x32_bf16 v[86:89], v[202:205], v[226:229], v[86:89]
	v_mfma_f32_16x16x32_bf16 v[82:85], v[202:205], v[234:237], v[82:85]
	v_mfma_f32_16x16x32_bf16 v[78:81], v[210:213], v[226:229], v[78:81]
	v_mfma_f32_16x16x32_bf16 v[74:77], v[210:213], v[234:237], v[74:77]
	v_mfma_f32_16x16x32_bf16 v[70:73], v[218:221], v[226:229], v[70:73]
	v_mfma_f32_16x16x32_bf16 v[66:69], v[218:221], v[234:237], v[66:69]
	v_mfma_f32_16x16x32_bf16 v[94:97], v[198:201], v[230:233], v[94:97]
	v_mfma_f32_16x16x32_bf16 v[90:93], v[198:201], v[238:241], v[90:93]
	v_mfma_f32_16x16x32_bf16 v[86:89], v[206:209], v[230:233], v[86:89]
	v_mfma_f32_16x16x32_bf16 v[82:85], v[206:209], v[238:241], v[82:85]
	v_mfma_f32_16x16x32_bf16 v[78:81], v[214:217], v[230:233], v[78:81]
	v_mfma_f32_16x16x32_bf16 v[74:77], v[214:217], v[238:241], v[74:77]
	v_mfma_f32_16x16x32_bf16 v[70:73], v[222:225], v[230:233], v[70:73]
	v_mfma_f32_16x16x32_bf16 v[66:69], v[222:225], v[238:241], v[66:69]
	v_readfirstlane_b32 s10, v169
	v_lshl_add_u64 v[242:243], v[242:243], 0, s[82:83]
	s_mov_b32 m0, s10
	v_readfirstlane_b32 s10, v170
	s_barrier
	ds_read_b128 v[194:197], v145 offset:49152
	ds_read_b128 v[198:201], v145 offset:50176
	ds_read_b128 v[202:205], v144 offset:49152
	ds_read_b128 v[206:209], v144 offset:50176
	ds_read_b128 v[210:213], v143 offset:49152
	ds_read_b128 v[214:217], v143 offset:50176
	ds_read_b128 v[218:221], v142 offset:49152
	ds_read_b128 v[222:225], v142 offset:50176
	global_load_lds_dwordx4 v[242:243], off
	v_lshl_add_u64 v[242:243], v[244:245], 0, s[82:83]
	s_mov_b32 m0, s10
	s_nop 0
	global_load_lds_dwordx4 v[242:243], off
	s_barrier
; #define STA(P, br, kt) STAGE(P, A, aoff0, aoff1, lda, br, kt)
; #define STB(P, br, kt) STAGE(P, Bt, boff0, boff1, ldb, br, kt)
; #define LDA(dst, b, h) _Pragma("unroll") for (int m = 0; m < 4; ++m) _Pragma("unroll") for (int k = 0; k < 2; ++k) \
;     dst[m][k] = *reinterpret_cast<const bf16x8*>((char*)SA(b, h) + lds_byte(wr * 64 + m * 16 + fr, k * 32 + fq * 8))
; #define LDB(dst, b, h) _Pragma("unroll") for (int n = 0; n < 2; ++n) _Pragma("unroll") for (int k = 0; k < 2; ++k) \
;     dst[n][k] = *reinterpret_cast<const bf16x8*>((char*)SB(b, h) + lds_byte(wc * 32 + n * 16 + fr, k * 32 + fq * 8))
; #define MMA(ai, bj, At, Bq) do { __builtin_amdgcn_s_setprio(1); \
;     _Pragma("unroll") for (int m = 0; m < 4; ++m) _Pragma("unroll") for (int n = 0; n < 2; ++n) _Pragma("unroll") for (int k = 0; k < 2; ++k) \
;       acc[ai][bj][m][n] = __builtin_amdgcn_mfma_f32_16x16x32_bf16(At[m][k], Bq[n][k], acc[ai][bj][m][n], 0, 0, 0); \
;     __builtin_amdgcn_s_setprio(0); } while (0)
; #define WAIT_V(n) asm volatile("s_waitcnt vmcnt(" #n ")" ::: "memory")
; #define WAIT_L(n) asm volatile("s_waitcnt lgkmcnt(" #n ")" ::: "memory")
; #define BAR __builtin_amdgcn_s_barrier()
; #define SCHED __builtin_amdgcn_sched_barrier(0)
; __device__ __forceinline__ void gemm256(const u16* __restrict__ A, int lda, const u16* __restrict__ Bt, int ldb, int K,
;                                         f32x4 (&acc)[2][2][4][2], const int g_wid) {
;     ...
;     BAR; WAIT_L(0); MMA(1, 0, At, B0); BAR; SCHED;
;     STB(SB(1, 1), HALF, t + 3);
;     WAIT_V(6); BAR; MMA(1, 1, At, B1); BAR;
;   }
;   { LDB(B0, 0, 0); LDA(At, 0, 0); STA(SA(1, 1), HALF, nt - 1);
;     BAR; WAIT_L(0); MMA(0, 0, At, B0); BAR;
;     LDB(B1, 0, 1); BAR; WAIT_L(0); MMA(0, 1, At, B1); BAR;
	s_waitcnt lgkmcnt(0)
	v_mfma_f32_16x16x32_bf16 v[62:65], v[194:197], v[178:181], v[62:65]
	v_mfma_f32_16x16x32_bf16 v[58:61], v[194:197], v[186:189], v[58:61]
	v_mfma_f32_16x16x32_bf16 v[54:57], v[202:205], v[178:181], v[54:57]
	v_mfma_f32_16x16x32_bf16 v[50:53], v[202:205], v[186:189], v[50:53]
	v_mfma_f32_16x16x32_bf16 v[46:49], v[210:213], v[178:181], v[46:49]
	v_mfma_f32_16x16x32_bf16 v[42:45], v[210:213], v[186:189], v[42:45]
	v_mfma_f32_16x16x32_bf16 v[38:41], v[218:221], v[178:181], v[38:41]
	v_mfma_f32_16x16x32_bf16 v[34:37], v[218:221], v[186:189], v[34:37]
	v_mfma_f32_16x16x32_bf16 v[62:65], v[198:201], v[182:185], v[62:65]
	v_mfma_f32_16x16x32_bf16 v[58:61], v[198:201], v[190:193], v[58:61]
	v_mfma_f32_16x16x32_bf16 v[54:57], v[206:209], v[182:185], v[54:57]
	v_mfma_f32_16x16x32_bf16 v[50:53], v[206:209], v[190:193], v[50:53]
	v_mfma_f32_16x16x32_bf16 v[46:49], v[214:217], v[182:185], v[46:49]
	v_mfma_f32_16x16x32_bf16 v[42:45], v[214:217], v[190:193], v[42:45]
	v_mfma_f32_16x16x32_bf16 v[38:41], v[222:225], v[182:185], v[38:41]
	v_mfma_f32_16x16x32_bf16 v[34:37], v[222:225], v[190:193], v[34:37]
	s_barrier
	v_readfirstlane_b32 s10, v171
	v_lshl_add_u64 v[178:179], v[246:247], 0, s[20:21]
	s_mov_b32 m0, s10
	v_readfirstlane_b32 s10, v172
	global_load_lds_dwordx4 v[178:179], off
	v_lshl_add_u64 v[178:179], v[248:249], 0, s[20:21]
	s_mov_b32 m0, s10
	s_nop 0
	global_load_lds_dwordx4 v[178:179], off
	s_waitcnt vmcnt(6)
	s_barrier
	v_mfma_f32_16x16x32_bf16 v[30:33], v[194:197], v[226:229], v[30:33]
	v_mfma_f32_16x16x32_bf16 v[26:29], v[194:197], v[234:237], v[26:29]
	v_mfma_f32_16x16x32_bf16 v[22:25], v[202:205], v[226:229], v[22:25]
	v_mfma_f32_16x16x32_bf16 v[18:21], v[202:205], v[234:237], v[18:21]
	v_mfma_f32_16x16x32_bf16 v[14:17], v[210:213], v[226:229], v[14:17]
	v_mfma_f32_16x16x32_bf16 v[10:13], v[210:213], v[234:237], v[10:13]
	v_mfma_f32_16x16x32_bf16 v[6:9], v[218:221], v[226:229], v[6:9]
	v_mfma_f32_16x16x32_bf16 v[2:5], v[218:221], v[234:237], v[2:5]
	v_mfma_f32_16x16x32_bf16 v[30:33], v[198:201], v[230:233], v[30:33]
	v_mfma_f32_16x16x32_bf16 v[26:29], v[198:201], v[238:241], v[26:29]
	v_mfma_f32_16x16x32_bf16 v[22:25], v[206:209], v[230:233], v[22:25]
	v_mfma_f32_16x16x32_bf16 v[18:21], v[206:209], v[238:241], v[18:21]
	v_mfma_f32_16x16x32_bf16 v[14:17], v[214:217], v[230:233], v[14:17]
	v_mfma_f32_16x16x32_bf16 v[10:13], v[214:217], v[238:241], v[10:13]
	v_mfma_f32_16x16x32_bf16 v[6:9], v[222:225], v[230:233], v[6:9]
	v_mfma_f32_16x16x32_bf16 v[2:5], v[222:225], v[238:241], v[2:5]
	s_add_i32 s14, s14, 2
	s_add_u32 s6, s6, 0x100
	s_addc_u32 s7, s7, 0
	s_cmp_lt_u32 s14, 12
	s_barrier
	s_cbranch_scc1 .LBB0_136
	s_add_u32 s6, s12, 0x40780
	s_addc_u32 s7, s13, 0
	v_readfirstlane_b32 s10, v175
	v_lshl_add_u64 v[132:133], v[132:133], 1, s[6:7]
	s_mov_b32 m0, s10
	v_lshl_add_u64 v[130:131], v[130:131], 1, s[6:7]
	v_readfirstlane_b32 s6, v176
	ds_read_b128 v[134:137], v174
	ds_read_b128 v[138:141], v174 offset:1024
	ds_read_b128 v[160:163], v174 offset:2048
	ds_read_b128 v[166:169], v174 offset:3072
	ds_read_b128 v[178:181], v145
	ds_read_b128 v[182:185], v145 offset:1024
	ds_read_b128 v[186:189], v144
	ds_read_b128 v[190:193], v144 offset:1024
	ds_read_b128 v[194:197], v143
	ds_read_b128 v[198:201], v143 offset:1024
	ds_read_b128 v[202:205], v142
	ds_read_b128 v[206:209], v142 offset:1024
	global_load_lds_dwordx4 v[132:133], off
	s_mov_b32 m0, s6
	s_nop 0
	global_load_lds_dwordx4 v[130:131], off
	s_barrier
	s_waitcnt lgkmcnt(0)
	v_mfma_f32_16x16x32_bf16 v[126:129], v[178:181], v[134:137], v[126:129]
	v_mfma_f32_16x16x32_bf16 v[122:125], v[178:181], v[160:163], v[122:125]
	v_mfma_f32_16x16x32_bf16 v[118:121], v[186:189], v[134:137], v[118:121]
	v_mfma_f32_16x16x32_bf16 v[114:117], v[186:189], v[160:163], v[114:117]
	v_mfma_f32_16x16x32_bf16 v[110:113], v[194:197], v[134:137], v[110:113]
	v_mfma_f32_16x16x32_bf16 v[106:109], v[194:197], v[160:163], v[106:109]
	v_mfma_f32_16x16x32_bf16 v[102:105], v[202:205], v[134:137], v[102:105]
	v_mfma_f32_16x16x32_bf16 v[98:101], v[202:205], v[160:163], v[98:101]
	v_mfma_f32_16x16x32_bf16 v[126:129], v[182:185], v[138:141], v[126:129]
	v_mfma_f32_16x16x32_bf16 v[122:125], v[182:185], v[166:169], v[122:125]
	v_mfma_f32_16x16x32_bf16 v[118:121], v[190:193], v[138:141], v[118:121]
	v_mfma_f32_16x16x32_bf16 v[114:117], v[190:193], v[166:169], v[114:117]
	v_mfma_f32_16x16x32_bf16 v[110:113], v[198:201], v[138:141], v[110:113]
	v_mfma_f32_16x16x32_bf16 v[106:109], v[198:201], v[166:169], v[106:109]
	v_mfma_f32_16x16x32_bf16 v[102:105], v[206:209], v[138:141], v[102:105]
	v_mfma_f32_16x16x32_bf16 v[98:101], v[206:209], v[166:169], v[98:101]
	s_barrier
	ds_read_b128 v[130:133], v173
	ds_read_b128 v[174:177], v173 offset:1024
	ds_read_b128 v[210:213], v173 offset:2048
	ds_read_b128 v[170:173], v173 offset:3072
	s_barrier
	s_waitcnt lgkmcnt(0)
	v_mfma_f32_16x16x32_bf16 v[86:89], v[186:189], v[130:133], v[86:89]
	v_mfma_f32_16x16x32_bf16 v[74:77], v[194:197], v[210:213], v[74:77]
	v_mfma_f32_16x16x32_bf16 v[70:73], v[202:205], v[130:133], v[70:73]
	v_mfma_f32_16x16x32_bf16 v[66:69], v[202:205], v[210:213], v[66:69]
	v_mfma_f32_16x16x32_bf16 v[94:97], v[178:181], v[130:133], v[94:97]
	v_mfma_f32_16x16x32_bf16 v[90:93], v[178:181], v[210:213], v[90:93]
	v_mfma_f32_16x16x32_bf16 v[86:89], v[190:193], v[174:177], v[86:89]
	v_mfma_f32_16x16x32_bf16 v[82:85], v[186:189], v[210:213], v[82:85]
	v_mfma_f32_16x16x32_bf16 v[78:81], v[194:197], v[130:133], v[78:81]
	v_mfma_f32_16x16x32_bf16 v[74:77], v[198:201], v[170:173], v[74:77]
	v_mfma_f32_16x16x32_bf16 v[70:73], v[206:209], v[174:177], v[70:73]
	v_mfma_f32_16x16x32_bf16 v[66:69], v[206:209], v[170:173], v[66:69]
	v_mfma_f32_16x16x32_bf16 v[214:217], v[182:185], v[174:177], v[94:97]
	v_mfma_f32_16x16x32_bf16 v[178:181], v[182:185], v[170:173], v[90:93]
	v_mfma_f32_16x16x32_bf16 v[182:185], v[190:193], v[170:173], v[82:85]
	v_mfma_f32_16x16x32_bf16 v[186:189], v[198:201], v[174:177], v[78:81]
	s_barrier
; #define LDA(dst, b, h) _Pragma("unroll") for (int m = 0; m < 4; ++m) _Pragma("unroll") for (int k = 0; k < 2; ++k) \
;     dst[m][k] = *reinterpret_cast<const bf16x8*>((char*)SA(b, h) + lds_byte(wr * 64 + m * 16 + fr, k * 32 + fq * 8))
; #define LDB(dst, b, h) _Pragma("unroll") for (int n = 0; n < 2; ++n) _Pragma("unroll") for (int k = 0; k < 2; ++k) \
;     dst[n][k] = *reinterpret_cast<const bf16x8*>((char*)SB(b, h) + lds_byte(wc * 32 + n * 16 + fr, k * 32 + fq * 8))
; #define MMA(ai, bj, At, Bq) do { __builtin_amdgcn_s_setprio(1); \
;     _Pragma("unroll") for (int m = 0; m < 4; ++m) _Pragma("unroll") for (int n = 0; n < 2; ++n) _Pragma("unroll") for (int k = 0; k < 2; ++k) \
;       acc[ai][bj][m][n] = __builtin_amdgcn_mfma_f32_16x16x32_bf16(At[m][k], Bq[n][k], acc[ai][bj][m][n], 0, 0, 0); \
;     __builtin_amdgcn_s_setprio(0); } while (0)
; #define WAIT_V(n) asm volatile("s_waitcnt vmcnt(" #n ")" ::: "memory")
; #define WAIT_L(n) asm volatile("s_waitcnt lgkmcnt(" #n ")" ::: "memory")
; #define BAR __builtin_amdgcn_s_barrier()
; __device__ __forceinline__ void gemm256(const u16* __restrict__ A, int lda, const u16* __restrict__ Bt, int ldb, int K,
;                                         f32x4 (&acc)[2][2][4][2], const int g_wid) {
;     ...
;     LDA(At, 0, 1); WAIT_V(4); BAR; WAIT_L(0); MMA(1, 0, At, B0); MMA(1, 1, At, B1); BAR; }
;   { LDB(B0, 1, 0); LDA(At, 1, 0); WAIT_V(2); BAR; WAIT_L(0); MMA(0, 0, At, B0); BAR;
	s_nop 0
	ds_read_b128 v[78:81], v145 offset:16384
	ds_read_b128 v[82:85], v145 offset:17408
	ds_read_b128 v[90:93], v144 offset:16384
	ds_read_b128 v[94:97], v144 offset:17408
	ds_read_b128 v[190:193], v143 offset:16384
	ds_read_b128 v[194:197], v143 offset:17408
	ds_read_b128 v[198:201], v142 offset:16384
	ds_read_b128 v[202:205], v142 offset:17408
	s_waitcnt vmcnt(4)
	s_barrier
	s_waitcnt lgkmcnt(0)
	v_mfma_f32_16x16x32_bf16 v[54:57], v[90:93], v[134:137], v[54:57]
	v_mfma_f32_16x16x32_bf16 v[42:45], v[190:193], v[160:163], v[42:45]
	v_mfma_f32_16x16x32_bf16 v[38:41], v[198:201], v[134:137], v[38:41]
	v_mfma_f32_16x16x32_bf16 v[34:37], v[198:201], v[160:163], v[34:37]
	v_mfma_f32_16x16x32_bf16 v[62:65], v[78:81], v[134:137], v[62:65]
	v_mfma_f32_16x16x32_bf16 v[58:61], v[78:81], v[160:163], v[58:61]
	v_mfma_f32_16x16x32_bf16 v[54:57], v[94:97], v[138:141], v[54:57]
	v_mfma_f32_16x16x32_bf16 v[50:53], v[90:93], v[160:163], v[50:53]
	v_mfma_f32_16x16x32_bf16 v[46:49], v[190:193], v[134:137], v[46:49]
	v_mfma_f32_16x16x32_bf16 v[42:45], v[194:197], v[166:169], v[42:45]
	v_mfma_f32_16x16x32_bf16 v[38:41], v[202:205], v[138:141], v[38:41]
	v_mfma_f32_16x16x32_bf16 v[34:37], v[202:205], v[166:169], v[34:37]
	v_mfma_f32_16x16x32_bf16 v[206:209], v[82:85], v[138:141], v[62:65]
	v_mfma_f32_16x16x32_bf16 v[218:221], v[82:85], v[166:169], v[58:61]
	v_mfma_f32_16x16x32_bf16 v[222:225], v[94:97], v[166:169], v[50:53]
	v_mfma_f32_16x16x32_bf16 v[226:229], v[194:197], v[138:141], v[46:49]
	v_mfma_f32_16x16x32_bf16 v[2:5], v[198:201], v[210:213], v[2:5]
	v_mfma_f32_16x16x32_bf16 v[30:33], v[78:81], v[130:133], v[30:33]
	v_mfma_f32_16x16x32_bf16 v[26:29], v[78:81], v[210:213], v[26:29]
	v_mfma_f32_16x16x32_bf16 v[22:25], v[90:93], v[130:133], v[22:25]
	v_mfma_f32_16x16x32_bf16 v[18:21], v[90:93], v[210:213], v[18:21]
	v_mfma_f32_16x16x32_bf16 v[14:17], v[190:193], v[130:133], v[14:17]
	v_mfma_f32_16x16x32_bf16 v[10:13], v[190:193], v[210:213], v[10:13]
	v_mfma_f32_16x16x32_bf16 v[6:9], v[198:201], v[130:133], v[6:9]
	v_mfma_f32_16x16x32_bf16 v[2:5], v[202:205], v[170:173], v[2:5]
	v_mfma_f32_16x16x32_bf16 v[134:137], v[82:85], v[174:177], v[30:33]
	v_mfma_f32_16x16x32_bf16 v[138:141], v[82:85], v[170:173], v[26:29]
	v_mfma_f32_16x16x32_bf16 v[160:163], v[94:97], v[174:177], v[22:25]
	v_mfma_f32_16x16x32_bf16 v[166:169], v[94:97], v[170:173], v[18:21]
	v_mfma_f32_16x16x32_bf16 v[230:233], v[194:197], v[174:177], v[14:17]
	v_mfma_f32_16x16x32_bf16 v[190:193], v[194:197], v[170:173], v[10:13]
	v_mfma_f32_16x16x32_bf16 v[130:133], v[202:205], v[174:177], v[6:9]
	s_barrier
	s_nop 0
	ds_read_b128 v[6:9], v165
	ds_read_b128 v[10:13], v165 offset:1024
	ds_read_b128 v[22:25], v165 offset:2048
	ds_read_b128 v[170:173], v165 offset:3072
	ds_read_b128 v[14:17], v145 offset:32768
	ds_read_b128 v[18:21], v145 offset:33792
	ds_read_b128 v[26:29], v144 offset:32768
	ds_read_b128 v[46:49], v144 offset:33792
	ds_read_b128 v[174:177], v143 offset:32768
	ds_read_b128 v[194:197], v143 offset:33792
	ds_read_b128 v[198:201], v142 offset:32768
	ds_read_b128 v[202:205], v142 offset:33792
	s_waitcnt vmcnt(2)
	s_barrier
	s_waitcnt lgkmcnt(0)
	v_mfma_f32_16x16x32_bf16 v[30:33], v[14:17], v[6:9], v[126:129]
	v_mfma_f32_16x16x32_bf16 v[126:129], v[18:21], v[10:13], v[30:33]
	v_mfma_f32_16x16x32_bf16 v[30:33], v[14:17], v[22:25], v[122:125]
	v_mfma_f32_16x16x32_bf16 v[94:97], v[18:21], v[170:173], v[30:33]
	v_mfma_f32_16x16x32_bf16 v[30:33], v[26:29], v[6:9], v[118:121]
	v_mfma_f32_16x16x32_bf16 v[122:125], v[46:49], v[10:13], v[30:33]
	v_mfma_f32_16x16x32_bf16 v[30:33], v[26:29], v[22:25], v[114:117]
	v_mfma_f32_16x16x32_bf16 v[90:93], v[46:49], v[170:173], v[30:33]
	v_mfma_f32_16x16x32_bf16 v[30:33], v[174:177], v[6:9], v[110:113]
	v_mfma_f32_16x16x32_bf16 v[114:117], v[194:197], v[10:13], v[30:33]
	v_mfma_f32_16x16x32_bf16 v[30:33], v[174:177], v[22:25], v[106:109]
	v_mfma_f32_16x16x32_bf16 v[82:85], v[194:197], v[170:173], v[30:33]
	v_mfma_f32_16x16x32_bf16 v[30:33], v[198:201], v[6:9], v[102:105]
	v_mfma_f32_16x16x32_bf16 v[110:113], v[202:205], v[10:13], v[30:33]
	v_mfma_f32_16x16x32_bf16 v[30:33], v[198:201], v[22:25], v[98:101]
	v_mfma_f32_16x16x32_bf16 v[78:81], v[202:205], v[170:173], v[30:33]
	s_barrier
; #define LDA(dst, b, h) _Pragma("unroll") for (int m = 0; m < 4; ++m) _Pragma("unroll") for (int k = 0; k < 2; ++k) \
;     dst[m][k] = *reinterpret_cast<const bf16x8*>((char*)SA(b, h) + lds_byte(wr * 64 + m * 16 + fr, k * 32 + fq * 8))
; #define LDB(dst, b, h) _Pragma("unroll") for (int n = 0; n < 2; ++n) _Pragma("unroll") for (int k = 0; k < 2; ++k) \
;     dst[n][k] = *reinterpret_cast<const bf16x8*>((char*)SB(b, h) + lds_byte(wc * 32 + n * 16 + fr, k * 32 + fq * 8))
; #define MMA(ai, bj, At, Bq) do { __builtin_amdgcn_s_setprio(1); \
;     _Pragma("unroll") for (int m = 0; m < 4; ++m) _Pragma("unroll") for (int n = 0; n < 2; ++n) _Pragma("unroll") for (int k = 0; k < 2; ++k) \
;       acc[ai][bj][m][n] = __builtin_amdgcn_mfma_f32_16x16x32_bf16(At[m][k], Bq[n][k], acc[ai][bj][m][n], 0, 0, 0); \
;     __builtin_amdgcn_s_setprio(0); } while (0)
; #define WAIT_V(n) asm volatile("s_waitcnt vmcnt(" #n ")" ::: "memory")
; #define WAIT_L(n) asm volatile("s_waitcnt lgkmcnt(" #n ")" ::: "memory")
; #define BAR __builtin_amdgcn_s_barrier()
; __device__ __forceinline__ void gemm256(const u16* __restrict__ A, int lda, const u16* __restrict__ Bt, int ldb, int K,
;                                         f32x4 (&acc)[2][2][4][2], const int g_wid) {
;     ...
;     LDB(B1, 1, 1); WAIT_V(0); BAR; WAIT_L(0); MMA(0, 1, At, B1); BAR;
;     LDA(At, 1, 1); BAR; WAIT_L(0); MMA(1, 0, At, B0); MMA(1, 1, At, B1); BAR; }
;   if (wr == 0) BAR;
; __device__ __forceinline__ void phase_g4(PP p, const int g_wid) {
;     ...
;         const float rs = rsl[tok0 + bj * 128 + n * 16];
; #pragma unroll
;         for (int ai = 0; ai < 2; ++ai)
; #pragma unroll
;           for (int m = 0; m < 4; ++m) {
;             f32x4 v = acc[ai][bj][m][n];
;             if (isg) {
; #pragma unroll
;               for (int j = 0; j < 4; ++j) v[j] = __builtin_amdgcn_rcpf(1.f + __expf(-v[j] * rs));
	ds_read_b128 v[210:213], v159
	ds_read_b128 v[234:237], v159 offset:1024
	ds_read_b128 v[238:241], v159 offset:2048
	ds_read_b128 v[242:245], v159 offset:3072
	s_waitcnt vmcnt(0)
	s_barrier
	s_waitcnt lgkmcnt(0)
	v_mfma_f32_16x16x32_bf16 v[30:33], v[14:17], v[210:213], v[214:217]
	v_mfma_f32_16x16x32_bf16 v[14:17], v[14:17], v[238:241], v[178:181]
	v_mfma_f32_16x16x32_bf16 v[62:65], v[18:21], v[234:237], v[30:33]
	v_mfma_f32_16x16x32_bf16 v[30:33], v[18:21], v[242:245], v[14:17]
	v_mfma_f32_16x16x32_bf16 v[14:17], v[26:29], v[210:213], v[86:89]
	v_mfma_f32_16x16x32_bf16 v[58:61], v[46:49], v[234:237], v[14:17]
	v_mfma_f32_16x16x32_bf16 v[14:17], v[26:29], v[238:241], v[182:185]
	v_mfma_f32_16x16x32_bf16 v[26:29], v[46:49], v[242:245], v[14:17]
	v_mfma_f32_16x16x32_bf16 v[14:17], v[174:177], v[210:213], v[186:189]
	v_mfma_f32_16x16x32_bf16 v[50:53], v[194:197], v[234:237], v[14:17]
	v_mfma_f32_16x16x32_bf16 v[14:17], v[174:177], v[238:241], v[74:77]
	v_mfma_f32_16x16x32_bf16 v[18:21], v[194:197], v[242:245], v[14:17]
	v_mfma_f32_16x16x32_bf16 v[14:17], v[198:201], v[210:213], v[70:73]
	v_mfma_f32_16x16x32_bf16 v[46:49], v[202:205], v[234:237], v[14:17]
	v_mfma_f32_16x16x32_bf16 v[14:17], v[198:201], v[238:241], v[66:69]
	v_mfma_f32_16x16x32_bf16 v[14:17], v[202:205], v[242:245], v[14:17]
	s_barrier
	ds_read_b128 v[174:177], v145 offset:49152
	ds_read_b128 v[178:181], v145 offset:50176
	ds_read_b128 v[182:185], v144 offset:49152
	ds_read_b128 v[144:147], v144 offset:50176
	ds_read_b128 v[186:189], v143 offset:49152
	ds_read_b128 v[194:197], v143 offset:50176
	ds_read_b128 v[198:201], v142 offset:49152
	ds_read_b128 v[202:205], v142 offset:50176
	s_barrier
	s_waitcnt lgkmcnt(0)
	v_mfma_f32_16x16x32_bf16 v[54:57], v[182:185], v[6:9], v[54:57]
	v_mfma_f32_16x16x32_bf16 v[106:109], v[144:147], v[10:13], v[54:57]
	v_mfma_f32_16x16x32_bf16 v[54:57], v[182:185], v[22:25], v[222:225]
	v_mfma_f32_16x16x32_bf16 v[66:69], v[174:177], v[6:9], v[206:209]
	v_mfma_f32_16x16x32_bf16 v[74:77], v[144:147], v[170:173], v[54:57]
	v_mfma_f32_16x16x32_bf16 v[54:57], v[186:189], v[6:9], v[226:229]
	v_mfma_f32_16x16x32_bf16 v[6:9], v[198:201], v[6:9], v[38:41]
	v_mfma_f32_16x16x32_bf16 v[118:121], v[178:181], v[10:13], v[66:69]
	v_mfma_f32_16x16x32_bf16 v[66:69], v[174:177], v[22:25], v[218:221]
	v_mfma_f32_16x16x32_bf16 v[42:45], v[186:189], v[22:25], v[42:45]
	v_mfma_f32_16x16x32_bf16 v[98:101], v[202:205], v[10:13], v[6:9]
	v_mfma_f32_16x16x32_bf16 v[6:9], v[198:201], v[22:25], v[34:37]
	v_mfma_f32_16x16x32_bf16 v[86:89], v[178:181], v[170:173], v[66:69]
	v_mfma_f32_16x16x32_bf16 v[102:105], v[194:197], v[10:13], v[54:57]
	v_mfma_f32_16x16x32_bf16 v[70:73], v[194:197], v[170:173], v[42:45]
	v_mfma_f32_16x16x32_bf16 v[66:69], v[202:205], v[170:173], v[6:9]
	v_mfma_f32_16x16x32_bf16 v[6:9], v[174:177], v[210:213], v[134:137]
	v_mfma_f32_16x16x32_bf16 v[54:57], v[178:181], v[234:237], v[6:9]
	v_mfma_f32_16x16x32_bf16 v[6:9], v[174:177], v[238:241], v[138:141]
	v_mfma_f32_16x16x32_bf16 v[22:25], v[178:181], v[242:245], v[6:9]
	v_mfma_f32_16x16x32_bf16 v[6:9], v[182:185], v[210:213], v[160:163]
	v_mfma_f32_16x16x32_bf16 v[42:45], v[144:147], v[234:237], v[6:9]
	v_mfma_f32_16x16x32_bf16 v[6:9], v[182:185], v[238:241], v[166:169]
	v_mfma_f32_16x16x32_bf16 v[10:13], v[144:147], v[242:245], v[6:9]
	v_mfma_f32_16x16x32_bf16 v[6:9], v[186:189], v[210:213], v[230:233]
	v_mfma_f32_16x16x32_bf16 v[38:41], v[194:197], v[234:237], v[6:9]
	v_mfma_f32_16x16x32_bf16 v[6:9], v[186:189], v[238:241], v[190:193]
	v_mfma_f32_16x16x32_bf16 v[34:37], v[198:201], v[210:213], v[130:133]
	v_mfma_f32_16x16x32_bf16 v[2:5], v[198:201], v[238:241], v[2:5]
	v_mfma_f32_16x16x32_bf16 v[6:9], v[194:197], v[242:245], v[6:9]
	v_mfma_f32_16x16x32_bf16 v[34:37], v[202:205], v[234:237], v[34:37]
	v_mfma_f32_16x16x32_bf16 v[2:5], v[202:205], v[242:245], v[2:5]
	s_setprio 0
	s_movk_i32 s6, 0x100
	v_cmp_gt_u32_e32 vcc, s6, v0
	s_barrier
	s_and_saveexec_b64 s[6:7], vcc
	s_cbranch_execz .LBB0_139
	s_barrier

; #define hw_tid() ((g_wid << 6) | hw_lane())
; #define STA(P, br, kt) STAGE(P, A, aoff0, aoff1, lda, br, kt)
; #define STB(P, br, kt) STAGE(P, Bt, boff0, boff1, ldb, br, kt)
; #define BAR __builtin_amdgcn_s_barrier()
; __device__ __forceinline__ void gemm256(const u16* __restrict__ A, int lda, const u16* __restrict__ Bt, int ldb, int K,
;                                         f32x4 (&acc)[2][2][4][2], const int g_wid) {
;   int tid = hw_tid(); asm volatile("" : "+v"(tid));
;   const int wid = tid >> 6, lane = tid & 63, wr = wid >> 2, wc = wid & 3, fr = lane & 15, fq = lane >> 4;
;   int r0, c0, r1, c1;
;   stage_rc(tid * 16, r0, c0);
;   stage_rc(tid * 16 + 8192, r1, c1);
;   const int aoff0 = r0 * lda + c0, aoff1 = r1 * lda + c1, boff0 = r0 * ldb + c0, boff1 = r1 * ldb + c1;
;   bf16x8 At[4][2], B0[2][2], B1[2][2];
;   const int nt = K / BK;
;   STB(SB(0, 0), 0, 0); STA(SA(0, 0), 0, 0);
;   STB(SB(0, 1), HALF, 0); STA(SA(0, 1), HALF, 0);
;   if (wr == 1) BAR;
; __device__ __forceinline__ void phase_g3(PP p, const int g_wid, int wrow0, int nN, u16* P, int ldp) {
;     ...
;   for (int t = bid; t < NMT * nN; t += gdim, par ^= 1) {
;     int pm, pn; tile_map(t, NMT, nN, pm, pn);
;     stage_rs(p, pm, par, tid);
;     f32x4 acc[2][2][4][2]; ZERO_ACC;
;     gemm256(p->Wm + (long)(wrow0 + pn * 256) * 1024, 1024, p->hb + (long)pm * 256 * 1024, 1024, 1024, acc, g_wid);
.LBB0_316:
	s_or_b64 exec, exec, s[14:15]
	s_sext_i32_i16 s11, s11
	s_lshl_b32 s14, s11, 8
	s_mov_b32 s11, -1
	s_add_i32 s16, s14, s29
	v_mbcnt_lo_u32_b32 v0, s11, 0
	v_mbcnt_hi_u32_b32 v0, s11, v0
	v_readlane_b32 s11, v254, 63
	s_ashr_i32 s17, s16, 31
	s_lshl_b64 s[18:19], s[16:17], 11
	v_or_b32_e32 v0, s11, v0
	s_waitcnt lgkmcnt(0)
	s_add_u32 s16, s4, s18
	v_ashrrev_i32_e32 v2, 31, v0
	v_lshrrev_b32_e32 v2, 26, v2
	v_add_u32_e32 v2, v0, v2
	v_ashrrev_i32_e32 v10, 6, v2
	v_bfe_i32 v2, v0, 27, 1
	v_lshlrev_b32_e32 v16, 4, v0
	v_lshrrev_b32_e32 v2, 22, v2
	v_add_u32_e32 v2, v16, v2
	v_and_b32_e32 v2, 0xfffffc00, v2
	v_sub_u32_e32 v2, v16, v2
	v_lshrrev_b32_e32 v3, 4, v2
	v_bitop3_b32 v2, v3, v2, 32 bitop3:0x6c
	v_ashrrev_i32_e32 v4, 31, v2
	v_lshrrev_b32_e32 v4, 26, v4
	v_add_u32_e32 v4, v2, v4
	v_ashrrev_i32_e32 v11, 6, v4
	v_and_b32_e32 v4, 0xc0, v4
	v_sub_u32_e32 v2, v2, v4
	v_ashrrev_i16_sdwa v14, v151, sext(v2) dst_sel:DWORD dst_unused:UNUSED_PAD src0_sel:DWORD src1_sel:BYTE_0
	v_add_u32_e32 v2, 0x2000, v16
	v_ashrrev_i32_e32 v4, 31, v2
	v_lshrrev_b32_e32 v4, 22, v4
	v_add_u32_e32 v4, v2, v4
	v_ashrrev_i32_e32 v15, 10, v4
	v_mul_i32_i24_e32 v4, 0x400, v15
	v_sub_u32_e32 v2, v2, v4
	v_lshrrev_b32_e32 v4, 4, v2
	v_lshlrev_b32_e32 v5, 5, v10
	v_bitop3_b32 v2, v4, v2, 32 bitop3:0x6c
	v_and_b32_e32 v13, 32, v5
	v_ashrrev_i32_e32 v5, 31, v2
	v_lshrrev_b32_e32 v5, 26, v5
	v_lshlrev_b32_e32 v3, 3, v10
	v_add_u32_e32 v5, v2, v5
	v_and_b32_e32 v3, 0x3ffff0, v3
	v_lshlrev_b32_e32 v4, 3, v15
	v_ashrrev_i32_e32 v17, 6, v5
	v_and_b32_e32 v5, 0xc0, v5
	v_add_u32_e32 v3, v11, v3
	v_and_b32_e32 v4, 0x3ffff0, v4
	v_lshlrev_b32_e32 v6, 5, v15
	v_sub_u32_e32 v2, v2, v5
	s_addc_u32 s17, s5, s19
	s_ashr_i32 s13, s12, 31
	v_add_u32_e32 v4, v17, v4
	v_and_b32_e32 v18, 32, v6
	v_ashrrev_i16_sdwa v19, v151, sext(v2) dst_sel:DWORD dst_unused:UNUSED_PAD src0_sel:DWORD src1_sel:BYTE_0
	v_lshl_or_b32 v2, v3, 10, v13
	s_lshl_b64 s[20:21], s[12:13], 19
	v_add_u32_sdwa v132, v2, sext(v14) dst_sel:DWORD dst_unused:UNUSED_PAD src0_sel:DWORD src1_sel:WORD_0
	v_lshl_or_b32 v2, v4, 10, v18
	v_readlane_b32 s11, v254, 40
	s_add_u32 s22, s6, s20
	v_add_u32_sdwa v130, v2, sext(v19) dst_sel:DWORD dst_unused:UNUSED_PAD src0_sel:DWORD src1_sel:WORD_0
	v_ashrrev_i32_e32 v133, 31, v132
	v_add_u32_e32 v159, s11, v16
	s_addc_u32 s23, s7, s21
	v_lshlrev_b64 v[20:21], 1, v[132:133]
	v_readfirstlane_b32 s11, v159
	v_ashrrev_i32_e32 v131, 31, v130
	v_add_u32_e32 v160, 0x2000, v159
	v_lshl_add_u64 v[2:3], s[22:23], 0, v[20:21]
	s_mov_b32 m0, s11
	v_lshlrev_b64 v[22:23], 1, v[130:131]
	v_readfirstlane_b32 s11, v160
	v_add_u32_e32 v161, 0, v16
	global_load_lds_dwordx4 v[2:3], off
	v_lshl_add_u64 v[6:7], s[22:23], 0, v[22:23]
	s_mov_b32 m0, s11
	v_readfirstlane_b32 s11, v161
	v_add_u32_e32 v163, 0x2000, v161
	global_load_lds_dwordx4 v[6:7], off
	v_lshl_add_u64 v[8:9], s[16:17], 0, v[20:21]
	s_mov_b32 m0, s11
	v_readfirstlane_b32 s11, v163
	global_load_lds_dwordx4 v[8:9], off
	s_mov_b32 m0, s11
	v_readlane_b32 s11, v254, 41
	s_add_u32 s24, s22, 0x40000
	v_lshl_add_u64 v[4:5], s[16:17], 0, v[22:23]
	v_add_u32_e32 v164, s11, v16
	s_addc_u32 s25, s23, 0
	v_readfirstlane_b32 s11, v164
	global_load_lds_dwordx4 v[4:5], off
	v_lshl_add_u64 v[24:25], s[24:25], 0, v[20:21]
	s_mov_b32 m0, s11
	v_add_u32_e32 v165, 0x2000, v164
	global_load_lds_dwordx4 v[24:25], off
	v_lshl_add_u64 v[24:25], s[24:25], 0, v[22:23]
	v_readfirstlane_b32 s11, v165
	s_add_u32 s24, s16, 0x40000
	v_add_u32_e32 v166, 0x4000, v161
	s_mov_b32 m0, s11
	s_addc_u32 s25, s17, 0
	v_readfirstlane_b32 s11, v166
	v_add_u32_e32 v167, 0x6000, v161
	global_load_lds_dwordx4 v[24:25], off
	v_lshl_add_u64 v[20:21], s[24:25], 0, v[20:21]
	s_mov_b32 m0, s11
	v_readfirstlane_b32 s11, v167
	global_load_lds_dwordx4 v[20:21], off
	v_lshl_add_u64 v[20:21], s[24:25], 0, v[22:23]
	s_mov_b32 m0, s11
	v_ashrrev_i32_e32 v12, 8, v0
	global_load_lds_dwordx4 v[20:21], off
	v_cmp_eq_u32_e32 vcc, 1, v12
	s_and_saveexec_b64 s[24:25], vcc
	s_cbranch_execz .LBB0_318
	s_setprio 3
	s_barrier

; #define STA(P, br, kt) STAGE(P, A, aoff0, aoff1, lda, br, kt)
; #define STB(P, br, kt) STAGE(P, Bt, boff0, boff1, ldb, br, kt)
; #define LDA(dst, b, h) _Pragma("unroll") for (int m = 0; m < 4; ++m) _Pragma("unroll") for (int k = 0; k < 2; ++k) \
;     dst[m][k] = *reinterpret_cast<const bf16x8*>((char*)SA(b, h) + lds_byte(wr * 64 + m * 16 + fr, k * 32 + fq * 8))
; #define LDB(dst, b, h) _Pragma("unroll") for (int n = 0; n < 2; ++n) _Pragma("unroll") for (int k = 0; k < 2; ++k) \
;     dst[n][k] = *reinterpret_cast<const bf16x8*>((char*)SB(b, h) + lds_byte(wc * 32 + n * 16 + fr, k * 32 + fq * 8))
; #define MMA(ai, bj, At, Bq) do { __builtin_amdgcn_s_setprio(1); \
;     _Pragma("unroll") for (int m = 0; m < 4; ++m) _Pragma("unroll") for (int n = 0; n < 2; ++n) _Pragma("unroll") for (int k = 0; k < 2; ++k) \
;       acc[ai][bj][m][n] = __builtin_amdgcn_mfma_f32_16x16x32_bf16(At[m][k], Bq[n][k], acc[ai][bj][m][n], 0, 0, 0); \
;     __builtin_amdgcn_s_setprio(0); } while (0)
; #define WAIT_L(n) asm volatile("s_waitcnt lgkmcnt(" #n ")" ::: "memory")
; #define BAR __builtin_amdgcn_s_barrier()
; #define SCHED __builtin_amdgcn_sched_barrier(0)
; __device__ __forceinline__ void gemm256(const u16* __restrict__ A, int lda, const u16* __restrict__ Bt, int ldb, int K,
;                                         f32x4 (&acc)[2][2][4][2], const int g_wid) {
;     ...
;   for (int t = 0; t < nt - 2; t += 2) {
;     LDB(B0, 0, 0); SCHED; LDA(At, 0, 0); STA(SA(1, 1), HALF, t + 1);
;     WAIT_L(8); BAR; WAIT_L(0); MMA(0, 0, At, B0); BAR; SCHED;
;     LDB(B1, 0, 1); STB(SB(0, 0), 0, t + 2);
;     BAR; WAIT_L(0); MMA(0, 1, At, B1); BAR;
;     LDA(At, 0, 1); STA(SA(0, 0), 0, t + 2);
;     BAR; WAIT_L(0); MMA(1, 0, At, B0); BAR; SCHED;
.LBB0_319:
	ds_read_b128 v[180:183], v176
	ds_read_b128 v[184:187], v176 offset:1024
	ds_read_b128 v[188:191], v176 offset:2048
	ds_read_b128 v[192:195], v176 offset:3072
	v_add_u32_e32 v177, 0xc000, v161
	v_lshl_add_u64 v[244:245], v[140:141], 0, s[18:19]
	v_readfirstlane_b32 s13, v177
	v_lshl_add_u64 v[178:179], v[244:245], 0, s[68:69]
	s_mov_b32 m0, s13
	ds_read_b128 v[196:199], v147
	ds_read_b128 v[200:203], v147 offset:1024
	ds_read_b128 v[204:207], v146
	ds_read_b128 v[208:211], v146 offset:1024
	ds_read_b128 v[212:215], v145
	ds_read_b128 v[216:219], v145 offset:1024
	ds_read_b128 v[220:223], v144
	ds_read_b128 v[224:227], v144 offset:1024
	global_load_lds_dwordx4 v[178:179], off
	v_add_u32_e32 v178, 0xe000, v161
	v_lshl_add_u64 v[246:247], v[138:139], 0, s[18:19]
	v_readfirstlane_b32 s13, v178
	v_lshl_add_u64 v[228:229], v[246:247], 0, s[68:69]
	s_mov_b32 m0, s13
	s_nop 0
	global_load_lds_dwordx4 v[228:229], off
	s_waitcnt lgkmcnt(8)
	s_barrier
	s_waitcnt lgkmcnt(0)
	v_mfma_f32_16x16x32_bf16 v[126:129], v[196:199], v[180:183], v[126:129]
	v_mfma_f32_16x16x32_bf16 v[122:125], v[196:199], v[188:191], v[122:125]
	v_mfma_f32_16x16x32_bf16 v[118:121], v[204:207], v[180:183], v[118:121]
	v_mfma_f32_16x16x32_bf16 v[114:117], v[204:207], v[188:191], v[114:117]
	v_mfma_f32_16x16x32_bf16 v[110:113], v[212:215], v[180:183], v[110:113]
	v_mfma_f32_16x16x32_bf16 v[106:109], v[212:215], v[188:191], v[106:109]
	v_mfma_f32_16x16x32_bf16 v[102:105], v[220:223], v[180:183], v[102:105]
	v_mfma_f32_16x16x32_bf16 v[98:101], v[220:223], v[188:191], v[98:101]
	v_mfma_f32_16x16x32_bf16 v[126:129], v[200:203], v[184:187], v[126:129]
	v_mfma_f32_16x16x32_bf16 v[122:125], v[200:203], v[192:195], v[122:125]
	v_mfma_f32_16x16x32_bf16 v[118:121], v[208:211], v[184:187], v[118:121]
	v_mfma_f32_16x16x32_bf16 v[114:117], v[208:211], v[192:195], v[114:117]
	v_mfma_f32_16x16x32_bf16 v[110:113], v[216:219], v[184:187], v[110:113]
	v_mfma_f32_16x16x32_bf16 v[106:109], v[216:219], v[192:195], v[106:109]
	v_mfma_f32_16x16x32_bf16 v[102:105], v[224:227], v[184:187], v[102:105]
	v_mfma_f32_16x16x32_bf16 v[98:101], v[224:227], v[192:195], v[98:101]
	s_barrier
	v_lshl_add_u64 v[248:249], v[136:137], 0, s[18:19]
	v_readfirstlane_b32 s13, v159
	v_lshl_add_u64 v[250:251], v[248:249], 0, s[74:75]
	s_mov_b32 m0, s13
	ds_read_b128 v[228:231], v175
	ds_read_b128 v[232:235], v175 offset:1024
	ds_read_b128 v[236:239], v175 offset:2048
	ds_read_b128 v[240:243], v175 offset:3072
	global_load_lds_dwordx4 v[250:251], off
	v_lshl_add_u64 v[250:251], v[134:135], 0, s[18:19]
	v_readfirstlane_b32 s13, v160
	v_lshl_add_u64 v[252:253], v[250:251], 0, s[74:75]
	s_mov_b32 m0, s13
	s_nop 0
	global_load_lds_dwordx4 v[252:253], off
	s_barrier
	s_waitcnt lgkmcnt(0)
	v_mfma_f32_16x16x32_bf16 v[94:97], v[196:199], v[228:231], v[94:97]
	v_mfma_f32_16x16x32_bf16 v[90:93], v[196:199], v[236:239], v[90:93]
	v_mfma_f32_16x16x32_bf16 v[86:89], v[204:207], v[228:231], v[86:89]
	v_mfma_f32_16x16x32_bf16 v[82:85], v[204:207], v[236:239], v[82:85]
	v_mfma_f32_16x16x32_bf16 v[78:81], v[212:215], v[228:231], v[78:81]
	v_mfma_f32_16x16x32_bf16 v[74:77], v[212:215], v[236:239], v[74:77]
	v_mfma_f32_16x16x32_bf16 v[70:73], v[220:223], v[228:231], v[70:73]
	v_mfma_f32_16x16x32_bf16 v[66:69], v[220:223], v[236:239], v[66:69]
	v_mfma_f32_16x16x32_bf16 v[94:97], v[200:203], v[232:235], v[94:97]
	v_mfma_f32_16x16x32_bf16 v[90:93], v[200:203], v[240:243], v[90:93]
	v_mfma_f32_16x16x32_bf16 v[86:89], v[208:211], v[232:235], v[86:89]
	v_mfma_f32_16x16x32_bf16 v[82:85], v[208:211], v[240:243], v[82:85]
	v_mfma_f32_16x16x32_bf16 v[78:81], v[216:219], v[232:235], v[78:81]
	v_mfma_f32_16x16x32_bf16 v[74:77], v[216:219], v[240:243], v[74:77]
	v_mfma_f32_16x16x32_bf16 v[70:73], v[224:227], v[232:235], v[70:73]
	v_mfma_f32_16x16x32_bf16 v[66:69], v[224:227], v[240:243], v[66:69]
	v_readfirstlane_b32 s13, v161
	v_lshl_add_u64 v[252:253], v[244:245], 0, s[74:75]
	s_mov_b32 m0, s13
	v_readfirstlane_b32 s13, v163
	s_barrier
	ds_read_b128 v[196:199], v147 offset:16384
	ds_read_b128 v[200:203], v147 offset:17408
	ds_read_b128 v[204:207], v146 offset:16384
	ds_read_b128 v[208:211], v146 offset:17408
	ds_read_b128 v[212:215], v145 offset:16384
	ds_read_b128 v[216:219], v145 offset:17408
	ds_read_b128 v[220:223], v144 offset:16384
	ds_read_b128 v[224:227], v144 offset:17408
	global_load_lds_dwordx4 v[252:253], off
	v_lshl_add_u64 v[252:253], v[246:247], 0, s[74:75]
	s_mov_b32 m0, s13
	s_nop 0
	global_load_lds_dwordx4 v[252:253], off
	s_barrier
	s_waitcnt lgkmcnt(0)
	v_mfma_f32_16x16x32_bf16 v[62:65], v[196:199], v[180:183], v[62:65]
	v_mfma_f32_16x16x32_bf16 v[58:61], v[196:199], v[188:191], v[58:61]
	v_mfma_f32_16x16x32_bf16 v[54:57], v[204:207], v[180:183], v[54:57]
	v_mfma_f32_16x16x32_bf16 v[50:53], v[204:207], v[188:191], v[50:53]
	v_mfma_f32_16x16x32_bf16 v[46:49], v[212:215], v[180:183], v[46:49]
	v_mfma_f32_16x16x32_bf16 v[42:45], v[212:215], v[188:191], v[42:45]
	v_mfma_f32_16x16x32_bf16 v[38:41], v[220:223], v[180:183], v[38:41]
	v_mfma_f32_16x16x32_bf16 v[34:37], v[220:223], v[188:191], v[34:37]
	v_mfma_f32_16x16x32_bf16 v[62:65], v[200:203], v[184:187], v[62:65]
	v_mfma_f32_16x16x32_bf16 v[58:61], v[200:203], v[192:195], v[58:61]
	v_mfma_f32_16x16x32_bf16 v[54:57], v[208:211], v[184:187], v[54:57]
	v_mfma_f32_16x16x32_bf16 v[50:53], v[208:211], v[192:195], v[50:53]
	v_mfma_f32_16x16x32_bf16 v[46:49], v[216:219], v[184:187], v[46:49]
	v_mfma_f32_16x16x32_bf16 v[42:45], v[216:219], v[192:195], v[42:45]
	v_mfma_f32_16x16x32_bf16 v[38:41], v[224:227], v[184:187], v[38:41]
	v_mfma_f32_16x16x32_bf16 v[34:37], v[224:227], v[192:195], v[34:37]
	s_barrier
; #define STA(P, br, kt) STAGE(P, A, aoff0, aoff1, lda, br, kt)
; #define STB(P, br, kt) STAGE(P, Bt, boff0, boff1, ldb, br, kt)
; #define LDA(dst, b, h) _Pragma("unroll") for (int m = 0; m < 4; ++m) _Pragma("unroll") for (int k = 0; k < 2; ++k) \
;     dst[m][k] = *reinterpret_cast<const bf16x8*>((char*)SA(b, h) + lds_byte(wr * 64 + m * 16 + fr, k * 32 + fq * 8))
; #define LDB(dst, b, h) _Pragma("unroll") for (int n = 0; n < 2; ++n) _Pragma("unroll") for (int k = 0; k < 2; ++k) \
;     dst[n][k] = *reinterpret_cast<const bf16x8*>((char*)SB(b, h) + lds_byte(wc * 32 + n * 16 + fr, k * 32 + fq * 8))
; #define MMA(ai, bj, At, Bq) do { __builtin_amdgcn_s_setprio(1); \
;     _Pragma("unroll") for (int m = 0; m < 4; ++m) _Pragma("unroll") for (int n = 0; n < 2; ++n) _Pragma("unroll") for (int k = 0; k < 2; ++k) \
;       acc[ai][bj][m][n] = __builtin_amdgcn_mfma_f32_16x16x32_bf16(At[m][k], Bq[n][k], acc[ai][bj][m][n], 0, 0, 0); \
;     __builtin_amdgcn_s_setprio(0); } while (0)
; #define WAIT_V(n) asm volatile("s_waitcnt vmcnt(" #n ")" ::: "memory")
; #define WAIT_L(n) asm volatile("s_waitcnt lgkmcnt(" #n ")" ::: "memory")
; #define BAR __builtin_amdgcn_s_barrier()
; #define SCHED __builtin_amdgcn_sched_barrier(0)
; __device__ __forceinline__ void gemm256(const u16* __restrict__ A, int lda, const u16* __restrict__ Bt, int ldb, int K,
;                                         f32x4 (&acc)[2][2][4][2], const int g_wid) {
;     ...
;     STB(SB(0, 1), HALF, t + 2);
;     WAIT_V(6); BAR; MMA(1, 1, At, B1); BAR;
;     LDB(B0, 1, 0); SCHED; LDA(At, 1, 0); STA(SA(0, 1), HALF, t + 2);
;     WAIT_L(8); BAR; WAIT_L(0); MMA(0, 0, At, B0); BAR; SCHED;
;     LDB(B1, 1, 1); STB(SB(1, 0), 0, t + 3);
;     BAR; WAIT_L(0); MMA(0, 1, At, B1); BAR;
	v_readfirstlane_b32 s13, v164
	v_lshl_add_u64 v[180:181], v[248:249], 0, s[78:79]
	s_mov_b32 m0, s13
	v_readfirstlane_b32 s13, v165
	global_load_lds_dwordx4 v[180:181], off
	v_lshl_add_u64 v[180:181], v[250:251], 0, s[78:79]
	s_mov_b32 m0, s13
	s_nop 0
	global_load_lds_dwordx4 v[180:181], off
	s_waitcnt vmcnt(6)
	s_barrier
	v_mfma_f32_16x16x32_bf16 v[30:33], v[196:199], v[228:231], v[30:33]
	v_mfma_f32_16x16x32_bf16 v[26:29], v[196:199], v[236:239], v[26:29]
	v_mfma_f32_16x16x32_bf16 v[22:25], v[204:207], v[228:231], v[22:25]
	v_mfma_f32_16x16x32_bf16 v[18:21], v[204:207], v[236:239], v[18:21]
	v_mfma_f32_16x16x32_bf16 v[14:17], v[212:215], v[228:231], v[14:17]
	v_mfma_f32_16x16x32_bf16 v[10:13], v[212:215], v[236:239], v[10:13]
	v_mfma_f32_16x16x32_bf16 v[6:9], v[220:223], v[228:231], v[6:9]
	v_mfma_f32_16x16x32_bf16 v[2:5], v[220:223], v[236:239], v[2:5]
	v_mfma_f32_16x16x32_bf16 v[30:33], v[200:203], v[232:235], v[30:33]
	v_mfma_f32_16x16x32_bf16 v[26:29], v[200:203], v[240:243], v[26:29]
	v_mfma_f32_16x16x32_bf16 v[22:25], v[208:211], v[232:235], v[22:25]
	v_mfma_f32_16x16x32_bf16 v[18:21], v[208:211], v[240:243], v[18:21]
	v_mfma_f32_16x16x32_bf16 v[14:17], v[216:219], v[232:235], v[14:17]
	v_mfma_f32_16x16x32_bf16 v[10:13], v[216:219], v[240:243], v[10:13]
	v_mfma_f32_16x16x32_bf16 v[6:9], v[224:227], v[232:235], v[6:9]
	v_mfma_f32_16x16x32_bf16 v[2:5], v[224:227], v[240:243], v[2:5]
	s_barrier
	ds_read_b128 v[180:183], v168
	ds_read_b128 v[184:187], v168 offset:1024
	ds_read_b128 v[188:191], v168 offset:2048
	ds_read_b128 v[192:195], v168 offset:3072
	v_readfirstlane_b32 s13, v166
	v_lshl_add_u64 v[228:229], v[244:245], 0, s[78:79]
	s_mov_b32 m0, s13
	v_readfirstlane_b32 s13, v167
	ds_read_b128 v[196:199], v147 offset:32768
	ds_read_b128 v[200:203], v147 offset:33792
	ds_read_b128 v[204:207], v146 offset:32768
	ds_read_b128 v[208:211], v146 offset:33792
	ds_read_b128 v[212:215], v145 offset:32768
	ds_read_b128 v[216:219], v145 offset:33792
	ds_read_b128 v[220:223], v144 offset:32768
	ds_read_b128 v[224:227], v144 offset:33792
	global_load_lds_dwordx4 v[228:229], off
	v_lshl_add_u64 v[228:229], v[246:247], 0, s[78:79]
	s_mov_b32 m0, s13
	s_nop 0
	global_load_lds_dwordx4 v[228:229], off
	s_waitcnt lgkmcnt(8)
	s_barrier
	s_waitcnt lgkmcnt(0)
	v_mfma_f32_16x16x32_bf16 v[126:129], v[196:199], v[180:183], v[126:129]
	v_mfma_f32_16x16x32_bf16 v[122:125], v[196:199], v[188:191], v[122:125]
	v_mfma_f32_16x16x32_bf16 v[118:121], v[204:207], v[180:183], v[118:121]
	v_mfma_f32_16x16x32_bf16 v[114:117], v[204:207], v[188:191], v[114:117]
	v_mfma_f32_16x16x32_bf16 v[110:113], v[212:215], v[180:183], v[110:113]
	v_mfma_f32_16x16x32_bf16 v[106:109], v[212:215], v[188:191], v[106:109]
	v_mfma_f32_16x16x32_bf16 v[102:105], v[220:223], v[180:183], v[102:105]
	v_mfma_f32_16x16x32_bf16 v[98:101], v[220:223], v[188:191], v[98:101]
	v_mfma_f32_16x16x32_bf16 v[126:129], v[200:203], v[184:187], v[126:129]
	v_mfma_f32_16x16x32_bf16 v[122:125], v[200:203], v[192:195], v[122:125]
	v_mfma_f32_16x16x32_bf16 v[118:121], v[208:211], v[184:187], v[118:121]
	v_mfma_f32_16x16x32_bf16 v[114:117], v[208:211], v[192:195], v[114:117]
	v_mfma_f32_16x16x32_bf16 v[110:113], v[216:219], v[184:187], v[110:113]
	v_mfma_f32_16x16x32_bf16 v[106:109], v[216:219], v[192:195], v[106:109]
	v_mfma_f32_16x16x32_bf16 v[102:105], v[224:227], v[184:187], v[102:105]
	v_mfma_f32_16x16x32_bf16 v[98:101], v[224:227], v[192:195], v[98:101]
	s_barrier
	v_readfirstlane_b32 s13, v169
	v_lshl_add_u64 v[252:253], v[248:249], 0, s[82:83]
	s_mov_b32 m0, s13
	v_readfirstlane_b32 s13, v170
	ds_read_b128 v[228:231], v162
	ds_read_b128 v[232:235], v162 offset:1024
	ds_read_b128 v[236:239], v162 offset:2048
	ds_read_b128 v[240:243], v162 offset:3072
	global_load_lds_dwordx4 v[252:253], off
	v_lshl_add_u64 v[252:253], v[250:251], 0, s[82:83]
	s_mov_b32 m0, s13
	s_nop 0
	global_load_lds_dwordx4 v[252:253], off
	s_barrier
	s_waitcnt lgkmcnt(0)
	v_mfma_f32_16x16x32_bf16 v[94:97], v[196:199], v[228:231], v[94:97]
	v_mfma_f32_16x16x32_bf16 v[90:93], v[196:199], v[236:239], v[90:93]
	v_mfma_f32_16x16x32_bf16 v[86:89], v[204:207], v[228:231], v[86:89]
	v_mfma_f32_16x16x32_bf16 v[82:85], v[204:207], v[236:239], v[82:85]
	v_mfma_f32_16x16x32_bf16 v[78:81], v[212:215], v[228:231], v[78:81]
	v_mfma_f32_16x16x32_bf16 v[74:77], v[212:215], v[236:239], v[74:77]
	v_mfma_f32_16x16x32_bf16 v[70:73], v[220:223], v[228:231], v[70:73]
	v_mfma_f32_16x16x32_bf16 v[66:69], v[220:223], v[236:239], v[66:69]
	v_mfma_f32_16x16x32_bf16 v[94:97], v[200:203], v[232:235], v[94:97]
	v_mfma_f32_16x16x32_bf16 v[90:93], v[200:203], v[240:243], v[90:93]
	v_mfma_f32_16x16x32_bf16 v[86:89], v[208:211], v[232:235], v[86:89]
	v_mfma_f32_16x16x32_bf16 v[82:85], v[208:211], v[240:243], v[82:85]
	v_mfma_f32_16x16x32_bf16 v[78:81], v[216:219], v[232:235], v[78:81]
	v_mfma_f32_16x16x32_bf16 v[74:77], v[216:219], v[240:243], v[74:77]
	v_mfma_f32_16x16x32_bf16 v[70:73], v[224:227], v[232:235], v[70:73]
	v_mfma_f32_16x16x32_bf16 v[66:69], v[224:227], v[240:243], v[66:69]
	v_readfirstlane_b32 s13, v171
	v_lshl_add_u64 v[244:245], v[244:245], 0, s[82:83]
	s_mov_b32 m0, s13
	v_readfirstlane_b32 s13, v172
	s_barrier
	ds_read_b128 v[196:199], v147 offset:49152
	ds_read_b128 v[200:203], v147 offset:50176
	ds_read_b128 v[204:207], v146 offset:49152
	ds_read_b128 v[208:211], v146 offset:50176
	ds_read_b128 v[212:215], v145 offset:49152
	ds_read_b128 v[216:219], v145 offset:50176
	ds_read_b128 v[220:223], v144 offset:49152
	ds_read_b128 v[224:227], v144 offset:50176
	global_load_lds_dwordx4 v[244:245], off
	v_lshl_add_u64 v[244:245], v[246:247], 0, s[82:83]
	s_mov_b32 m0, s13
	s_nop 0
	global_load_lds_dwordx4 v[244:245], off
	s_barrier
; #define STA(P, br, kt) STAGE(P, A, aoff0, aoff1, lda, br, kt)
; #define STB(P, br, kt) STAGE(P, Bt, boff0, boff1, ldb, br, kt)
; #define LDA(dst, b, h) _Pragma("unroll") for (int m = 0; m < 4; ++m) _Pragma("unroll") for (int k = 0; k < 2; ++k) \
;     dst[m][k] = *reinterpret_cast<const bf16x8*>((char*)SA(b, h) + lds_byte(wr * 64 + m * 16 + fr, k * 32 + fq * 8))
; #define LDB(dst, b, h) _Pragma("unroll") for (int n = 0; n < 2; ++n) _Pragma("unroll") for (int k = 0; k < 2; ++k) \
;     dst[n][k] = *reinterpret_cast<const bf16x8*>((char*)SB(b, h) + lds_byte(wc * 32 + n * 16 + fr, k * 32 + fq * 8))
; #define MMA(ai, bj, At, Bq) do { __builtin_amdgcn_s_setprio(1); \
;     _Pragma("unroll") for (int m = 0; m < 4; ++m) _Pragma("unroll") for (int n = 0; n < 2; ++n) _Pragma("unroll") for (int k = 0; k < 2; ++k) \
;       acc[ai][bj][m][n] = __builtin_amdgcn_mfma_f32_16x16x32_bf16(At[m][k], Bq[n][k], acc[ai][bj][m][n], 0, 0, 0); \
;     __builtin_amdgcn_s_setprio(0); } while (0)
; #define WAIT_V(n) asm volatile("s_waitcnt vmcnt(" #n ")" ::: "memory")
; #define WAIT_L(n) asm volatile("s_waitcnt lgkmcnt(" #n ")" ::: "memory")
; #define BAR __builtin_amdgcn_s_barrier()
; #define SCHED __builtin_amdgcn_sched_barrier(0)
; __device__ __forceinline__ void gemm256(const u16* __restrict__ A, int lda, const u16* __restrict__ Bt, int ldb, int K,
;                                         f32x4 (&acc)[2][2][4][2], const int g_wid) {
;     ...
;     LDA(At, 1, 1); STA(SA(1, 0), 0, t + 3);
;     BAR; WAIT_L(0); MMA(1, 0, At, B0); BAR; SCHED;
;     STB(SB(1, 1), HALF, t + 3);
;     WAIT_V(6); BAR; MMA(1, 1, At, B1); BAR;
;   }
;   { LDB(B0, 0, 0); LDA(At, 0, 0); STA(SA(1, 1), HALF, nt - 1);
;     BAR; WAIT_L(0); MMA(0, 0, At, B0); BAR;
	s_waitcnt lgkmcnt(0)
	v_mfma_f32_16x16x32_bf16 v[62:65], v[196:199], v[180:183], v[62:65]
	v_mfma_f32_16x16x32_bf16 v[58:61], v[196:199], v[188:191], v[58:61]
	v_mfma_f32_16x16x32_bf16 v[54:57], v[204:207], v[180:183], v[54:57]
	v_mfma_f32_16x16x32_bf16 v[50:53], v[204:207], v[188:191], v[50:53]
	v_mfma_f32_16x16x32_bf16 v[46:49], v[212:215], v[180:183], v[46:49]
	v_mfma_f32_16x16x32_bf16 v[42:45], v[212:215], v[188:191], v[42:45]
	v_mfma_f32_16x16x32_bf16 v[38:41], v[220:223], v[180:183], v[38:41]
	v_mfma_f32_16x16x32_bf16 v[34:37], v[220:223], v[188:191], v[34:37]
	v_mfma_f32_16x16x32_bf16 v[62:65], v[200:203], v[184:187], v[62:65]
	v_mfma_f32_16x16x32_bf16 v[58:61], v[200:203], v[192:195], v[58:61]
	v_mfma_f32_16x16x32_bf16 v[54:57], v[208:211], v[184:187], v[54:57]
	v_mfma_f32_16x16x32_bf16 v[50:53], v[208:211], v[192:195], v[50:53]
	v_mfma_f32_16x16x32_bf16 v[46:49], v[216:219], v[184:187], v[46:49]
	v_mfma_f32_16x16x32_bf16 v[42:45], v[216:219], v[192:195], v[42:45]
	v_mfma_f32_16x16x32_bf16 v[38:41], v[224:227], v[184:187], v[38:41]
	v_mfma_f32_16x16x32_bf16 v[34:37], v[224:227], v[192:195], v[34:37]
	s_barrier
	v_readfirstlane_b32 s13, v173
	v_lshl_add_u64 v[180:181], v[248:249], 0, s[86:87]
	s_mov_b32 m0, s13
	v_readfirstlane_b32 s13, v174
	global_load_lds_dwordx4 v[180:181], off
	v_lshl_add_u64 v[180:181], v[250:251], 0, s[86:87]
	s_mov_b32 m0, s13
	s_nop 0
	global_load_lds_dwordx4 v[180:181], off
	s_waitcnt vmcnt(6)
	s_barrier
	v_mfma_f32_16x16x32_bf16 v[30:33], v[196:199], v[228:231], v[30:33]
	v_mfma_f32_16x16x32_bf16 v[26:29], v[196:199], v[236:239], v[26:29]
	v_mfma_f32_16x16x32_bf16 v[22:25], v[204:207], v[228:231], v[22:25]
	v_mfma_f32_16x16x32_bf16 v[18:21], v[204:207], v[236:239], v[18:21]
	v_mfma_f32_16x16x32_bf16 v[14:17], v[212:215], v[228:231], v[14:17]
	v_mfma_f32_16x16x32_bf16 v[10:13], v[212:215], v[236:239], v[10:13]
	v_mfma_f32_16x16x32_bf16 v[6:9], v[220:223], v[228:231], v[6:9]
	v_mfma_f32_16x16x32_bf16 v[2:5], v[220:223], v[236:239], v[2:5]
	v_mfma_f32_16x16x32_bf16 v[30:33], v[200:203], v[232:235], v[30:33]
	v_mfma_f32_16x16x32_bf16 v[26:29], v[200:203], v[240:243], v[26:29]
	v_mfma_f32_16x16x32_bf16 v[22:25], v[208:211], v[232:235], v[22:25]
	v_mfma_f32_16x16x32_bf16 v[18:21], v[208:211], v[240:243], v[18:21]
	v_mfma_f32_16x16x32_bf16 v[14:17], v[216:219], v[232:235], v[14:17]
	v_mfma_f32_16x16x32_bf16 v[10:13], v[216:219], v[240:243], v[10:13]
	v_mfma_f32_16x16x32_bf16 v[6:9], v[224:227], v[232:235], v[6:9]
	v_mfma_f32_16x16x32_bf16 v[2:5], v[224:227], v[240:243], v[2:5]
	s_add_i32 s11, s11, 2
	s_add_u32 s18, s18, 0x100
	s_addc_u32 s19, s19, 0
	s_cmp_lt_u32 s11, 12
	s_barrier
	s_cbranch_scc1 .LBB0_319
	s_add_u32 s16, s16, 0x40780
	s_addc_u32 s17, s17, 0
	v_readfirstlane_b32 s11, v177
	v_lshl_add_u64 v[132:133], v[132:133], 1, s[16:17]
	s_mov_b32 m0, s11
	v_readfirstlane_b32 s11, v178
	ds_read_b128 v[134:137], v176
	ds_read_b128 v[138:141], v176 offset:1024
	ds_read_b128 v[164:167], v176 offset:2048
	ds_read_b128 v[170:173], v176 offset:3072
	ds_read_b128 v[180:183], v147
	ds_read_b128 v[184:187], v147 offset:1024
	ds_read_b128 v[188:191], v146
	ds_read_b128 v[192:195], v146 offset:1024
	ds_read_b128 v[196:199], v145
	ds_read_b128 v[200:203], v145 offset:1024
	ds_read_b128 v[204:207], v144
	ds_read_b128 v[208:211], v144 offset:1024
	global_load_lds_dwordx4 v[132:133], off
	v_lshl_add_u64 v[130:131], v[130:131], 1, s[16:17]
	s_mov_b32 m0, s11
	s_nop 0
	global_load_lds_dwordx4 v[130:131], off
	s_barrier
	s_waitcnt lgkmcnt(0)
	v_mfma_f32_16x16x32_bf16 v[126:129], v[180:183], v[134:137], v[126:129]
	v_mfma_f32_16x16x32_bf16 v[122:125], v[180:183], v[164:167], v[122:125]
	v_mfma_f32_16x16x32_bf16 v[110:113], v[196:199], v[134:137], v[110:113]
	v_mfma_f32_16x16x32_bf16 v[106:109], v[196:199], v[164:167], v[106:109]
	v_mfma_f32_16x16x32_bf16 v[126:129], v[184:187], v[138:141], v[126:129]
	v_mfma_f32_16x16x32_bf16 v[122:125], v[184:187], v[170:173], v[122:125]
	v_mfma_f32_16x16x32_bf16 v[118:121], v[188:191], v[134:137], v[118:121]
	v_mfma_f32_16x16x32_bf16 v[114:117], v[188:191], v[164:167], v[114:117]
	v_mfma_f32_16x16x32_bf16 v[110:113], v[200:203], v[138:141], v[110:113]
	v_mfma_f32_16x16x32_bf16 v[106:109], v[200:203], v[170:173], v[106:109]
	v_mfma_f32_16x16x32_bf16 v[102:105], v[204:207], v[134:137], v[102:105]
	v_mfma_f32_16x16x32_bf16 v[98:101], v[204:207], v[164:167], v[98:101]
	v_mfma_f32_16x16x32_bf16 v[130:133], v[192:195], v[138:141], v[118:121]
	v_mfma_f32_16x16x32_bf16 v[176:179], v[192:195], v[170:173], v[114:117]
	v_mfma_f32_16x16x32_bf16 v[212:215], v[208:211], v[138:141], v[102:105]
	v_mfma_f32_16x16x32_bf16 v[216:219], v[208:211], v[170:173], v[98:101]
	s_barrier
	s_nop 1
	ds_read_b128 v[98:101], v175
	ds_read_b128 v[102:105], v175 offset:1024
	ds_read_b128 v[114:117], v175 offset:2048
	ds_read_b128 v[118:121], v175 offset:3072
	s_barrier
	s_waitcnt lgkmcnt(0)
	v_mfma_f32_16x16x32_bf16 v[94:97], v[180:183], v[98:101], v[94:97]
	v_mfma_f32_16x16x32_bf16 v[90:93], v[180:183], v[114:117], v[90:93]
	v_mfma_f32_16x16x32_bf16 v[78:81], v[196:199], v[98:101], v[78:81]
	v_mfma_f32_16x16x32_bf16 v[74:77], v[196:199], v[114:117], v[74:77]
	v_mfma_f32_16x16x32_bf16 v[94:97], v[184:187], v[102:105], v[94:97]
	v_mfma_f32_16x16x32_bf16 v[90:93], v[184:187], v[118:121], v[90:93]
	v_mfma_f32_16x16x32_bf16 v[86:89], v[188:191], v[98:101], v[86:89]
	v_mfma_f32_16x16x32_bf16 v[82:85], v[188:191], v[114:117], v[82:85]
	v_mfma_f32_16x16x32_bf16 v[78:81], v[200:203], v[102:105], v[78:81]
	v_mfma_f32_16x16x32_bf16 v[74:77], v[200:203], v[118:121], v[74:77]
	v_mfma_f32_16x16x32_bf16 v[70:73], v[204:207], v[98:101], v[70:73]
	v_mfma_f32_16x16x32_bf16 v[66:69], v[204:207], v[114:117], v[66:69]
	v_mfma_f32_16x16x32_bf16 v[180:183], v[192:195], v[102:105], v[86:89]
	v_mfma_f32_16x16x32_bf16 v[184:187], v[192:195], v[118:121], v[82:85]
	v_mfma_f32_16x16x32_bf16 v[188:191], v[208:211], v[102:105], v[70:73]
	v_mfma_f32_16x16x32_bf16 v[192:195], v[208:211], v[118:121], v[66:69]
	s_barrier
; #define LDA(dst, b, h) _Pragma("unroll") for (int m = 0; m < 4; ++m) _Pragma("unroll") for (int k = 0; k < 2; ++k) \
;     dst[m][k] = *reinterpret_cast<const bf16x8*>((char*)SA(b, h) + lds_byte(wr * 64 + m * 16 + fr, k * 32 + fq * 8))
; #define LDB(dst, b, h) _Pragma("unroll") for (int n = 0; n < 2; ++n) _Pragma("unroll") for (int k = 0; k < 2; ++k) \
;     dst[n][k] = *reinterpret_cast<const bf16x8*>((char*)SB(b, h) + lds_byte(wc * 32 + n * 16 + fr, k * 32 + fq * 8))
; #define MMA(ai, bj, At, Bq) do { __builtin_amdgcn_s_setprio(1); \
;     _Pragma("unroll") for (int m = 0; m < 4; ++m) _Pragma("unroll") for (int n = 0; n < 2; ++n) _Pragma("unroll") for (int k = 0; k < 2; ++k) \
;       acc[ai][bj][m][n] = __builtin_amdgcn_mfma_f32_16x16x32_bf16(At[m][k], Bq[n][k], acc[ai][bj][m][n], 0, 0, 0); \
;     __builtin_amdgcn_s_setprio(0); } while (0)
; #define WAIT_V(n) asm volatile("s_waitcnt vmcnt(" #n ")" ::: "memory")
; #define WAIT_L(n) asm volatile("s_waitcnt lgkmcnt(" #n ")" ::: "memory")
; #define BAR __builtin_amdgcn_s_barrier()
; __device__ __forceinline__ void gemm256(const u16* __restrict__ A, int lda, const u16* __restrict__ Bt, int ldb, int K,
;                                         f32x4 (&acc)[2][2][4][2], const int g_wid) {
;     ...
;     LDA(At, 0, 1); WAIT_V(4); BAR; WAIT_L(0); MMA(1, 0, At, B0); MMA(1, 1, At, B1); BAR; }
;   { LDB(B0, 1, 0); LDA(At, 1, 0); WAIT_V(2); BAR; WAIT_L(0); MMA(0, 0, At, B0); BAR;
	s_nop 1
	ds_read_b128 v[66:69], v147 offset:16384
	ds_read_b128 v[70:73], v147 offset:17408
	ds_read_b128 v[82:85], v146 offset:16384
	ds_read_b128 v[86:89], v146 offset:17408
	ds_read_b128 v[196:199], v145 offset:16384
	ds_read_b128 v[200:203], v145 offset:17408
	ds_read_b128 v[204:207], v144 offset:16384
	ds_read_b128 v[208:211], v144 offset:17408
	s_waitcnt vmcnt(4)
	s_barrier
	s_waitcnt lgkmcnt(0)
	v_mfma_f32_16x16x32_bf16 v[62:65], v[66:69], v[134:137], v[62:65]
	v_mfma_f32_16x16x32_bf16 v[54:57], v[82:85], v[134:137], v[54:57]
	v_mfma_f32_16x16x32_bf16 v[46:49], v[196:199], v[134:137], v[46:49]
	v_mfma_f32_16x16x32_bf16 v[38:41], v[204:207], v[134:137], v[38:41]
	v_mfma_f32_16x16x32_bf16 v[62:65], v[70:73], v[138:141], v[62:65]
	v_mfma_f32_16x16x32_bf16 v[58:61], v[66:69], v[164:167], v[58:61]
	v_mfma_f32_16x16x32_bf16 v[54:57], v[86:89], v[138:141], v[54:57]
	v_mfma_f32_16x16x32_bf16 v[50:53], v[82:85], v[164:167], v[50:53]
	v_mfma_f32_16x16x32_bf16 v[46:49], v[200:203], v[138:141], v[46:49]
	v_mfma_f32_16x16x32_bf16 v[42:45], v[196:199], v[164:167], v[42:45]
	v_mfma_f32_16x16x32_bf16 v[38:41], v[208:211], v[138:141], v[38:41]
	v_mfma_f32_16x16x32_bf16 v[34:37], v[204:207], v[164:167], v[34:37]
	v_mfma_f32_16x16x32_bf16 v[220:223], v[70:73], v[170:173], v[58:61]
	v_mfma_f32_16x16x32_bf16 v[224:227], v[86:89], v[170:173], v[50:53]
	v_mfma_f32_16x16x32_bf16 v[228:231], v[200:203], v[170:173], v[42:45]
	v_mfma_f32_16x16x32_bf16 v[134:137], v[208:211], v[170:173], v[34:37]
	v_mfma_f32_16x16x32_bf16 v[30:33], v[66:69], v[98:101], v[30:33]
	v_mfma_f32_16x16x32_bf16 v[22:25], v[82:85], v[98:101], v[22:25]
	v_mfma_f32_16x16x32_bf16 v[14:17], v[196:199], v[98:101], v[14:17]
	v_mfma_f32_16x16x32_bf16 v[6:9], v[204:207], v[98:101], v[6:9]
	v_mfma_f32_16x16x32_bf16 v[30:33], v[70:73], v[102:105], v[30:33]
	v_mfma_f32_16x16x32_bf16 v[26:29], v[66:69], v[114:117], v[26:29]
	v_mfma_f32_16x16x32_bf16 v[22:25], v[86:89], v[102:105], v[22:25]
	v_mfma_f32_16x16x32_bf16 v[18:21], v[82:85], v[114:117], v[18:21]
	v_mfma_f32_16x16x32_bf16 v[14:17], v[200:203], v[102:105], v[14:17]
	v_mfma_f32_16x16x32_bf16 v[10:13], v[196:199], v[114:117], v[10:13]
	v_mfma_f32_16x16x32_bf16 v[6:9], v[208:211], v[102:105], v[6:9]
	v_mfma_f32_16x16x32_bf16 v[2:5], v[204:207], v[114:117], v[2:5]
	v_mfma_f32_16x16x32_bf16 v[138:141], v[70:73], v[118:121], v[26:29]
	v_mfma_f32_16x16x32_bf16 v[164:167], v[86:89], v[118:121], v[18:21]
	v_mfma_f32_16x16x32_bf16 v[170:173], v[200:203], v[118:121], v[10:13]
	v_mfma_f32_16x16x32_bf16 v[196:199], v[208:211], v[118:121], v[2:5]
	s_barrier
	ds_read_b128 v[200:203], v168
	ds_read_b128 v[204:207], v168 offset:1024
	ds_read_b128 v[208:211], v168 offset:2048
	ds_read_b128 v[232:235], v168 offset:3072
	ds_read_b128 v[2:5], v147 offset:32768
	ds_read_b128 v[10:13], v147 offset:33792
	ds_read_b128 v[18:21], v146 offset:32768
	ds_read_b128 v[34:37], v146 offset:33792
	ds_read_b128 v[236:239], v145 offset:32768
	ds_read_b128 v[240:243], v145 offset:33792
	ds_read_b128 v[244:247], v144 offset:32768
	ds_read_b128 v[248:251], v144 offset:33792
	s_waitcnt vmcnt(2)
	s_barrier
	s_waitcnt lgkmcnt(0)
	v_mfma_f32_16x16x32_bf16 v[26:29], v[2:5], v[200:203], v[126:129]
	v_mfma_f32_16x16x32_bf16 v[118:121], v[10:13], v[204:207], v[26:29]
	v_mfma_f32_16x16x32_bf16 v[26:29], v[2:5], v[208:211], v[122:125]
	v_mfma_f32_16x16x32_bf16 v[86:89], v[10:13], v[232:235], v[26:29]
	v_mfma_f32_16x16x32_bf16 v[26:29], v[18:21], v[200:203], v[130:133]
	v_mfma_f32_16x16x32_bf16 v[114:117], v[34:37], v[204:207], v[26:29]
	v_mfma_f32_16x16x32_bf16 v[26:29], v[18:21], v[208:211], v[176:179]
	v_mfma_f32_16x16x32_bf16 v[82:85], v[34:37], v[232:235], v[26:29]
	v_mfma_f32_16x16x32_bf16 v[26:29], v[236:239], v[200:203], v[110:113]
	v_mfma_f32_16x16x32_bf16 v[102:105], v[240:243], v[204:207], v[26:29]
	v_mfma_f32_16x16x32_bf16 v[26:29], v[236:239], v[208:211], v[106:109]
	v_mfma_f32_16x16x32_bf16 v[70:73], v[240:243], v[232:235], v[26:29]
	v_mfma_f32_16x16x32_bf16 v[26:29], v[244:247], v[200:203], v[212:215]
	v_mfma_f32_16x16x32_bf16 v[98:101], v[248:251], v[204:207], v[26:29]
	v_mfma_f32_16x16x32_bf16 v[26:29], v[244:247], v[208:211], v[216:219]
	v_mfma_f32_16x16x32_bf16 v[66:69], v[248:251], v[232:235], v[26:29]
	s_barrier
; #define LDA(dst, b, h) _Pragma("unroll") for (int m = 0; m < 4; ++m) _Pragma("unroll") for (int k = 0; k < 2; ++k) \
;     dst[m][k] = *reinterpret_cast<const bf16x8*>((char*)SA(b, h) + lds_byte(wr * 64 + m * 16 + fr, k * 32 + fq * 8))
; #define LDB(dst, b, h) _Pragma("unroll") for (int n = 0; n < 2; ++n) _Pragma("unroll") for (int k = 0; k < 2; ++k) \
;     dst[n][k] = *reinterpret_cast<const bf16x8*>((char*)SB(b, h) + lds_byte(wc * 32 + n * 16 + fr, k * 32 + fq * 8))
; #define MMA(ai, bj, At, Bq) do { __builtin_amdgcn_s_setprio(1); \
;     _Pragma("unroll") for (int m = 0; m < 4; ++m) _Pragma("unroll") for (int n = 0; n < 2; ++n) _Pragma("unroll") for (int k = 0; k < 2; ++k) \
;       acc[ai][bj][m][n] = __builtin_amdgcn_mfma_f32_16x16x32_bf16(At[m][k], Bq[n][k], acc[ai][bj][m][n], 0, 0, 0); \
;     __builtin_amdgcn_s_setprio(0); } while (0)
; #define WAIT_V(n) asm volatile("s_waitcnt vmcnt(" #n ")" ::: "memory")
; #define WAIT_L(n) asm volatile("s_waitcnt lgkmcnt(" #n ")" ::: "memory")
; #define BAR __builtin_amdgcn_s_barrier()
; __device__ __forceinline__ void gemm256(const u16* __restrict__ A, int lda, const u16* __restrict__ Bt, int ldb, int K,
;                                         f32x4 (&acc)[2][2][4][2], const int g_wid) {
;     ...
;   { LDB(B0, 1, 0); LDA(At, 1, 0); WAIT_V(2); BAR; WAIT_L(0); MMA(0, 0, At, B0); BAR;
;     LDB(B1, 1, 1); WAIT_V(0); BAR; WAIT_L(0); MMA(0, 1, At, B1); BAR;
;     LDA(At, 1, 1); BAR; WAIT_L(0); MMA(1, 0, At, B0); MMA(1, 1, At, B1); BAR; }
;   if (wr == 0) BAR;
	ds_read_b128 v[130:133], v162
	ds_read_b128 v[174:177], v162 offset:1024
	ds_read_b128 v[212:215], v162 offset:2048
	ds_read_b128 v[160:163], v162 offset:3072
	s_waitcnt vmcnt(0)
	s_barrier
	s_waitcnt lgkmcnt(0)
	v_mfma_f32_16x16x32_bf16 v[26:29], v[2:5], v[130:133], v[94:97]
	v_mfma_f32_16x16x32_bf16 v[2:5], v[2:5], v[212:215], v[90:93]
	v_mfma_f32_16x16x32_bf16 v[58:61], v[10:13], v[174:177], v[26:29]
	v_mfma_f32_16x16x32_bf16 v[26:29], v[10:13], v[160:163], v[2:5]
	v_mfma_f32_16x16x32_bf16 v[2:5], v[18:21], v[130:133], v[180:183]
	v_mfma_f32_16x16x32_bf16 v[50:53], v[34:37], v[174:177], v[2:5]
	v_mfma_f32_16x16x32_bf16 v[2:5], v[18:21], v[212:215], v[184:187]
	v_mfma_f32_16x16x32_bf16 v[18:21], v[34:37], v[160:163], v[2:5]
	v_mfma_f32_16x16x32_bf16 v[2:5], v[236:239], v[130:133], v[78:81]
	v_mfma_f32_16x16x32_bf16 v[42:45], v[240:243], v[174:177], v[2:5]
	v_mfma_f32_16x16x32_bf16 v[2:5], v[236:239], v[212:215], v[74:77]
	v_mfma_f32_16x16x32_bf16 v[10:13], v[240:243], v[160:163], v[2:5]
	v_mfma_f32_16x16x32_bf16 v[2:5], v[244:247], v[130:133], v[188:191]
	v_mfma_f32_16x16x32_bf16 v[34:37], v[248:251], v[174:177], v[2:5]
	v_mfma_f32_16x16x32_bf16 v[2:5], v[244:247], v[212:215], v[192:195]
	v_mfma_f32_16x16x32_bf16 v[2:5], v[248:251], v[160:163], v[2:5]
	s_barrier
	ds_read_b128 v[178:181], v147 offset:49152
	ds_read_b128 v[182:185], v147 offset:50176
	ds_read_b128 v[186:189], v146 offset:49152
	ds_read_b128 v[190:193], v146 offset:50176
	ds_read_b128 v[216:219], v145 offset:49152
	ds_read_b128 v[236:239], v145 offset:50176
	ds_read_b128 v[240:243], v144 offset:49152
	ds_read_b128 v[144:147], v144 offset:50176
	s_barrier
	s_waitcnt lgkmcnt(0)
	v_mfma_f32_16x16x32_bf16 v[62:65], v[178:181], v[200:203], v[62:65]
	v_mfma_f32_16x16x32_bf16 v[54:57], v[186:189], v[200:203], v[54:57]
	v_mfma_f32_16x16x32_bf16 v[46:49], v[216:219], v[200:203], v[46:49]
	v_mfma_f32_16x16x32_bf16 v[38:41], v[240:243], v[200:203], v[38:41]
	v_mfma_f32_16x16x32_bf16 v[126:129], v[182:185], v[204:207], v[62:65]
	v_mfma_f32_16x16x32_bf16 v[62:65], v[178:181], v[208:211], v[220:223]
	v_mfma_f32_16x16x32_bf16 v[122:125], v[190:193], v[204:207], v[54:57]
	v_mfma_f32_16x16x32_bf16 v[54:57], v[186:189], v[208:211], v[224:227]
	v_mfma_f32_16x16x32_bf16 v[110:113], v[236:239], v[204:207], v[46:49]
	v_mfma_f32_16x16x32_bf16 v[46:49], v[216:219], v[208:211], v[228:231]
	v_mfma_f32_16x16x32_bf16 v[106:109], v[144:147], v[204:207], v[38:41]
	v_mfma_f32_16x16x32_bf16 v[38:41], v[240:243], v[208:211], v[134:137]
	v_mfma_f32_16x16x32_bf16 v[94:97], v[182:185], v[232:235], v[62:65]
	v_mfma_f32_16x16x32_bf16 v[90:93], v[190:193], v[232:235], v[54:57]
	v_mfma_f32_16x16x32_bf16 v[78:81], v[236:239], v[232:235], v[46:49]
	v_mfma_f32_16x16x32_bf16 v[74:77], v[144:147], v[232:235], v[38:41]
	v_mfma_f32_16x16x32_bf16 v[30:33], v[178:181], v[130:133], v[30:33]
	v_mfma_f32_16x16x32_bf16 v[22:25], v[186:189], v[130:133], v[22:25]
	v_mfma_f32_16x16x32_bf16 v[14:17], v[216:219], v[130:133], v[14:17]
	v_mfma_f32_16x16x32_bf16 v[6:9], v[240:243], v[130:133], v[6:9]
	v_mfma_f32_16x16x32_bf16 v[62:65], v[182:185], v[174:177], v[30:33]
	v_mfma_f32_16x16x32_bf16 v[30:33], v[178:181], v[212:215], v[138:141]
	v_mfma_f32_16x16x32_bf16 v[54:57], v[190:193], v[174:177], v[22:25]
	v_mfma_f32_16x16x32_bf16 v[22:25], v[186:189], v[212:215], v[164:167]
	v_mfma_f32_16x16x32_bf16 v[46:49], v[236:239], v[174:177], v[14:17]
	v_mfma_f32_16x16x32_bf16 v[14:17], v[216:219], v[212:215], v[170:173]
	v_mfma_f32_16x16x32_bf16 v[38:41], v[144:147], v[174:177], v[6:9]
	v_mfma_f32_16x16x32_bf16 v[6:9], v[240:243], v[212:215], v[196:199]
	v_mfma_f32_16x16x32_bf16 v[30:33], v[182:185], v[160:163], v[30:33]
	v_mfma_f32_16x16x32_bf16 v[22:25], v[190:193], v[160:163], v[22:25]
	v_mfma_f32_16x16x32_bf16 v[14:17], v[236:239], v[160:163], v[14:17]
	v_mfma_f32_16x16x32_bf16 v[6:9], v[144:147], v[160:163], v[6:9]
	s_setprio 0
	s_movk_i32 s11, 0x100
	v_cmp_gt_u32_e32 vcc, s11, v0
	s_barrier
	s_and_saveexec_b64 s[16:17], vcc
	s_cbranch_execz .LBB0_309
	s_barrier
	s_branch .LBB0_309

; #define hw_tid() ((g_wid << 6) | hw_lane())
; #define STA(P, br, kt) STAGE(P, A, aoff0, aoff1, lda, br, kt)
; #define STB(P, br, kt) STAGE(P, Bt, boff0, boff1, ldb, br, kt)
; #define BAR __builtin_amdgcn_s_barrier()
; __device__ __forceinline__ void gemm256(const u16* __restrict__ A, int lda, const u16* __restrict__ Bt, int ldb, int K,
;                                         f32x4 (&acc)[2][2][4][2], const int g_wid) {
;   int tid = hw_tid(); asm volatile("" : "+v"(tid));
;   const int wid = tid >> 6, lane = tid & 63, wr = wid >> 2, wc = wid & 3, fr = lane & 15, fq = lane >> 4;
;   int r0, c0, r1, c1;
;   stage_rc(tid * 16, r0, c0);
;   stage_rc(tid * 16 + 8192, r1, c1);
;   const int aoff0 = r0 * lda + c0, aoff1 = r1 * lda + c1, boff0 = r0 * ldb + c0, boff1 = r1 * ldb + c1;
;   bf16x8 At[4][2], B0[2][2], B1[2][2];
;   const int nt = K / BK;
;   STB(SB(0, 0), 0, 0); STA(SA(0, 0), 0, 0);
;   STB(SB(0, 1), HALF, 0); STA(SA(0, 1), HALF, 0);
;   if (wr == 1) BAR;
; __device__ __forceinline__ void tile_map(int t, int nM, int nN, int& pm, int& pn) {
;   int nwg = nM * nN, q = nwg / 8, r = nwg % 8, xcd = t % 8, off = t / 8;
;   int wgid = (xcd < r ? xcd * (q + 1) : r * (q + 1) + (xcd - r) * q) + off;
;   const int WGM = 8;
;   int nig = WGM * nN, gid = wgid / nig, fm = gid * WGM, gsz = min(nM - fm, WGM);
;   pm = __builtin_amdgcn_readfirstlane(fm + ((wgid % nig) % gsz)); pn = __builtin_amdgcn_readfirstlane((wgid % nig) / gsz);
.LBB0_338:
	s_ashr_i32 s2, s19, 31
	s_lshr_b32 s2, s2, 29
	s_add_i32 s2, s19, s2
	s_ashr_i32 s3, s2, 3
	s_and_b32 s2, s2, -8
	s_sub_i32 s2, s19, s2
	s_mov_b32 s14, -1
	s_cmp_lt_i32 s2, 0
	s_movk_i32 s10, 0x61
	s_cselect_b32 s12, s10, 0x60
	v_mbcnt_lo_u32_b32 v0, s14, 0
	v_mbcnt_hi_u32_b32 v0, s14, v0
	v_readlane_b32 s10, v254, 63
	s_mul_i32 s2, s12, s2
	s_add_i32 s2, s2, s3
	v_or_b32_e32 v0, s10, v0
	s_ashr_i32 s3, s2, 31
	s_waitcnt lgkmcnt(0)
	v_ashrrev_i32_e32 v2, 31, v0
	v_lshrrev_b32_e32 v2, 26, v2
	v_add_u32_e32 v2, v0, v2
	v_ashrrev_i32_e32 v11, 6, v2
	v_bfe_i32 v2, v0, 27, 1
	v_lshlrev_b32_e32 v19, 4, v0
	v_lshrrev_b32_e32 v2, 22, v2
	v_add_u32_e32 v2, v19, v2
	v_and_b32_e32 v2, 0xfffffc00, v2
	v_sub_u32_e32 v2, v19, v2
	v_lshrrev_b32_e32 v3, 4, v2
	v_bitop3_b32 v2, v3, v2, 32 bitop3:0x6c
	v_ashrrev_i32_e32 v4, 31, v2
	v_lshrrev_b32_e32 v4, 26, v4
	v_add_u32_e32 v4, v2, v4
	v_ashrrev_i32_e32 v14, 6, v4
	v_and_b32_e32 v4, 0xc0, v4
	v_sub_u32_e32 v2, v2, v4
	v_ashrrev_i16_sdwa v15, v151, sext(v2) dst_sel:DWORD dst_unused:UNUSED_PAD src0_sel:DWORD src1_sel:BYTE_0
	v_add_u32_e32 v2, 0x2000, v19
	v_ashrrev_i32_e32 v4, 31, v2
	v_lshrrev_b32_e32 v4, 22, v4
	v_add_u32_e32 v4, v2, v4
	s_lshr_b32 s3, s3, 27
	v_ashrrev_i32_e32 v12, 10, v4
	s_add_i32 s3, s2, s3
	v_mul_i32_i24_e32 v4, 0x400, v12
	s_ashr_i32 s12, s3, 5
	s_and_b32 s3, s3, 0xffe0
	v_sub_u32_e32 v2, v2, v4
	s_sub_i32 s2, s2, s3
	v_lshrrev_b32_e32 v4, 4, v2
	s_bfe_i32 s3, s2, 0x80000
	v_lshlrev_b32_e32 v5, 5, v11
	v_bitop3_b32 v2, v4, v2, 32 bitop3:0x6c
	s_bfe_u32 s3, s3, 0x3000c
	v_and_b32_e32 v13, 32, v5
	v_ashrrev_i32_e32 v5, 31, v2
	s_add_i32 s3, s2, s3
	v_lshrrev_b32_e32 v5, 26, v5
	s_lshl_b32 s16, s12, 3
	s_bfe_i32 s12, s3, 0x80000
	v_lshlrev_b32_e32 v3, 3, v11
	v_add_u32_e32 v5, v2, v5
	s_sext_i32_i16 s12, s12
	s_and_b32 s3, s3, 0xf8
	v_and_b32_e32 v3, 0xfffff0, v3
	v_ashrrev_i32_e32 v17, 6, v5
	v_and_b32_e32 v5, 0xc0, v5
	s_ashr_i32 s12, s12, 3
	s_sub_i32 s2, s2, s3
	v_add_u32_e32 v3, v14, v3
	v_lshlrev_b32_e32 v4, 3, v12
	v_sub_u32_e32 v2, v2, v5
	s_movk_i32 s10, 0xb00
	s_sext_i32_i8 s2, s2
	s_sext_i32_i16 s20, s12
	v_and_b32_e32 v4, 0xfffff0, v4
	v_ashrrev_i16_sdwa v18, v151, sext(v2) dst_sel:DWORD dst_unused:UNUSED_PAD src0_sel:DWORD src1_sel:BYTE_0
	v_mul_lo_u32 v2, v3, s10
	s_add_i32 s16, s16, s2
	s_mul_i32 s21, s20, 0x160000
	v_add_u32_e32 v4, v17, v4
	v_lshlrev_b32_e32 v6, 5, v12
	v_or_b32_e32 v2, v2, v13
	s_mul_hi_i32 s17, s20, 0x160000
	s_add_u32 s2, s7, s21
	v_and_b32_e32 v16, 32, v6
	v_add_u32_sdwa v130, v2, sext(v15) dst_sel:DWORD dst_unused:UNUSED_PAD src0_sel:DWORD src1_sel:WORD_0
	v_mul_lo_u32 v2, v4, s10
	s_addc_u32 s3, s18, s17
	s_mul_i32 s23, s16, 0x160000
	v_or_b32_e32 v2, v2, v16
	v_readlane_b32 s10, v254, 40
	s_mul_hi_i32 s22, s16, 0x160000
	s_add_u32 s12, s4, s23
	v_add_u32_sdwa v132, v2, sext(v18) dst_sel:DWORD dst_unused:UNUSED_PAD src0_sel:DWORD src1_sel:WORD_0
	v_ashrrev_i32_e32 v131, 31, v130
	v_add_u32_e32 v146, s10, v19
	s_addc_u32 s13, s5, s22
	v_lshlrev_b64 v[20:21], 1, v[130:131]
	v_readfirstlane_b32 s14, v146
	v_ashrrev_i32_e32 v133, 31, v132
	v_add_u32_e32 v147, 0x2000, v146
	v_lshl_add_u64 v[2:3], s[12:13], 0, v[20:21]
	s_mov_b32 m0, s14
	v_lshlrev_b64 v[22:23], 1, v[132:133]
	v_readfirstlane_b32 s14, v147
	v_add_u32_e32 v159, 0, v19
	global_load_lds_dwordx4 v[2:3], off
	v_lshl_add_u64 v[6:7], s[12:13], 0, v[22:23]
	s_mov_b32 m0, s14
	v_readfirstlane_b32 s14, v159
	v_add_u32_e32 v161, 0x2000, v159
	global_load_lds_dwordx4 v[6:7], off
	v_lshl_add_u64 v[8:9], s[2:3], 0, v[20:21]
	s_mov_b32 m0, s14
	v_readfirstlane_b32 s14, v161
	v_readlane_b32 s10, v254, 41
	global_load_lds_dwordx4 v[8:9], off
	s_mov_b32 m0, s14
	s_add_u32 s14, s12, 0xb0000
	v_add_u32_e32 v162, s10, v19
	v_lshl_add_u64 v[4:5], s[2:3], 0, v[22:23]
	s_addc_u32 s15, s13, 0
	v_readfirstlane_b32 s24, v162
	global_load_lds_dwordx4 v[4:5], off
	v_lshl_add_u64 v[24:25], s[14:15], 0, v[20:21]
	s_mov_b32 m0, s24
	v_add_u32_e32 v163, 0x2000, v162
	global_load_lds_dwordx4 v[24:25], off
	v_lshl_add_u64 v[24:25], s[14:15], 0, v[22:23]
	v_readfirstlane_b32 s14, v163
	s_mov_b32 m0, s14
	s_add_u32 s14, s2, 0xb0000
	v_add_u32_e32 v164, 0x4000, v159
	s_addc_u32 s15, s3, 0
	v_readfirstlane_b32 s24, v164
	global_load_lds_dwordx4 v[24:25], off
	v_lshl_add_u64 v[20:21], s[14:15], 0, v[20:21]
	s_mov_b32 m0, s24
	v_add_u32_e32 v165, 0x6000, v159
	global_load_lds_dwordx4 v[20:21], off
	v_lshl_add_u64 v[20:21], s[14:15], 0, v[22:23]
	v_readfirstlane_b32 s14, v165
	s_mov_b32 m0, s14
	v_ashrrev_i32_e32 v10, 8, v0
	global_load_lds_dwordx4 v[20:21], off
	v_cmp_eq_u32_e32 vcc, 1, v10
	s_and_saveexec_b64 s[14:15], vcc
	s_cbranch_execz .LBB0_340
	s_setprio 3
	s_barrier

; #define STA(P, br, kt) STAGE(P, A, aoff0, aoff1, lda, br, kt)
; #define STB(P, br, kt) STAGE(P, Bt, boff0, boff1, ldb, br, kt)
; #define LDA(dst, b, h) _Pragma("unroll") for (int m = 0; m < 4; ++m) _Pragma("unroll") for (int k = 0; k < 2; ++k) \
;     dst[m][k] = *reinterpret_cast<const bf16x8*>((char*)SA(b, h) + lds_byte(wr * 64 + m * 16 + fr, k * 32 + fq * 8))
; #define LDB(dst, b, h) _Pragma("unroll") for (int n = 0; n < 2; ++n) _Pragma("unroll") for (int k = 0; k < 2; ++k) \
;     dst[n][k] = *reinterpret_cast<const bf16x8*>((char*)SB(b, h) + lds_byte(wc * 32 + n * 16 + fr, k * 32 + fq * 8))
; #define MMA(ai, bj, At, Bq) do { __builtin_amdgcn_s_setprio(1); \
;     _Pragma("unroll") for (int m = 0; m < 4; ++m) _Pragma("unroll") for (int n = 0; n < 2; ++n) _Pragma("unroll") for (int k = 0; k < 2; ++k) \
;       acc[ai][bj][m][n] = __builtin_amdgcn_mfma_f32_16x16x32_bf16(At[m][k], Bq[n][k], acc[ai][bj][m][n], 0, 0, 0); \
;     __builtin_amdgcn_s_setprio(0); } while (0)
; #define WAIT_L(n) asm volatile("s_waitcnt lgkmcnt(" #n ")" ::: "memory")
; #define BAR __builtin_amdgcn_s_barrier()
; #define SCHED __builtin_amdgcn_sched_barrier(0)
; __device__ __forceinline__ void gemm256(const u16* __restrict__ A, int lda, const u16* __restrict__ Bt, int ldb, int K,
;                                         f32x4 (&acc)[2][2][4][2], const int g_wid) {
;     ...
;   for (int t = 0; t < nt - 2; t += 2) {
;     LDB(B0, 0, 0); SCHED; LDA(At, 0, 0); STA(SA(1, 1), HALF, t + 1);
;     WAIT_L(8); BAR; WAIT_L(0); MMA(0, 0, At, B0); BAR; SCHED;
;     LDB(B1, 0, 1); STB(SB(0, 0), 0, t + 2);
;     BAR; WAIT_L(0); MMA(0, 1, At, B1); BAR;
;     LDA(At, 0, 1); STA(SA(0, 0), 0, t + 2);
;     BAR; WAIT_L(0); MMA(1, 0, At, B0); BAR; SCHED;
.LBB0_341:
	ds_read_b128 v[178:181], v174
	ds_read_b128 v[182:185], v174 offset:1024
	ds_read_b128 v[186:189], v174 offset:2048
	ds_read_b128 v[190:193], v174 offset:3072
	v_add_u32_e32 v175, 0xc000, v159
	v_lshl_add_u64 v[242:243], v[138:139], 0, s[12:13]
	v_readfirstlane_b32 s15, v175
	v_lshl_add_u64 v[176:177], v[242:243], 0, s[10:11]
	s_mov_b32 m0, s15
	ds_read_b128 v[194:197], v145
	ds_read_b128 v[198:201], v145 offset:1024
	ds_read_b128 v[202:205], v144
	ds_read_b128 v[206:209], v144 offset:1024
	ds_read_b128 v[210:213], v143
	ds_read_b128 v[214:217], v143 offset:1024
	ds_read_b128 v[218:221], v142
	ds_read_b128 v[222:225], v142 offset:1024
	global_load_lds_dwordx4 v[176:177], off
	v_add_u32_e32 v176, 0xe000, v159
	v_lshl_add_u64 v[244:245], v[140:141], 0, s[12:13]
	v_readfirstlane_b32 s15, v176
	v_lshl_add_u64 v[226:227], v[244:245], 0, s[10:11]
	s_mov_b32 m0, s15
	s_nop 0
	global_load_lds_dwordx4 v[226:227], off
	s_waitcnt lgkmcnt(8)
	s_barrier
	s_waitcnt lgkmcnt(0)
	v_mfma_f32_16x16x32_bf16 v[126:129], v[194:197], v[178:181], v[126:129]
	v_mfma_f32_16x16x32_bf16 v[122:125], v[194:197], v[186:189], v[122:125]
	v_mfma_f32_16x16x32_bf16 v[118:121], v[202:205], v[178:181], v[118:121]
	v_mfma_f32_16x16x32_bf16 v[114:117], v[202:205], v[186:189], v[114:117]
	v_mfma_f32_16x16x32_bf16 v[110:113], v[210:213], v[178:181], v[110:113]
	v_mfma_f32_16x16x32_bf16 v[106:109], v[210:213], v[186:189], v[106:109]
	v_mfma_f32_16x16x32_bf16 v[102:105], v[218:221], v[178:181], v[102:105]
	v_mfma_f32_16x16x32_bf16 v[98:101], v[218:221], v[186:189], v[98:101]
	v_mfma_f32_16x16x32_bf16 v[126:129], v[198:201], v[182:185], v[126:129]
	v_mfma_f32_16x16x32_bf16 v[122:125], v[198:201], v[190:193], v[122:125]
	v_mfma_f32_16x16x32_bf16 v[118:121], v[206:209], v[182:185], v[118:121]
	v_mfma_f32_16x16x32_bf16 v[114:117], v[206:209], v[190:193], v[114:117]
	v_mfma_f32_16x16x32_bf16 v[110:113], v[214:217], v[182:185], v[110:113]
	v_mfma_f32_16x16x32_bf16 v[106:109], v[214:217], v[190:193], v[106:109]
	v_mfma_f32_16x16x32_bf16 v[102:105], v[222:225], v[182:185], v[102:105]
	v_mfma_f32_16x16x32_bf16 v[98:101], v[222:225], v[190:193], v[98:101]
	s_barrier
	v_lshl_add_u64 v[246:247], v[134:135], 0, s[12:13]
	v_readfirstlane_b32 s15, v146
	v_lshl_add_u64 v[248:249], v[246:247], 0, s[74:75]
	s_mov_b32 m0, s15
	ds_read_b128 v[226:229], v173
	ds_read_b128 v[230:233], v173 offset:1024
	ds_read_b128 v[234:237], v173 offset:2048
	ds_read_b128 v[238:241], v173 offset:3072
	global_load_lds_dwordx4 v[248:249], off
	v_lshl_add_u64 v[248:249], v[136:137], 0, s[12:13]
	v_readfirstlane_b32 s15, v147
	v_lshl_add_u64 v[250:251], v[248:249], 0, s[74:75]
	s_mov_b32 m0, s15
	s_nop 0
	global_load_lds_dwordx4 v[250:251], off
	s_barrier
	s_waitcnt lgkmcnt(0)
	v_mfma_f32_16x16x32_bf16 v[94:97], v[194:197], v[226:229], v[94:97]
	v_mfma_f32_16x16x32_bf16 v[90:93], v[194:197], v[234:237], v[90:93]
	v_mfma_f32_16x16x32_bf16 v[86:89], v[202:205], v[226:229], v[86:89]
	v_mfma_f32_16x16x32_bf16 v[82:85], v[202:205], v[234:237], v[82:85]
	v_mfma_f32_16x16x32_bf16 v[78:81], v[210:213], v[226:229], v[78:81]
	v_mfma_f32_16x16x32_bf16 v[74:77], v[210:213], v[234:237], v[74:77]
	v_mfma_f32_16x16x32_bf16 v[70:73], v[218:221], v[226:229], v[70:73]
	v_mfma_f32_16x16x32_bf16 v[66:69], v[218:221], v[234:237], v[66:69]
	v_mfma_f32_16x16x32_bf16 v[94:97], v[198:201], v[230:233], v[94:97]
	v_mfma_f32_16x16x32_bf16 v[90:93], v[198:201], v[238:241], v[90:93]
	v_mfma_f32_16x16x32_bf16 v[86:89], v[206:209], v[230:233], v[86:89]
	v_mfma_f32_16x16x32_bf16 v[82:85], v[206:209], v[238:241], v[82:85]
	v_mfma_f32_16x16x32_bf16 v[78:81], v[214:217], v[230:233], v[78:81]
	v_mfma_f32_16x16x32_bf16 v[74:77], v[214:217], v[238:241], v[74:77]
	v_mfma_f32_16x16x32_bf16 v[70:73], v[222:225], v[230:233], v[70:73]
	v_mfma_f32_16x16x32_bf16 v[66:69], v[222:225], v[238:241], v[66:69]
	v_readfirstlane_b32 s15, v159
	v_lshl_add_u64 v[250:251], v[242:243], 0, s[22:23]
	s_mov_b32 m0, s15
	v_readfirstlane_b32 s15, v161
	s_barrier
	ds_read_b128 v[194:197], v145 offset:16384
	ds_read_b128 v[198:201], v145 offset:17408
	ds_read_b128 v[202:205], v144 offset:16384
	ds_read_b128 v[206:209], v144 offset:17408
	ds_read_b128 v[210:213], v143 offset:16384
	ds_read_b128 v[214:217], v143 offset:17408
	ds_read_b128 v[218:221], v142 offset:16384
	ds_read_b128 v[222:225], v142 offset:17408
	global_load_lds_dwordx4 v[250:251], off
	v_lshl_add_u64 v[250:251], v[244:245], 0, s[22:23]
	s_mov_b32 m0, s15
	s_nop 0
	global_load_lds_dwordx4 v[250:251], off
	s_barrier
	s_waitcnt lgkmcnt(0)
	v_mfma_f32_16x16x32_bf16 v[62:65], v[194:197], v[178:181], v[62:65]
	v_mfma_f32_16x16x32_bf16 v[58:61], v[194:197], v[186:189], v[58:61]
	v_mfma_f32_16x16x32_bf16 v[54:57], v[202:205], v[178:181], v[54:57]
	v_mfma_f32_16x16x32_bf16 v[50:53], v[202:205], v[186:189], v[50:53]
	v_mfma_f32_16x16x32_bf16 v[46:49], v[210:213], v[178:181], v[46:49]
	v_mfma_f32_16x16x32_bf16 v[42:45], v[210:213], v[186:189], v[42:45]
	v_mfma_f32_16x16x32_bf16 v[38:41], v[218:221], v[178:181], v[38:41]
	v_mfma_f32_16x16x32_bf16 v[34:37], v[218:221], v[186:189], v[34:37]
	v_mfma_f32_16x16x32_bf16 v[62:65], v[198:201], v[182:185], v[62:65]
	v_mfma_f32_16x16x32_bf16 v[58:61], v[198:201], v[190:193], v[58:61]
	v_mfma_f32_16x16x32_bf16 v[54:57], v[206:209], v[182:185], v[54:57]
	v_mfma_f32_16x16x32_bf16 v[50:53], v[206:209], v[190:193], v[50:53]
	v_mfma_f32_16x16x32_bf16 v[46:49], v[214:217], v[182:185], v[46:49]
	v_mfma_f32_16x16x32_bf16 v[42:45], v[214:217], v[190:193], v[42:45]
	v_mfma_f32_16x16x32_bf16 v[38:41], v[222:225], v[182:185], v[38:41]
	v_mfma_f32_16x16x32_bf16 v[34:37], v[222:225], v[190:193], v[34:37]
	s_barrier
; #define STA(P, br, kt) STAGE(P, A, aoff0, aoff1, lda, br, kt)
; #define STB(P, br, kt) STAGE(P, Bt, boff0, boff1, ldb, br, kt)
; #define LDA(dst, b, h) _Pragma("unroll") for (int m = 0; m < 4; ++m) _Pragma("unroll") for (int k = 0; k < 2; ++k) \
;     dst[m][k] = *reinterpret_cast<const bf16x8*>((char*)SA(b, h) + lds_byte(wr * 64 + m * 16 + fr, k * 32 + fq * 8))
; #define LDB(dst, b, h) _Pragma("unroll") for (int n = 0; n < 2; ++n) _Pragma("unroll") for (int k = 0; k < 2; ++k) \
;     dst[n][k] = *reinterpret_cast<const bf16x8*>((char*)SB(b, h) + lds_byte(wc * 32 + n * 16 + fr, k * 32 + fq * 8))
; #define MMA(ai, bj, At, Bq) do { __builtin_amdgcn_s_setprio(1); \
;     _Pragma("unroll") for (int m = 0; m < 4; ++m) _Pragma("unroll") for (int n = 0; n < 2; ++n) _Pragma("unroll") for (int k = 0; k < 2; ++k) \
;       acc[ai][bj][m][n] = __builtin_amdgcn_mfma_f32_16x16x32_bf16(At[m][k], Bq[n][k], acc[ai][bj][m][n], 0, 0, 0); \
;     __builtin_amdgcn_s_setprio(0); } while (0)
; #define WAIT_V(n) asm volatile("s_waitcnt vmcnt(" #n ")" ::: "memory")
; #define WAIT_L(n) asm volatile("s_waitcnt lgkmcnt(" #n ")" ::: "memory")
; #define BAR __builtin_amdgcn_s_barrier()
; #define SCHED __builtin_amdgcn_sched_barrier(0)
; __device__ __forceinline__ void gemm256(const u16* __restrict__ A, int lda, const u16* __restrict__ Bt, int ldb, int K,
;                                         f32x4 (&acc)[2][2][4][2], const int g_wid) {
;     ...
;     STB(SB(0, 1), HALF, t + 2);
;     WAIT_V(6); BAR; MMA(1, 1, At, B1); BAR;
;     LDB(B0, 1, 0); SCHED; LDA(At, 1, 0); STA(SA(0, 1), HALF, t + 2);
;     WAIT_L(8); BAR; WAIT_L(0); MMA(0, 0, At, B0); BAR; SCHED;
;     LDB(B1, 1, 1); STB(SB(1, 0), 0, t + 3);
;     BAR; WAIT_L(0); MMA(0, 1, At, B1); BAR;
	v_readfirstlane_b32 s15, v162
	v_lshl_add_u64 v[178:179], v[246:247], 0, s[24:25]
	s_mov_b32 m0, s15
	v_readfirstlane_b32 s15, v163
	global_load_lds_dwordx4 v[178:179], off
	v_lshl_add_u64 v[178:179], v[248:249], 0, s[24:25]
	s_mov_b32 m0, s15
	s_nop 0
	global_load_lds_dwordx4 v[178:179], off
	s_waitcnt vmcnt(6)
	s_barrier
	v_mfma_f32_16x16x32_bf16 v[30:33], v[194:197], v[226:229], v[30:33]
	v_mfma_f32_16x16x32_bf16 v[26:29], v[194:197], v[234:237], v[26:29]
	v_mfma_f32_16x16x32_bf16 v[22:25], v[202:205], v[226:229], v[22:25]
	v_mfma_f32_16x16x32_bf16 v[18:21], v[202:205], v[234:237], v[18:21]
	v_mfma_f32_16x16x32_bf16 v[14:17], v[210:213], v[226:229], v[14:17]
	v_mfma_f32_16x16x32_bf16 v[10:13], v[210:213], v[234:237], v[10:13]
	v_mfma_f32_16x16x32_bf16 v[6:9], v[218:221], v[226:229], v[6:9]
	v_mfma_f32_16x16x32_bf16 v[2:5], v[218:221], v[234:237], v[2:5]
	v_mfma_f32_16x16x32_bf16 v[30:33], v[198:201], v[230:233], v[30:33]
	v_mfma_f32_16x16x32_bf16 v[26:29], v[198:201], v[238:241], v[26:29]
	v_mfma_f32_16x16x32_bf16 v[22:25], v[206:209], v[230:233], v[22:25]
	v_mfma_f32_16x16x32_bf16 v[18:21], v[206:209], v[238:241], v[18:21]
	v_mfma_f32_16x16x32_bf16 v[14:17], v[214:217], v[230:233], v[14:17]
	v_mfma_f32_16x16x32_bf16 v[10:13], v[214:217], v[238:241], v[10:13]
	v_mfma_f32_16x16x32_bf16 v[6:9], v[222:225], v[230:233], v[6:9]
	v_mfma_f32_16x16x32_bf16 v[2:5], v[222:225], v[238:241], v[2:5]
	s_barrier
	ds_read_b128 v[178:181], v166
	ds_read_b128 v[182:185], v166 offset:1024
	ds_read_b128 v[186:189], v166 offset:2048
	ds_read_b128 v[190:193], v166 offset:3072
	v_readfirstlane_b32 s15, v164
	v_lshl_add_u64 v[226:227], v[242:243], 0, s[26:27]
	s_mov_b32 m0, s15
	v_readfirstlane_b32 s15, v165
	ds_read_b128 v[194:197], v145 offset:32768
	ds_read_b128 v[198:201], v145 offset:33792
	ds_read_b128 v[202:205], v144 offset:32768
	ds_read_b128 v[206:209], v144 offset:33792
	ds_read_b128 v[210:213], v143 offset:32768
	ds_read_b128 v[214:217], v143 offset:33792
	ds_read_b128 v[218:221], v142 offset:32768
	ds_read_b128 v[222:225], v142 offset:33792
	global_load_lds_dwordx4 v[226:227], off
	v_lshl_add_u64 v[226:227], v[244:245], 0, s[26:27]
	s_mov_b32 m0, s15
	s_nop 0
	global_load_lds_dwordx4 v[226:227], off
	s_waitcnt lgkmcnt(8)
	s_barrier
	s_waitcnt lgkmcnt(0)
	v_mfma_f32_16x16x32_bf16 v[126:129], v[194:197], v[178:181], v[126:129]
	v_mfma_f32_16x16x32_bf16 v[122:125], v[194:197], v[186:189], v[122:125]
	v_mfma_f32_16x16x32_bf16 v[118:121], v[202:205], v[178:181], v[118:121]
	v_mfma_f32_16x16x32_bf16 v[114:117], v[202:205], v[186:189], v[114:117]
	v_mfma_f32_16x16x32_bf16 v[110:113], v[210:213], v[178:181], v[110:113]
	v_mfma_f32_16x16x32_bf16 v[106:109], v[210:213], v[186:189], v[106:109]
	v_mfma_f32_16x16x32_bf16 v[102:105], v[218:221], v[178:181], v[102:105]
	v_mfma_f32_16x16x32_bf16 v[98:101], v[218:221], v[186:189], v[98:101]
	v_mfma_f32_16x16x32_bf16 v[126:129], v[198:201], v[182:185], v[126:129]
	v_mfma_f32_16x16x32_bf16 v[122:125], v[198:201], v[190:193], v[122:125]
	v_mfma_f32_16x16x32_bf16 v[118:121], v[206:209], v[182:185], v[118:121]
	v_mfma_f32_16x16x32_bf16 v[114:117], v[206:209], v[190:193], v[114:117]
	v_mfma_f32_16x16x32_bf16 v[110:113], v[214:217], v[182:185], v[110:113]
	v_mfma_f32_16x16x32_bf16 v[106:109], v[214:217], v[190:193], v[106:109]
	v_mfma_f32_16x16x32_bf16 v[102:105], v[222:225], v[182:185], v[102:105]
	v_mfma_f32_16x16x32_bf16 v[98:101], v[222:225], v[190:193], v[98:101]
	s_barrier
	v_readfirstlane_b32 s15, v167
	v_lshl_add_u64 v[250:251], v[246:247], 0, s[82:83]
	s_mov_b32 m0, s15
	v_readfirstlane_b32 s15, v168
	ds_read_b128 v[226:229], v160
	ds_read_b128 v[230:233], v160 offset:1024
	ds_read_b128 v[234:237], v160 offset:2048
	ds_read_b128 v[238:241], v160 offset:3072
	global_load_lds_dwordx4 v[250:251], off
	v_lshl_add_u64 v[250:251], v[248:249], 0, s[82:83]
	s_mov_b32 m0, s15
	s_nop 0
	global_load_lds_dwordx4 v[250:251], off
	s_barrier
	s_waitcnt lgkmcnt(0)
	v_mfma_f32_16x16x32_bf16 v[94:97], v[194:197], v[226:229], v[94:97]
	v_mfma_f32_16x16x32_bf16 v[90:93], v[194:197], v[234:237], v[90:93]
	v_mfma_f32_16x16x32_bf16 v[86:89], v[202:205], v[226:229], v[86:89]
	v_mfma_f32_16x16x32_bf16 v[82:85], v[202:205], v[234:237], v[82:85]
	v_mfma_f32_16x16x32_bf16 v[78:81], v[210:213], v[226:229], v[78:81]
	v_mfma_f32_16x16x32_bf16 v[74:77], v[210:213], v[234:237], v[74:77]
	v_mfma_f32_16x16x32_bf16 v[70:73], v[218:221], v[226:229], v[70:73]
	v_mfma_f32_16x16x32_bf16 v[66:69], v[218:221], v[234:237], v[66:69]
	v_mfma_f32_16x16x32_bf16 v[94:97], v[198:201], v[230:233], v[94:97]
	v_mfma_f32_16x16x32_bf16 v[90:93], v[198:201], v[238:241], v[90:93]
	v_mfma_f32_16x16x32_bf16 v[86:89], v[206:209], v[230:233], v[86:89]
	v_mfma_f32_16x16x32_bf16 v[82:85], v[206:209], v[238:241], v[82:85]
	v_mfma_f32_16x16x32_bf16 v[78:81], v[214:217], v[230:233], v[78:81]
	v_mfma_f32_16x16x32_bf16 v[74:77], v[214:217], v[238:241], v[74:77]
	v_mfma_f32_16x16x32_bf16 v[70:73], v[222:225], v[230:233], v[70:73]
	v_mfma_f32_16x16x32_bf16 v[66:69], v[222:225], v[238:241], v[66:69]
	v_readfirstlane_b32 s15, v169
	v_lshl_add_u64 v[242:243], v[242:243], 0, s[28:29]
	s_mov_b32 m0, s15
	v_readfirstlane_b32 s15, v170
	s_barrier
	ds_read_b128 v[194:197], v145 offset:49152
	ds_read_b128 v[198:201], v145 offset:50176
	ds_read_b128 v[202:205], v144 offset:49152
	ds_read_b128 v[206:209], v144 offset:50176
	ds_read_b128 v[210:213], v143 offset:49152
	ds_read_b128 v[214:217], v143 offset:50176
	ds_read_b128 v[218:221], v142 offset:49152
	ds_read_b128 v[222:225], v142 offset:50176
	global_load_lds_dwordx4 v[242:243], off
	v_lshl_add_u64 v[242:243], v[244:245], 0, s[28:29]
	s_mov_b32 m0, s15
	s_nop 0
	global_load_lds_dwordx4 v[242:243], off
	s_barrier
; #define STA(P, br, kt) STAGE(P, A, aoff0, aoff1, lda, br, kt)
; #define STB(P, br, kt) STAGE(P, Bt, boff0, boff1, ldb, br, kt)
; #define LDA(dst, b, h) _Pragma("unroll") for (int m = 0; m < 4; ++m) _Pragma("unroll") for (int k = 0; k < 2; ++k) \
;     dst[m][k] = *reinterpret_cast<const bf16x8*>((char*)SA(b, h) + lds_byte(wr * 64 + m * 16 + fr, k * 32 + fq * 8))
; #define LDB(dst, b, h) _Pragma("unroll") for (int n = 0; n < 2; ++n) _Pragma("unroll") for (int k = 0; k < 2; ++k) \
;     dst[n][k] = *reinterpret_cast<const bf16x8*>((char*)SB(b, h) + lds_byte(wc * 32 + n * 16 + fr, k * 32 + fq * 8))
; #define MMA(ai, bj, At, Bq) do { __builtin_amdgcn_s_setprio(1); \
;     _Pragma("unroll") for (int m = 0; m < 4; ++m) _Pragma("unroll") for (int n = 0; n < 2; ++n) _Pragma("unroll") for (int k = 0; k < 2; ++k) \
;       acc[ai][bj][m][n] = __builtin_amdgcn_mfma_f32_16x16x32_bf16(At[m][k], Bq[n][k], acc[ai][bj][m][n], 0, 0, 0); \
;     __builtin_amdgcn_s_setprio(0); } while (0)
; #define WAIT_V(n) asm volatile("s_waitcnt vmcnt(" #n ")" ::: "memory")
; #define WAIT_L(n) asm volatile("s_waitcnt lgkmcnt(" #n ")" ::: "memory")
; #define BAR __builtin_amdgcn_s_barrier()
; #define SCHED __builtin_amdgcn_sched_barrier(0)
; __device__ __forceinline__ void gemm256(const u16* __restrict__ A, int lda, const u16* __restrict__ Bt, int ldb, int K,
;                                         f32x4 (&acc)[2][2][4][2], const int g_wid) {
;     ...
;     LDA(At, 1, 1); STA(SA(1, 0), 0, t + 3);
;     BAR; WAIT_L(0); MMA(1, 0, At, B0); BAR; SCHED;
;     STB(SB(1, 1), HALF, t + 3);
;     WAIT_V(6); BAR; MMA(1, 1, At, B1); BAR;
;   }
;   { LDB(B0, 0, 0); LDA(At, 0, 0); STA(SA(1, 1), HALF, nt - 1);
;     BAR; WAIT_L(0); MMA(0, 0, At, B0); BAR;
	s_waitcnt lgkmcnt(0)
	v_mfma_f32_16x16x32_bf16 v[62:65], v[194:197], v[178:181], v[62:65]
	v_mfma_f32_16x16x32_bf16 v[58:61], v[194:197], v[186:189], v[58:61]
	v_mfma_f32_16x16x32_bf16 v[54:57], v[202:205], v[178:181], v[54:57]
	v_mfma_f32_16x16x32_bf16 v[50:53], v[202:205], v[186:189], v[50:53]
	v_mfma_f32_16x16x32_bf16 v[46:49], v[210:213], v[178:181], v[46:49]
	v_mfma_f32_16x16x32_bf16 v[42:45], v[210:213], v[186:189], v[42:45]
	v_mfma_f32_16x16x32_bf16 v[38:41], v[218:221], v[178:181], v[38:41]
	v_mfma_f32_16x16x32_bf16 v[34:37], v[218:221], v[186:189], v[34:37]
	v_mfma_f32_16x16x32_bf16 v[62:65], v[198:201], v[182:185], v[62:65]
	v_mfma_f32_16x16x32_bf16 v[58:61], v[198:201], v[190:193], v[58:61]
	v_mfma_f32_16x16x32_bf16 v[54:57], v[206:209], v[182:185], v[54:57]
	v_mfma_f32_16x16x32_bf16 v[50:53], v[206:209], v[190:193], v[50:53]
	v_mfma_f32_16x16x32_bf16 v[46:49], v[214:217], v[182:185], v[46:49]
	v_mfma_f32_16x16x32_bf16 v[42:45], v[214:217], v[190:193], v[42:45]
	v_mfma_f32_16x16x32_bf16 v[38:41], v[222:225], v[182:185], v[38:41]
	v_mfma_f32_16x16x32_bf16 v[34:37], v[222:225], v[190:193], v[34:37]
	s_barrier
	v_readfirstlane_b32 s15, v171
	v_lshl_add_u64 v[178:179], v[246:247], 0, s[50:51]
	s_mov_b32 m0, s15
	v_readfirstlane_b32 s15, v172
	global_load_lds_dwordx4 v[178:179], off
	v_lshl_add_u64 v[178:179], v[248:249], 0, s[50:51]
	s_mov_b32 m0, s15
	s_nop 0
	global_load_lds_dwordx4 v[178:179], off
	s_waitcnt vmcnt(6)
	s_barrier
	v_mfma_f32_16x16x32_bf16 v[30:33], v[194:197], v[226:229], v[30:33]
	v_mfma_f32_16x16x32_bf16 v[26:29], v[194:197], v[234:237], v[26:29]
	v_mfma_f32_16x16x32_bf16 v[22:25], v[202:205], v[226:229], v[22:25]
	v_mfma_f32_16x16x32_bf16 v[18:21], v[202:205], v[234:237], v[18:21]
	v_mfma_f32_16x16x32_bf16 v[14:17], v[210:213], v[226:229], v[14:17]
	v_mfma_f32_16x16x32_bf16 v[10:13], v[210:213], v[234:237], v[10:13]
	v_mfma_f32_16x16x32_bf16 v[6:9], v[218:221], v[226:229], v[6:9]
	v_mfma_f32_16x16x32_bf16 v[2:5], v[218:221], v[234:237], v[2:5]
	v_mfma_f32_16x16x32_bf16 v[30:33], v[198:201], v[230:233], v[30:33]
	v_mfma_f32_16x16x32_bf16 v[26:29], v[198:201], v[238:241], v[26:29]
	v_mfma_f32_16x16x32_bf16 v[22:25], v[206:209], v[230:233], v[22:25]
	v_mfma_f32_16x16x32_bf16 v[18:21], v[206:209], v[238:241], v[18:21]
	v_mfma_f32_16x16x32_bf16 v[14:17], v[214:217], v[230:233], v[14:17]
	v_mfma_f32_16x16x32_bf16 v[10:13], v[214:217], v[238:241], v[10:13]
	v_mfma_f32_16x16x32_bf16 v[6:9], v[222:225], v[230:233], v[6:9]
	v_mfma_f32_16x16x32_bf16 v[2:5], v[222:225], v[238:241], v[2:5]
	s_add_i32 s14, s14, 2
	s_add_u32 s12, s12, 0x100
	s_addc_u32 s13, s13, 0
	s_cmp_lt_u32 s14, 40
	s_barrier
	s_cbranch_scc1 .LBB0_341
	s_add_u32 s2, s2, 0xb1580
	s_addc_u32 s3, s3, 0
	v_readfirstlane_b32 s12, v175
	v_lshl_add_u64 v[130:131], v[130:131], 1, s[2:3]
	s_mov_b32 m0, s12
	ds_read_b128 v[134:137], v174
	ds_read_b128 v[138:141], v174 offset:1024
	ds_read_b128 v[162:165], v174 offset:2048
	ds_read_b128 v[168:171], v174 offset:3072
	ds_read_b128 v[178:181], v145
	ds_read_b128 v[182:185], v145 offset:1024
	ds_read_b128 v[186:189], v144
	ds_read_b128 v[190:193], v144 offset:1024
	ds_read_b128 v[194:197], v143
	ds_read_b128 v[198:201], v143 offset:1024
	ds_read_b128 v[202:205], v142
	ds_read_b128 v[206:209], v142 offset:1024
	global_load_lds_dwordx4 v[130:131], off
	v_lshl_add_u64 v[130:131], v[132:133], 1, s[2:3]
	v_readfirstlane_b32 s2, v176
	s_mov_b32 m0, s2
	s_nop 0
	global_load_lds_dwordx4 v[130:131], off
	s_barrier
	s_waitcnt lgkmcnt(0)
	v_mfma_f32_16x16x32_bf16 v[126:129], v[178:181], v[134:137], v[126:129]
	v_mfma_f32_16x16x32_bf16 v[118:121], v[186:189], v[134:137], v[118:121]
	v_mfma_f32_16x16x32_bf16 v[114:117], v[186:189], v[162:165], v[114:117]
	v_mfma_f32_16x16x32_bf16 v[110:113], v[194:197], v[134:137], v[110:113]
	v_mfma_f32_16x16x32_bf16 v[106:109], v[194:197], v[162:165], v[106:109]
	v_mfma_f32_16x16x32_bf16 v[102:105], v[202:205], v[134:137], v[102:105]
	v_mfma_f32_16x16x32_bf16 v[98:101], v[202:205], v[162:165], v[98:101]
	v_mfma_f32_16x16x32_bf16 v[126:129], v[182:185], v[138:141], v[126:129]
	v_mfma_f32_16x16x32_bf16 v[122:125], v[178:181], v[162:165], v[122:125]
	v_mfma_f32_16x16x32_bf16 v[118:121], v[190:193], v[138:141], v[118:121]
	v_mfma_f32_16x16x32_bf16 v[114:117], v[190:193], v[168:171], v[114:117]
	v_mfma_f32_16x16x32_bf16 v[110:113], v[198:201], v[138:141], v[110:113]
	v_mfma_f32_16x16x32_bf16 v[106:109], v[198:201], v[168:171], v[106:109]
	v_mfma_f32_16x16x32_bf16 v[102:105], v[206:209], v[138:141], v[102:105]
	v_mfma_f32_16x16x32_bf16 v[98:101], v[206:209], v[168:171], v[98:101]
	v_mfma_f32_16x16x32_bf16 v[130:133], v[182:185], v[168:171], v[122:125]
	s_barrier
	s_nop 0
	ds_read_b128 v[122:125], v173
	ds_read_b128 v[174:177], v173 offset:1024
	ds_read_b128 v[210:213], v173 offset:2048
	ds_read_b128 v[214:217], v173 offset:3072
	s_barrier
	s_waitcnt lgkmcnt(0)
	v_mfma_f32_16x16x32_bf16 v[78:81], v[194:197], v[122:125], v[78:81]
	v_mfma_f32_16x16x32_bf16 v[74:77], v[194:197], v[210:213], v[74:77]
	v_mfma_f32_16x16x32_bf16 v[70:73], v[202:205], v[122:125], v[70:73]
	v_mfma_f32_16x16x32_bf16 v[66:69], v[202:205], v[210:213], v[66:69]
	v_mfma_f32_16x16x32_bf16 v[94:97], v[178:181], v[122:125], v[94:97]
	v_mfma_f32_16x16x32_bf16 v[90:93], v[178:181], v[210:213], v[90:93]
	v_mfma_f32_16x16x32_bf16 v[86:89], v[186:189], v[122:125], v[86:89]
	v_mfma_f32_16x16x32_bf16 v[82:85], v[186:189], v[210:213], v[82:85]
	v_mfma_f32_16x16x32_bf16 v[78:81], v[198:201], v[174:177], v[78:81]
	v_mfma_f32_16x16x32_bf16 v[74:77], v[198:201], v[214:217], v[74:77]
	v_mfma_f32_16x16x32_bf16 v[70:73], v[206:209], v[174:177], v[70:73]
	v_mfma_f32_16x16x32_bf16 v[66:69], v[206:209], v[214:217], v[66:69]
	v_mfma_f32_16x16x32_bf16 v[218:221], v[182:185], v[174:177], v[94:97]
	v_mfma_f32_16x16x32_bf16 v[178:181], v[182:185], v[214:217], v[90:93]
	v_mfma_f32_16x16x32_bf16 v[182:185], v[190:193], v[174:177], v[86:89]
	v_mfma_f32_16x16x32_bf16 v[186:189], v[190:193], v[214:217], v[82:85]
	s_barrier
; #define LDA(dst, b, h) _Pragma("unroll") for (int m = 0; m < 4; ++m) _Pragma("unroll") for (int k = 0; k < 2; ++k) \
;     dst[m][k] = *reinterpret_cast<const bf16x8*>((char*)SA(b, h) + lds_byte(wr * 64 + m * 16 + fr, k * 32 + fq * 8))
; #define LDB(dst, b, h) _Pragma("unroll") for (int n = 0; n < 2; ++n) _Pragma("unroll") for (int k = 0; k < 2; ++k) \
;     dst[n][k] = *reinterpret_cast<const bf16x8*>((char*)SB(b, h) + lds_byte(wc * 32 + n * 16 + fr, k * 32 + fq * 8))
; #define MMA(ai, bj, At, Bq) do { __builtin_amdgcn_s_setprio(1); \
;     _Pragma("unroll") for (int m = 0; m < 4; ++m) _Pragma("unroll") for (int n = 0; n < 2; ++n) _Pragma("unroll") for (int k = 0; k < 2; ++k) \
;       acc[ai][bj][m][n] = __builtin_amdgcn_mfma_f32_16x16x32_bf16(At[m][k], Bq[n][k], acc[ai][bj][m][n], 0, 0, 0); \
;     __builtin_amdgcn_s_setprio(0); } while (0)
; #define WAIT_V(n) asm volatile("s_waitcnt vmcnt(" #n ")" ::: "memory")
; #define WAIT_L(n) asm volatile("s_waitcnt lgkmcnt(" #n ")" ::: "memory")
; #define BAR __builtin_amdgcn_s_barrier()
; __device__ __forceinline__ void gemm256(const u16* __restrict__ A, int lda, const u16* __restrict__ Bt, int ldb, int K,
;                                         f32x4 (&acc)[2][2][4][2], const int g_wid) {
;     ...
;     LDA(At, 0, 1); WAIT_V(4); BAR; WAIT_L(0); MMA(1, 0, At, B0); MMA(1, 1, At, B1); BAR; }
;   { LDB(B0, 1, 0); LDA(At, 1, 0); WAIT_V(2); BAR; WAIT_L(0); MMA(0, 0, At, B0); BAR;
	s_nop 0
	ds_read_b128 v[82:85], v145 offset:16384
	ds_read_b128 v[86:89], v145 offset:17408
	ds_read_b128 v[90:93], v144 offset:16384
	ds_read_b128 v[94:97], v144 offset:17408
	ds_read_b128 v[190:193], v143 offset:16384
	ds_read_b128 v[194:197], v143 offset:17408
	ds_read_b128 v[198:201], v142 offset:16384
	ds_read_b128 v[202:205], v142 offset:17408
	s_waitcnt vmcnt(4)
	s_barrier
	s_waitcnt lgkmcnt(0)
	v_mfma_f32_16x16x32_bf16 v[46:49], v[190:193], v[134:137], v[46:49]
	v_mfma_f32_16x16x32_bf16 v[42:45], v[190:193], v[162:165], v[42:45]
	v_mfma_f32_16x16x32_bf16 v[38:41], v[198:201], v[134:137], v[38:41]
	v_mfma_f32_16x16x32_bf16 v[34:37], v[198:201], v[162:165], v[34:37]
	v_mfma_f32_16x16x32_bf16 v[62:65], v[82:85], v[134:137], v[62:65]
	v_mfma_f32_16x16x32_bf16 v[58:61], v[82:85], v[162:165], v[58:61]
	v_mfma_f32_16x16x32_bf16 v[54:57], v[90:93], v[134:137], v[54:57]
	v_mfma_f32_16x16x32_bf16 v[50:53], v[90:93], v[162:165], v[50:53]
	v_mfma_f32_16x16x32_bf16 v[46:49], v[194:197], v[138:141], v[46:49]
	v_mfma_f32_16x16x32_bf16 v[42:45], v[194:197], v[168:171], v[42:45]
	v_mfma_f32_16x16x32_bf16 v[38:41], v[202:205], v[138:141], v[38:41]
	v_mfma_f32_16x16x32_bf16 v[34:37], v[202:205], v[168:171], v[34:37]
	v_mfma_f32_16x16x32_bf16 v[206:209], v[86:89], v[138:141], v[62:65]
	v_mfma_f32_16x16x32_bf16 v[222:225], v[86:89], v[168:171], v[58:61]
	v_mfma_f32_16x16x32_bf16 v[226:229], v[94:97], v[138:141], v[54:57]
	v_mfma_f32_16x16x32_bf16 v[230:233], v[94:97], v[168:171], v[50:53]
	v_mfma_f32_16x16x32_bf16 v[2:5], v[198:201], v[210:213], v[2:5]
	v_mfma_f32_16x16x32_bf16 v[30:33], v[82:85], v[122:125], v[30:33]
	v_mfma_f32_16x16x32_bf16 v[26:29], v[82:85], v[210:213], v[26:29]
	v_mfma_f32_16x16x32_bf16 v[22:25], v[90:93], v[122:125], v[22:25]
	v_mfma_f32_16x16x32_bf16 v[18:21], v[90:93], v[210:213], v[18:21]
	v_mfma_f32_16x16x32_bf16 v[14:17], v[190:193], v[122:125], v[14:17]
	v_mfma_f32_16x16x32_bf16 v[10:13], v[190:193], v[210:213], v[10:13]
	v_mfma_f32_16x16x32_bf16 v[6:9], v[198:201], v[122:125], v[6:9]
	v_mfma_f32_16x16x32_bf16 v[2:5], v[202:205], v[214:217], v[2:5]
	v_mfma_f32_16x16x32_bf16 v[134:137], v[86:89], v[174:177], v[30:33]
	v_mfma_f32_16x16x32_bf16 v[138:141], v[86:89], v[214:217], v[26:29]
	v_mfma_f32_16x16x32_bf16 v[162:165], v[94:97], v[174:177], v[22:25]
	v_mfma_f32_16x16x32_bf16 v[168:171], v[94:97], v[214:217], v[18:21]
	v_mfma_f32_16x16x32_bf16 v[234:237], v[194:197], v[174:177], v[14:17]
	v_mfma_f32_16x16x32_bf16 v[190:193], v[194:197], v[214:217], v[10:13]
	v_mfma_f32_16x16x32_bf16 v[172:175], v[202:205], v[174:177], v[6:9]
	s_barrier
	s_nop 0
	ds_read_b128 v[6:9], v166
	ds_read_b128 v[10:13], v166 offset:1024
	ds_read_b128 v[14:17], v166 offset:2048
	ds_read_b128 v[194:197], v166 offset:3072
	ds_read_b128 v[18:21], v145 offset:32768
	ds_read_b128 v[22:25], v145 offset:33792
	ds_read_b128 v[30:33], v144 offset:32768
	ds_read_b128 v[50:53], v144 offset:33792
	ds_read_b128 v[198:201], v143 offset:32768
	ds_read_b128 v[202:205], v143 offset:33792
	ds_read_b128 v[210:213], v142 offset:32768
	ds_read_b128 v[214:217], v142 offset:33792
	s_waitcnt vmcnt(2)
	s_barrier
	s_waitcnt lgkmcnt(0)
	v_mfma_f32_16x16x32_bf16 v[26:29], v[18:21], v[6:9], v[126:129]
	v_mfma_f32_16x16x32_bf16 v[122:125], v[22:25], v[10:13], v[26:29]
	v_mfma_f32_16x16x32_bf16 v[26:29], v[18:21], v[14:17], v[130:133]
	v_mfma_f32_16x16x32_bf16 v[90:93], v[22:25], v[194:197], v[26:29]
	v_mfma_f32_16x16x32_bf16 v[26:29], v[30:33], v[6:9], v[118:121]
	v_mfma_f32_16x16x32_bf16 v[126:129], v[50:53], v[10:13], v[26:29]
	v_mfma_f32_16x16x32_bf16 v[26:29], v[30:33], v[14:17], v[114:117]
	v_mfma_f32_16x16x32_bf16 v[94:97], v[50:53], v[194:197], v[26:29]
	v_mfma_f32_16x16x32_bf16 v[26:29], v[198:201], v[6:9], v[110:113]
	v_mfma_f32_16x16x32_bf16 v[118:121], v[202:205], v[10:13], v[26:29]
	v_mfma_f32_16x16x32_bf16 v[26:29], v[198:201], v[14:17], v[106:109]
	v_mfma_f32_16x16x32_bf16 v[86:89], v[202:205], v[194:197], v[26:29]
	v_mfma_f32_16x16x32_bf16 v[26:29], v[210:213], v[6:9], v[102:105]
	v_mfma_f32_16x16x32_bf16 v[114:117], v[214:217], v[10:13], v[26:29]
	v_mfma_f32_16x16x32_bf16 v[26:29], v[210:213], v[14:17], v[98:101]
	v_mfma_f32_16x16x32_bf16 v[82:85], v[214:217], v[194:197], v[26:29]
	s_barrier
; #define LDA(dst, b, h) _Pragma("unroll") for (int m = 0; m < 4; ++m) _Pragma("unroll") for (int k = 0; k < 2; ++k) \
;     dst[m][k] = *reinterpret_cast<const bf16x8*>((char*)SA(b, h) + lds_byte(wr * 64 + m * 16 + fr, k * 32 + fq * 8))
; #define LDB(dst, b, h) _Pragma("unroll") for (int n = 0; n < 2; ++n) _Pragma("unroll") for (int k = 0; k < 2; ++k) \
;     dst[n][k] = *reinterpret_cast<const bf16x8*>((char*)SB(b, h) + lds_byte(wc * 32 + n * 16 + fr, k * 32 + fq * 8))
; #define MMA(ai, bj, At, Bq) do { __builtin_amdgcn_s_setprio(1); \
;     _Pragma("unroll") for (int m = 0; m < 4; ++m) _Pragma("unroll") for (int n = 0; n < 2; ++n) _Pragma("unroll") for (int k = 0; k < 2; ++k) \
;       acc[ai][bj][m][n] = __builtin_amdgcn_mfma_f32_16x16x32_bf16(At[m][k], Bq[n][k], acc[ai][bj][m][n], 0, 0, 0); \
;     __builtin_amdgcn_s_setprio(0); } while (0)
; #define WAIT_V(n) asm volatile("s_waitcnt vmcnt(" #n ")" ::: "memory")
; #define WAIT_L(n) asm volatile("s_waitcnt lgkmcnt(" #n ")" ::: "memory")
; #define BAR __builtin_amdgcn_s_barrier()
; __device__ __forceinline__ void gemm256(const u16* __restrict__ A, int lda, const u16* __restrict__ Bt, int ldb, int K,
;                                         f32x4 (&acc)[2][2][4][2], const int g_wid) {
;     ...
;   { LDB(B0, 1, 0); LDA(At, 1, 0); WAIT_V(2); BAR; WAIT_L(0); MMA(0, 0, At, B0); BAR;
;     LDB(B1, 1, 1); WAIT_V(0); BAR; WAIT_L(0); MMA(0, 1, At, B1); BAR;
;     LDA(At, 1, 1); BAR; WAIT_L(0); MMA(1, 0, At, B0); MMA(1, 1, At, B1); BAR; }
;   if (wr == 0) BAR;
	ds_read_b128 v[130:133], v160
	ds_read_b128 v[238:241], v160 offset:1024
	ds_read_b128 v[242:245], v160 offset:2048
	ds_read_b128 v[246:249], v160 offset:3072
	s_waitcnt vmcnt(0)
	s_barrier
	s_waitcnt lgkmcnt(0)
	v_mfma_f32_16x16x32_bf16 v[26:29], v[18:21], v[130:133], v[218:221]
	v_mfma_f32_16x16x32_bf16 v[18:21], v[18:21], v[242:245], v[178:181]
	v_mfma_f32_16x16x32_bf16 v[58:61], v[22:25], v[238:241], v[26:29]
	v_mfma_f32_16x16x32_bf16 v[26:29], v[22:25], v[246:249], v[18:21]
	v_mfma_f32_16x16x32_bf16 v[18:21], v[30:33], v[130:133], v[182:185]
	v_mfma_f32_16x16x32_bf16 v[62:65], v[50:53], v[238:241], v[18:21]
	v_mfma_f32_16x16x32_bf16 v[18:21], v[30:33], v[242:245], v[186:189]
	v_mfma_f32_16x16x32_bf16 v[30:33], v[50:53], v[246:249], v[18:21]
	v_mfma_f32_16x16x32_bf16 v[18:21], v[198:201], v[130:133], v[78:81]
	v_mfma_f32_16x16x32_bf16 v[54:57], v[202:205], v[238:241], v[18:21]
	v_mfma_f32_16x16x32_bf16 v[18:21], v[198:201], v[242:245], v[74:77]
	v_mfma_f32_16x16x32_bf16 v[22:25], v[202:205], v[246:249], v[18:21]
	v_mfma_f32_16x16x32_bf16 v[18:21], v[210:213], v[130:133], v[70:73]
	v_mfma_f32_16x16x32_bf16 v[50:53], v[214:217], v[238:241], v[18:21]
	v_mfma_f32_16x16x32_bf16 v[18:21], v[210:213], v[242:245], v[66:69]
	v_mfma_f32_16x16x32_bf16 v[18:21], v[214:217], v[246:249], v[18:21]
	s_barrier
	ds_read_b128 v[176:179], v145 offset:49152
	ds_read_b128 v[180:183], v145 offset:50176
	ds_read_b128 v[184:187], v144 offset:49152
	ds_read_b128 v[144:147], v144 offset:50176
	ds_read_b128 v[198:201], v143 offset:49152
	ds_read_b128 v[202:205], v143 offset:50176
	ds_read_b128 v[210:213], v142 offset:49152
	ds_read_b128 v[214:217], v142 offset:50176
	s_barrier
	s_waitcnt lgkmcnt(0)
	v_mfma_f32_16x16x32_bf16 v[66:69], v[176:179], v[6:9], v[206:209]
	v_mfma_f32_16x16x32_bf16 v[110:113], v[180:183], v[10:13], v[66:69]
	v_mfma_f32_16x16x32_bf16 v[66:69], v[176:179], v[14:17], v[222:225]
	v_mfma_f32_16x16x32_bf16 v[78:81], v[180:183], v[194:197], v[66:69]
	v_mfma_f32_16x16x32_bf16 v[66:69], v[184:187], v[6:9], v[226:229]
	v_mfma_f32_16x16x32_bf16 v[46:49], v[198:201], v[6:9], v[46:49]
	v_mfma_f32_16x16x32_bf16 v[6:9], v[210:213], v[6:9], v[38:41]
	v_mfma_f32_16x16x32_bf16 v[106:109], v[144:147], v[10:13], v[66:69]
	v_mfma_f32_16x16x32_bf16 v[66:69], v[184:187], v[14:17], v[230:233]
	v_mfma_f32_16x16x32_bf16 v[42:45], v[198:201], v[14:17], v[42:45]
	v_mfma_f32_16x16x32_bf16 v[98:101], v[214:217], v[10:13], v[6:9]
	v_mfma_f32_16x16x32_bf16 v[6:9], v[210:213], v[14:17], v[34:37]
	v_mfma_f32_16x16x32_bf16 v[74:77], v[144:147], v[194:197], v[66:69]
	v_mfma_f32_16x16x32_bf16 v[102:105], v[202:205], v[10:13], v[46:49]
	v_mfma_f32_16x16x32_bf16 v[70:73], v[202:205], v[194:197], v[42:45]
	v_mfma_f32_16x16x32_bf16 v[66:69], v[214:217], v[194:197], v[6:9]
	v_mfma_f32_16x16x32_bf16 v[6:9], v[176:179], v[130:133], v[134:137]
	v_mfma_f32_16x16x32_bf16 v[46:49], v[180:183], v[238:241], v[6:9]
	v_mfma_f32_16x16x32_bf16 v[6:9], v[176:179], v[242:245], v[138:141]
	v_mfma_f32_16x16x32_bf16 v[14:17], v[180:183], v[246:249], v[6:9]
	v_mfma_f32_16x16x32_bf16 v[6:9], v[184:187], v[130:133], v[162:165]
	v_mfma_f32_16x16x32_bf16 v[42:45], v[144:147], v[238:241], v[6:9]
	v_mfma_f32_16x16x32_bf16 v[6:9], v[184:187], v[242:245], v[168:171]
	v_mfma_f32_16x16x32_bf16 v[10:13], v[144:147], v[246:249], v[6:9]
	v_mfma_f32_16x16x32_bf16 v[6:9], v[198:201], v[130:133], v[234:237]
	v_mfma_f32_16x16x32_bf16 v[38:41], v[202:205], v[238:241], v[6:9]
	v_mfma_f32_16x16x32_bf16 v[6:9], v[198:201], v[242:245], v[190:193]
	v_mfma_f32_16x16x32_bf16 v[34:37], v[210:213], v[130:133], v[172:175]
	v_mfma_f32_16x16x32_bf16 v[2:5], v[210:213], v[242:245], v[2:5]
	v_mfma_f32_16x16x32_bf16 v[6:9], v[202:205], v[246:249], v[6:9]
	v_mfma_f32_16x16x32_bf16 v[34:37], v[214:217], v[238:241], v[34:37]
	v_mfma_f32_16x16x32_bf16 v[2:5], v[214:217], v[246:249], v[2:5]
	s_setprio 0
	s_movk_i32 s2, 0x100
	v_cmp_gt_u32_e32 vcc, s2, v0
	s_barrier
	s_and_saveexec_b64 s[2:3], vcc
	s_cbranch_execz .LBB0_344
	s_barrier

; #define hw_tid() ((g_wid << 6) | hw_lane())
; #define STA(P, br, kt) STAGE(P, A, aoff0, aoff1, lda, br, kt)
; #define STB(P, br, kt) STAGE(P, Bt, boff0, boff1, ldb, br, kt)
; #define WAIT_V(n) asm volatile("s_waitcnt vmcnt(" #n ")" ::: "memory")
; #define BAR __builtin_amdgcn_s_barrier()
; __device__ __forceinline__ void gemm256(const u16* __restrict__ A, int lda, const u16* __restrict__ Bt, int ldb, int K,
;                                         f32x4 (&acc)[2][2][4][2], const int g_wid) {
;   int tid = hw_tid(); asm volatile("" : "+v"(tid));
;   const int wid = tid >> 6, lane = tid & 63, wr = wid >> 2, wc = wid & 3, fr = lane & 15, fq = lane >> 4;
;   int r0, c0, r1, c1;
;   stage_rc(tid * 16, r0, c0);
;   stage_rc(tid * 16 + 8192, r1, c1);
;   const int aoff0 = r0 * lda + c0, aoff1 = r1 * lda + c1, boff0 = r0 * ldb + c0, boff1 = r1 * ldb + c1;
;   bf16x8 At[4][2], B0[2][2], B1[2][2];
;   const int nt = K / BK;
;   STB(SB(0, 0), 0, 0); STA(SA(0, 0), 0, 0);
;   STB(SB(0, 1), HALF, 0); STA(SA(0, 1), HALF, 0);
;   if (wr == 1) BAR;
;   WAIT_V(4); BAR;
;   STB(SB(1, 0), 0, 1); STA(SA(1, 0), 0, 1); STB(SB(1, 1), HALF, 1);
;   WAIT_V(6); BAR;
; template <int lda, int K>
; __device__ __forceinline__ void phase_resid(PP p, const int g_wid, const u16* Abase, const u16* Btbase, const float alpha_in) {
;     ...
;     if (bid < 44) {
;       const int pn = bid & 3, ks = bid >> 2;
;       f32x4 acc[2][2][4][2]; ZERO_ACC;
;       gemm256(Btbase + (long)pn * 256 * K + ks * 256, K, Abase + (long)192 * 256 * lda + ks * 256, lda, 256, acc, g_wid);
.LBB0_384:
	s_cmp_lt_i32 s6, 44
	s_cbranch_scc0 .LBB0_390
	s_lshl_b32 s2, s6, 8
	s_and_b32 s2, s2, 0x300
	s_mulk_i32 s2, 0x1600
	s_add_u32 s7, s7, s2
	s_addc_u32 s14, s18, 0
	s_lshl_b32 s2, s6, 6
	s_and_b32 s2, s2, 0xffffff00
	s_ashr_i32 s3, s2, 31
	s_lshl_b64 s[12:13], s[2:3], 1
	s_add_u32 s2, s7, s12
	s_addc_u32 s3, s14, s13
	s_mov_b32 s14, -1
	v_readlane_b32 s10, v254, 63
	v_mbcnt_lo_u32_b32 v0, s14, 0
	v_mbcnt_hi_u32_b32 v0, s14, v0
	v_or_b32_e32 v0, s10, v0
	s_movk_i32 s10, 0xb00
	v_bfe_i32 v3, v0, 27, 1
	v_lshlrev_b32_e32 v15, 4, v0
	v_lshrrev_b32_e32 v3, 22, v3
	v_add_u32_e32 v3, v15, v3
	v_and_b32_e32 v3, 0xfffffc00, v3
	v_sub_u32_e32 v3, v15, v3
	v_lshrrev_b32_e32 v4, 4, v3
	s_waitcnt lgkmcnt(0)
	v_ashrrev_i32_e32 v2, 31, v0
	v_bitop3_b32 v3, v4, v3, 32 bitop3:0x6c
	v_lshrrev_b32_e32 v2, 26, v2
	v_ashrrev_i32_e32 v5, 31, v3
	v_add_u32_e32 v2, v0, v2
	v_lshrrev_b32_e32 v5, 26, v5
	v_ashrrev_i32_e32 v2, 6, v2
	v_add_u32_e32 v5, v3, v5
	v_lshlrev_b32_e32 v4, 3, v2
	v_lshrrev_b32_e32 v6, 6, v5
	v_and_b32_e32 v5, 0xc0, v5
	v_and_b32_e32 v4, 0xfffff0, v4
	v_sub_u32_e32 v3, v3, v5
	v_add_u32_e32 v5, 0x2000, v15
	v_add_u32_e32 v4, v6, v4
	v_ashrrev_i32_e32 v6, 31, v5
	v_lshrrev_b32_e32 v6, 22, v6
	v_add_u32_e32 v6, v5, v6
	v_ashrrev_i32_e32 v6, 10, v6
	v_mul_i32_i24_e32 v7, 0x400, v6
	v_sub_u32_e32 v5, v5, v7
	v_lshrrev_b32_e32 v7, 4, v5
	v_bitop3_b32 v5, v7, v5, 32 bitop3:0x6c
	v_ashrrev_i32_e32 v8, 31, v5
	v_lshrrev_b32_e32 v8, 26, v8
	v_lshlrev_b32_e32 v7, 3, v6
	v_add_u32_e32 v8, v5, v8
	v_lshlrev_b32_e32 v2, 5, v2
	v_and_b32_e32 v7, 0xfffff0, v7
	v_lshrrev_b32_e32 v9, 6, v8
	v_mul_lo_u32 v4, v4, s10
	v_ashrrev_i16_sdwa v3, v151, sext(v3) dst_sel:DWORD dst_unused:UNUSED_PAD src0_sel:DWORD src1_sel:BYTE_0
	v_add_u32_e32 v7, v9, v7
	v_and_b32_e32 v8, 0xc0, v8
	v_and_or_b32 v2, v2, 32, v4
	s_add_u32 s7, s4, s12
	v_lshlrev_b32_e32 v6, 5, v6
	v_sub_u32_e32 v5, v5, v8
	v_add_u32_sdwa v2, v2, sext(v3) dst_sel:DWORD dst_unused:UNUSED_PAD src0_sel:DWORD src1_sel:WORD_0
	v_mul_lo_u32 v3, v7, s10
	s_addc_u32 s15, s5, s13
	v_ashrrev_i16_sdwa v5, v151, sext(v5) dst_sel:DWORD dst_unused:UNUSED_PAD src0_sel:DWORD src1_sel:BYTE_0
	v_and_or_b32 v3, v6, 32, v3
	v_readlane_b32 s10, v254, 40
	s_add_u32 s12, s7, 0x10800000
	v_add_u32_sdwa v4, v3, sext(v5) dst_sel:DWORD dst_unused:UNUSED_PAD src0_sel:DWORD src1_sel:WORD_0
	v_ashrrev_i32_e32 v3, 31, v2
	v_add_u32_e32 v22, s10, v15
	s_addc_u32 s13, s15, 0
	v_lshlrev_b64 v[2:3], 1, v[2:3]
	v_readfirstlane_b32 s14, v22
	v_ashrrev_i32_e32 v5, 31, v4
	v_add_u32_e32 v23, 0x2000, v22
	v_lshl_add_u64 v[10:11], s[12:13], 0, v[2:3]
	s_mov_b32 m0, s14
	v_lshlrev_b64 v[4:5], 1, v[4:5]
	v_readfirstlane_b32 s14, v23
	v_add_u32_e32 v20, 0, v15
	global_load_lds_dwordx4 v[10:11], off
	v_lshl_add_u64 v[12:13], s[12:13], 0, v[4:5]
	s_mov_b32 m0, s14
	v_readfirstlane_b32 s14, v20
	v_add_u32_e32 v21, 0x2000, v20
	global_load_lds_dwordx4 v[12:13], off
	v_lshl_add_u64 v[6:7], s[2:3], 0, v[2:3]
	s_mov_b32 m0, s14
	v_readfirstlane_b32 s14, v21
	global_load_lds_dwordx4 v[6:7], off
	s_mov_b32 m0, s14
	s_add_u32 s14, s7, 0x108b0000
	v_readlane_b32 s7, v254, 41
	v_lshl_add_u64 v[8:9], s[2:3], 0, v[4:5]
	s_addc_u32 s15, s15, 0
	v_add_u32_e32 v18, s7, v15
	v_add_u32_e32 v19, 0x2000, v18
	v_readfirstlane_b32 s7, v18
	global_load_lds_dwordx4 v[8:9], off
	v_lshl_add_u64 v[16:17], s[14:15], 0, v[2:3]
	s_mov_b32 m0, s7
	v_readfirstlane_b32 s7, v19
	global_load_lds_dwordx4 v[16:17], off
	v_lshl_add_u64 v[16:17], s[14:15], 0, v[4:5]
	s_mov_b32 m0, s7
	s_add_u32 s14, s2, 0xb0000
	global_load_lds_dwordx4 v[16:17], off
	v_add_u32_e32 v16, 0x4000, v20
	s_addc_u32 s15, s3, 0
	v_readfirstlane_b32 s7, v16
	v_add_u32_e32 v17, 0x6000, v20
	v_lshl_add_u64 v[24:25], s[14:15], 0, v[2:3]
	s_mov_b32 m0, s7
	v_readfirstlane_b32 s7, v17
	global_load_lds_dwordx4 v[24:25], off
	v_lshl_add_u64 v[24:25], s[14:15], 0, v[4:5]
	s_mov_b32 m0, s7
	v_ashrrev_i32_e32 v14, 8, v0
	global_load_lds_dwordx4 v[24:25], off
	v_cmp_eq_u32_e32 vcc, 1, v14
	s_and_saveexec_b64 s[14:15], vcc
	s_cbranch_execz .LBB0_387
	s_setprio 3
	s_barrier
.LBB0_387:
	s_or_b64 exec, exec, s[14:15]
	v_readlane_b32 s11, v254, 42
	s_mov_b64 s[14:15], 0x80
	v_lshl_add_u64 v[24:25], v[10:11], 0, s[14:15]
	v_add_u32_e32 v28, s11, v15
	s_waitcnt vmcnt(4)
	s_barrier
	v_readfirstlane_b32 s19, v28
	v_add_u32_e32 v28, 0x2000, v28
	s_mov_b32 m0, s19
	v_readfirstlane_b32 s18, v28
	v_add_u32_e32 v28, 0x8000, v20
	global_load_lds_dwordx4 v[24:25], off
	v_lshl_add_u64 v[24:25], v[12:13], 0, s[14:15]
	s_mov_b32 m0, s18
	v_readfirstlane_b32 s16, v28
	global_load_lds_dwordx4 v[24:25], off
	v_lshl_add_u64 v[24:25], v[6:7], 0, s[14:15]
	s_mov_b32 m0, s16
	v_add_u32_e32 v28, 0xa000, v20
	v_readlane_b32 s17, v254, 43
	global_load_lds_dwordx4 v[24:25], off
	v_lshl_add_u64 v[24:25], v[8:9], 0, s[14:15]
	v_readfirstlane_b32 s15, v28
	s_add_u32 s20, s12, 0xb0080
	v_add_u32_e32 v15, s17, v15
	s_mov_b32 m0, s15
	s_addc_u32 s21, s13, 0
	v_readfirstlane_b32 s14, v15
	v_add_u32_e32 v15, 0x2000, v15
	global_load_lds_dwordx4 v[24:25], off
	v_lshl_add_u64 v[24:25], s[20:21], 0, v[2:3]
	s_mov_b32 m0, s14
	v_readfirstlane_b32 s7, v15
	global_load_lds_dwordx4 v[24:25], off
	v_lshl_add_u64 v[24:25], s[20:21], 0, v[4:5]
	s_mov_b32 m0, s7
	v_and_b32_e32 v26, 15, v0
	global_load_lds_dwordx4 v[24:25], off
	v_lshlrev_b32_e32 v24, 2, v0
	v_and_b32_e32 v27, 48, v0
	v_lshlrev_b32_e32 v15, 6, v26
	v_and_b32_e32 v24, 32, v24
	v_lshlrev_b32_e32 v26, 6, v0
	v_bitop3_b32 v25, v15, v24, v27 bitop3:0x36
	v_and_b32_e32 v28, 0x3000, v26
	v_readlane_b32 s10, v254, 40
	v_and_b32_e32 v26, 0x3c0, v26
	v_lshlrev_b32_e32 v14, 13, v14
	v_add3_u32 v159, s10, v25, v28
	v_bitop3_b32 v24, v26, v24, v27 bitop3:0x36
	v_readlane_b32 s10, v254, 41
	s_waitcnt vmcnt(6)
	s_barrier
; #define STA(P, br, kt) STAGE(P, A, aoff0, aoff1, lda, br, kt)
; #define STB(P, br, kt) STAGE(P, Bt, boff0, boff1, ldb, br, kt)
; #define LDA(dst, b, h) _Pragma("unroll") for (int m = 0; m < 4; ++m) _Pragma("unroll") for (int k = 0; k < 2; ++k) \
;     dst[m][k] = *reinterpret_cast<const bf16x8*>((char*)SA(b, h) + lds_byte(wr * 64 + m * 16 + fr, k * 32 + fq * 8))
; #define LDB(dst, b, h) _Pragma("unroll") for (int n = 0; n < 2; ++n) _Pragma("unroll") for (int k = 0; k < 2; ++k) \
;     dst[n][k] = *reinterpret_cast<const bf16x8*>((char*)SB(b, h) + lds_byte(wc * 32 + n * 16 + fr, k * 32 + fq * 8))
; #define MMA(ai, bj, At, Bq) do { __builtin_amdgcn_s_setprio(1); \
;     _Pragma("unroll") for (int m = 0; m < 4; ++m) _Pragma("unroll") for (int n = 0; n < 2; ++n) _Pragma("unroll") for (int k = 0; k < 2; ++k) \
;       acc[ai][bj][m][n] = __builtin_amdgcn_mfma_f32_16x16x32_bf16(At[m][k], Bq[n][k], acc[ai][bj][m][n], 0, 0, 0); \
;     __builtin_amdgcn_s_setprio(0); } while (0)
; #define WAIT_L(n) asm volatile("s_waitcnt lgkmcnt(" #n ")" ::: "memory")
; #define BAR __builtin_amdgcn_s_barrier()
; #define SCHED __builtin_amdgcn_sched_barrier(0)
; __device__ __forceinline__ void gemm256(const u16* __restrict__ A, int lda, const u16* __restrict__ Bt, int ldb, int K,
;                                         f32x4 (&acc)[2][2][4][2], const int g_wid) {
;     ...
;   for (int t = 0; t < nt - 2; t += 2) {
;     LDB(B0, 0, 0); SCHED; LDA(At, 0, 0); STA(SA(1, 1), HALF, t + 1);
;     WAIT_L(8); BAR; WAIT_L(0); MMA(0, 0, At, B0); BAR; SCHED;
;     LDB(B1, 0, 1); STB(SB(0, 0), 0, t + 2);
;     BAR; WAIT_L(0); MMA(0, 1, At, B1); BAR;
;     LDA(At, 0, 1); STA(SA(0, 0), 0, t + 2);
;     BAR; WAIT_L(0); MMA(1, 0, At, B0); BAR; SCHED;
;     STB(SB(0, 1), HALF, t + 2);
	v_add3_u32 v15, 0, v25, v14
	v_add3_u32 v14, 0, v24, v14
	v_add3_u32 v220, s10, v25, v28
	v_add3_u32 v221, s11, v25, v28
	v_add3_u32 v236, s17, v25, v28
	ds_read_b128 v[24:27], v159
	ds_read_b128 v[28:31], v159 offset:1024
	ds_read_b128 v[32:35], v159 offset:2048
	ds_read_b128 v[36:39], v159 offset:3072
	s_add_u32 s22, s2, 0xb0080
	v_add_u32_e32 v74, 0xc000, v20
	s_addc_u32 s23, s3, 0
	v_readfirstlane_b32 s20, v74
	v_add_u32_e32 v74, 0xe000, v20
	v_lshl_add_u64 v[72:73], s[22:23], 0, v[2:3]
	s_mov_b32 m0, s20
	v_readfirstlane_b32 s17, v74
	ds_read_b128 v[40:43], v15
	ds_read_b128 v[44:47], v15 offset:1024
	ds_read_b128 v[48:51], v14 offset:2048
	ds_read_b128 v[52:55], v14 offset:3072
	ds_read_b128 v[56:59], v14 offset:4096
	ds_read_b128 v[60:63], v14 offset:5120
	ds_read_b128 v[64:67], v14 offset:6144
	ds_read_b128 v[68:71], v14 offset:7168
	global_load_lds_dwordx4 v[72:73], off
	v_lshl_add_u64 v[72:73], s[22:23], 0, v[4:5]
	s_mov_b32 m0, s17
	s_nop 0
	global_load_lds_dwordx4 v[72:73], off
	s_waitcnt lgkmcnt(8)
	s_barrier
	s_waitcnt lgkmcnt(0)
	v_mfma_f32_16x16x32_bf16 v[72:75], v[40:43], v[24:27], 0
	v_mfma_f32_16x16x32_bf16 v[76:79], v[40:43], v[32:35], 0
	v_mfma_f32_16x16x32_bf16 v[80:83], v[48:51], v[24:27], 0
	v_mfma_f32_16x16x32_bf16 v[84:87], v[48:51], v[32:35], 0
	v_mfma_f32_16x16x32_bf16 v[88:91], v[56:59], v[24:27], 0
	v_mfma_f32_16x16x32_bf16 v[92:95], v[56:59], v[32:35], 0
	v_mfma_f32_16x16x32_bf16 v[96:99], v[64:67], v[24:27], 0
	v_mfma_f32_16x16x32_bf16 v[100:103], v[64:67], v[32:35], 0
	v_mfma_f32_16x16x32_bf16 v[72:75], v[44:47], v[28:31], v[72:75]
	v_mfma_f32_16x16x32_bf16 v[76:79], v[44:47], v[36:39], v[76:79]
	v_mfma_f32_16x16x32_bf16 v[80:83], v[52:55], v[28:31], v[80:83]
	v_mfma_f32_16x16x32_bf16 v[84:87], v[52:55], v[36:39], v[84:87]
	v_mfma_f32_16x16x32_bf16 v[88:91], v[60:63], v[28:31], v[88:91]
	v_mfma_f32_16x16x32_bf16 v[92:95], v[60:63], v[36:39], v[92:95]
	v_mfma_f32_16x16x32_bf16 v[96:99], v[68:71], v[28:31], v[96:99]
	v_mfma_f32_16x16x32_bf16 v[100:103], v[68:71], v[36:39], v[100:103]
	s_barrier
	v_readfirstlane_b32 s21, v22
	v_lshl_add_u64 v[120:121], v[10:11], 0, s[74:75]
	s_mov_b32 m0, s21
	v_readfirstlane_b32 s21, v23
	ds_read_b128 v[104:107], v220
	ds_read_b128 v[108:111], v220 offset:1024
	ds_read_b128 v[112:115], v220 offset:2048
	ds_read_b128 v[116:119], v220 offset:3072
	global_load_lds_dwordx4 v[120:121], off
	v_lshl_add_u64 v[120:121], v[12:13], 0, s[74:75]
	s_mov_b32 m0, s21
	s_nop 0
	global_load_lds_dwordx4 v[120:121], off
	s_barrier
	s_waitcnt lgkmcnt(0)
	v_mfma_f32_16x16x32_bf16 v[120:123], v[40:43], v[104:107], 0
	v_mfma_f32_16x16x32_bf16 v[40:43], v[40:43], v[112:115], 0
	v_mfma_f32_16x16x32_bf16 v[120:123], v[44:47], v[108:111], v[120:123]
	v_mfma_f32_16x16x32_bf16 v[40:43], v[44:47], v[116:119], v[40:43]
	v_mfma_f32_16x16x32_bf16 v[44:47], v[48:51], v[104:107], 0
	v_mfma_f32_16x16x32_bf16 v[48:51], v[48:51], v[112:115], 0
	v_mfma_f32_16x16x32_bf16 v[44:47], v[52:55], v[108:111], v[44:47]
	v_mfma_f32_16x16x32_bf16 v[48:51], v[52:55], v[116:119], v[48:51]
	v_mfma_f32_16x16x32_bf16 v[52:55], v[56:59], v[104:107], 0
	v_mfma_f32_16x16x32_bf16 v[56:59], v[56:59], v[112:115], 0
	v_mfma_f32_16x16x32_bf16 v[52:55], v[60:63], v[108:111], v[52:55]
	v_mfma_f32_16x16x32_bf16 v[56:59], v[60:63], v[116:119], v[56:59]
	v_mfma_f32_16x16x32_bf16 v[60:63], v[64:67], v[104:107], 0
	v_mfma_f32_16x16x32_bf16 v[64:67], v[64:67], v[112:115], 0
	v_mfma_f32_16x16x32_bf16 v[60:63], v[68:71], v[108:111], v[60:63]
	v_mfma_f32_16x16x32_bf16 v[64:67], v[68:71], v[116:119], v[64:67]
	v_readfirstlane_b32 s21, v20
	v_lshl_add_u64 v[22:23], v[6:7], 0, s[74:75]
	s_mov_b32 m0, s21
	v_readfirstlane_b32 s21, v21
	s_barrier
	ds_read_b128 v[68:71], v15 offset:16384
	ds_read_b128 v[124:127], v15 offset:17408
	ds_read_b128 v[128:131], v14 offset:18432
	ds_read_b128 v[132:135], v14 offset:19456
	ds_read_b128 v[136:139], v14 offset:20480
	ds_read_b128 v[140:143], v14 offset:21504
	ds_read_b128 v[144:147], v14 offset:22528
	ds_read_b128 v[160:163], v14 offset:23552
	global_load_lds_dwordx4 v[22:23], off
	v_lshl_add_u64 v[22:23], v[8:9], 0, s[74:75]
	s_mov_b32 m0, s21
	s_nop 0
	global_load_lds_dwordx4 v[22:23], off
	s_barrier
	s_waitcnt lgkmcnt(0)
	v_mfma_f32_16x16x32_bf16 v[20:23], v[68:71], v[24:27], 0
	v_mfma_f32_16x16x32_bf16 v[168:171], v[128:131], v[24:27], 0
	v_mfma_f32_16x16x32_bf16 v[176:179], v[136:139], v[24:27], 0
	v_mfma_f32_16x16x32_bf16 v[24:27], v[144:147], v[24:27], 0
	v_mfma_f32_16x16x32_bf16 v[20:23], v[124:127], v[28:31], v[20:23]
	v_mfma_f32_16x16x32_bf16 v[168:171], v[132:135], v[28:31], v[168:171]
	v_mfma_f32_16x16x32_bf16 v[176:179], v[140:143], v[28:31], v[176:179]
	v_mfma_f32_16x16x32_bf16 v[24:27], v[160:163], v[28:31], v[24:27]
	v_mfma_f32_16x16x32_bf16 v[28:31], v[144:147], v[32:35], 0
	v_mfma_f32_16x16x32_bf16 v[164:167], v[68:71], v[32:35], 0
	v_mfma_f32_16x16x32_bf16 v[172:175], v[128:131], v[32:35], 0
	v_mfma_f32_16x16x32_bf16 v[180:183], v[136:139], v[32:35], 0
	v_mfma_f32_16x16x32_bf16 v[28:31], v[160:163], v[36:39], v[28:31]
	v_mfma_f32_16x16x32_bf16 v[164:167], v[124:127], v[36:39], v[164:167]
	v_mfma_f32_16x16x32_bf16 v[172:175], v[132:135], v[36:39], v[172:175]
	v_mfma_f32_16x16x32_bf16 v[180:183], v[140:143], v[36:39], v[180:183]
	s_barrier
	s_add_u32 s22, s12, 0xb0100
	s_addc_u32 s23, s13, 0
	v_readfirstlane_b32 s21, v18
	v_lshl_add_u64 v[32:33], s[22:23], 0, v[2:3]
	s_mov_b32 m0, s21
	v_readfirstlane_b32 s21, v19
	global_load_lds_dwordx4 v[32:33], off
	v_lshl_add_u64 v[32:33], s[22:23], 0, v[4:5]
	s_mov_b32 m0, s21
	s_nop 0
	global_load_lds_dwordx4 v[32:33], off
	s_waitcnt vmcnt(6)
	s_barrier
; #define STA(P, br, kt) STAGE(P, A, aoff0, aoff1, lda, br, kt)
; #define STB(P, br, kt) STAGE(P, Bt, boff0, boff1, ldb, br, kt)
; #define LDA(dst, b, h) _Pragma("unroll") for (int m = 0; m < 4; ++m) _Pragma("unroll") for (int k = 0; k < 2; ++k) \
;     dst[m][k] = *reinterpret_cast<const bf16x8*>((char*)SA(b, h) + lds_byte(wr * 64 + m * 16 + fr, k * 32 + fq * 8))
; #define LDB(dst, b, h) _Pragma("unroll") for (int n = 0; n < 2; ++n) _Pragma("unroll") for (int k = 0; k < 2; ++k) \
;     dst[n][k] = *reinterpret_cast<const bf16x8*>((char*)SB(b, h) + lds_byte(wc * 32 + n * 16 + fr, k * 32 + fq * 8))
; #define MMA(ai, bj, At, Bq) do { __builtin_amdgcn_s_setprio(1); \
;     _Pragma("unroll") for (int m = 0; m < 4; ++m) _Pragma("unroll") for (int n = 0; n < 2; ++n) _Pragma("unroll") for (int k = 0; k < 2; ++k) \
;       acc[ai][bj][m][n] = __builtin_amdgcn_mfma_f32_16x16x32_bf16(At[m][k], Bq[n][k], acc[ai][bj][m][n], 0, 0, 0); \
;     __builtin_amdgcn_s_setprio(0); } while (0)
; #define WAIT_V(n) asm volatile("s_waitcnt vmcnt(" #n ")" ::: "memory")
; #define WAIT_L(n) asm volatile("s_waitcnt lgkmcnt(" #n ")" ::: "memory")
; #define BAR __builtin_amdgcn_s_barrier()
; #define SCHED __builtin_amdgcn_sched_barrier(0)
; __device__ __forceinline__ void gemm256(const u16* __restrict__ A, int lda, const u16* __restrict__ Bt, int ldb, int K,
;                                         f32x4 (&acc)[2][2][4][2], const int g_wid) {
;     ...
;     WAIT_V(6); BAR; MMA(1, 1, At, B1); BAR;
;     LDB(B0, 1, 0); SCHED; LDA(At, 1, 0); STA(SA(0, 1), HALF, t + 2);
;     WAIT_L(8); BAR; WAIT_L(0); MMA(0, 0, At, B0); BAR; SCHED;
;     LDB(B1, 1, 1); STB(SB(1, 0), 0, t + 3);
;     BAR; WAIT_L(0); MMA(0, 1, At, B1); BAR;
	v_mfma_f32_16x16x32_bf16 v[32:35], v[68:71], v[104:107], 0
	v_mfma_f32_16x16x32_bf16 v[36:39], v[68:71], v[112:115], 0
	v_mfma_f32_16x16x32_bf16 v[32:35], v[124:127], v[108:111], v[32:35]
	v_mfma_f32_16x16x32_bf16 v[36:39], v[124:127], v[116:119], v[36:39]
	v_mfma_f32_16x16x32_bf16 v[68:71], v[128:131], v[104:107], 0
	v_mfma_f32_16x16x32_bf16 v[124:127], v[128:131], v[112:115], 0
	v_mfma_f32_16x16x32_bf16 v[128:131], v[136:139], v[104:107], 0
	v_mfma_f32_16x16x32_bf16 v[104:107], v[144:147], v[104:107], 0
	v_mfma_f32_16x16x32_bf16 v[68:71], v[132:135], v[108:111], v[68:71]
	v_mfma_f32_16x16x32_bf16 v[128:131], v[140:143], v[108:111], v[128:131]
	v_mfma_f32_16x16x32_bf16 v[104:107], v[160:163], v[108:111], v[104:107]
	v_mfma_f32_16x16x32_bf16 v[108:111], v[144:147], v[112:115], 0
	v_mfma_f32_16x16x32_bf16 v[124:127], v[132:135], v[116:119], v[124:127]
	v_mfma_f32_16x16x32_bf16 v[132:135], v[136:139], v[112:115], 0
	v_mfma_f32_16x16x32_bf16 v[108:111], v[160:163], v[116:119], v[108:111]
	v_mfma_f32_16x16x32_bf16 v[132:135], v[140:143], v[116:119], v[132:135]
	s_barrier
	ds_read_b128 v[112:115], v221
	ds_read_b128 v[116:119], v221 offset:1024
	ds_read_b128 v[136:139], v221 offset:2048
	ds_read_b128 v[140:143], v221 offset:3072
	s_add_u32 s22, s2, 0xb0100
	s_addc_u32 s23, s3, 0
	v_readfirstlane_b32 s21, v16
	v_lshl_add_u64 v[18:19], s[22:23], 0, v[2:3]
	s_mov_b32 m0, s21
	v_readfirstlane_b32 s21, v17
	ds_read_b128 v[144:147], v15 offset:32768
	ds_read_b128 v[160:163], v15 offset:33792
	ds_read_b128 v[184:187], v14 offset:34816
	ds_read_b128 v[188:191], v14 offset:35840
	ds_read_b128 v[192:195], v14 offset:36864
	ds_read_b128 v[196:199], v14 offset:37888
	ds_read_b128 v[200:203], v14 offset:38912
	ds_read_b128 v[204:207], v14 offset:39936
	global_load_lds_dwordx4 v[18:19], off
	v_lshl_add_u64 v[18:19], s[22:23], 0, v[4:5]
	s_mov_b32 m0, s21
	s_nop 0
	global_load_lds_dwordx4 v[18:19], off
	s_waitcnt lgkmcnt(8)
	s_barrier
	s_waitcnt lgkmcnt(0)
	v_mfma_f32_16x16x32_bf16 v[16:19], v[144:147], v[112:115], v[72:75]
	v_mfma_f32_16x16x32_bf16 v[72:75], v[144:147], v[136:139], v[76:79]
	v_mfma_f32_16x16x32_bf16 v[76:79], v[184:187], v[112:115], v[80:83]
	v_mfma_f32_16x16x32_bf16 v[80:83], v[184:187], v[136:139], v[84:87]
	v_mfma_f32_16x16x32_bf16 v[84:87], v[192:195], v[112:115], v[88:91]
	v_mfma_f32_16x16x32_bf16 v[88:91], v[192:195], v[136:139], v[92:95]
	v_mfma_f32_16x16x32_bf16 v[92:95], v[200:203], v[112:115], v[96:99]
	v_mfma_f32_16x16x32_bf16 v[96:99], v[200:203], v[136:139], v[100:103]
	v_mfma_f32_16x16x32_bf16 v[16:19], v[160:163], v[116:119], v[16:19]
	v_mfma_f32_16x16x32_bf16 v[72:75], v[160:163], v[140:143], v[72:75]
	v_mfma_f32_16x16x32_bf16 v[76:79], v[188:191], v[116:119], v[76:79]
	v_mfma_f32_16x16x32_bf16 v[80:83], v[188:191], v[140:143], v[80:83]
	v_mfma_f32_16x16x32_bf16 v[84:87], v[196:199], v[116:119], v[84:87]
	v_mfma_f32_16x16x32_bf16 v[88:91], v[196:199], v[140:143], v[88:91]
	v_mfma_f32_16x16x32_bf16 v[92:95], v[204:207], v[116:119], v[92:95]
	v_mfma_f32_16x16x32_bf16 v[96:99], v[204:207], v[140:143], v[96:99]
	s_barrier
	s_mov_b32 m0, s19
	v_lshl_add_u64 v[10:11], v[10:11], 0, s[82:83]
	ds_read_b128 v[100:103], v236
	ds_read_b128 v[208:211], v236 offset:1024
	ds_read_b128 v[212:215], v236 offset:2048
	ds_read_b128 v[216:219], v236 offset:3072
	global_load_lds_dwordx4 v[10:11], off
	v_lshl_add_u64 v[10:11], v[12:13], 0, s[82:83]
	s_mov_b32 m0, s18
	s_nop 0
	global_load_lds_dwordx4 v[10:11], off
	s_barrier
	s_waitcnt lgkmcnt(0)
	v_mfma_f32_16x16x32_bf16 v[10:13], v[144:147], v[100:103], v[120:123]
	v_mfma_f32_16x16x32_bf16 v[40:43], v[144:147], v[212:215], v[40:43]
	v_mfma_f32_16x16x32_bf16 v[44:47], v[184:187], v[100:103], v[44:47]
	v_mfma_f32_16x16x32_bf16 v[48:51], v[184:187], v[212:215], v[48:51]
	v_mfma_f32_16x16x32_bf16 v[52:55], v[192:195], v[100:103], v[52:55]
	v_mfma_f32_16x16x32_bf16 v[56:59], v[192:195], v[212:215], v[56:59]
	v_mfma_f32_16x16x32_bf16 v[60:63], v[200:203], v[100:103], v[60:63]
	v_mfma_f32_16x16x32_bf16 v[64:67], v[200:203], v[212:215], v[64:67]
	v_mfma_f32_16x16x32_bf16 v[10:13], v[160:163], v[208:211], v[10:13]
	v_mfma_f32_16x16x32_bf16 v[40:43], v[160:163], v[216:219], v[40:43]
	v_mfma_f32_16x16x32_bf16 v[44:47], v[188:191], v[208:211], v[44:47]
	v_mfma_f32_16x16x32_bf16 v[48:51], v[188:191], v[216:219], v[48:51]
	v_mfma_f32_16x16x32_bf16 v[52:55], v[196:199], v[208:211], v[52:55]
	v_mfma_f32_16x16x32_bf16 v[56:59], v[196:199], v[216:219], v[56:59]
	v_mfma_f32_16x16x32_bf16 v[60:63], v[204:207], v[208:211], v[60:63]
	v_mfma_f32_16x16x32_bf16 v[64:67], v[204:207], v[216:219], v[64:67]
	s_mov_b32 m0, s16
	v_lshl_add_u64 v[6:7], v[6:7], 0, s[82:83]
	s_barrier
	ds_read_b128 v[120:123], v15 offset:49152
	ds_read_b128 v[144:147], v15 offset:50176
	ds_read_b128 v[160:163], v14 offset:51200
	ds_read_b128 v[184:187], v14 offset:52224
	ds_read_b128 v[188:191], v14 offset:53248
	ds_read_b128 v[192:195], v14 offset:54272
	ds_read_b128 v[196:199], v14 offset:55296
	ds_read_b128 v[200:203], v14 offset:56320
	global_load_lds_dwordx4 v[6:7], off
	v_lshl_add_u64 v[6:7], v[8:9], 0, s[82:83]
	s_mov_b32 m0, s15
	s_nop 0
	global_load_lds_dwordx4 v[6:7], off
	s_barrier
; #define STA(P, br, kt) STAGE(P, A, aoff0, aoff1, lda, br, kt)
; #define STB(P, br, kt) STAGE(P, Bt, boff0, boff1, ldb, br, kt)
; #define LDA(dst, b, h) _Pragma("unroll") for (int m = 0; m < 4; ++m) _Pragma("unroll") for (int k = 0; k < 2; ++k) \
;     dst[m][k] = *reinterpret_cast<const bf16x8*>((char*)SA(b, h) + lds_byte(wr * 64 + m * 16 + fr, k * 32 + fq * 8))
; #define LDB(dst, b, h) _Pragma("unroll") for (int n = 0; n < 2; ++n) _Pragma("unroll") for (int k = 0; k < 2; ++k) \
;     dst[n][k] = *reinterpret_cast<const bf16x8*>((char*)SB(b, h) + lds_byte(wc * 32 + n * 16 + fr, k * 32 + fq * 8))
; #define MMA(ai, bj, At, Bq) do { __builtin_amdgcn_s_setprio(1); \
;     _Pragma("unroll") for (int m = 0; m < 4; ++m) _Pragma("unroll") for (int n = 0; n < 2; ++n) _Pragma("unroll") for (int k = 0; k < 2; ++k) \
;       acc[ai][bj][m][n] = __builtin_amdgcn_mfma_f32_16x16x32_bf16(At[m][k], Bq[n][k], acc[ai][bj][m][n], 0, 0, 0); \
;     __builtin_amdgcn_s_setprio(0); } while (0)
; #define WAIT_V(n) asm volatile("s_waitcnt vmcnt(" #n ")" ::: "memory")
; #define WAIT_L(n) asm volatile("s_waitcnt lgkmcnt(" #n ")" ::: "memory")
; #define BAR __builtin_amdgcn_s_barrier()
; #define SCHED __builtin_amdgcn_sched_barrier(0)
; __device__ __forceinline__ void gemm256(const u16* __restrict__ A, int lda, const u16* __restrict__ Bt, int ldb, int K,
;                                         f32x4 (&acc)[2][2][4][2], const int g_wid) {
;     ...
;     LDA(At, 1, 1); STA(SA(1, 0), 0, t + 3);
;     BAR; WAIT_L(0); MMA(1, 0, At, B0); BAR; SCHED;
;     STB(SB(1, 1), HALF, t + 3);
;     WAIT_V(6); BAR; MMA(1, 1, At, B1); BAR;
;   }
;   { LDB(B0, 0, 0); LDA(At, 0, 0); STA(SA(1, 1), HALF, nt - 1);
;     BAR; WAIT_L(0); MMA(0, 0, At, B0); BAR;
;     LDB(B1, 0, 1); BAR; WAIT_L(0); MMA(0, 1, At, B1); BAR;
	s_waitcnt lgkmcnt(0)
	v_mfma_f32_16x16x32_bf16 v[6:9], v[120:123], v[112:115], v[20:23]
	v_mfma_f32_16x16x32_bf16 v[20:23], v[120:123], v[136:139], v[164:167]
	v_mfma_f32_16x16x32_bf16 v[24:27], v[196:199], v[112:115], v[24:27]
	v_mfma_f32_16x16x32_bf16 v[28:31], v[196:199], v[136:139], v[28:31]
	v_mfma_f32_16x16x32_bf16 v[6:9], v[144:147], v[116:119], v[6:9]
	v_mfma_f32_16x16x32_bf16 v[20:23], v[144:147], v[140:143], v[20:23]
	v_mfma_f32_16x16x32_bf16 v[164:167], v[160:163], v[112:115], v[168:171]
	v_mfma_f32_16x16x32_bf16 v[168:171], v[160:163], v[136:139], v[172:175]
	v_mfma_f32_16x16x32_bf16 v[172:175], v[188:191], v[112:115], v[176:179]
	v_mfma_f32_16x16x32_bf16 v[176:179], v[188:191], v[136:139], v[180:183]
	v_mfma_f32_16x16x32_bf16 v[24:27], v[200:203], v[116:119], v[24:27]
	v_mfma_f32_16x16x32_bf16 v[28:31], v[200:203], v[140:143], v[28:31]
	v_mfma_f32_16x16x32_bf16 v[164:167], v[184:187], v[116:119], v[164:167]
	v_mfma_f32_16x16x32_bf16 v[168:171], v[184:187], v[140:143], v[168:171]
	v_mfma_f32_16x16x32_bf16 v[172:175], v[192:195], v[116:119], v[172:175]
	v_mfma_f32_16x16x32_bf16 v[176:179], v[192:195], v[140:143], v[176:179]
	s_barrier
	s_add_u32 s12, s12, 0xb0180
	s_addc_u32 s13, s13, 0
	s_mov_b32 m0, s14
	v_lshl_add_u64 v[112:113], s[12:13], 0, v[2:3]
	global_load_lds_dwordx4 v[112:113], off
	v_lshl_add_u64 v[112:113], s[12:13], 0, v[4:5]
	s_mov_b32 m0, s7
	s_nop 0
	global_load_lds_dwordx4 v[112:113], off
	s_waitcnt vmcnt(6)
	s_barrier
	v_mfma_f32_16x16x32_bf16 v[32:35], v[120:123], v[100:103], v[32:35]
	v_mfma_f32_16x16x32_bf16 v[36:39], v[120:123], v[212:215], v[36:39]
	v_mfma_f32_16x16x32_bf16 v[68:71], v[160:163], v[100:103], v[68:71]
	v_mfma_f32_16x16x32_bf16 v[112:115], v[160:163], v[212:215], v[124:127]
	v_mfma_f32_16x16x32_bf16 v[116:119], v[188:191], v[100:103], v[128:131]
	v_mfma_f32_16x16x32_bf16 v[120:123], v[188:191], v[212:215], v[132:135]
	v_mfma_f32_16x16x32_bf16 v[100:103], v[196:199], v[100:103], v[104:107]
	v_mfma_f32_16x16x32_bf16 v[104:107], v[196:199], v[212:215], v[108:111]
	v_mfma_f32_16x16x32_bf16 v[32:35], v[144:147], v[208:211], v[32:35]
	v_mfma_f32_16x16x32_bf16 v[36:39], v[144:147], v[216:219], v[36:39]
	v_mfma_f32_16x16x32_bf16 v[68:71], v[184:187], v[208:211], v[68:71]
	v_mfma_f32_16x16x32_bf16 v[112:115], v[184:187], v[216:219], v[112:115]
	v_mfma_f32_16x16x32_bf16 v[116:119], v[192:195], v[208:211], v[116:119]
	v_mfma_f32_16x16x32_bf16 v[120:123], v[192:195], v[216:219], v[120:123]
	v_mfma_f32_16x16x32_bf16 v[100:103], v[200:203], v[208:211], v[100:103]
	v_mfma_f32_16x16x32_bf16 v[104:107], v[200:203], v[216:219], v[104:107]
	s_add_u32 s2, s2, 0xb0180
	s_addc_u32 s3, s3, 0
	s_mov_b32 m0, s20
	v_lshl_add_u64 v[2:3], s[2:3], 0, v[2:3]
	s_barrier
	ds_read_b128 v[108:111], v159
	ds_read_b128 v[124:127], v159 offset:1024
	ds_read_b128 v[128:131], v159 offset:2048
	ds_read_b128 v[132:135], v159 offset:3072
	ds_read_b128 v[136:139], v15
	ds_read_b128 v[140:143], v15 offset:1024
	ds_read_b128 v[144:147], v14 offset:2048
	ds_read_b128 v[160:163], v14 offset:3072
	ds_read_b128 v[180:183], v14 offset:4096
	ds_read_b128 v[184:187], v14 offset:5120
	ds_read_b128 v[188:191], v14 offset:6144
	ds_read_b128 v[192:195], v14 offset:7168
	global_load_lds_dwordx4 v[2:3], off
	v_lshl_add_u64 v[2:3], s[2:3], 0, v[4:5]
	s_mov_b32 m0, s17
	s_nop 0
	global_load_lds_dwordx4 v[2:3], off
	s_barrier
	s_waitcnt lgkmcnt(0)
	v_mfma_f32_16x16x32_bf16 v[2:5], v[136:139], v[108:111], v[16:19]
	v_mfma_f32_16x16x32_bf16 v[16:19], v[136:139], v[128:131], v[72:75]
	v_mfma_f32_16x16x32_bf16 v[72:75], v[144:147], v[108:111], v[76:79]
	v_mfma_f32_16x16x32_bf16 v[76:79], v[144:147], v[128:131], v[80:83]
	v_mfma_f32_16x16x32_bf16 v[80:83], v[180:183], v[108:111], v[84:87]
	v_mfma_f32_16x16x32_bf16 v[84:87], v[180:183], v[128:131], v[88:91]
	v_mfma_f32_16x16x32_bf16 v[88:91], v[188:191], v[108:111], v[92:95]
	v_mfma_f32_16x16x32_bf16 v[92:95], v[188:191], v[128:131], v[96:99]
	v_mfma_f32_16x16x32_bf16 v[2:5], v[140:143], v[124:127], v[2:5]
	v_mfma_f32_16x16x32_bf16 v[16:19], v[140:143], v[132:135], v[16:19]
	v_mfma_f32_16x16x32_bf16 v[72:75], v[160:163], v[124:127], v[72:75]
	v_mfma_f32_16x16x32_bf16 v[76:79], v[160:163], v[132:135], v[76:79]
	v_mfma_f32_16x16x32_bf16 v[80:83], v[184:187], v[124:127], v[80:83]
	v_mfma_f32_16x16x32_bf16 v[84:87], v[184:187], v[132:135], v[84:87]
	v_mfma_f32_16x16x32_bf16 v[88:91], v[192:195], v[124:127], v[88:91]
	v_mfma_f32_16x16x32_bf16 v[92:95], v[192:195], v[132:135], v[92:95]
	s_barrier
	ds_read_b128 v[96:99], v220
	ds_read_b128 v[196:199], v220 offset:1024
	ds_read_b128 v[200:203], v220 offset:2048
	ds_read_b128 v[204:207], v220 offset:3072
	s_barrier
	s_waitcnt lgkmcnt(0)
	v_mfma_f32_16x16x32_bf16 v[10:13], v[136:139], v[96:99], v[10:13]
	v_mfma_f32_16x16x32_bf16 v[40:43], v[136:139], v[200:203], v[40:43]
	v_mfma_f32_16x16x32_bf16 v[44:47], v[144:147], v[96:99], v[44:47]
	v_mfma_f32_16x16x32_bf16 v[48:51], v[144:147], v[200:203], v[48:51]
	v_mfma_f32_16x16x32_bf16 v[52:55], v[180:183], v[96:99], v[52:55]
	v_mfma_f32_16x16x32_bf16 v[56:59], v[180:183], v[200:203], v[56:59]
	v_mfma_f32_16x16x32_bf16 v[60:63], v[188:191], v[96:99], v[60:63]
	v_mfma_f32_16x16x32_bf16 v[10:13], v[140:143], v[196:199], v[10:13]
	v_mfma_f32_16x16x32_bf16 v[40:43], v[140:143], v[204:207], v[40:43]
	v_mfma_f32_16x16x32_bf16 v[44:47], v[160:163], v[196:199], v[44:47]
	v_mfma_f32_16x16x32_bf16 v[48:51], v[160:163], v[204:207], v[48:51]
	v_mfma_f32_16x16x32_bf16 v[52:55], v[184:187], v[196:199], v[52:55]
	v_mfma_f32_16x16x32_bf16 v[56:59], v[184:187], v[204:207], v[56:59]
	v_mfma_f32_16x16x32_bf16 v[60:63], v[192:195], v[196:199], v[60:63]
	v_mfma_f32_16x16x32_bf16 v[64:67], v[188:191], v[200:203], v[64:67]
	v_mfma_f32_16x16x32_bf16 v[136:139], v[192:195], v[204:207], v[64:67]
	s_barrier
; #define LDA(dst, b, h) _Pragma("unroll") for (int m = 0; m < 4; ++m) _Pragma("unroll") for (int k = 0; k < 2; ++k) \
;     dst[m][k] = *reinterpret_cast<const bf16x8*>((char*)SA(b, h) + lds_byte(wr * 64 + m * 16 + fr, k * 32 + fq * 8))
; #define LDB(dst, b, h) _Pragma("unroll") for (int n = 0; n < 2; ++n) _Pragma("unroll") for (int k = 0; k < 2; ++k) \
;     dst[n][k] = *reinterpret_cast<const bf16x8*>((char*)SB(b, h) + lds_byte(wc * 32 + n * 16 + fr, k * 32 + fq * 8))
; #define MMA(ai, bj, At, Bq) do { __builtin_amdgcn_s_setprio(1); \
;     _Pragma("unroll") for (int m = 0; m < 4; ++m) _Pragma("unroll") for (int n = 0; n < 2; ++n) _Pragma("unroll") for (int k = 0; k < 2; ++k) \
;       acc[ai][bj][m][n] = __builtin_amdgcn_mfma_f32_16x16x32_bf16(At[m][k], Bq[n][k], acc[ai][bj][m][n], 0, 0, 0); \
;     __builtin_amdgcn_s_setprio(0); } while (0)
; #define WAIT_V(n) asm volatile("s_waitcnt vmcnt(" #n ")" ::: "memory")
; #define WAIT_L(n) asm volatile("s_waitcnt lgkmcnt(" #n ")" ::: "memory")
; #define BAR __builtin_amdgcn_s_barrier()
; __device__ __forceinline__ void gemm256(const u16* __restrict__ A, int lda, const u16* __restrict__ Bt, int ldb, int K,
;                                         f32x4 (&acc)[2][2][4][2], const int g_wid) {
;     ...
;     LDA(At, 0, 1); WAIT_V(4); BAR; WAIT_L(0); MMA(1, 0, At, B0); MMA(1, 1, At, B1); BAR; }
;   { LDB(B0, 1, 0); LDA(At, 1, 0); WAIT_V(2); BAR; WAIT_L(0); MMA(0, 0, At, B0); BAR;
	s_nop 4
	ds_read_b128 v[64:67], v15 offset:16384
	ds_read_b128 v[140:143], v15 offset:17408
	ds_read_b128 v[144:147], v14 offset:18432
	ds_read_b128 v[160:163], v14 offset:19456
	ds_read_b128 v[180:183], v14 offset:20480
	ds_read_b128 v[184:187], v14 offset:21504
	ds_read_b128 v[188:191], v14 offset:22528
	ds_read_b128 v[192:195], v14 offset:23552
	s_waitcnt vmcnt(4)
	s_barrier
	s_waitcnt lgkmcnt(0)
	v_mfma_f32_16x16x32_bf16 v[6:9], v[64:67], v[108:111], v[6:9]
	v_mfma_f32_16x16x32_bf16 v[20:23], v[64:67], v[128:131], v[20:23]
	v_mfma_f32_16x16x32_bf16 v[24:27], v[188:191], v[108:111], v[24:27]
	v_mfma_f32_16x16x32_bf16 v[28:31], v[188:191], v[128:131], v[28:31]
	v_mfma_f32_16x16x32_bf16 v[6:9], v[140:143], v[124:127], v[6:9]
	v_mfma_f32_16x16x32_bf16 v[20:23], v[140:143], v[132:135], v[20:23]
	v_mfma_f32_16x16x32_bf16 v[164:167], v[144:147], v[108:111], v[164:167]
	v_mfma_f32_16x16x32_bf16 v[168:171], v[144:147], v[128:131], v[168:171]
	v_mfma_f32_16x16x32_bf16 v[172:175], v[180:183], v[108:111], v[172:175]
	v_mfma_f32_16x16x32_bf16 v[176:179], v[180:183], v[128:131], v[176:179]
	v_mfma_f32_16x16x32_bf16 v[24:27], v[192:195], v[124:127], v[24:27]
	v_mfma_f32_16x16x32_bf16 v[28:31], v[192:195], v[132:135], v[28:31]
	v_mfma_f32_16x16x32_bf16 v[164:167], v[160:163], v[124:127], v[164:167]
	v_mfma_f32_16x16x32_bf16 v[168:171], v[160:163], v[132:135], v[168:171]
	v_mfma_f32_16x16x32_bf16 v[172:175], v[184:187], v[124:127], v[172:175]
	v_mfma_f32_16x16x32_bf16 v[176:179], v[184:187], v[132:135], v[176:179]
	v_mfma_f32_16x16x32_bf16 v[32:35], v[64:67], v[96:99], v[32:35]
	v_mfma_f32_16x16x32_bf16 v[130:133], v[140:143], v[196:199], v[32:35]
	v_mfma_f32_16x16x32_bf16 v[32:35], v[64:67], v[200:203], v[36:39]
	v_mfma_f32_16x16x32_bf16 v[140:143], v[140:143], v[204:207], v[32:35]
	v_mfma_f32_16x16x32_bf16 v[32:35], v[144:147], v[96:99], v[68:71]
	v_mfma_f32_16x16x32_bf16 v[208:211], v[160:163], v[196:199], v[32:35]
	v_mfma_f32_16x16x32_bf16 v[32:35], v[144:147], v[200:203], v[112:115]
	v_mfma_f32_16x16x32_bf16 v[144:147], v[160:163], v[204:207], v[32:35]
	v_mfma_f32_16x16x32_bf16 v[32:35], v[180:183], v[96:99], v[116:119]
	v_mfma_f32_16x16x32_bf16 v[160:163], v[184:187], v[196:199], v[32:35]
	v_mfma_f32_16x16x32_bf16 v[32:35], v[180:183], v[200:203], v[120:123]
	v_mfma_f32_16x16x32_bf16 v[180:183], v[184:187], v[204:207], v[32:35]
	v_mfma_f32_16x16x32_bf16 v[32:35], v[188:191], v[96:99], v[100:103]
	v_mfma_f32_16x16x32_bf16 v[184:187], v[192:195], v[196:199], v[32:35]
	v_mfma_f32_16x16x32_bf16 v[32:35], v[188:191], v[200:203], v[104:107]
	v_mfma_f32_16x16x32_bf16 v[188:191], v[192:195], v[204:207], v[32:35]
	s_barrier
	s_nop 4
	ds_read_b128 v[32:35], v221
	ds_read_b128 v[36:39], v221 offset:1024
	ds_read_b128 v[192:195], v221 offset:2048
	ds_read_b128 v[196:199], v221 offset:3072
	ds_read_b128 v[64:67], v15 offset:32768
	ds_read_b128 v[68:71], v15 offset:33792
	ds_read_b128 v[200:203], v14 offset:34816
	ds_read_b128 v[204:207], v14 offset:35840
	ds_read_b128 v[212:215], v14 offset:36864
	ds_read_b128 v[216:219], v14 offset:37888
	ds_read_b128 v[220:223], v14 offset:38912
	ds_read_b128 v[224:227], v14 offset:39936
	s_waitcnt vmcnt(2)
	s_barrier
	s_waitcnt lgkmcnt(0)
	v_mfma_f32_16x16x32_bf16 v[2:5], v[64:67], v[32:35], v[2:5]
	v_mfma_f32_16x16x32_bf16 v[126:129], v[68:71], v[36:39], v[2:5]
	v_mfma_f32_16x16x32_bf16 v[2:5], v[64:67], v[192:195], v[16:19]
	v_mfma_f32_16x16x32_bf16 v[122:125], v[68:71], v[196:199], v[2:5]
	v_mfma_f32_16x16x32_bf16 v[2:5], v[200:203], v[32:35], v[72:75]
	v_mfma_f32_16x16x32_bf16 v[118:121], v[204:207], v[36:39], v[2:5]
	v_mfma_f32_16x16x32_bf16 v[2:5], v[200:203], v[192:195], v[76:79]
	v_mfma_f32_16x16x32_bf16 v[114:117], v[204:207], v[196:199], v[2:5]
	v_mfma_f32_16x16x32_bf16 v[2:5], v[212:215], v[32:35], v[80:83]
	v_mfma_f32_16x16x32_bf16 v[110:113], v[216:219], v[36:39], v[2:5]
	v_mfma_f32_16x16x32_bf16 v[2:5], v[212:215], v[192:195], v[84:87]
	v_mfma_f32_16x16x32_bf16 v[106:109], v[216:219], v[196:199], v[2:5]
	v_mfma_f32_16x16x32_bf16 v[2:5], v[220:223], v[32:35], v[88:91]
	v_mfma_f32_16x16x32_bf16 v[102:105], v[224:227], v[36:39], v[2:5]
	v_mfma_f32_16x16x32_bf16 v[2:5], v[220:223], v[192:195], v[92:95]
	v_mfma_f32_16x16x32_bf16 v[94:97], v[224:227], v[196:199], v[2:5]
	s_barrier
; #define LDA(dst, b, h) _Pragma("unroll") for (int m = 0; m < 4; ++m) _Pragma("unroll") for (int k = 0; k < 2; ++k) \
;     dst[m][k] = *reinterpret_cast<const bf16x8*>((char*)SA(b, h) + lds_byte(wr * 64 + m * 16 + fr, k * 32 + fq * 8))
; #define LDB(dst, b, h) _Pragma("unroll") for (int n = 0; n < 2; ++n) _Pragma("unroll") for (int k = 0; k < 2; ++k) \
;     dst[n][k] = *reinterpret_cast<const bf16x8*>((char*)SB(b, h) + lds_byte(wc * 32 + n * 16 + fr, k * 32 + fq * 8))
; #define MMA(ai, bj, At, Bq) do { __builtin_amdgcn_s_setprio(1); \
;     _Pragma("unroll") for (int m = 0; m < 4; ++m) _Pragma("unroll") for (int n = 0; n < 2; ++n) _Pragma("unroll") for (int k = 0; k < 2; ++k) \
;       acc[ai][bj][m][n] = __builtin_amdgcn_mfma_f32_16x16x32_bf16(At[m][k], Bq[n][k], acc[ai][bj][m][n], 0, 0, 0); \
;     __builtin_amdgcn_s_setprio(0); } while (0)
; #define WAIT_V(n) asm volatile("s_waitcnt vmcnt(" #n ")" ::: "memory")
; #define WAIT_L(n) asm volatile("s_waitcnt lgkmcnt(" #n ")" ::: "memory")
; #define BAR __builtin_amdgcn_s_barrier()
; __device__ __forceinline__ void gemm256(const u16* __restrict__ A, int lda, const u16* __restrict__ Bt, int ldb, int K,
;                                         f32x4 (&acc)[2][2][4][2], const int g_wid) {
;     ...
;   { LDB(B0, 1, 0); LDA(At, 1, 0); WAIT_V(2); BAR; WAIT_L(0); MMA(0, 0, At, B0); BAR;
;     LDB(B1, 1, 1); WAIT_V(0); BAR; WAIT_L(0); MMA(0, 1, At, B1); BAR;
;     LDA(At, 1, 1); BAR; WAIT_L(0); MMA(1, 0, At, B0); MMA(1, 1, At, B1); BAR; }
;   if (wr == 0) BAR;
	s_nop 4
	ds_read_b128 v[2:5], v236
	ds_read_b128 v[228:231], v236 offset:1024
	ds_read_b128 v[232:235], v236 offset:2048
	ds_read_b128 v[236:239], v236 offset:3072
	s_waitcnt vmcnt(0)
	s_barrier
	s_waitcnt lgkmcnt(0)
	v_mfma_f32_16x16x32_bf16 v[10:13], v[64:67], v[2:5], v[10:13]
	v_mfma_f32_16x16x32_bf16 v[98:101], v[68:71], v[228:231], v[10:13]
	v_mfma_f32_16x16x32_bf16 v[10:13], v[64:67], v[232:235], v[40:43]
	v_mfma_f32_16x16x32_bf16 v[90:93], v[68:71], v[236:239], v[10:13]
	v_mfma_f32_16x16x32_bf16 v[10:13], v[200:203], v[2:5], v[44:47]
	v_mfma_f32_16x16x32_bf16 v[86:89], v[204:207], v[228:231], v[10:13]
	v_mfma_f32_16x16x32_bf16 v[10:13], v[200:203], v[232:235], v[48:51]
	v_mfma_f32_16x16x32_bf16 v[82:85], v[204:207], v[236:239], v[10:13]
	v_mfma_f32_16x16x32_bf16 v[10:13], v[212:215], v[2:5], v[52:55]
	v_mfma_f32_16x16x32_bf16 v[78:81], v[216:219], v[228:231], v[10:13]
	v_mfma_f32_16x16x32_bf16 v[10:13], v[212:215], v[232:235], v[56:59]
	v_mfma_f32_16x16x32_bf16 v[74:77], v[216:219], v[236:239], v[10:13]
	v_mfma_f32_16x16x32_bf16 v[10:13], v[220:223], v[2:5], v[60:63]
	v_mfma_f32_16x16x32_bf16 v[66:69], v[224:227], v[228:231], v[10:13]
	v_mfma_f32_16x16x32_bf16 v[10:13], v[220:223], v[232:235], v[136:139]
	v_mfma_f32_16x16x32_bf16 v[58:61], v[224:227], v[236:239], v[10:13]
	s_barrier
	s_nop 4
	ds_read_b128 v[10:13], v15 offset:49152
	ds_read_b128 v[16:19], v15 offset:50176
	ds_read_b128 v[134:137], v14 offset:51200
	ds_read_b128 v[200:203], v14 offset:52224
	ds_read_b128 v[204:207], v14 offset:53248
	ds_read_b128 v[212:215], v14 offset:54272
	ds_read_b128 v[216:219], v14 offset:55296
	ds_read_b128 v[220:223], v14 offset:56320
	s_barrier
	s_waitcnt lgkmcnt(0)
	v_mfma_f32_16x16x32_bf16 v[6:9], v[10:13], v[32:35], v[6:9]
	v_mfma_f32_16x16x32_bf16 v[70:73], v[16:19], v[36:39], v[6:9]
	v_mfma_f32_16x16x32_bf16 v[6:9], v[10:13], v[192:195], v[20:23]
	v_mfma_f32_16x16x32_bf16 v[62:65], v[16:19], v[196:199], v[6:9]
	v_mfma_f32_16x16x32_bf16 v[6:9], v[134:137], v[32:35], v[164:167]
	v_mfma_f32_16x16x32_bf16 v[54:57], v[200:203], v[36:39], v[6:9]
	v_mfma_f32_16x16x32_bf16 v[6:9], v[134:137], v[192:195], v[168:171]
	v_mfma_f32_16x16x32_bf16 v[50:53], v[200:203], v[196:199], v[6:9]
	v_mfma_f32_16x16x32_bf16 v[6:9], v[204:207], v[32:35], v[172:175]
	v_mfma_f32_16x16x32_bf16 v[46:49], v[212:215], v[36:39], v[6:9]
	v_mfma_f32_16x16x32_bf16 v[6:9], v[204:207], v[192:195], v[176:179]
	v_mfma_f32_16x16x32_bf16 v[42:45], v[212:215], v[196:199], v[6:9]
	v_mfma_f32_16x16x32_bf16 v[6:9], v[216:219], v[32:35], v[24:27]
	v_mfma_f32_16x16x32_bf16 v[38:41], v[220:223], v[36:39], v[6:9]
	v_mfma_f32_16x16x32_bf16 v[6:9], v[216:219], v[192:195], v[28:31]
	v_mfma_f32_16x16x32_bf16 v[34:37], v[220:223], v[196:199], v[6:9]
	v_mfma_f32_16x16x32_bf16 v[6:9], v[10:13], v[2:5], v[130:133]
	v_mfma_f32_16x16x32_bf16 v[30:33], v[16:19], v[228:231], v[6:9]
	v_mfma_f32_16x16x32_bf16 v[6:9], v[10:13], v[232:235], v[140:143]
	v_mfma_f32_16x16x32_bf16 v[26:29], v[16:19], v[236:239], v[6:9]
	v_mfma_f32_16x16x32_bf16 v[6:9], v[134:137], v[2:5], v[208:211]
	v_mfma_f32_16x16x32_bf16 v[22:25], v[200:203], v[228:231], v[6:9]
	v_mfma_f32_16x16x32_bf16 v[6:9], v[134:137], v[232:235], v[144:147]
	v_mfma_f32_16x16x32_bf16 v[18:21], v[200:203], v[236:239], v[6:9]
	v_mfma_f32_16x16x32_bf16 v[6:9], v[204:207], v[2:5], v[160:163]
	v_mfma_f32_16x16x32_bf16 v[14:17], v[212:215], v[228:231], v[6:9]
	v_mfma_f32_16x16x32_bf16 v[6:9], v[204:207], v[232:235], v[180:183]
	v_mfma_f32_16x16x32_bf16 v[2:5], v[216:219], v[2:5], v[184:187]
	v_mfma_f32_16x16x32_bf16 v[10:13], v[212:215], v[236:239], v[6:9]
	v_mfma_f32_16x16x32_bf16 v[6:9], v[220:223], v[228:231], v[2:5]
	v_mfma_f32_16x16x32_bf16 v[2:5], v[216:219], v[232:235], v[188:191]
	v_mfma_f32_16x16x32_bf16 v[2:5], v[220:223], v[236:239], v[2:5]
	s_setprio 0
	s_movk_i32 s2, 0x100
	v_cmp_gt_u32_e32 vcc, s2, v0
	s_barrier
	s_and_saveexec_b64 s[2:3], vcc
	s_cbranch_execz .LBB0_389
	s_barrier

; #define hw_tid() ((g_wid << 6) | hw_lane())
; #define STA(P, br, kt) STAGE(P, A, aoff0, aoff1, lda, br, kt)
; #define STB(P, br, kt) STAGE(P, Bt, boff0, boff1, ldb, br, kt)
; #define BAR __builtin_amdgcn_s_barrier()
; __device__ __forceinline__ void gemm256(const u16* __restrict__ A, int lda, const u16* __restrict__ Bt, int ldb, int K,
;                                         f32x4 (&acc)[2][2][4][2], const int g_wid) {
;   int tid = hw_tid(); asm volatile("" : "+v"(tid));
;   const int wid = tid >> 6, lane = tid & 63, wr = wid >> 2, wc = wid & 3, fr = lane & 15, fq = lane >> 4;
;   int r0, c0, r1, c1;
;   stage_rc(tid * 16, r0, c0);
;   stage_rc(tid * 16 + 8192, r1, c1);
;   const int aoff0 = r0 * lda + c0, aoff1 = r1 * lda + c1, boff0 = r0 * ldb + c0, boff1 = r1 * ldb + c1;
;   bf16x8 At[4][2], B0[2][2], B1[2][2];
;   const int nt = K / BK;
;   STB(SB(0, 0), 0, 0); STA(SA(0, 0), 0, 0);
;   STB(SB(0, 1), HALF, 0); STA(SA(0, 1), HALF, 0);
;   if (wr == 1) BAR;
; __device__ __forceinline__ void phase_g1(PP p, const int g_wid) {
;     ...
;   for (int t = bid; t < NMT * 22; t += gdim, par ^= 1) {
;     int pm, pn; tile_map(t, NMT, 22, pm, pn);
;     stage_rs(p, pm, par, tid);
;     f32x4 acc[2][2][4][2]; ZERO_ACC;
;     gemm256(p->W + (long)pn * 256 * 1024, 1024, p->hb + (long)pm * 256 * 1024, 1024, 1024, acc, g_wid);
.LBB0_462:
	s_or_b64 exec, exec, s[12:13]
	s_sext_i32_i16 s12, s9
	s_ashr_i32 s13, s12, 31
	s_lshl_b64 s[16:17], s[12:13], 19
	s_waitcnt lgkmcnt(0)
	s_add_u32 s14, s4, s16
	s_addc_u32 s15, s5, s17
	s_ashr_i32 s9, s8, 31
	s_lshl_b64 s[18:19], s[8:9], 19
	s_mov_b32 s9, -1
	s_add_u32 s20, s6, s18
	v_mbcnt_lo_u32_b32 v0, s9, 0
	v_mbcnt_hi_u32_b32 v0, s9, v0
	v_readlane_b32 s9, v254, 63
	s_addc_u32 s21, s7, s19
	s_add_u32 s22, s20, 0x40000
	v_or_b32_e32 v0, s9, v0
	v_readlane_b32 s9, v254, 40
	v_ashrrev_i32_e32 v2, 31, v0
	v_lshrrev_b32_e32 v2, 26, v2
	v_add_u32_e32 v2, v0, v2
	v_ashrrev_i32_e32 v10, 6, v2
	v_bfe_i32 v2, v0, 27, 1
	v_lshlrev_b32_e32 v15, 4, v0
	v_lshrrev_b32_e32 v2, 22, v2
	v_add_u32_e32 v2, v15, v2
	v_and_b32_e32 v2, 0xfffffc00, v2
	v_sub_u32_e32 v2, v15, v2
	v_lshrrev_b32_e32 v3, 4, v2
	v_bitop3_b32 v2, v3, v2, 32 bitop3:0x6c
	v_ashrrev_i32_e32 v4, 31, v2
	v_lshrrev_b32_e32 v4, 26, v4
	v_add_u32_e32 v4, v2, v4
	v_ashrrev_i32_e32 v11, 6, v4
	v_and_b32_e32 v4, 0xc0, v4
	v_sub_u32_e32 v2, v2, v4
	v_ashrrev_i16_sdwa v13, v151, sext(v2) dst_sel:DWORD dst_unused:UNUSED_PAD src0_sel:DWORD src1_sel:BYTE_0
	v_add_u32_e32 v2, 0x2000, v15
	v_ashrrev_i32_e32 v4, 31, v2
	v_lshrrev_b32_e32 v4, 22, v4
	v_add_u32_e32 v4, v2, v4
	v_ashrrev_i32_e32 v14, 10, v4
	v_mul_i32_i24_e32 v4, 0x400, v14
	v_sub_u32_e32 v2, v2, v4
	v_lshrrev_b32_e32 v4, 4, v2
	v_lshlrev_b32_e32 v5, 5, v10
	v_bitop3_b32 v2, v4, v2, 32 bitop3:0x6c
	v_and_b32_e32 v12, 32, v5
	v_ashrrev_i32_e32 v5, 31, v2
	v_lshrrev_b32_e32 v5, 26, v5
	v_lshlrev_b32_e32 v3, 3, v10
	v_add_u32_e32 v5, v2, v5
	v_and_b32_e32 v3, 0x3ffff0, v3
	v_lshlrev_b32_e32 v4, 3, v14
	v_ashrrev_i32_e32 v16, 6, v5
	v_and_b32_e32 v5, 0xc0, v5
	v_add_u32_e32 v3, v11, v3
	v_and_b32_e32 v4, 0x3ffff0, v4
	v_lshlrev_b32_e32 v6, 5, v14
	v_sub_u32_e32 v2, v2, v5
	v_add_u32_e32 v4, v16, v4
	v_and_b32_e32 v17, 32, v6
	v_ashrrev_i16_sdwa v18, v151, sext(v2) dst_sel:DWORD dst_unused:UNUSED_PAD src0_sel:DWORD src1_sel:BYTE_0
	v_lshl_or_b32 v2, v3, 10, v12
	v_add_u32_sdwa v132, v2, sext(v13) dst_sel:DWORD dst_unused:UNUSED_PAD src0_sel:DWORD src1_sel:WORD_0
	v_lshl_or_b32 v2, v4, 10, v17
	v_add_u32_sdwa v130, v2, sext(v18) dst_sel:DWORD dst_unused:UNUSED_PAD src0_sel:DWORD src1_sel:WORD_0
	v_ashrrev_i32_e32 v133, 31, v132
	v_add_u32_e32 v159, s9, v15
	v_lshlrev_b64 v[20:21], 1, v[132:133]
	v_readfirstlane_b32 s9, v159
	v_ashrrev_i32_e32 v131, 31, v130
	v_add_u32_e32 v160, 0x2000, v159
	v_lshl_add_u64 v[2:3], s[20:21], 0, v[20:21]
	s_mov_b32 m0, s9
	v_lshlrev_b64 v[22:23], 1, v[130:131]
	v_readfirstlane_b32 s9, v160
	v_add_u32_e32 v162, 0, v15
	v_lshl_add_u64 v[6:7], s[20:21], 0, v[22:23]
	s_mov_b32 m0, s9
	v_readfirstlane_b32 s9, v162
	v_add_u32_e32 v163, 0x2000, v162
	v_lshl_add_u64 v[8:9], s[14:15], 0, v[20:21]
	s_mov_b32 m0, s9
	v_readfirstlane_b32 s9, v163
	s_mov_b32 m0, s9
	v_readlane_b32 s9, v254, 41
	v_lshl_add_u64 v[4:5], s[14:15], 0, v[22:23]
	s_addc_u32 s23, s21, 0
	v_add_u32_e32 v164, s9, v15
	v_readfirstlane_b32 s9, v164
	v_lshl_add_u64 v[24:25], s[22:23], 0, v[20:21]
	s_mov_b32 m0, s9
	v_add_u32_e32 v165, 0x2000, v164
	v_lshl_add_u64 v[24:25], s[22:23], 0, v[22:23]
	v_readfirstlane_b32 s9, v165
	s_add_u32 s22, s14, 0x40000
	v_add_u32_e32 v166, 0x4000, v162
	s_mov_b32 m0, s9
	s_addc_u32 s23, s15, 0
	v_readfirstlane_b32 s9, v166
	v_add_u32_e32 v168, 0x6000, v162
	v_lshl_add_u64 v[20:21], s[22:23], 0, v[20:21]
	s_mov_b32 m0, s9
	v_readfirstlane_b32 s9, v168
	v_lshl_add_u64 v[20:21], s[22:23], 0, v[22:23]
	s_mov_b32 m0, s9
	v_ashrrev_i32_e32 v19, 8, v0
	v_cmp_eq_u32_e32 vcc, 1, v19
	s_and_saveexec_b64 s[22:23], vcc
	s_cbranch_execz .LBB0_464
	s_setprio 3
	s_barrier

; #define STA(P, br, kt) STAGE(P, A, aoff0, aoff1, lda, br, kt)
; #define STB(P, br, kt) STAGE(P, Bt, boff0, boff1, ldb, br, kt)
; #define LDA(dst, b, h) _Pragma("unroll") for (int m = 0; m < 4; ++m) _Pragma("unroll") for (int k = 0; k < 2; ++k) \
;     dst[m][k] = *reinterpret_cast<const bf16x8*>((char*)SA(b, h) + lds_byte(wr * 64 + m * 16 + fr, k * 32 + fq * 8))
; #define LDB(dst, b, h) _Pragma("unroll") for (int n = 0; n < 2; ++n) _Pragma("unroll") for (int k = 0; k < 2; ++k) \
;     dst[n][k] = *reinterpret_cast<const bf16x8*>((char*)SB(b, h) + lds_byte(wc * 32 + n * 16 + fr, k * 32 + fq * 8))
; #define MMA(ai, bj, At, Bq) do { __builtin_amdgcn_s_setprio(1); \
;     _Pragma("unroll") for (int m = 0; m < 4; ++m) _Pragma("unroll") for (int n = 0; n < 2; ++n) _Pragma("unroll") for (int k = 0; k < 2; ++k) \
;       acc[ai][bj][m][n] = __builtin_amdgcn_mfma_f32_16x16x32_bf16(At[m][k], Bq[n][k], acc[ai][bj][m][n], 0, 0, 0); \
;     __builtin_amdgcn_s_setprio(0); } while (0)
; #define WAIT_L(n) asm volatile("s_waitcnt lgkmcnt(" #n ")" ::: "memory")
; #define BAR __builtin_amdgcn_s_barrier()
; #define SCHED __builtin_amdgcn_sched_barrier(0)
; __device__ __forceinline__ void gemm256(const u16* __restrict__ A, int lda, const u16* __restrict__ Bt, int ldb, int K,
;                                         f32x4 (&acc)[2][2][4][2], const int g_wid) {
;     ...
;   for (int t = 0; t < nt - 2; t += 2) {
;     LDB(B0, 0, 0); SCHED; LDA(At, 0, 0); STA(SA(1, 1), HALF, t + 1);
;     WAIT_L(8); BAR; WAIT_L(0); MMA(0, 0, At, B0); BAR; SCHED;
;     LDB(B1, 0, 1); STB(SB(0, 0), 0, t + 2);
;     BAR; WAIT_L(0); MMA(0, 1, At, B1); BAR;
;     LDA(At, 0, 1); STA(SA(0, 0), 0, t + 2);
;     BAR; WAIT_L(0); MMA(1, 0, At, B0); BAR; SCHED;
.LBB0_465:
	ds_read_b128 v[180:183], v176
	ds_read_b128 v[184:187], v176 offset:1024
	ds_read_b128 v[188:191], v176 offset:2048
	ds_read_b128 v[192:195], v176 offset:3072
	v_add_u32_e32 v177, 0xc000, v162
	v_lshl_add_u64 v[244:245], v[140:141], 0, s[16:17]
	v_readfirstlane_b32 s13, v177
	v_lshl_add_u64 v[178:179], v[244:245], 0, s[68:69]
	s_mov_b32 m0, s13
	ds_read_b128 v[196:199], v147
	ds_read_b128 v[200:203], v147 offset:1024
	ds_read_b128 v[204:207], v146
	ds_read_b128 v[208:211], v146 offset:1024
	ds_read_b128 v[212:215], v145
	ds_read_b128 v[216:219], v145 offset:1024
	ds_read_b128 v[220:223], v144
	ds_read_b128 v[224:227], v144 offset:1024
	global_load_lds_dwordx4 v[178:179], off
	v_add_u32_e32 v178, 0xe000, v162
	v_lshl_add_u64 v[246:247], v[138:139], 0, s[16:17]
	v_readfirstlane_b32 s13, v178
	v_lshl_add_u64 v[228:229], v[246:247], 0, s[68:69]
	s_mov_b32 m0, s13
	s_nop 0
	global_load_lds_dwordx4 v[228:229], off
	s_waitcnt lgkmcnt(8)
	s_barrier
	s_waitcnt lgkmcnt(0)
	v_mfma_f32_16x16x32_bf16 v[126:129], v[196:199], v[180:183], v[126:129]
	v_mfma_f32_16x16x32_bf16 v[122:125], v[196:199], v[188:191], v[122:125]
	v_mfma_f32_16x16x32_bf16 v[118:121], v[204:207], v[180:183], v[118:121]
	v_mfma_f32_16x16x32_bf16 v[114:117], v[204:207], v[188:191], v[114:117]
	v_mfma_f32_16x16x32_bf16 v[110:113], v[212:215], v[180:183], v[110:113]
	v_mfma_f32_16x16x32_bf16 v[106:109], v[212:215], v[188:191], v[106:109]
	v_mfma_f32_16x16x32_bf16 v[102:105], v[220:223], v[180:183], v[102:105]
	v_mfma_f32_16x16x32_bf16 v[98:101], v[220:223], v[188:191], v[98:101]
	v_mfma_f32_16x16x32_bf16 v[126:129], v[200:203], v[184:187], v[126:129]
	v_mfma_f32_16x16x32_bf16 v[122:125], v[200:203], v[192:195], v[122:125]
	v_mfma_f32_16x16x32_bf16 v[118:121], v[208:211], v[184:187], v[118:121]
	v_mfma_f32_16x16x32_bf16 v[114:117], v[208:211], v[192:195], v[114:117]
	v_mfma_f32_16x16x32_bf16 v[110:113], v[216:219], v[184:187], v[110:113]
	v_mfma_f32_16x16x32_bf16 v[106:109], v[216:219], v[192:195], v[106:109]
	v_mfma_f32_16x16x32_bf16 v[102:105], v[224:227], v[184:187], v[102:105]
	v_mfma_f32_16x16x32_bf16 v[98:101], v[224:227], v[192:195], v[98:101]
	s_barrier
	v_lshl_add_u64 v[248:249], v[136:137], 0, s[16:17]
	v_readfirstlane_b32 s13, v159
	v_lshl_add_u64 v[250:251], v[248:249], 0, s[74:75]
	s_mov_b32 m0, s13
	ds_read_b128 v[228:231], v175
	ds_read_b128 v[232:235], v175 offset:1024
	ds_read_b128 v[236:239], v175 offset:2048
	ds_read_b128 v[240:243], v175 offset:3072
	global_load_lds_dwordx4 v[250:251], off
	v_lshl_add_u64 v[250:251], v[134:135], 0, s[16:17]
	v_readfirstlane_b32 s13, v160
	v_lshl_add_u64 v[252:253], v[250:251], 0, s[74:75]
	s_mov_b32 m0, s13
	s_nop 0
	global_load_lds_dwordx4 v[252:253], off
	s_barrier
	s_waitcnt lgkmcnt(0)
	v_mfma_f32_16x16x32_bf16 v[94:97], v[196:199], v[228:231], v[94:97]
	v_mfma_f32_16x16x32_bf16 v[90:93], v[196:199], v[236:239], v[90:93]
	v_mfma_f32_16x16x32_bf16 v[86:89], v[204:207], v[228:231], v[86:89]
	v_mfma_f32_16x16x32_bf16 v[82:85], v[204:207], v[236:239], v[82:85]
	v_mfma_f32_16x16x32_bf16 v[78:81], v[212:215], v[228:231], v[78:81]
	v_mfma_f32_16x16x32_bf16 v[74:77], v[212:215], v[236:239], v[74:77]
	v_mfma_f32_16x16x32_bf16 v[70:73], v[220:223], v[228:231], v[70:73]
	v_mfma_f32_16x16x32_bf16 v[66:69], v[220:223], v[236:239], v[66:69]
	v_mfma_f32_16x16x32_bf16 v[94:97], v[200:203], v[232:235], v[94:97]
	v_mfma_f32_16x16x32_bf16 v[90:93], v[200:203], v[240:243], v[90:93]
	v_mfma_f32_16x16x32_bf16 v[86:89], v[208:211], v[232:235], v[86:89]
	v_mfma_f32_16x16x32_bf16 v[82:85], v[208:211], v[240:243], v[82:85]
	v_mfma_f32_16x16x32_bf16 v[78:81], v[216:219], v[232:235], v[78:81]
	v_mfma_f32_16x16x32_bf16 v[74:77], v[216:219], v[240:243], v[74:77]
	v_mfma_f32_16x16x32_bf16 v[70:73], v[224:227], v[232:235], v[70:73]
	v_mfma_f32_16x16x32_bf16 v[66:69], v[224:227], v[240:243], v[66:69]
	v_readfirstlane_b32 s13, v162
	v_lshl_add_u64 v[252:253], v[244:245], 0, s[74:75]
	s_mov_b32 m0, s13
	v_readfirstlane_b32 s13, v163
	s_barrier
	ds_read_b128 v[196:199], v147 offset:16384
	ds_read_b128 v[200:203], v147 offset:17408
	ds_read_b128 v[204:207], v146 offset:16384
	ds_read_b128 v[208:211], v146 offset:17408
	ds_read_b128 v[212:215], v145 offset:16384
	ds_read_b128 v[216:219], v145 offset:17408
	ds_read_b128 v[220:223], v144 offset:16384
	ds_read_b128 v[224:227], v144 offset:17408
	global_load_lds_dwordx4 v[252:253], off
	v_lshl_add_u64 v[252:253], v[246:247], 0, s[74:75]
	s_mov_b32 m0, s13
	s_nop 0
	global_load_lds_dwordx4 v[252:253], off
	s_barrier
	s_waitcnt lgkmcnt(0)
	v_mfma_f32_16x16x32_bf16 v[62:65], v[196:199], v[180:183], v[62:65]
	v_mfma_f32_16x16x32_bf16 v[58:61], v[196:199], v[188:191], v[58:61]
	v_mfma_f32_16x16x32_bf16 v[54:57], v[204:207], v[180:183], v[54:57]
	v_mfma_f32_16x16x32_bf16 v[50:53], v[204:207], v[188:191], v[50:53]
	v_mfma_f32_16x16x32_bf16 v[46:49], v[212:215], v[180:183], v[46:49]
	v_mfma_f32_16x16x32_bf16 v[42:45], v[212:215], v[188:191], v[42:45]
	v_mfma_f32_16x16x32_bf16 v[38:41], v[220:223], v[180:183], v[38:41]
	v_mfma_f32_16x16x32_bf16 v[34:37], v[220:223], v[188:191], v[34:37]
	v_mfma_f32_16x16x32_bf16 v[62:65], v[200:203], v[184:187], v[62:65]
	v_mfma_f32_16x16x32_bf16 v[58:61], v[200:203], v[192:195], v[58:61]
	v_mfma_f32_16x16x32_bf16 v[54:57], v[208:211], v[184:187], v[54:57]
	v_mfma_f32_16x16x32_bf16 v[50:53], v[208:211], v[192:195], v[50:53]
	v_mfma_f32_16x16x32_bf16 v[46:49], v[216:219], v[184:187], v[46:49]
	v_mfma_f32_16x16x32_bf16 v[42:45], v[216:219], v[192:195], v[42:45]
	v_mfma_f32_16x16x32_bf16 v[38:41], v[224:227], v[184:187], v[38:41]
	v_mfma_f32_16x16x32_bf16 v[34:37], v[224:227], v[192:195], v[34:37]
	s_barrier
; #define STA(P, br, kt) STAGE(P, A, aoff0, aoff1, lda, br, kt)
; #define STB(P, br, kt) STAGE(P, Bt, boff0, boff1, ldb, br, kt)
; #define LDA(dst, b, h) _Pragma("unroll") for (int m = 0; m < 4; ++m) _Pragma("unroll") for (int k = 0; k < 2; ++k) \
;     dst[m][k] = *reinterpret_cast<const bf16x8*>((char*)SA(b, h) + lds_byte(wr * 64 + m * 16 + fr, k * 32 + fq * 8))
; #define LDB(dst, b, h) _Pragma("unroll") for (int n = 0; n < 2; ++n) _Pragma("unroll") for (int k = 0; k < 2; ++k) \
;     dst[n][k] = *reinterpret_cast<const bf16x8*>((char*)SB(b, h) + lds_byte(wc * 32 + n * 16 + fr, k * 32 + fq * 8))
; #define MMA(ai, bj, At, Bq) do { __builtin_amdgcn_s_setprio(1); \
;     _Pragma("unroll") for (int m = 0; m < 4; ++m) _Pragma("unroll") for (int n = 0; n < 2; ++n) _Pragma("unroll") for (int k = 0; k < 2; ++k) \
;       acc[ai][bj][m][n] = __builtin_amdgcn_mfma_f32_16x16x32_bf16(At[m][k], Bq[n][k], acc[ai][bj][m][n], 0, 0, 0); \
;     __builtin_amdgcn_s_setprio(0); } while (0)
; #define WAIT_V(n) asm volatile("s_waitcnt vmcnt(" #n ")" ::: "memory")
; #define WAIT_L(n) asm volatile("s_waitcnt lgkmcnt(" #n ")" ::: "memory")
; #define BAR __builtin_amdgcn_s_barrier()
; #define SCHED __builtin_amdgcn_sched_barrier(0)
; __device__ __forceinline__ void gemm256(const u16* __restrict__ A, int lda, const u16* __restrict__ Bt, int ldb, int K,
;                                         f32x4 (&acc)[2][2][4][2], const int g_wid) {
;     ...
;     STB(SB(0, 1), HALF, t + 2);
;     WAIT_V(6); BAR; MMA(1, 1, At, B1); BAR;
;     LDB(B0, 1, 0); SCHED; LDA(At, 1, 0); STA(SA(0, 1), HALF, t + 2);
;     WAIT_L(8); BAR; WAIT_L(0); MMA(0, 0, At, B0); BAR; SCHED;
;     LDB(B1, 1, 1); STB(SB(1, 0), 0, t + 3);
;     BAR; WAIT_L(0); MMA(0, 1, At, B1); BAR;
	v_readfirstlane_b32 s13, v164
	v_lshl_add_u64 v[180:181], v[248:249], 0, s[78:79]
	s_mov_b32 m0, s13
	v_readfirstlane_b32 s13, v165
	global_load_lds_dwordx4 v[180:181], off
	v_lshl_add_u64 v[180:181], v[250:251], 0, s[78:79]
	s_mov_b32 m0, s13
	s_nop 0
	global_load_lds_dwordx4 v[180:181], off
	s_waitcnt vmcnt(6)
	s_barrier
	v_mfma_f32_16x16x32_bf16 v[30:33], v[196:199], v[228:231], v[30:33]
	v_mfma_f32_16x16x32_bf16 v[26:29], v[196:199], v[236:239], v[26:29]
	v_mfma_f32_16x16x32_bf16 v[22:25], v[204:207], v[228:231], v[22:25]
	v_mfma_f32_16x16x32_bf16 v[18:21], v[204:207], v[236:239], v[18:21]
	v_mfma_f32_16x16x32_bf16 v[14:17], v[212:215], v[228:231], v[14:17]
	v_mfma_f32_16x16x32_bf16 v[10:13], v[212:215], v[236:239], v[10:13]
	v_mfma_f32_16x16x32_bf16 v[6:9], v[220:223], v[228:231], v[6:9]
	v_mfma_f32_16x16x32_bf16 v[2:5], v[220:223], v[236:239], v[2:5]
	v_mfma_f32_16x16x32_bf16 v[30:33], v[200:203], v[232:235], v[30:33]
	v_mfma_f32_16x16x32_bf16 v[26:29], v[200:203], v[240:243], v[26:29]
	v_mfma_f32_16x16x32_bf16 v[22:25], v[208:211], v[232:235], v[22:25]
	v_mfma_f32_16x16x32_bf16 v[18:21], v[208:211], v[240:243], v[18:21]
	v_mfma_f32_16x16x32_bf16 v[14:17], v[216:219], v[232:235], v[14:17]
	v_mfma_f32_16x16x32_bf16 v[10:13], v[216:219], v[240:243], v[10:13]
	v_mfma_f32_16x16x32_bf16 v[6:9], v[224:227], v[232:235], v[6:9]
	v_mfma_f32_16x16x32_bf16 v[2:5], v[224:227], v[240:243], v[2:5]
	s_barrier
	ds_read_b128 v[180:183], v167
	ds_read_b128 v[184:187], v167 offset:1024
	ds_read_b128 v[188:191], v167 offset:2048
	ds_read_b128 v[192:195], v167 offset:3072
	v_readfirstlane_b32 s13, v166
	v_lshl_add_u64 v[228:229], v[244:245], 0, s[78:79]
	s_mov_b32 m0, s13
	v_readfirstlane_b32 s13, v168
	ds_read_b128 v[196:199], v147 offset:32768
	ds_read_b128 v[200:203], v147 offset:33792
	ds_read_b128 v[204:207], v146 offset:32768
	ds_read_b128 v[208:211], v146 offset:33792
	ds_read_b128 v[212:215], v145 offset:32768
	ds_read_b128 v[216:219], v145 offset:33792
	ds_read_b128 v[220:223], v144 offset:32768
	ds_read_b128 v[224:227], v144 offset:33792
	global_load_lds_dwordx4 v[228:229], off
	v_lshl_add_u64 v[228:229], v[246:247], 0, s[78:79]
	s_mov_b32 m0, s13
	s_nop 0
	global_load_lds_dwordx4 v[228:229], off
	s_waitcnt lgkmcnt(8)
	s_barrier
	s_waitcnt lgkmcnt(0)
	v_mfma_f32_16x16x32_bf16 v[126:129], v[196:199], v[180:183], v[126:129]
	v_mfma_f32_16x16x32_bf16 v[122:125], v[196:199], v[188:191], v[122:125]
	v_mfma_f32_16x16x32_bf16 v[118:121], v[204:207], v[180:183], v[118:121]
	v_mfma_f32_16x16x32_bf16 v[114:117], v[204:207], v[188:191], v[114:117]
	v_mfma_f32_16x16x32_bf16 v[110:113], v[212:215], v[180:183], v[110:113]
	v_mfma_f32_16x16x32_bf16 v[106:109], v[212:215], v[188:191], v[106:109]
	v_mfma_f32_16x16x32_bf16 v[102:105], v[220:223], v[180:183], v[102:105]
	v_mfma_f32_16x16x32_bf16 v[98:101], v[220:223], v[188:191], v[98:101]
	v_mfma_f32_16x16x32_bf16 v[126:129], v[200:203], v[184:187], v[126:129]
	v_mfma_f32_16x16x32_bf16 v[122:125], v[200:203], v[192:195], v[122:125]
	v_mfma_f32_16x16x32_bf16 v[118:121], v[208:211], v[184:187], v[118:121]
	v_mfma_f32_16x16x32_bf16 v[114:117], v[208:211], v[192:195], v[114:117]
	v_mfma_f32_16x16x32_bf16 v[110:113], v[216:219], v[184:187], v[110:113]
	v_mfma_f32_16x16x32_bf16 v[106:109], v[216:219], v[192:195], v[106:109]
	v_mfma_f32_16x16x32_bf16 v[102:105], v[224:227], v[184:187], v[102:105]
	v_mfma_f32_16x16x32_bf16 v[98:101], v[224:227], v[192:195], v[98:101]
	s_barrier
	v_readfirstlane_b32 s13, v169
	v_lshl_add_u64 v[252:253], v[248:249], 0, s[82:83]
	s_mov_b32 m0, s13
	v_readfirstlane_b32 s13, v170
	ds_read_b128 v[228:231], v161
	ds_read_b128 v[232:235], v161 offset:1024
	ds_read_b128 v[236:239], v161 offset:2048
	ds_read_b128 v[240:243], v161 offset:3072
	global_load_lds_dwordx4 v[252:253], off
	v_lshl_add_u64 v[252:253], v[250:251], 0, s[82:83]
	s_mov_b32 m0, s13
	s_nop 0
	global_load_lds_dwordx4 v[252:253], off
	s_barrier
	s_waitcnt lgkmcnt(0)
	v_mfma_f32_16x16x32_bf16 v[94:97], v[196:199], v[228:231], v[94:97]
	v_mfma_f32_16x16x32_bf16 v[90:93], v[196:199], v[236:239], v[90:93]
	v_mfma_f32_16x16x32_bf16 v[86:89], v[204:207], v[228:231], v[86:89]
	v_mfma_f32_16x16x32_bf16 v[82:85], v[204:207], v[236:239], v[82:85]
	v_mfma_f32_16x16x32_bf16 v[78:81], v[212:215], v[228:231], v[78:81]
	v_mfma_f32_16x16x32_bf16 v[74:77], v[212:215], v[236:239], v[74:77]
	v_mfma_f32_16x16x32_bf16 v[70:73], v[220:223], v[228:231], v[70:73]
	v_mfma_f32_16x16x32_bf16 v[66:69], v[220:223], v[236:239], v[66:69]
	v_mfma_f32_16x16x32_bf16 v[94:97], v[200:203], v[232:235], v[94:97]
	v_mfma_f32_16x16x32_bf16 v[90:93], v[200:203], v[240:243], v[90:93]
	v_mfma_f32_16x16x32_bf16 v[86:89], v[208:211], v[232:235], v[86:89]
	v_mfma_f32_16x16x32_bf16 v[82:85], v[208:211], v[240:243], v[82:85]
	v_mfma_f32_16x16x32_bf16 v[78:81], v[216:219], v[232:235], v[78:81]
	v_mfma_f32_16x16x32_bf16 v[74:77], v[216:219], v[240:243], v[74:77]
	v_mfma_f32_16x16x32_bf16 v[70:73], v[224:227], v[232:235], v[70:73]
	v_mfma_f32_16x16x32_bf16 v[66:69], v[224:227], v[240:243], v[66:69]
	v_readfirstlane_b32 s13, v171
	v_lshl_add_u64 v[244:245], v[244:245], 0, s[82:83]
	s_mov_b32 m0, s13
	v_readfirstlane_b32 s13, v172
	s_barrier
	ds_read_b128 v[196:199], v147 offset:49152
	ds_read_b128 v[200:203], v147 offset:50176
	ds_read_b128 v[204:207], v146 offset:49152
	ds_read_b128 v[208:211], v146 offset:50176
	ds_read_b128 v[212:215], v145 offset:49152
	ds_read_b128 v[216:219], v145 offset:50176
	ds_read_b128 v[220:223], v144 offset:49152
	ds_read_b128 v[224:227], v144 offset:50176
	global_load_lds_dwordx4 v[244:245], off
	v_lshl_add_u64 v[244:245], v[246:247], 0, s[82:83]
	s_mov_b32 m0, s13
	s_nop 0
	global_load_lds_dwordx4 v[244:245], off
	s_barrier
; #define STA(P, br, kt) STAGE(P, A, aoff0, aoff1, lda, br, kt)
; #define STB(P, br, kt) STAGE(P, Bt, boff0, boff1, ldb, br, kt)
; #define LDA(dst, b, h) _Pragma("unroll") for (int m = 0; m < 4; ++m) _Pragma("unroll") for (int k = 0; k < 2; ++k) \
;     dst[m][k] = *reinterpret_cast<const bf16x8*>((char*)SA(b, h) + lds_byte(wr * 64 + m * 16 + fr, k * 32 + fq * 8))
; #define LDB(dst, b, h) _Pragma("unroll") for (int n = 0; n < 2; ++n) _Pragma("unroll") for (int k = 0; k < 2; ++k) \
;     dst[n][k] = *reinterpret_cast<const bf16x8*>((char*)SB(b, h) + lds_byte(wc * 32 + n * 16 + fr, k * 32 + fq * 8))
; #define MMA(ai, bj, At, Bq) do { __builtin_amdgcn_s_setprio(1); \
;     _Pragma("unroll") for (int m = 0; m < 4; ++m) _Pragma("unroll") for (int n = 0; n < 2; ++n) _Pragma("unroll") for (int k = 0; k < 2; ++k) \
;       acc[ai][bj][m][n] = __builtin_amdgcn_mfma_f32_16x16x32_bf16(At[m][k], Bq[n][k], acc[ai][bj][m][n], 0, 0, 0); \
;     __builtin_amdgcn_s_setprio(0); } while (0)
; #define WAIT_V(n) asm volatile("s_waitcnt vmcnt(" #n ")" ::: "memory")
; #define WAIT_L(n) asm volatile("s_waitcnt lgkmcnt(" #n ")" ::: "memory")
; #define BAR __builtin_amdgcn_s_barrier()
; #define SCHED __builtin_amdgcn_sched_barrier(0)
; __device__ __forceinline__ void gemm256(const u16* __restrict__ A, int lda, const u16* __restrict__ Bt, int ldb, int K,
;                                         f32x4 (&acc)[2][2][4][2], const int g_wid) {
;     ...
;     LDA(At, 1, 1); STA(SA(1, 0), 0, t + 3);
;     BAR; WAIT_L(0); MMA(1, 0, At, B0); BAR; SCHED;
;     STB(SB(1, 1), HALF, t + 3);
;     WAIT_V(6); BAR; MMA(1, 1, At, B1); BAR;
;   }
;   { LDB(B0, 0, 0); LDA(At, 0, 0); STA(SA(1, 1), HALF, nt - 1);
;     BAR; WAIT_L(0); MMA(0, 0, At, B0); BAR;
	s_waitcnt lgkmcnt(0)
	v_mfma_f32_16x16x32_bf16 v[62:65], v[196:199], v[180:183], v[62:65]
	v_mfma_f32_16x16x32_bf16 v[58:61], v[196:199], v[188:191], v[58:61]
	v_mfma_f32_16x16x32_bf16 v[54:57], v[204:207], v[180:183], v[54:57]
	v_mfma_f32_16x16x32_bf16 v[50:53], v[204:207], v[188:191], v[50:53]
	v_mfma_f32_16x16x32_bf16 v[46:49], v[212:215], v[180:183], v[46:49]
	v_mfma_f32_16x16x32_bf16 v[42:45], v[212:215], v[188:191], v[42:45]
	v_mfma_f32_16x16x32_bf16 v[38:41], v[220:223], v[180:183], v[38:41]
	v_mfma_f32_16x16x32_bf16 v[34:37], v[220:223], v[188:191], v[34:37]
	v_mfma_f32_16x16x32_bf16 v[62:65], v[200:203], v[184:187], v[62:65]
	v_mfma_f32_16x16x32_bf16 v[58:61], v[200:203], v[192:195], v[58:61]
	v_mfma_f32_16x16x32_bf16 v[54:57], v[208:211], v[184:187], v[54:57]
	v_mfma_f32_16x16x32_bf16 v[50:53], v[208:211], v[192:195], v[50:53]
	v_mfma_f32_16x16x32_bf16 v[46:49], v[216:219], v[184:187], v[46:49]
	v_mfma_f32_16x16x32_bf16 v[42:45], v[216:219], v[192:195], v[42:45]
	v_mfma_f32_16x16x32_bf16 v[38:41], v[224:227], v[184:187], v[38:41]
	v_mfma_f32_16x16x32_bf16 v[34:37], v[224:227], v[192:195], v[34:37]
	s_barrier
	v_readfirstlane_b32 s13, v173
	v_lshl_add_u64 v[180:181], v[248:249], 0, s[86:87]
	s_mov_b32 m0, s13
	v_readfirstlane_b32 s13, v174
	global_load_lds_dwordx4 v[180:181], off
	v_lshl_add_u64 v[180:181], v[250:251], 0, s[86:87]
	s_mov_b32 m0, s13
	s_nop 0
	global_load_lds_dwordx4 v[180:181], off
	s_waitcnt vmcnt(6)
	s_barrier
	v_mfma_f32_16x16x32_bf16 v[30:33], v[196:199], v[228:231], v[30:33]
	v_mfma_f32_16x16x32_bf16 v[26:29], v[196:199], v[236:239], v[26:29]
	v_mfma_f32_16x16x32_bf16 v[22:25], v[204:207], v[228:231], v[22:25]
	v_mfma_f32_16x16x32_bf16 v[18:21], v[204:207], v[236:239], v[18:21]
	v_mfma_f32_16x16x32_bf16 v[14:17], v[212:215], v[228:231], v[14:17]
	v_mfma_f32_16x16x32_bf16 v[10:13], v[212:215], v[236:239], v[10:13]
	v_mfma_f32_16x16x32_bf16 v[6:9], v[220:223], v[228:231], v[6:9]
	v_mfma_f32_16x16x32_bf16 v[2:5], v[220:223], v[236:239], v[2:5]
	v_mfma_f32_16x16x32_bf16 v[30:33], v[200:203], v[232:235], v[30:33]
	v_mfma_f32_16x16x32_bf16 v[26:29], v[200:203], v[240:243], v[26:29]
	v_mfma_f32_16x16x32_bf16 v[22:25], v[208:211], v[232:235], v[22:25]
	v_mfma_f32_16x16x32_bf16 v[18:21], v[208:211], v[240:243], v[18:21]
	v_mfma_f32_16x16x32_bf16 v[14:17], v[216:219], v[232:235], v[14:17]
	v_mfma_f32_16x16x32_bf16 v[10:13], v[216:219], v[240:243], v[10:13]
	v_mfma_f32_16x16x32_bf16 v[6:9], v[224:227], v[232:235], v[6:9]
	v_mfma_f32_16x16x32_bf16 v[2:5], v[224:227], v[240:243], v[2:5]
	s_add_i32 s9, s9, 2
	s_add_u32 s16, s16, 0x100
	s_addc_u32 s17, s17, 0
	s_cmp_lt_u32 s9, 12
	s_barrier
	s_cbranch_scc1 .LBB0_465
	s_add_u32 s14, s14, 0x40780
	s_addc_u32 s15, s15, 0
	v_readfirstlane_b32 s9, v177
	v_lshl_add_u64 v[132:133], v[132:133], 1, s[14:15]
	s_mov_b32 m0, s9
	v_readfirstlane_b32 s9, v178
	ds_read_b128 v[134:137], v176
	ds_read_b128 v[138:141], v176 offset:1024
	ds_read_b128 v[162:165], v176 offset:2048
	ds_read_b128 v[168:171], v176 offset:3072
	ds_read_b128 v[180:183], v147
	ds_read_b128 v[184:187], v147 offset:1024
	ds_read_b128 v[188:191], v146
	ds_read_b128 v[192:195], v146 offset:1024
	ds_read_b128 v[196:199], v145
	ds_read_b128 v[200:203], v145 offset:1024
	ds_read_b128 v[204:207], v144
	ds_read_b128 v[208:211], v144 offset:1024
	global_load_lds_dwordx4 v[132:133], off
	v_lshl_add_u64 v[130:131], v[130:131], 1, s[14:15]
	s_mov_b32 m0, s9
	s_nop 0
	global_load_lds_dwordx4 v[130:131], off
	s_barrier
	s_waitcnt lgkmcnt(0)
	v_mfma_f32_16x16x32_bf16 v[126:129], v[180:183], v[134:137], v[126:129]
	v_mfma_f32_16x16x32_bf16 v[118:121], v[188:191], v[134:137], v[118:121]
	v_mfma_f32_16x16x32_bf16 v[114:117], v[188:191], v[162:165], v[114:117]
	v_mfma_f32_16x16x32_bf16 v[102:105], v[204:207], v[134:137], v[102:105]
	v_mfma_f32_16x16x32_bf16 v[126:129], v[184:187], v[138:141], v[126:129]
	v_mfma_f32_16x16x32_bf16 v[122:125], v[180:183], v[162:165], v[122:125]
	v_mfma_f32_16x16x32_bf16 v[118:121], v[192:195], v[138:141], v[118:121]
	v_mfma_f32_16x16x32_bf16 v[114:117], v[192:195], v[168:171], v[114:117]
	v_mfma_f32_16x16x32_bf16 v[110:113], v[196:199], v[134:137], v[110:113]
	v_mfma_f32_16x16x32_bf16 v[106:109], v[196:199], v[162:165], v[106:109]
	v_mfma_f32_16x16x32_bf16 v[102:105], v[208:211], v[138:141], v[102:105]
	v_mfma_f32_16x16x32_bf16 v[98:101], v[204:207], v[162:165], v[98:101]
	v_mfma_f32_16x16x32_bf16 v[130:133], v[184:187], v[168:171], v[122:125]
	v_mfma_f32_16x16x32_bf16 v[176:179], v[200:203], v[138:141], v[110:113]
	v_mfma_f32_16x16x32_bf16 v[212:215], v[200:203], v[168:171], v[106:109]
	v_mfma_f32_16x16x32_bf16 v[216:219], v[208:211], v[168:171], v[98:101]
	s_barrier
	s_nop 1
	ds_read_b128 v[98:101], v175
	ds_read_b128 v[106:109], v175 offset:1024
	ds_read_b128 v[110:113], v175 offset:2048
	ds_read_b128 v[122:125], v175 offset:3072
	s_barrier
	s_waitcnt lgkmcnt(0)
	v_mfma_f32_16x16x32_bf16 v[94:97], v[180:183], v[98:101], v[94:97]
	v_mfma_f32_16x16x32_bf16 v[86:89], v[188:191], v[98:101], v[86:89]
	v_mfma_f32_16x16x32_bf16 v[82:85], v[188:191], v[110:113], v[82:85]
	v_mfma_f32_16x16x32_bf16 v[70:73], v[204:207], v[98:101], v[70:73]
	v_mfma_f32_16x16x32_bf16 v[94:97], v[184:187], v[106:109], v[94:97]
	v_mfma_f32_16x16x32_bf16 v[90:93], v[180:183], v[110:113], v[90:93]
	v_mfma_f32_16x16x32_bf16 v[86:89], v[192:195], v[106:109], v[86:89]
	v_mfma_f32_16x16x32_bf16 v[82:85], v[192:195], v[122:125], v[82:85]
	v_mfma_f32_16x16x32_bf16 v[78:81], v[196:199], v[98:101], v[78:81]
	v_mfma_f32_16x16x32_bf16 v[74:77], v[196:199], v[110:113], v[74:77]
	v_mfma_f32_16x16x32_bf16 v[70:73], v[208:211], v[106:109], v[70:73]
	v_mfma_f32_16x16x32_bf16 v[66:69], v[204:207], v[110:113], v[66:69]
	v_mfma_f32_16x16x32_bf16 v[172:175], v[184:187], v[122:125], v[90:93]
	v_mfma_f32_16x16x32_bf16 v[180:183], v[200:203], v[106:109], v[78:81]
	v_mfma_f32_16x16x32_bf16 v[184:187], v[200:203], v[122:125], v[74:77]
	v_mfma_f32_16x16x32_bf16 v[188:191], v[208:211], v[122:125], v[66:69]
	s_barrier
; #define LDA(dst, b, h) _Pragma("unroll") for (int m = 0; m < 4; ++m) _Pragma("unroll") for (int k = 0; k < 2; ++k) \
;     dst[m][k] = *reinterpret_cast<const bf16x8*>((char*)SA(b, h) + lds_byte(wr * 64 + m * 16 + fr, k * 32 + fq * 8))
; #define LDB(dst, b, h) _Pragma("unroll") for (int n = 0; n < 2; ++n) _Pragma("unroll") for (int k = 0; k < 2; ++k) \
;     dst[n][k] = *reinterpret_cast<const bf16x8*>((char*)SB(b, h) + lds_byte(wc * 32 + n * 16 + fr, k * 32 + fq * 8))
; #define MMA(ai, bj, At, Bq) do { __builtin_amdgcn_s_setprio(1); \
;     _Pragma("unroll") for (int m = 0; m < 4; ++m) _Pragma("unroll") for (int n = 0; n < 2; ++n) _Pragma("unroll") for (int k = 0; k < 2; ++k) \
;       acc[ai][bj][m][n] = __builtin_amdgcn_mfma_f32_16x16x32_bf16(At[m][k], Bq[n][k], acc[ai][bj][m][n], 0, 0, 0); \
;     __builtin_amdgcn_s_setprio(0); } while (0)
; #define WAIT_V(n) asm volatile("s_waitcnt vmcnt(" #n ")" ::: "memory")
; #define WAIT_L(n) asm volatile("s_waitcnt lgkmcnt(" #n ")" ::: "memory")
; #define BAR __builtin_amdgcn_s_barrier()
; __device__ __forceinline__ void gemm256(const u16* __restrict__ A, int lda, const u16* __restrict__ Bt, int ldb, int K,
;                                         f32x4 (&acc)[2][2][4][2], const int g_wid) {
;     ...
;     LDA(At, 0, 1); WAIT_V(4); BAR; WAIT_L(0); MMA(1, 0, At, B0); MMA(1, 1, At, B1); BAR; }
;   { LDB(B0, 1, 0); LDA(At, 1, 0); WAIT_V(2); BAR; WAIT_L(0); MMA(0, 0, At, B0); BAR;
	s_nop 1
	ds_read_b128 v[66:69], v147 offset:16384
	ds_read_b128 v[74:77], v147 offset:17408
	ds_read_b128 v[78:81], v146 offset:16384
	ds_read_b128 v[90:93], v146 offset:17408
	ds_read_b128 v[192:195], v145 offset:16384
	ds_read_b128 v[196:199], v145 offset:17408
	ds_read_b128 v[200:203], v144 offset:16384
	ds_read_b128 v[204:207], v144 offset:17408
	s_waitcnt vmcnt(4)
	s_barrier
	s_waitcnt lgkmcnt(0)
	v_mfma_f32_16x16x32_bf16 v[62:65], v[66:69], v[134:137], v[62:65]
	v_mfma_f32_16x16x32_bf16 v[54:57], v[78:81], v[134:137], v[54:57]
	v_mfma_f32_16x16x32_bf16 v[46:49], v[192:195], v[134:137], v[46:49]
	v_mfma_f32_16x16x32_bf16 v[38:41], v[200:203], v[134:137], v[38:41]
	v_mfma_f32_16x16x32_bf16 v[62:65], v[74:77], v[138:141], v[62:65]
	v_mfma_f32_16x16x32_bf16 v[58:61], v[66:69], v[162:165], v[58:61]
	v_mfma_f32_16x16x32_bf16 v[54:57], v[90:93], v[138:141], v[54:57]
	v_mfma_f32_16x16x32_bf16 v[50:53], v[78:81], v[162:165], v[50:53]
	v_mfma_f32_16x16x32_bf16 v[46:49], v[196:199], v[138:141], v[46:49]
	v_mfma_f32_16x16x32_bf16 v[42:45], v[192:195], v[162:165], v[42:45]
	v_mfma_f32_16x16x32_bf16 v[38:41], v[204:207], v[138:141], v[38:41]
	v_mfma_f32_16x16x32_bf16 v[34:37], v[200:203], v[162:165], v[34:37]
	v_mfma_f32_16x16x32_bf16 v[208:211], v[74:77], v[168:171], v[58:61]
	v_mfma_f32_16x16x32_bf16 v[220:223], v[90:93], v[168:171], v[50:53]
	v_mfma_f32_16x16x32_bf16 v[224:227], v[196:199], v[168:171], v[42:45]
	v_mfma_f32_16x16x32_bf16 v[134:137], v[204:207], v[168:171], v[34:37]
	v_mfma_f32_16x16x32_bf16 v[30:33], v[66:69], v[98:101], v[30:33]
	v_mfma_f32_16x16x32_bf16 v[22:25], v[78:81], v[98:101], v[22:25]
	v_mfma_f32_16x16x32_bf16 v[14:17], v[192:195], v[98:101], v[14:17]
	v_mfma_f32_16x16x32_bf16 v[6:9], v[200:203], v[98:101], v[6:9]
	v_mfma_f32_16x16x32_bf16 v[30:33], v[74:77], v[106:109], v[30:33]
	v_mfma_f32_16x16x32_bf16 v[26:29], v[66:69], v[110:113], v[26:29]
	v_mfma_f32_16x16x32_bf16 v[22:25], v[90:93], v[106:109], v[22:25]
	v_mfma_f32_16x16x32_bf16 v[18:21], v[78:81], v[110:113], v[18:21]
	v_mfma_f32_16x16x32_bf16 v[14:17], v[196:199], v[106:109], v[14:17]
	v_mfma_f32_16x16x32_bf16 v[10:13], v[192:195], v[110:113], v[10:13]
	v_mfma_f32_16x16x32_bf16 v[6:9], v[204:207], v[106:109], v[6:9]
	v_mfma_f32_16x16x32_bf16 v[2:5], v[200:203], v[110:113], v[2:5]
	v_mfma_f32_16x16x32_bf16 v[138:141], v[74:77], v[122:125], v[26:29]
	v_mfma_f32_16x16x32_bf16 v[162:165], v[90:93], v[122:125], v[18:21]
	v_mfma_f32_16x16x32_bf16 v[168:171], v[196:199], v[122:125], v[10:13]
	v_mfma_f32_16x16x32_bf16 v[192:195], v[204:207], v[122:125], v[2:5]
	s_barrier
	ds_read_b128 v[196:199], v167
	ds_read_b128 v[200:203], v167 offset:1024
	ds_read_b128 v[204:207], v167 offset:2048
	ds_read_b128 v[228:231], v167 offset:3072
	ds_read_b128 v[2:5], v147 offset:32768
	ds_read_b128 v[10:13], v147 offset:33792
	ds_read_b128 v[18:21], v146 offset:32768
	ds_read_b128 v[34:37], v146 offset:33792
	ds_read_b128 v[232:235], v145 offset:32768
	ds_read_b128 v[236:239], v145 offset:33792
	ds_read_b128 v[240:243], v144 offset:32768
	ds_read_b128 v[244:247], v144 offset:33792
	s_waitcnt vmcnt(2)
	s_barrier
	s_waitcnt lgkmcnt(0)
	v_mfma_f32_16x16x32_bf16 v[26:29], v[2:5], v[196:199], v[126:129]
	v_mfma_f32_16x16x32_bf16 v[122:125], v[10:13], v[200:203], v[26:29]
	v_mfma_f32_16x16x32_bf16 v[26:29], v[2:5], v[204:207], v[130:133]
	v_mfma_f32_16x16x32_bf16 v[90:93], v[10:13], v[228:231], v[26:29]
	v_mfma_f32_16x16x32_bf16 v[26:29], v[18:21], v[196:199], v[118:121]
	v_mfma_f32_16x16x32_bf16 v[110:113], v[34:37], v[200:203], v[26:29]
	v_mfma_f32_16x16x32_bf16 v[26:29], v[18:21], v[204:207], v[114:117]
	v_mfma_f32_16x16x32_bf16 v[78:81], v[34:37], v[228:231], v[26:29]
	v_mfma_f32_16x16x32_bf16 v[26:29], v[232:235], v[196:199], v[176:179]
	v_mfma_f32_16x16x32_bf16 v[106:109], v[236:239], v[200:203], v[26:29]
	v_mfma_f32_16x16x32_bf16 v[26:29], v[232:235], v[204:207], v[212:215]
	v_mfma_f32_16x16x32_bf16 v[74:77], v[236:239], v[228:231], v[26:29]
	v_mfma_f32_16x16x32_bf16 v[26:29], v[240:243], v[196:199], v[102:105]
	v_mfma_f32_16x16x32_bf16 v[98:101], v[244:247], v[200:203], v[26:29]
	v_mfma_f32_16x16x32_bf16 v[26:29], v[240:243], v[204:207], v[216:219]
	v_mfma_f32_16x16x32_bf16 v[66:69], v[244:247], v[228:231], v[26:29]
	s_barrier
; #define LDA(dst, b, h) _Pragma("unroll") for (int m = 0; m < 4; ++m) _Pragma("unroll") for (int k = 0; k < 2; ++k) \
;     dst[m][k] = *reinterpret_cast<const bf16x8*>((char*)SA(b, h) + lds_byte(wr * 64 + m * 16 + fr, k * 32 + fq * 8))
; #define LDB(dst, b, h) _Pragma("unroll") for (int n = 0; n < 2; ++n) _Pragma("unroll") for (int k = 0; k < 2; ++k) \
;     dst[n][k] = *reinterpret_cast<const bf16x8*>((char*)SB(b, h) + lds_byte(wc * 32 + n * 16 + fr, k * 32 + fq * 8))
; #define MMA(ai, bj, At, Bq) do { __builtin_amdgcn_s_setprio(1); \
;     _Pragma("unroll") for (int m = 0; m < 4; ++m) _Pragma("unroll") for (int n = 0; n < 2; ++n) _Pragma("unroll") for (int k = 0; k < 2; ++k) \
;       acc[ai][bj][m][n] = __builtin_amdgcn_mfma_f32_16x16x32_bf16(At[m][k], Bq[n][k], acc[ai][bj][m][n], 0, 0, 0); \
;     __builtin_amdgcn_s_setprio(0); } while (0)
; #define WAIT_V(n) asm volatile("s_waitcnt vmcnt(" #n ")" ::: "memory")
; #define WAIT_L(n) asm volatile("s_waitcnt lgkmcnt(" #n ")" ::: "memory")
; #define BAR __builtin_amdgcn_s_barrier()
; __device__ __forceinline__ void gemm256(const u16* __restrict__ A, int lda, const u16* __restrict__ Bt, int ldb, int K,
;                                         f32x4 (&acc)[2][2][4][2], const int g_wid) {
;     ...
;   { LDB(B0, 1, 0); LDA(At, 1, 0); WAIT_V(2); BAR; WAIT_L(0); MMA(0, 0, At, B0); BAR;
;     LDB(B1, 1, 1); WAIT_V(0); BAR; WAIT_L(0); MMA(0, 1, At, B1); BAR;
;     LDA(At, 1, 1); BAR; WAIT_L(0); MMA(1, 0, At, B0); MMA(1, 1, At, B1); BAR; }
;   if (wr == 0) BAR;
	ds_read_b128 v[130:133], v161
	ds_read_b128 v[176:179], v161 offset:1024
	ds_read_b128 v[212:215], v161 offset:2048
	ds_read_b128 v[216:219], v161 offset:3072
	s_waitcnt vmcnt(0)
	s_barrier
	s_waitcnt lgkmcnt(0)
	v_mfma_f32_16x16x32_bf16 v[26:29], v[2:5], v[130:133], v[94:97]
	v_mfma_f32_16x16x32_bf16 v[2:5], v[2:5], v[212:215], v[172:175]
	v_mfma_f32_16x16x32_bf16 v[58:61], v[10:13], v[176:179], v[26:29]
	v_mfma_f32_16x16x32_bf16 v[26:29], v[10:13], v[216:219], v[2:5]
	v_mfma_f32_16x16x32_bf16 v[2:5], v[18:21], v[130:133], v[86:89]
	v_mfma_f32_16x16x32_bf16 v[50:53], v[34:37], v[176:179], v[2:5]
	v_mfma_f32_16x16x32_bf16 v[2:5], v[18:21], v[212:215], v[82:85]
	v_mfma_f32_16x16x32_bf16 v[18:21], v[34:37], v[216:219], v[2:5]
	v_mfma_f32_16x16x32_bf16 v[2:5], v[232:235], v[130:133], v[180:183]
	v_mfma_f32_16x16x32_bf16 v[42:45], v[236:239], v[176:179], v[2:5]
	v_mfma_f32_16x16x32_bf16 v[2:5], v[232:235], v[212:215], v[184:187]
	v_mfma_f32_16x16x32_bf16 v[10:13], v[236:239], v[216:219], v[2:5]
	v_mfma_f32_16x16x32_bf16 v[2:5], v[240:243], v[130:133], v[70:73]
	v_mfma_f32_16x16x32_bf16 v[34:37], v[244:247], v[176:179], v[2:5]
	v_mfma_f32_16x16x32_bf16 v[2:5], v[240:243], v[212:215], v[188:191]
	v_mfma_f32_16x16x32_bf16 v[2:5], v[244:247], v[216:219], v[2:5]
	s_barrier
	ds_read_b128 v[172:175], v147 offset:49152
	ds_read_b128 v[180:183], v147 offset:50176
	ds_read_b128 v[184:187], v146 offset:49152
	ds_read_b128 v[188:191], v146 offset:50176
	ds_read_b128 v[232:235], v145 offset:49152
	ds_read_b128 v[236:239], v145 offset:50176
	ds_read_b128 v[240:243], v144 offset:49152
	ds_read_b128 v[144:147], v144 offset:50176
	s_barrier
	s_waitcnt lgkmcnt(0)
	v_mfma_f32_16x16x32_bf16 v[62:65], v[172:175], v[196:199], v[62:65]
	v_mfma_f32_16x16x32_bf16 v[54:57], v[184:187], v[196:199], v[54:57]
	v_mfma_f32_16x16x32_bf16 v[46:49], v[232:235], v[196:199], v[46:49]
	v_mfma_f32_16x16x32_bf16 v[38:41], v[240:243], v[196:199], v[38:41]
	v_mfma_f32_16x16x32_bf16 v[126:129], v[180:183], v[200:203], v[62:65]
	v_mfma_f32_16x16x32_bf16 v[62:65], v[172:175], v[204:207], v[208:211]
	v_mfma_f32_16x16x32_bf16 v[118:121], v[188:191], v[200:203], v[54:57]
	v_mfma_f32_16x16x32_bf16 v[54:57], v[184:187], v[204:207], v[220:223]
	v_mfma_f32_16x16x32_bf16 v[114:117], v[236:239], v[200:203], v[46:49]
	v_mfma_f32_16x16x32_bf16 v[46:49], v[232:235], v[204:207], v[224:227]
	v_mfma_f32_16x16x32_bf16 v[102:105], v[144:147], v[200:203], v[38:41]
	v_mfma_f32_16x16x32_bf16 v[38:41], v[240:243], v[204:207], v[134:137]
	v_mfma_f32_16x16x32_bf16 v[94:97], v[180:183], v[228:231], v[62:65]
	v_mfma_f32_16x16x32_bf16 v[86:89], v[188:191], v[228:231], v[54:57]
	v_mfma_f32_16x16x32_bf16 v[82:85], v[236:239], v[228:231], v[46:49]
	v_mfma_f32_16x16x32_bf16 v[70:73], v[144:147], v[228:231], v[38:41]
	v_mfma_f32_16x16x32_bf16 v[30:33], v[172:175], v[130:133], v[30:33]
	v_mfma_f32_16x16x32_bf16 v[22:25], v[184:187], v[130:133], v[22:25]
	v_mfma_f32_16x16x32_bf16 v[14:17], v[232:235], v[130:133], v[14:17]
	v_mfma_f32_16x16x32_bf16 v[6:9], v[240:243], v[130:133], v[6:9]
	v_mfma_f32_16x16x32_bf16 v[62:65], v[180:183], v[176:179], v[30:33]
	v_mfma_f32_16x16x32_bf16 v[30:33], v[172:175], v[212:215], v[138:141]
	v_mfma_f32_16x16x32_bf16 v[54:57], v[188:191], v[176:179], v[22:25]
	v_mfma_f32_16x16x32_bf16 v[22:25], v[184:187], v[212:215], v[162:165]
	v_mfma_f32_16x16x32_bf16 v[46:49], v[236:239], v[176:179], v[14:17]
	v_mfma_f32_16x16x32_bf16 v[14:17], v[232:235], v[212:215], v[168:171]
	v_mfma_f32_16x16x32_bf16 v[38:41], v[144:147], v[176:179], v[6:9]
	v_mfma_f32_16x16x32_bf16 v[6:9], v[240:243], v[212:215], v[192:195]
	v_mfma_f32_16x16x32_bf16 v[30:33], v[180:183], v[216:219], v[30:33]
	v_mfma_f32_16x16x32_bf16 v[22:25], v[188:191], v[216:219], v[22:25]
	v_mfma_f32_16x16x32_bf16 v[14:17], v[236:239], v[216:219], v[14:17]
	v_mfma_f32_16x16x32_bf16 v[6:9], v[144:147], v[216:219], v[6:9]
	s_setprio 0
	s_movk_i32 s9, 0x100
	v_cmp_gt_u32_e32 vcc, s9, v0
	s_barrier
	s_and_saveexec_b64 s[14:15], vcc
	s_cbranch_execz .LBB0_455
	s_barrier
	s_branch .LBB0_455

; #define hw_tid() ((g_wid << 6) | hw_lane())
; #define STA(P, br, kt) STAGE(P, A, aoff0, aoff1, lda, br, kt)
; #define STB(P, br, kt) STAGE(P, Bt, boff0, boff1, ldb, br, kt)
; #define BAR __builtin_amdgcn_s_barrier()
; __device__ __forceinline__ void gemm256(const u16* __restrict__ A, int lda, const u16* __restrict__ Bt, int ldb, int K,
;                                         f32x4 (&acc)[2][2][4][2], const int g_wid) {
;   int tid = hw_tid(); asm volatile("" : "+v"(tid));
;   const int wid = tid >> 6, lane = tid & 63, wr = wid >> 2, wc = wid & 3, fr = lane & 15, fq = lane >> 4;
;   int r0, c0, r1, c1;
;   stage_rc(tid * 16, r0, c0);
;   stage_rc(tid * 16 + 8192, r1, c1);
;   const int aoff0 = r0 * lda + c0, aoff1 = r1 * lda + c1, boff0 = r0 * ldb + c0, boff1 = r1 * ldb + c1;
;   bf16x8 At[4][2], B0[2][2], B1[2][2];
;   const int nt = K / BK;
;   STB(SB(0, 0), 0, 0); STA(SA(0, 0), 0, 0);
;   STB(SB(0, 1), HALF, 0); STA(SA(0, 1), HALF, 0);
;   if (wr == 1) BAR;
; __device__ __forceinline__ void tile_map(int t, int nM, int nN, int& pm, int& pn) {
;   int nwg = nM * nN, q = nwg / 8, r = nwg % 8, xcd = t % 8, off = t / 8;
;   int wgid = (xcd < r ? xcd * (q + 1) : r * (q + 1) + (xcd - r) * q) + off;
;   const int WGM = 8;
;   int nig = WGM * nN, gid = wgid / nig, fm = gid * WGM, gsz = min(nM - fm, WGM);
;   pm = __builtin_amdgcn_readfirstlane(fm + ((wgid % nig) % gsz)); pn = __builtin_amdgcn_readfirstlane((wgid % nig) / gsz);
; }
.LBB0_485:
	s_add_i32 s2, s9, s2
	s_ashr_i32 s3, s2, 31
	s_lshr_b32 s3, s3, 27
	s_add_i32 s3, s2, s3
	s_ashr_i32 s8, s3, 5
	s_lshl_b32 s9, s8, 3
	s_sub_i32 s8, 0xc1, s9
	s_min_u32 s10, s8, 8
	s_andn2_b32 s3, s3, 31
	s_sub_i32 s11, s2, s3
	s_waitcnt lgkmcnt(0)
	v_cvt_f32_ubyte0_e32 v2, s10
	v_cvt_f32_i32_e32 v0, s11
	v_rcp_iflag_f32_e32 v3, v2
	s_ashr_i32 s2, s11, 30
	s_or_b32 s8, s2, 1
	v_mul_f32_e32 v3, v0, v3
	v_trunc_f32_e32 v3, v3
	v_fma_f32 v0, -v3, v2, v0
	v_cvt_i32_f32_e32 v3, v3
	v_cmp_ge_f32_e64 s[2:3], |v0|, v2
	s_and_b64 s[2:3], s[2:3], exec
	s_cselect_b32 s2, s8, 0
	v_readfirstlane_b32 s3, v3
	s_add_i32 s2, s3, s2
	s_sext_i32_i8 s8, s2
	s_mul_i32 s2, s2, s10
	s_sub_i32 s2, s11, s2
	s_sext_i32_i8 s2, s2
	s_bfe_i64 s[10:11], s[8:9], 0x100000
	s_add_i32 s2, s9, s2
	s_lshl_b64 s[12:13], s[10:11], 19
	s_add_u32 s10, s23, s12
	s_addc_u32 s11, s24, s13
	s_ashr_i32 s3, s2, 31
	s_lshl_b64 s[14:15], s[2:3], 19
	s_mov_b32 s3, -1
	s_add_u32 s16, s21, s14
	v_mbcnt_lo_u32_b32 v0, s3, 0
	v_mbcnt_hi_u32_b32 v0, s3, v0
	v_readlane_b32 s3, v254, 63
	s_addc_u32 s17, s22, s15
	s_add_u32 s18, s16, 0x40000
	v_or_b32_e32 v0, s3, v0
	v_readlane_b32 s3, v254, 40
	v_ashrrev_i32_e32 v2, 31, v0
	v_lshrrev_b32_e32 v2, 26, v2
	v_add_u32_e32 v2, v0, v2
	v_ashrrev_i32_e32 v11, 6, v2
	v_bfe_i32 v2, v0, 27, 1
	v_lshlrev_b32_e32 v19, 4, v0
	v_lshrrev_b32_e32 v2, 22, v2
	v_add_u32_e32 v2, v19, v2
	v_and_b32_e32 v2, 0xfffffc00, v2
	v_sub_u32_e32 v2, v19, v2
	v_lshrrev_b32_e32 v3, 4, v2
	v_bitop3_b32 v2, v3, v2, 32 bitop3:0x6c
	v_ashrrev_i32_e32 v4, 31, v2
	v_lshrrev_b32_e32 v4, 26, v4
	v_add_u32_e32 v4, v2, v4
	v_ashrrev_i32_e32 v13, 6, v4
	v_and_b32_e32 v4, 0xc0, v4
	v_sub_u32_e32 v2, v2, v4
	v_ashrrev_i16_sdwa v15, v151, sext(v2) dst_sel:DWORD dst_unused:UNUSED_PAD src0_sel:DWORD src1_sel:BYTE_0
	v_add_u32_e32 v2, 0x2000, v19
	v_ashrrev_i32_e32 v4, 31, v2
	v_lshrrev_b32_e32 v4, 22, v4
	v_add_u32_e32 v4, v2, v4
	v_ashrrev_i32_e32 v12, 10, v4
	v_mul_i32_i24_e32 v4, 0x400, v12
	v_sub_u32_e32 v2, v2, v4
	v_lshrrev_b32_e32 v4, 4, v2
	v_lshlrev_b32_e32 v5, 5, v11
	v_bitop3_b32 v2, v4, v2, 32 bitop3:0x6c
	v_and_b32_e32 v14, 32, v5
	v_ashrrev_i32_e32 v5, 31, v2
	v_lshrrev_b32_e32 v5, 26, v5
	v_lshlrev_b32_e32 v3, 3, v11
	v_add_u32_e32 v5, v2, v5
	v_and_b32_e32 v3, 0x3ffff0, v3
	v_lshlrev_b32_e32 v4, 3, v12
	v_ashrrev_i32_e32 v16, 6, v5
	v_and_b32_e32 v5, 0xc0, v5
	v_add_u32_e32 v3, v13, v3
	v_and_b32_e32 v4, 0x3ffff0, v4
	v_lshlrev_b32_e32 v6, 5, v12
	v_sub_u32_e32 v2, v2, v5
	v_add_u32_e32 v4, v16, v4
	v_and_b32_e32 v17, 32, v6
	v_ashrrev_i16_sdwa v18, v151, sext(v2) dst_sel:DWORD dst_unused:UNUSED_PAD src0_sel:DWORD src1_sel:BYTE_0
	v_lshl_or_b32 v2, v3, 10, v14
	v_add_u32_sdwa v132, v2, sext(v15) dst_sel:DWORD dst_unused:UNUSED_PAD src0_sel:DWORD src1_sel:WORD_0
	v_lshl_or_b32 v2, v4, 10, v17
	v_add_u32_sdwa v130, v2, sext(v18) dst_sel:DWORD dst_unused:UNUSED_PAD src0_sel:DWORD src1_sel:WORD_0
	v_ashrrev_i32_e32 v133, 31, v132
	v_add_u32_e32 v146, s3, v19
	v_lshlrev_b64 v[20:21], 1, v[132:133]
	v_readfirstlane_b32 s3, v146
	v_ashrrev_i32_e32 v131, 31, v130
	v_add_u32_e32 v147, 0x2000, v146
	v_lshl_add_u64 v[2:3], s[16:17], 0, v[20:21]
	s_mov_b32 m0, s3
	v_lshlrev_b64 v[22:23], 1, v[130:131]
	v_readfirstlane_b32 s3, v147
	v_add_u32_e32 v159, 0, v19
	global_load_lds_dwordx4 v[2:3], off
	v_lshl_add_u64 v[6:7], s[16:17], 0, v[22:23]
	s_mov_b32 m0, s3
	v_readfirstlane_b32 s3, v159
	v_add_u32_e32 v161, 0x2000, v159
	global_load_lds_dwordx4 v[6:7], off
	v_lshl_add_u64 v[8:9], s[10:11], 0, v[20:21]
	s_mov_b32 m0, s3
	v_readfirstlane_b32 s3, v161
	global_load_lds_dwordx4 v[8:9], off
	s_mov_b32 m0, s3
	v_readlane_b32 s3, v254, 41
	v_lshl_add_u64 v[4:5], s[10:11], 0, v[22:23]
	s_addc_u32 s19, s17, 0
	v_add_u32_e32 v162, s3, v19
	global_load_lds_dwordx4 v[4:5], off
	v_readfirstlane_b32 s3, v162
	v_lshl_add_u64 v[24:25], s[18:19], 0, v[20:21]
	s_mov_b32 m0, s3
	v_add_u32_e32 v163, 0x2000, v162
	global_load_lds_dwordx4 v[24:25], off
	v_lshl_add_u64 v[24:25], s[18:19], 0, v[22:23]
	v_readfirstlane_b32 s3, v163
	s_add_u32 s18, s10, 0x40000
	v_add_u32_e32 v164, 0x4000, v159
	s_mov_b32 m0, s3
	s_addc_u32 s19, s11, 0
	v_readfirstlane_b32 s3, v164
	v_add_u32_e32 v165, 0x6000, v159
	global_load_lds_dwordx4 v[24:25], off
	v_lshl_add_u64 v[20:21], s[18:19], 0, v[20:21]
	s_mov_b32 m0, s3
	v_readfirstlane_b32 s3, v165
	global_load_lds_dwordx4 v[20:21], off
	v_lshl_add_u64 v[20:21], s[18:19], 0, v[22:23]
	s_mov_b32 m0, s3
	v_ashrrev_i32_e32 v10, 8, v0
	global_load_lds_dwordx4 v[20:21], off
	v_cmp_eq_u32_e32 vcc, 1, v10
	s_and_saveexec_b64 s[18:19], vcc
	s_cbranch_execz .LBB0_487
	s_setprio 3
	s_barrier

; #define STA(P, br, kt) STAGE(P, A, aoff0, aoff1, lda, br, kt)
; #define STB(P, br, kt) STAGE(P, Bt, boff0, boff1, ldb, br, kt)
; #define LDA(dst, b, h) _Pragma("unroll") for (int m = 0; m < 4; ++m) _Pragma("unroll") for (int k = 0; k < 2; ++k) \
;     dst[m][k] = *reinterpret_cast<const bf16x8*>((char*)SA(b, h) + lds_byte(wr * 64 + m * 16 + fr, k * 32 + fq * 8))
; #define LDB(dst, b, h) _Pragma("unroll") for (int n = 0; n < 2; ++n) _Pragma("unroll") for (int k = 0; k < 2; ++k) \
;     dst[n][k] = *reinterpret_cast<const bf16x8*>((char*)SB(b, h) + lds_byte(wc * 32 + n * 16 + fr, k * 32 + fq * 8))
; #define MMA(ai, bj, At, Bq) do { __builtin_amdgcn_s_setprio(1); \
;     _Pragma("unroll") for (int m = 0; m < 4; ++m) _Pragma("unroll") for (int n = 0; n < 2; ++n) _Pragma("unroll") for (int k = 0; k < 2; ++k) \
;       acc[ai][bj][m][n] = __builtin_amdgcn_mfma_f32_16x16x32_bf16(At[m][k], Bq[n][k], acc[ai][bj][m][n], 0, 0, 0); \
;     __builtin_amdgcn_s_setprio(0); } while (0)
; #define WAIT_L(n) asm volatile("s_waitcnt lgkmcnt(" #n ")" ::: "memory")
; #define BAR __builtin_amdgcn_s_barrier()
; #define SCHED __builtin_amdgcn_sched_barrier(0)
; __device__ __forceinline__ void gemm256(const u16* __restrict__ A, int lda, const u16* __restrict__ Bt, int ldb, int K,
;                                         f32x4 (&acc)[2][2][4][2], const int g_wid) {
;     ...
;     LDB(B0, 0, 0); SCHED; LDA(At, 0, 0); STA(SA(1, 1), HALF, t + 1);
;     WAIT_L(8); BAR; WAIT_L(0); MMA(0, 0, At, B0); BAR; SCHED;
;     LDB(B1, 0, 1); STB(SB(0, 0), 0, t + 2);
;     BAR; WAIT_L(0); MMA(0, 1, At, B1); BAR;
;     LDA(At, 0, 1); STA(SA(0, 0), 0, t + 2);
;     BAR; WAIT_L(0); MMA(1, 0, At, B0); BAR; SCHED;
;     STB(SB(0, 1), HALF, t + 2);
.LBB0_488:
	ds_read_b128 v[178:181], v174
	ds_read_b128 v[182:185], v174 offset:1024
	ds_read_b128 v[186:189], v174 offset:2048
	ds_read_b128 v[190:193], v174 offset:3072
	v_add_u32_e32 v175, 0xc000, v159
	v_lshl_add_u64 v[242:243], v[138:139], 0, s[12:13]
	v_readfirstlane_b32 s9, v175
	v_lshl_add_u64 v[176:177], v[242:243], 0, s[44:45]
	s_mov_b32 m0, s9
	ds_read_b128 v[194:197], v145
	ds_read_b128 v[198:201], v145 offset:1024
	ds_read_b128 v[202:205], v144
	ds_read_b128 v[206:209], v144 offset:1024
	ds_read_b128 v[210:213], v143
	ds_read_b128 v[214:217], v143 offset:1024
	ds_read_b128 v[218:221], v142
	ds_read_b128 v[222:225], v142 offset:1024
	global_load_lds_dwordx4 v[176:177], off
	v_add_u32_e32 v176, 0xe000, v159
	v_lshl_add_u64 v[244:245], v[140:141], 0, s[12:13]
	v_readfirstlane_b32 s9, v176
	v_lshl_add_u64 v[226:227], v[244:245], 0, s[44:45]
	s_mov_b32 m0, s9
	s_nop 0
	global_load_lds_dwordx4 v[226:227], off
	s_waitcnt lgkmcnt(8)
	s_barrier
	s_waitcnt lgkmcnt(0)
	v_mfma_f32_16x16x32_bf16 v[126:129], v[194:197], v[178:181], v[126:129]
	v_mfma_f32_16x16x32_bf16 v[122:125], v[194:197], v[186:189], v[122:125]
	v_mfma_f32_16x16x32_bf16 v[118:121], v[202:205], v[178:181], v[118:121]
	v_mfma_f32_16x16x32_bf16 v[114:117], v[202:205], v[186:189], v[114:117]
	v_mfma_f32_16x16x32_bf16 v[110:113], v[210:213], v[178:181], v[110:113]
	v_mfma_f32_16x16x32_bf16 v[106:109], v[210:213], v[186:189], v[106:109]
	v_mfma_f32_16x16x32_bf16 v[102:105], v[218:221], v[178:181], v[102:105]
	v_mfma_f32_16x16x32_bf16 v[98:101], v[218:221], v[186:189], v[98:101]
	v_mfma_f32_16x16x32_bf16 v[126:129], v[198:201], v[182:185], v[126:129]
	v_mfma_f32_16x16x32_bf16 v[122:125], v[198:201], v[190:193], v[122:125]
	v_mfma_f32_16x16x32_bf16 v[118:121], v[206:209], v[182:185], v[118:121]
	v_mfma_f32_16x16x32_bf16 v[114:117], v[206:209], v[190:193], v[114:117]
	v_mfma_f32_16x16x32_bf16 v[110:113], v[214:217], v[182:185], v[110:113]
	v_mfma_f32_16x16x32_bf16 v[106:109], v[214:217], v[190:193], v[106:109]
	v_mfma_f32_16x16x32_bf16 v[102:105], v[222:225], v[182:185], v[102:105]
	v_mfma_f32_16x16x32_bf16 v[98:101], v[222:225], v[190:193], v[98:101]
	s_barrier
	v_lshl_add_u64 v[246:247], v[134:135], 0, s[12:13]
	v_readfirstlane_b32 s9, v146
	v_lshl_add_u64 v[248:249], v[246:247], 0, s[64:65]
	s_mov_b32 m0, s9
	ds_read_b128 v[226:229], v173
	ds_read_b128 v[230:233], v173 offset:1024
	ds_read_b128 v[234:237], v173 offset:2048
	ds_read_b128 v[238:241], v173 offset:3072
	global_load_lds_dwordx4 v[248:249], off
	v_lshl_add_u64 v[248:249], v[136:137], 0, s[12:13]
	v_readfirstlane_b32 s9, v147
	v_lshl_add_u64 v[250:251], v[248:249], 0, s[64:65]
	s_mov_b32 m0, s9
	s_nop 0
	global_load_lds_dwordx4 v[250:251], off
	s_barrier
	s_waitcnt lgkmcnt(0)
	v_mfma_f32_16x16x32_bf16 v[94:97], v[194:197], v[226:229], v[94:97]
	v_mfma_f32_16x16x32_bf16 v[90:93], v[194:197], v[234:237], v[90:93]
	v_mfma_f32_16x16x32_bf16 v[86:89], v[202:205], v[226:229], v[86:89]
	v_mfma_f32_16x16x32_bf16 v[82:85], v[202:205], v[234:237], v[82:85]
	v_mfma_f32_16x16x32_bf16 v[78:81], v[210:213], v[226:229], v[78:81]
	v_mfma_f32_16x16x32_bf16 v[74:77], v[210:213], v[234:237], v[74:77]
	v_mfma_f32_16x16x32_bf16 v[70:73], v[218:221], v[226:229], v[70:73]
	v_mfma_f32_16x16x32_bf16 v[66:69], v[218:221], v[234:237], v[66:69]
	v_mfma_f32_16x16x32_bf16 v[94:97], v[198:201], v[230:233], v[94:97]
	v_mfma_f32_16x16x32_bf16 v[90:93], v[198:201], v[238:241], v[90:93]
	v_mfma_f32_16x16x32_bf16 v[86:89], v[206:209], v[230:233], v[86:89]
	v_mfma_f32_16x16x32_bf16 v[82:85], v[206:209], v[238:241], v[82:85]
	v_mfma_f32_16x16x32_bf16 v[78:81], v[214:217], v[230:233], v[78:81]
	v_mfma_f32_16x16x32_bf16 v[74:77], v[214:217], v[238:241], v[74:77]
	v_mfma_f32_16x16x32_bf16 v[70:73], v[222:225], v[230:233], v[70:73]
	v_mfma_f32_16x16x32_bf16 v[66:69], v[222:225], v[238:241], v[66:69]
	v_readfirstlane_b32 s9, v159
	v_lshl_add_u64 v[250:251], v[242:243], 0, s[70:71]
	s_mov_b32 m0, s9
	v_readfirstlane_b32 s9, v161
	s_barrier
	ds_read_b128 v[194:197], v145 offset:16384
	ds_read_b128 v[198:201], v145 offset:17408
	ds_read_b128 v[202:205], v144 offset:16384
	ds_read_b128 v[206:209], v144 offset:17408
	ds_read_b128 v[210:213], v143 offset:16384
	ds_read_b128 v[214:217], v143 offset:17408
	ds_read_b128 v[218:221], v142 offset:16384
	ds_read_b128 v[222:225], v142 offset:17408
	global_load_lds_dwordx4 v[250:251], off
	v_lshl_add_u64 v[250:251], v[244:245], 0, s[70:71]
	s_mov_b32 m0, s9
	s_nop 0
	global_load_lds_dwordx4 v[250:251], off
	s_barrier
	s_waitcnt lgkmcnt(0)
	v_mfma_f32_16x16x32_bf16 v[62:65], v[194:197], v[178:181], v[62:65]
	v_mfma_f32_16x16x32_bf16 v[58:61], v[194:197], v[186:189], v[58:61]
	v_mfma_f32_16x16x32_bf16 v[54:57], v[202:205], v[178:181], v[54:57]
	v_mfma_f32_16x16x32_bf16 v[50:53], v[202:205], v[186:189], v[50:53]
	v_mfma_f32_16x16x32_bf16 v[46:49], v[210:213], v[178:181], v[46:49]
	v_mfma_f32_16x16x32_bf16 v[42:45], v[210:213], v[186:189], v[42:45]
	v_mfma_f32_16x16x32_bf16 v[38:41], v[218:221], v[178:181], v[38:41]
	v_mfma_f32_16x16x32_bf16 v[34:37], v[218:221], v[186:189], v[34:37]
	v_mfma_f32_16x16x32_bf16 v[62:65], v[198:201], v[182:185], v[62:65]
	v_mfma_f32_16x16x32_bf16 v[58:61], v[198:201], v[190:193], v[58:61]
	v_mfma_f32_16x16x32_bf16 v[54:57], v[206:209], v[182:185], v[54:57]
	v_mfma_f32_16x16x32_bf16 v[50:53], v[206:209], v[190:193], v[50:53]
	v_mfma_f32_16x16x32_bf16 v[46:49], v[214:217], v[182:185], v[46:49]
	v_mfma_f32_16x16x32_bf16 v[42:45], v[214:217], v[190:193], v[42:45]
	v_mfma_f32_16x16x32_bf16 v[38:41], v[222:225], v[182:185], v[38:41]
	v_mfma_f32_16x16x32_bf16 v[34:37], v[222:225], v[190:193], v[34:37]
	s_barrier
; #define STA(P, br, kt) STAGE(P, A, aoff0, aoff1, lda, br, kt)
; #define STB(P, br, kt) STAGE(P, Bt, boff0, boff1, ldb, br, kt)
; #define LDA(dst, b, h) _Pragma("unroll") for (int m = 0; m < 4; ++m) _Pragma("unroll") for (int k = 0; k < 2; ++k) \
;     dst[m][k] = *reinterpret_cast<const bf16x8*>((char*)SA(b, h) + lds_byte(wr * 64 + m * 16 + fr, k * 32 + fq * 8))
; #define LDB(dst, b, h) _Pragma("unroll") for (int n = 0; n < 2; ++n) _Pragma("unroll") for (int k = 0; k < 2; ++k) \
;     dst[n][k] = *reinterpret_cast<const bf16x8*>((char*)SB(b, h) + lds_byte(wc * 32 + n * 16 + fr, k * 32 + fq * 8))
; #define MMA(ai, bj, At, Bq) do { __builtin_amdgcn_s_setprio(1); \
;     _Pragma("unroll") for (int m = 0; m < 4; ++m) _Pragma("unroll") for (int n = 0; n < 2; ++n) _Pragma("unroll") for (int k = 0; k < 2; ++k) \
;       acc[ai][bj][m][n] = __builtin_amdgcn_mfma_f32_16x16x32_bf16(At[m][k], Bq[n][k], acc[ai][bj][m][n], 0, 0, 0); \
;     __builtin_amdgcn_s_setprio(0); } while (0)
; #define WAIT_V(n) asm volatile("s_waitcnt vmcnt(" #n ")" ::: "memory")
; #define WAIT_L(n) asm volatile("s_waitcnt lgkmcnt(" #n ")" ::: "memory")
; #define BAR __builtin_amdgcn_s_barrier()
; #define SCHED __builtin_amdgcn_sched_barrier(0)
; __device__ __forceinline__ void gemm256(const u16* __restrict__ A, int lda, const u16* __restrict__ Bt, int ldb, int K,
;                                         f32x4 (&acc)[2][2][4][2], const int g_wid) {
;     ...
;     STB(SB(0, 1), HALF, t + 2);
;     WAIT_V(6); BAR; MMA(1, 1, At, B1); BAR;
;     LDB(B0, 1, 0); SCHED; LDA(At, 1, 0); STA(SA(0, 1), HALF, t + 2);
;     WAIT_L(8); BAR; WAIT_L(0); MMA(0, 0, At, B0); BAR; SCHED;
;     LDB(B1, 1, 1); STB(SB(1, 0), 0, t + 3);
;     BAR; WAIT_L(0); MMA(0, 1, At, B1); BAR;
	v_readfirstlane_b32 s9, v162
	v_lshl_add_u64 v[178:179], v[246:247], 0, s[0:1]
	s_mov_b32 m0, s9
	v_readfirstlane_b32 s9, v163
	global_load_lds_dwordx4 v[178:179], off
	v_lshl_add_u64 v[178:179], v[248:249], 0, s[0:1]
	s_mov_b32 m0, s9
	s_nop 0
	global_load_lds_dwordx4 v[178:179], off
	s_waitcnt vmcnt(6)
	s_barrier
	v_mfma_f32_16x16x32_bf16 v[30:33], v[194:197], v[226:229], v[30:33]
	v_mfma_f32_16x16x32_bf16 v[26:29], v[194:197], v[234:237], v[26:29]
	v_mfma_f32_16x16x32_bf16 v[22:25], v[202:205], v[226:229], v[22:25]
	v_mfma_f32_16x16x32_bf16 v[18:21], v[202:205], v[234:237], v[18:21]
	v_mfma_f32_16x16x32_bf16 v[14:17], v[210:213], v[226:229], v[14:17]
	v_mfma_f32_16x16x32_bf16 v[10:13], v[210:213], v[234:237], v[10:13]
	v_mfma_f32_16x16x32_bf16 v[6:9], v[218:221], v[226:229], v[6:9]
	v_mfma_f32_16x16x32_bf16 v[2:5], v[218:221], v[234:237], v[2:5]
	v_mfma_f32_16x16x32_bf16 v[30:33], v[198:201], v[230:233], v[30:33]
	v_mfma_f32_16x16x32_bf16 v[26:29], v[198:201], v[238:241], v[26:29]
	v_mfma_f32_16x16x32_bf16 v[22:25], v[206:209], v[230:233], v[22:25]
	v_mfma_f32_16x16x32_bf16 v[18:21], v[206:209], v[238:241], v[18:21]
	v_mfma_f32_16x16x32_bf16 v[14:17], v[214:217], v[230:233], v[14:17]
	v_mfma_f32_16x16x32_bf16 v[10:13], v[214:217], v[238:241], v[10:13]
	v_mfma_f32_16x16x32_bf16 v[6:9], v[222:225], v[230:233], v[6:9]
	v_mfma_f32_16x16x32_bf16 v[2:5], v[222:225], v[238:241], v[2:5]
	s_barrier
	ds_read_b128 v[178:181], v166
	ds_read_b128 v[182:185], v166 offset:1024
	ds_read_b128 v[186:189], v166 offset:2048
	ds_read_b128 v[190:193], v166 offset:3072
	v_readfirstlane_b32 s9, v164
	v_lshl_add_u64 v[226:227], v[242:243], 0, s[52:53]
	s_mov_b32 m0, s9
	v_readfirstlane_b32 s9, v165
	ds_read_b128 v[194:197], v145 offset:32768
	ds_read_b128 v[198:201], v145 offset:33792
	ds_read_b128 v[202:205], v144 offset:32768
	ds_read_b128 v[206:209], v144 offset:33792
	ds_read_b128 v[210:213], v143 offset:32768
	ds_read_b128 v[214:217], v143 offset:33792
	ds_read_b128 v[218:221], v142 offset:32768
	ds_read_b128 v[222:225], v142 offset:33792
	global_load_lds_dwordx4 v[226:227], off
	v_lshl_add_u64 v[226:227], v[244:245], 0, s[52:53]
	s_mov_b32 m0, s9
	s_nop 0
	global_load_lds_dwordx4 v[226:227], off
	s_waitcnt lgkmcnt(8)
	s_barrier
	s_waitcnt lgkmcnt(0)
	v_mfma_f32_16x16x32_bf16 v[126:129], v[194:197], v[178:181], v[126:129]
	v_mfma_f32_16x16x32_bf16 v[122:125], v[194:197], v[186:189], v[122:125]
	v_mfma_f32_16x16x32_bf16 v[118:121], v[202:205], v[178:181], v[118:121]
	v_mfma_f32_16x16x32_bf16 v[114:117], v[202:205], v[186:189], v[114:117]
	v_mfma_f32_16x16x32_bf16 v[110:113], v[210:213], v[178:181], v[110:113]
	v_mfma_f32_16x16x32_bf16 v[106:109], v[210:213], v[186:189], v[106:109]
	v_mfma_f32_16x16x32_bf16 v[102:105], v[218:221], v[178:181], v[102:105]
	v_mfma_f32_16x16x32_bf16 v[98:101], v[218:221], v[186:189], v[98:101]
	v_mfma_f32_16x16x32_bf16 v[126:129], v[198:201], v[182:185], v[126:129]
	v_mfma_f32_16x16x32_bf16 v[122:125], v[198:201], v[190:193], v[122:125]
	v_mfma_f32_16x16x32_bf16 v[118:121], v[206:209], v[182:185], v[118:121]
	v_mfma_f32_16x16x32_bf16 v[114:117], v[206:209], v[190:193], v[114:117]
	v_mfma_f32_16x16x32_bf16 v[110:113], v[214:217], v[182:185], v[110:113]
	v_mfma_f32_16x16x32_bf16 v[106:109], v[214:217], v[190:193], v[106:109]
	v_mfma_f32_16x16x32_bf16 v[102:105], v[222:225], v[182:185], v[102:105]
	v_mfma_f32_16x16x32_bf16 v[98:101], v[222:225], v[190:193], v[98:101]
	s_barrier
	v_readfirstlane_b32 s9, v167
	v_lshl_add_u64 v[250:251], v[246:247], 0, s[58:59]
	s_mov_b32 m0, s9
	v_readfirstlane_b32 s9, v168
	ds_read_b128 v[226:229], v160
	ds_read_b128 v[230:233], v160 offset:1024
	ds_read_b128 v[234:237], v160 offset:2048
	ds_read_b128 v[238:241], v160 offset:3072
	global_load_lds_dwordx4 v[250:251], off
	v_lshl_add_u64 v[250:251], v[248:249], 0, s[58:59]
	s_mov_b32 m0, s9
	s_nop 0
	global_load_lds_dwordx4 v[250:251], off
	s_barrier
	s_waitcnt lgkmcnt(0)
	v_mfma_f32_16x16x32_bf16 v[94:97], v[194:197], v[226:229], v[94:97]
	v_mfma_f32_16x16x32_bf16 v[90:93], v[194:197], v[234:237], v[90:93]
	v_mfma_f32_16x16x32_bf16 v[86:89], v[202:205], v[226:229], v[86:89]
	v_mfma_f32_16x16x32_bf16 v[82:85], v[202:205], v[234:237], v[82:85]
	v_mfma_f32_16x16x32_bf16 v[78:81], v[210:213], v[226:229], v[78:81]
	v_mfma_f32_16x16x32_bf16 v[74:77], v[210:213], v[234:237], v[74:77]
	v_mfma_f32_16x16x32_bf16 v[70:73], v[218:221], v[226:229], v[70:73]
	v_mfma_f32_16x16x32_bf16 v[66:69], v[218:221], v[234:237], v[66:69]
	v_mfma_f32_16x16x32_bf16 v[94:97], v[198:201], v[230:233], v[94:97]
	v_mfma_f32_16x16x32_bf16 v[90:93], v[198:201], v[238:241], v[90:93]
	v_mfma_f32_16x16x32_bf16 v[86:89], v[206:209], v[230:233], v[86:89]
	v_mfma_f32_16x16x32_bf16 v[82:85], v[206:209], v[238:241], v[82:85]
	v_mfma_f32_16x16x32_bf16 v[78:81], v[214:217], v[230:233], v[78:81]
	v_mfma_f32_16x16x32_bf16 v[74:77], v[214:217], v[238:241], v[74:77]
	v_mfma_f32_16x16x32_bf16 v[70:73], v[222:225], v[230:233], v[70:73]
	v_mfma_f32_16x16x32_bf16 v[66:69], v[222:225], v[238:241], v[66:69]
	v_readfirstlane_b32 s9, v169
	v_lshl_add_u64 v[242:243], v[242:243], 0, s[60:61]
	s_mov_b32 m0, s9
	v_readfirstlane_b32 s9, v170
	s_barrier
	ds_read_b128 v[194:197], v145 offset:49152
	ds_read_b128 v[198:201], v145 offset:50176
	ds_read_b128 v[202:205], v144 offset:49152
	ds_read_b128 v[206:209], v144 offset:50176
	ds_read_b128 v[210:213], v143 offset:49152
	ds_read_b128 v[214:217], v143 offset:50176
	ds_read_b128 v[218:221], v142 offset:49152
	ds_read_b128 v[222:225], v142 offset:50176
	global_load_lds_dwordx4 v[242:243], off
	v_lshl_add_u64 v[242:243], v[244:245], 0, s[60:61]
	s_mov_b32 m0, s9
	s_nop 0
	global_load_lds_dwordx4 v[242:243], off
	s_barrier
; #define STA(P, br, kt) STAGE(P, A, aoff0, aoff1, lda, br, kt)
; #define STB(P, br, kt) STAGE(P, Bt, boff0, boff1, ldb, br, kt)
; #define LDA(dst, b, h) _Pragma("unroll") for (int m = 0; m < 4; ++m) _Pragma("unroll") for (int k = 0; k < 2; ++k) \
;     dst[m][k] = *reinterpret_cast<const bf16x8*>((char*)SA(b, h) + lds_byte(wr * 64 + m * 16 + fr, k * 32 + fq * 8))
; #define LDB(dst, b, h) _Pragma("unroll") for (int n = 0; n < 2; ++n) _Pragma("unroll") for (int k = 0; k < 2; ++k) \
;     dst[n][k] = *reinterpret_cast<const bf16x8*>((char*)SB(b, h) + lds_byte(wc * 32 + n * 16 + fr, k * 32 + fq * 8))
; #define MMA(ai, bj, At, Bq) do { __builtin_amdgcn_s_setprio(1); \
;     _Pragma("unroll") for (int m = 0; m < 4; ++m) _Pragma("unroll") for (int n = 0; n < 2; ++n) _Pragma("unroll") for (int k = 0; k < 2; ++k) \
;       acc[ai][bj][m][n] = __builtin_amdgcn_mfma_f32_16x16x32_bf16(At[m][k], Bq[n][k], acc[ai][bj][m][n], 0, 0, 0); \
;     __builtin_amdgcn_s_setprio(0); } while (0)
; #define WAIT_V(n) asm volatile("s_waitcnt vmcnt(" #n ")" ::: "memory")
; #define WAIT_L(n) asm volatile("s_waitcnt lgkmcnt(" #n ")" ::: "memory")
; #define BAR __builtin_amdgcn_s_barrier()
; #define SCHED __builtin_amdgcn_sched_barrier(0)
; __device__ __forceinline__ void gemm256(const u16* __restrict__ A, int lda, const u16* __restrict__ Bt, int ldb, int K,
;                                         f32x4 (&acc)[2][2][4][2], const int g_wid) {
;     ...
;     LDA(At, 1, 1); STA(SA(1, 0), 0, t + 3);
;     BAR; WAIT_L(0); MMA(1, 0, At, B0); BAR; SCHED;
;     STB(SB(1, 1), HALF, t + 3);
;     WAIT_V(6); BAR; MMA(1, 1, At, B1); BAR;
;   }
;   { LDB(B0, 0, 0); LDA(At, 0, 0); STA(SA(1, 1), HALF, nt - 1);
;     BAR; WAIT_L(0); MMA(0, 0, At, B0); BAR;
;     LDB(B1, 0, 1); BAR; WAIT_L(0); MMA(0, 1, At, B1); BAR;
	s_waitcnt lgkmcnt(0)
	v_mfma_f32_16x16x32_bf16 v[62:65], v[194:197], v[178:181], v[62:65]
	v_mfma_f32_16x16x32_bf16 v[58:61], v[194:197], v[186:189], v[58:61]
	v_mfma_f32_16x16x32_bf16 v[54:57], v[202:205], v[178:181], v[54:57]
	v_mfma_f32_16x16x32_bf16 v[50:53], v[202:205], v[186:189], v[50:53]
	v_mfma_f32_16x16x32_bf16 v[46:49], v[210:213], v[178:181], v[46:49]
	v_mfma_f32_16x16x32_bf16 v[42:45], v[210:213], v[186:189], v[42:45]
	v_mfma_f32_16x16x32_bf16 v[38:41], v[218:221], v[178:181], v[38:41]
	v_mfma_f32_16x16x32_bf16 v[34:37], v[218:221], v[186:189], v[34:37]
	v_mfma_f32_16x16x32_bf16 v[62:65], v[198:201], v[182:185], v[62:65]
	v_mfma_f32_16x16x32_bf16 v[58:61], v[198:201], v[190:193], v[58:61]
	v_mfma_f32_16x16x32_bf16 v[54:57], v[206:209], v[182:185], v[54:57]
	v_mfma_f32_16x16x32_bf16 v[50:53], v[206:209], v[190:193], v[50:53]
	v_mfma_f32_16x16x32_bf16 v[46:49], v[214:217], v[182:185], v[46:49]
	v_mfma_f32_16x16x32_bf16 v[42:45], v[214:217], v[190:193], v[42:45]
	v_mfma_f32_16x16x32_bf16 v[38:41], v[222:225], v[182:185], v[38:41]
	v_mfma_f32_16x16x32_bf16 v[34:37], v[222:225], v[190:193], v[34:37]
	s_barrier
	v_readfirstlane_b32 s9, v171
	v_lshl_add_u64 v[178:179], v[246:247], 0, s[48:49]
	s_mov_b32 m0, s9
	v_readfirstlane_b32 s9, v172
	global_load_lds_dwordx4 v[178:179], off
	v_lshl_add_u64 v[178:179], v[248:249], 0, s[48:49]
	s_mov_b32 m0, s9
	s_nop 0
	global_load_lds_dwordx4 v[178:179], off
	s_waitcnt vmcnt(6)
	s_barrier
	v_mfma_f32_16x16x32_bf16 v[30:33], v[194:197], v[226:229], v[30:33]
	v_mfma_f32_16x16x32_bf16 v[26:29], v[194:197], v[234:237], v[26:29]
	v_mfma_f32_16x16x32_bf16 v[22:25], v[202:205], v[226:229], v[22:25]
	v_mfma_f32_16x16x32_bf16 v[18:21], v[202:205], v[234:237], v[18:21]
	v_mfma_f32_16x16x32_bf16 v[14:17], v[210:213], v[226:229], v[14:17]
	v_mfma_f32_16x16x32_bf16 v[10:13], v[210:213], v[234:237], v[10:13]
	v_mfma_f32_16x16x32_bf16 v[6:9], v[218:221], v[226:229], v[6:9]
	v_mfma_f32_16x16x32_bf16 v[2:5], v[218:221], v[234:237], v[2:5]
	v_mfma_f32_16x16x32_bf16 v[30:33], v[198:201], v[230:233], v[30:33]
	v_mfma_f32_16x16x32_bf16 v[26:29], v[198:201], v[238:241], v[26:29]
	v_mfma_f32_16x16x32_bf16 v[22:25], v[206:209], v[230:233], v[22:25]
	v_mfma_f32_16x16x32_bf16 v[18:21], v[206:209], v[238:241], v[18:21]
	v_mfma_f32_16x16x32_bf16 v[14:17], v[214:217], v[230:233], v[14:17]
	v_mfma_f32_16x16x32_bf16 v[10:13], v[214:217], v[238:241], v[10:13]
	v_mfma_f32_16x16x32_bf16 v[6:9], v[222:225], v[230:233], v[6:9]
	v_mfma_f32_16x16x32_bf16 v[2:5], v[222:225], v[238:241], v[2:5]
	s_add_i32 s3, s3, 2
	s_add_u32 s12, s12, 0x100
	s_addc_u32 s13, s13, 0
	s_cmp_lt_u32 s3, 12
	s_barrier
	s_cbranch_scc1 .LBB0_488
	s_add_u32 s10, s10, 0x40780
	s_addc_u32 s11, s11, 0
	v_readfirstlane_b32 s3, v175
	v_lshl_add_u64 v[132:133], v[132:133], 1, s[10:11]
	s_mov_b32 m0, s3
	v_readfirstlane_b32 s3, v176
	ds_read_b128 v[134:137], v174
	ds_read_b128 v[138:141], v174 offset:1024
	ds_read_b128 v[162:165], v174 offset:2048
	ds_read_b128 v[168:171], v174 offset:3072
	ds_read_b128 v[178:181], v145
	ds_read_b128 v[182:185], v145 offset:1024
	ds_read_b128 v[186:189], v144
	ds_read_b128 v[190:193], v144 offset:1024
	ds_read_b128 v[194:197], v143
	ds_read_b128 v[198:201], v143 offset:1024
	ds_read_b128 v[202:205], v142
	ds_read_b128 v[206:209], v142 offset:1024
	global_load_lds_dwordx4 v[132:133], off
	v_lshl_add_u64 v[130:131], v[130:131], 1, s[10:11]
	s_mov_b32 m0, s3
	s_nop 0
	global_load_lds_dwordx4 v[130:131], off
	s_barrier
	s_waitcnt lgkmcnt(0)
	v_mfma_f32_16x16x32_bf16 v[126:129], v[178:181], v[134:137], v[126:129]
	v_mfma_f32_16x16x32_bf16 v[118:121], v[186:189], v[134:137], v[118:121]
	v_mfma_f32_16x16x32_bf16 v[114:117], v[186:189], v[162:165], v[114:117]
	v_mfma_f32_16x16x32_bf16 v[110:113], v[194:197], v[134:137], v[110:113]
	v_mfma_f32_16x16x32_bf16 v[106:109], v[194:197], v[162:165], v[106:109]
	v_mfma_f32_16x16x32_bf16 v[102:105], v[202:205], v[134:137], v[102:105]
	v_mfma_f32_16x16x32_bf16 v[98:101], v[202:205], v[162:165], v[98:101]
	v_mfma_f32_16x16x32_bf16 v[126:129], v[182:185], v[138:141], v[126:129]
	v_mfma_f32_16x16x32_bf16 v[122:125], v[178:181], v[162:165], v[122:125]
	v_mfma_f32_16x16x32_bf16 v[118:121], v[190:193], v[138:141], v[118:121]
	v_mfma_f32_16x16x32_bf16 v[114:117], v[190:193], v[168:171], v[114:117]
	v_mfma_f32_16x16x32_bf16 v[110:113], v[198:201], v[138:141], v[110:113]
	v_mfma_f32_16x16x32_bf16 v[106:109], v[198:201], v[168:171], v[106:109]
	v_mfma_f32_16x16x32_bf16 v[102:105], v[206:209], v[138:141], v[102:105]
	v_mfma_f32_16x16x32_bf16 v[98:101], v[206:209], v[168:171], v[98:101]
	v_mfma_f32_16x16x32_bf16 v[130:133], v[182:185], v[168:171], v[122:125]
	s_barrier
	s_nop 0
	ds_read_b128 v[122:125], v173
	ds_read_b128 v[174:177], v173 offset:1024
	ds_read_b128 v[210:213], v173 offset:2048
	ds_read_b128 v[214:217], v173 offset:3072
	s_barrier
	s_waitcnt lgkmcnt(0)
	v_mfma_f32_16x16x32_bf16 v[78:81], v[194:197], v[122:125], v[78:81]
	v_mfma_f32_16x16x32_bf16 v[74:77], v[194:197], v[210:213], v[74:77]
	v_mfma_f32_16x16x32_bf16 v[70:73], v[202:205], v[122:125], v[70:73]
	v_mfma_f32_16x16x32_bf16 v[66:69], v[202:205], v[210:213], v[66:69]
	v_mfma_f32_16x16x32_bf16 v[94:97], v[178:181], v[122:125], v[94:97]
	v_mfma_f32_16x16x32_bf16 v[90:93], v[178:181], v[210:213], v[90:93]
	v_mfma_f32_16x16x32_bf16 v[86:89], v[186:189], v[122:125], v[86:89]
	v_mfma_f32_16x16x32_bf16 v[82:85], v[186:189], v[210:213], v[82:85]
	v_mfma_f32_16x16x32_bf16 v[78:81], v[198:201], v[174:177], v[78:81]
	v_mfma_f32_16x16x32_bf16 v[74:77], v[198:201], v[214:217], v[74:77]
	v_mfma_f32_16x16x32_bf16 v[70:73], v[206:209], v[174:177], v[70:73]
	v_mfma_f32_16x16x32_bf16 v[66:69], v[206:209], v[214:217], v[66:69]
	v_mfma_f32_16x16x32_bf16 v[218:221], v[182:185], v[174:177], v[94:97]
	v_mfma_f32_16x16x32_bf16 v[178:181], v[182:185], v[214:217], v[90:93]
	v_mfma_f32_16x16x32_bf16 v[182:185], v[190:193], v[174:177], v[86:89]
	v_mfma_f32_16x16x32_bf16 v[186:189], v[190:193], v[214:217], v[82:85]
	s_barrier
; #define LDA(dst, b, h) _Pragma("unroll") for (int m = 0; m < 4; ++m) _Pragma("unroll") for (int k = 0; k < 2; ++k) \
;     dst[m][k] = *reinterpret_cast<const bf16x8*>((char*)SA(b, h) + lds_byte(wr * 64 + m * 16 + fr, k * 32 + fq * 8))
; #define LDB(dst, b, h) _Pragma("unroll") for (int n = 0; n < 2; ++n) _Pragma("unroll") for (int k = 0; k < 2; ++k) \
;     dst[n][k] = *reinterpret_cast<const bf16x8*>((char*)SB(b, h) + lds_byte(wc * 32 + n * 16 + fr, k * 32 + fq * 8))
; #define MMA(ai, bj, At, Bq) do { __builtin_amdgcn_s_setprio(1); \
;     _Pragma("unroll") for (int m = 0; m < 4; ++m) _Pragma("unroll") for (int n = 0; n < 2; ++n) _Pragma("unroll") for (int k = 0; k < 2; ++k) \
;       acc[ai][bj][m][n] = __builtin_amdgcn_mfma_f32_16x16x32_bf16(At[m][k], Bq[n][k], acc[ai][bj][m][n], 0, 0, 0); \
;     __builtin_amdgcn_s_setprio(0); } while (0)
; #define WAIT_V(n) asm volatile("s_waitcnt vmcnt(" #n ")" ::: "memory")
; #define WAIT_L(n) asm volatile("s_waitcnt lgkmcnt(" #n ")" ::: "memory")
; #define BAR __builtin_amdgcn_s_barrier()
; __device__ __forceinline__ void gemm256(const u16* __restrict__ A, int lda, const u16* __restrict__ Bt, int ldb, int K,
;                                         f32x4 (&acc)[2][2][4][2], const int g_wid) {
;     ...
;     LDB(B1, 0, 1); BAR; WAIT_L(0); MMA(0, 1, At, B1); BAR;
;     LDA(At, 0, 1); WAIT_V(4); BAR; WAIT_L(0); MMA(1, 0, At, B0); MMA(1, 1, At, B1); BAR; }
;   { LDB(B0, 1, 0); LDA(At, 1, 0); WAIT_V(2); BAR; WAIT_L(0); MMA(0, 0, At, B0); BAR;
	s_nop 0
	ds_read_b128 v[82:85], v145 offset:16384
	ds_read_b128 v[86:89], v145 offset:17408
	ds_read_b128 v[90:93], v144 offset:16384
	ds_read_b128 v[94:97], v144 offset:17408
	ds_read_b128 v[190:193], v143 offset:16384
	ds_read_b128 v[194:197], v143 offset:17408
	ds_read_b128 v[198:201], v142 offset:16384
	ds_read_b128 v[202:205], v142 offset:17408
	s_waitcnt vmcnt(4)
	s_barrier
	s_waitcnt lgkmcnt(0)
	v_mfma_f32_16x16x32_bf16 v[46:49], v[190:193], v[134:137], v[46:49]
	v_mfma_f32_16x16x32_bf16 v[42:45], v[190:193], v[162:165], v[42:45]
	v_mfma_f32_16x16x32_bf16 v[38:41], v[198:201], v[134:137], v[38:41]
	v_mfma_f32_16x16x32_bf16 v[34:37], v[198:201], v[162:165], v[34:37]
	v_mfma_f32_16x16x32_bf16 v[62:65], v[82:85], v[134:137], v[62:65]
	v_mfma_f32_16x16x32_bf16 v[58:61], v[82:85], v[162:165], v[58:61]
	v_mfma_f32_16x16x32_bf16 v[54:57], v[90:93], v[134:137], v[54:57]
	v_mfma_f32_16x16x32_bf16 v[50:53], v[90:93], v[162:165], v[50:53]
	v_mfma_f32_16x16x32_bf16 v[46:49], v[194:197], v[138:141], v[46:49]
	v_mfma_f32_16x16x32_bf16 v[42:45], v[194:197], v[168:171], v[42:45]
	v_mfma_f32_16x16x32_bf16 v[38:41], v[202:205], v[138:141], v[38:41]
	v_mfma_f32_16x16x32_bf16 v[34:37], v[202:205], v[168:171], v[34:37]
	v_mfma_f32_16x16x32_bf16 v[206:209], v[86:89], v[138:141], v[62:65]
	v_mfma_f32_16x16x32_bf16 v[222:225], v[86:89], v[168:171], v[58:61]
	v_mfma_f32_16x16x32_bf16 v[226:229], v[94:97], v[138:141], v[54:57]
	v_mfma_f32_16x16x32_bf16 v[230:233], v[94:97], v[168:171], v[50:53]
	v_mfma_f32_16x16x32_bf16 v[2:5], v[198:201], v[210:213], v[2:5]
	v_mfma_f32_16x16x32_bf16 v[30:33], v[82:85], v[122:125], v[30:33]
	v_mfma_f32_16x16x32_bf16 v[26:29], v[82:85], v[210:213], v[26:29]
	v_mfma_f32_16x16x32_bf16 v[22:25], v[90:93], v[122:125], v[22:25]
	v_mfma_f32_16x16x32_bf16 v[18:21], v[90:93], v[210:213], v[18:21]
	v_mfma_f32_16x16x32_bf16 v[14:17], v[190:193], v[122:125], v[14:17]
	v_mfma_f32_16x16x32_bf16 v[10:13], v[190:193], v[210:213], v[10:13]
	v_mfma_f32_16x16x32_bf16 v[6:9], v[198:201], v[122:125], v[6:9]
	v_mfma_f32_16x16x32_bf16 v[2:5], v[202:205], v[214:217], v[2:5]
	v_mfma_f32_16x16x32_bf16 v[134:137], v[86:89], v[174:177], v[30:33]
	v_mfma_f32_16x16x32_bf16 v[138:141], v[86:89], v[214:217], v[26:29]
	v_mfma_f32_16x16x32_bf16 v[162:165], v[94:97], v[174:177], v[22:25]
	v_mfma_f32_16x16x32_bf16 v[168:171], v[94:97], v[214:217], v[18:21]
	v_mfma_f32_16x16x32_bf16 v[234:237], v[194:197], v[174:177], v[14:17]
	v_mfma_f32_16x16x32_bf16 v[190:193], v[194:197], v[214:217], v[10:13]
	v_mfma_f32_16x16x32_bf16 v[172:175], v[202:205], v[174:177], v[6:9]
	s_barrier
	s_nop 0
	ds_read_b128 v[6:9], v166
	ds_read_b128 v[10:13], v166 offset:1024
	ds_read_b128 v[14:17], v166 offset:2048
	ds_read_b128 v[194:197], v166 offset:3072
	ds_read_b128 v[18:21], v145 offset:32768
	ds_read_b128 v[22:25], v145 offset:33792
	ds_read_b128 v[30:33], v144 offset:32768
	ds_read_b128 v[50:53], v144 offset:33792
	ds_read_b128 v[198:201], v143 offset:32768
	ds_read_b128 v[202:205], v143 offset:33792
	ds_read_b128 v[210:213], v142 offset:32768
	ds_read_b128 v[214:217], v142 offset:33792
	s_waitcnt vmcnt(2)
	s_barrier
	s_waitcnt lgkmcnt(0)
	v_mfma_f32_16x16x32_bf16 v[26:29], v[18:21], v[6:9], v[126:129]
	v_mfma_f32_16x16x32_bf16 v[122:125], v[22:25], v[10:13], v[26:29]
	v_mfma_f32_16x16x32_bf16 v[26:29], v[18:21], v[14:17], v[130:133]
	v_mfma_f32_16x16x32_bf16 v[90:93], v[22:25], v[194:197], v[26:29]
	v_mfma_f32_16x16x32_bf16 v[26:29], v[30:33], v[6:9], v[118:121]
	v_mfma_f32_16x16x32_bf16 v[126:129], v[50:53], v[10:13], v[26:29]
	v_mfma_f32_16x16x32_bf16 v[26:29], v[30:33], v[14:17], v[114:117]
	v_mfma_f32_16x16x32_bf16 v[94:97], v[50:53], v[194:197], v[26:29]
	v_mfma_f32_16x16x32_bf16 v[26:29], v[198:201], v[6:9], v[110:113]
	v_mfma_f32_16x16x32_bf16 v[118:121], v[202:205], v[10:13], v[26:29]
	v_mfma_f32_16x16x32_bf16 v[26:29], v[198:201], v[14:17], v[106:109]
	v_mfma_f32_16x16x32_bf16 v[86:89], v[202:205], v[194:197], v[26:29]
	v_mfma_f32_16x16x32_bf16 v[26:29], v[210:213], v[6:9], v[102:105]
	v_mfma_f32_16x16x32_bf16 v[114:117], v[214:217], v[10:13], v[26:29]
	v_mfma_f32_16x16x32_bf16 v[26:29], v[210:213], v[14:17], v[98:101]
	v_mfma_f32_16x16x32_bf16 v[82:85], v[214:217], v[194:197], v[26:29]
	s_barrier
; #define LDA(dst, b, h) _Pragma("unroll") for (int m = 0; m < 4; ++m) _Pragma("unroll") for (int k = 0; k < 2; ++k) \
;     dst[m][k] = *reinterpret_cast<const bf16x8*>((char*)SA(b, h) + lds_byte(wr * 64 + m * 16 + fr, k * 32 + fq * 8))
; #define LDB(dst, b, h) _Pragma("unroll") for (int n = 0; n < 2; ++n) _Pragma("unroll") for (int k = 0; k < 2; ++k) \
;     dst[n][k] = *reinterpret_cast<const bf16x8*>((char*)SB(b, h) + lds_byte(wc * 32 + n * 16 + fr, k * 32 + fq * 8))
; #define MMA(ai, bj, At, Bq) do { __builtin_amdgcn_s_setprio(1); \
;     _Pragma("unroll") for (int m = 0; m < 4; ++m) _Pragma("unroll") for (int n = 0; n < 2; ++n) _Pragma("unroll") for (int k = 0; k < 2; ++k) \
;       acc[ai][bj][m][n] = __builtin_amdgcn_mfma_f32_16x16x32_bf16(At[m][k], Bq[n][k], acc[ai][bj][m][n], 0, 0, 0); \
;     __builtin_amdgcn_s_setprio(0); } while (0)
; #define WAIT_V(n) asm volatile("s_waitcnt vmcnt(" #n ")" ::: "memory")
; #define WAIT_L(n) asm volatile("s_waitcnt lgkmcnt(" #n ")" ::: "memory")
; #define BAR __builtin_amdgcn_s_barrier()
; __device__ __forceinline__ void gemm256(const u16* __restrict__ A, int lda, const u16* __restrict__ Bt, int ldb, int K,
;                                         f32x4 (&acc)[2][2][4][2], const int g_wid) {
;     ...
;   { LDB(B0, 1, 0); LDA(At, 1, 0); WAIT_V(2); BAR; WAIT_L(0); MMA(0, 0, At, B0); BAR;
;     LDB(B1, 1, 1); WAIT_V(0); BAR; WAIT_L(0); MMA(0, 1, At, B1); BAR;
;     LDA(At, 1, 1); BAR; WAIT_L(0); MMA(1, 0, At, B0); MMA(1, 1, At, B1); BAR; }
;   if (wr == 0) BAR;
	ds_read_b128 v[130:133], v160
	ds_read_b128 v[238:241], v160 offset:1024
	ds_read_b128 v[242:245], v160 offset:2048
	ds_read_b128 v[246:249], v160 offset:3072
	s_waitcnt vmcnt(0)
	s_barrier
	s_waitcnt lgkmcnt(0)
	v_mfma_f32_16x16x32_bf16 v[26:29], v[18:21], v[130:133], v[218:221]
	v_mfma_f32_16x16x32_bf16 v[18:21], v[18:21], v[242:245], v[178:181]
	v_mfma_f32_16x16x32_bf16 v[58:61], v[22:25], v[238:241], v[26:29]
	v_mfma_f32_16x16x32_bf16 v[26:29], v[22:25], v[246:249], v[18:21]
	v_mfma_f32_16x16x32_bf16 v[18:21], v[30:33], v[130:133], v[182:185]
	v_mfma_f32_16x16x32_bf16 v[62:65], v[50:53], v[238:241], v[18:21]
	v_mfma_f32_16x16x32_bf16 v[18:21], v[30:33], v[242:245], v[186:189]
	v_mfma_f32_16x16x32_bf16 v[30:33], v[50:53], v[246:249], v[18:21]
	v_mfma_f32_16x16x32_bf16 v[18:21], v[198:201], v[130:133], v[78:81]
	v_mfma_f32_16x16x32_bf16 v[54:57], v[202:205], v[238:241], v[18:21]
	v_mfma_f32_16x16x32_bf16 v[18:21], v[198:201], v[242:245], v[74:77]
	v_mfma_f32_16x16x32_bf16 v[22:25], v[202:205], v[246:249], v[18:21]
	v_mfma_f32_16x16x32_bf16 v[18:21], v[210:213], v[130:133], v[70:73]
	v_mfma_f32_16x16x32_bf16 v[50:53], v[214:217], v[238:241], v[18:21]
	v_mfma_f32_16x16x32_bf16 v[18:21], v[210:213], v[242:245], v[66:69]
	v_mfma_f32_16x16x32_bf16 v[18:21], v[214:217], v[246:249], v[18:21]
	s_barrier
	ds_read_b128 v[176:179], v145 offset:49152
	ds_read_b128 v[180:183], v145 offset:50176
	ds_read_b128 v[184:187], v144 offset:49152
	ds_read_b128 v[144:147], v144 offset:50176
	ds_read_b128 v[198:201], v143 offset:49152
	ds_read_b128 v[202:205], v143 offset:50176
	ds_read_b128 v[210:213], v142 offset:49152
	ds_read_b128 v[214:217], v142 offset:50176
	s_barrier
	s_waitcnt lgkmcnt(0)
	v_mfma_f32_16x16x32_bf16 v[66:69], v[176:179], v[6:9], v[206:209]
	v_mfma_f32_16x16x32_bf16 v[110:113], v[180:183], v[10:13], v[66:69]
	v_mfma_f32_16x16x32_bf16 v[66:69], v[176:179], v[14:17], v[222:225]
	v_mfma_f32_16x16x32_bf16 v[78:81], v[180:183], v[194:197], v[66:69]
	v_mfma_f32_16x16x32_bf16 v[66:69], v[184:187], v[6:9], v[226:229]
	v_mfma_f32_16x16x32_bf16 v[46:49], v[198:201], v[6:9], v[46:49]
	v_mfma_f32_16x16x32_bf16 v[6:9], v[210:213], v[6:9], v[38:41]
	v_mfma_f32_16x16x32_bf16 v[106:109], v[144:147], v[10:13], v[66:69]
	v_mfma_f32_16x16x32_bf16 v[66:69], v[184:187], v[14:17], v[230:233]
	v_mfma_f32_16x16x32_bf16 v[42:45], v[198:201], v[14:17], v[42:45]
	v_mfma_f32_16x16x32_bf16 v[98:101], v[214:217], v[10:13], v[6:9]
	v_mfma_f32_16x16x32_bf16 v[6:9], v[210:213], v[14:17], v[34:37]
	v_mfma_f32_16x16x32_bf16 v[74:77], v[144:147], v[194:197], v[66:69]
	v_mfma_f32_16x16x32_bf16 v[102:105], v[202:205], v[10:13], v[46:49]
	v_mfma_f32_16x16x32_bf16 v[70:73], v[202:205], v[194:197], v[42:45]
	v_mfma_f32_16x16x32_bf16 v[66:69], v[214:217], v[194:197], v[6:9]
	v_mfma_f32_16x16x32_bf16 v[6:9], v[176:179], v[130:133], v[134:137]
	v_mfma_f32_16x16x32_bf16 v[46:49], v[180:183], v[238:241], v[6:9]
	v_mfma_f32_16x16x32_bf16 v[6:9], v[176:179], v[242:245], v[138:141]
	v_mfma_f32_16x16x32_bf16 v[14:17], v[180:183], v[246:249], v[6:9]
	v_mfma_f32_16x16x32_bf16 v[6:9], v[184:187], v[130:133], v[162:165]
	v_mfma_f32_16x16x32_bf16 v[42:45], v[144:147], v[238:241], v[6:9]
	v_mfma_f32_16x16x32_bf16 v[6:9], v[184:187], v[242:245], v[168:171]
	v_mfma_f32_16x16x32_bf16 v[10:13], v[144:147], v[246:249], v[6:9]
	v_mfma_f32_16x16x32_bf16 v[6:9], v[198:201], v[130:133], v[234:237]
	v_mfma_f32_16x16x32_bf16 v[38:41], v[202:205], v[238:241], v[6:9]
	v_mfma_f32_16x16x32_bf16 v[6:9], v[198:201], v[242:245], v[190:193]
	v_mfma_f32_16x16x32_bf16 v[34:37], v[210:213], v[130:133], v[172:175]
	v_mfma_f32_16x16x32_bf16 v[2:5], v[210:213], v[242:245], v[2:5]
	v_mfma_f32_16x16x32_bf16 v[6:9], v[202:205], v[246:249], v[6:9]
	v_mfma_f32_16x16x32_bf16 v[34:37], v[214:217], v[238:241], v[34:37]
	v_mfma_f32_16x16x32_bf16 v[2:5], v[214:217], v[246:249], v[2:5]
	s_setprio 0
	s_movk_i32 s3, 0x100
	v_cmp_gt_u32_e32 vcc, s3, v0
	s_barrier
	s_and_saveexec_b64 s[10:11], vcc
	s_cbranch_execz .LBB0_491
	s_barrier
